# block-local optimizer on compiler f32 code: scalarise packed ops with a dead half, dead-code removal, copy forwarding, split packed ops fed by register copies (each block symbolically verified)
# speedup vs baseline: 1.1462x; 1.0160x over previous
.LBB0_116:
	s_or_b64 exec, exec, s[50:51]
	v_mov_b32_e32 v1, v6
	s_barrier
	s_waitcnt vmcnt(0)
	v_mul_f32_e32 v4, v15, v14
	v_ashrrev_i32_e32 v2, 31, v1
	v_lshrrev_b32_e32 v2, 24, v2
	v_and_b32_e32 v17, 0xff, v1
	v_add_lshl_u32 v1, v1, v2, 4
	v_and_or_b32 v1, v1, s87, v17
	v_ashrrev_i32_e32 v2, 4, v1
	v_lshlrev_b32_e32 v1, 3, v1
	v_lshl_add_u32 v82, v2, 3, v1
	v_pk_add_f32 v[2:3], v[4:5], 0 op_sel_hi:[1,0]
	v_cvt_f32_i32_e32 v1, v17
	v_sub_f32_e32 v16, 0, v5
	v_add_f32_e32 v22, v2, v3
	v_mov_b32_e32 v23, v0
	v_add_f32_e32 v1, v1, v1
	v_mul_f32_e32 v1, 0x39800000, v1
	v_mul_f32_e32 v1, 0.5, v1
	v_readlane_b32 s4, v245, 24
	v_sin_f32_e32 v28, v1
	ds_write_b64 v82, v[22:23]
	v_sub_f32_e64 v23, 0, -v5
	v_mul_f32_e64 v22, -v16, s21
	v_readlane_b32 s5, v245, 25
	v_cos_f32_e32 v34, v1
	s_nop 2
	v_add_f32_e32 v36, s4, v22
	v_mul_f32_e32 v23, s71, v23
	v_sub_f32_e32 v38, 0, v23
	v_add_f32_e32 v22, v36, v2
	v_add_f32_e32 v23, v23, v0
	v_xor_b32_e32 v35, 0x80000000, v28
	v_pk_mul_f32 v[44:45], v[22:23], v[28:29] op_sel_hi:[1,0]
	v_sub_f32_e32 v42, 0, v23
	v_fma_f32 v46, v22, v34, v45
	v_fma_f32 v47, v23, v34, -v44
	v_mov_b32_e32 v29, v34
	v_mul_f32_e32 v22, v28, v28
	v_mul_f32_e32 v23, v29, v35
	v_sub_f32_e32 v18, 0, v3
	v_pk_fma_f32 v[44:45], v[34:35], v[34:35], v[22:23] op_sel_hi:[0,1,1] neg_lo:[0,0,1] neg_hi:[0,0,1]
	v_pk_fma_f32 v[22:23], v[34:35], v[34:35], v[22:23] op_sel_hi:[0,1,1]
	v_fma_f32 v20, v18, s3, 0
	v_pk_mov_b32 v[48:49], v[22:23], v[44:45] op_sel:[1,0]
	v_add_f32_e32 v26, v2, v20
	ds_write_b64 v82, v[46:47] offset:2176
	v_mov_b32_e32 v46, v44
	v_mov_b32_e32 v47, v23
	v_mul_f32_e32 v27, v34, v44
	v_pk_mul_f32 v[50:51], v[20:21], v[48:49] op_sel_hi:[0,1]
	v_fma_f32 v52, v26, v44, -v50
	v_fma_f32 v53, v26, v47, v51
	v_pk_mul_f32 v[48:49], v[48:49], v[22:23] op_sel:[0,1]
	ds_write_b64 v82, v[52:53] offset:4352
	v_mov_b32_e32 v179, v44
	v_pk_fma_f32 v[52:53], v[44:45], v[46:47], v[48:49] op_sel_hi:[0,1,1] neg_lo:[0,0,1] neg_hi:[0,0,1]
	v_pk_fma_f32 v[44:45], v[44:45], v[46:47], v[48:49] op_sel_hi:[0,1,1]
	v_mov_b32_e32 v48, v52
	v_mov_b32_e32 v49, v45
	v_pk_mul_f32 v[66:67], v[48:49], v[44:45] op_sel:[0,1]
	v_mul_f32_e32 v22, v34, v45
	v_pk_fma_f32 v[68:69], v[52:53], v[48:49], v[66:67] op_sel:[0,0,1] op_sel_hi:[0,1,0] neg_lo:[0,0,1] neg_hi:[0,0,1]
	v_pk_fma_f32 v[66:67], v[52:53], v[48:49], v[66:67] op_sel:[0,0,1] op_sel_hi:[0,1,0]
	v_pk_mov_b32 v[72:73], v[66:67], v[68:69] op_sel:[1,0]
	v_mov_b32_e32 v70, v68
	v_mov_b32_e32 v71, v67
	v_pk_add_f32 v[76:77], v[2:3], v[2:3] op_sel:[0,1] op_sel_hi:[0,1] neg_lo:[0,1] neg_hi:[0,1]
	v_pk_mul_f32 v[78:79], v[72:73], 0 op_sel_hi:[1,0]
	v_fma_f32 v17, v18, s20, 0
	v_pk_fma_f32 v[54:55], v[28:29], v[48:49], v[22:23] op_sel_hi:[1,1,0] neg_lo:[1,0,0] neg_hi:[1,0,0]
	v_mul_f32_e32 v22, v23, v68
	v_fma_f32 v68, v76, v68, -v78
	v_fma_f32 v69, v77, v71, v79
	v_add_f32_e32 v30, v2, v17
	v_sub_f32_e32 v32, v2, v17
	v_mul_f32_e32 v19, v28, v23
	v_mov_b32_e32 v17, v28
	v_mul_f32_e32 v39, v28, v45
	v_pk_mul_f32 v[28:29], v[28:29], v[70:71] op_sel_hi:[0,1]
	ds_write_b64 v82, v[68:69] offset:17408
	v_fma_f32 v68, v34, v70, v29
	v_fma_f32 v29, v34, v71, -v28
	v_sub_f32_e64 v24, 0, -v3
	v_mul_f32_e32 v25, v34, v52
	v_pk_mov_b32 v[56:57], v[44:45], v[52:53] op_sel:[1,0]
	v_mov_b32_e32 v35, v29
	v_sub_f32_e32 v40, v2, v36
	v_mul_f32_e32 v1, v34, v23
	v_pk_mul_f32 v[58:59], v[24:25], v[56:57] op_sel_hi:[0,1]
	v_mul_f32_e32 v28, v42, v29
	v_mul_f32_e32 v29, v42, v68
	v_fma_f32 v60, v2, v52, -v58
	v_fma_f32 v61, v2, v49, v59
	v_pk_mul_f32 v[74:75], v[46:47], v[70:71]
	v_fma_f32 v42, v40, v68, -v28
	v_fma_f32 v43, v40, v35, v29
	v_pk_mul_f32 v[58:59], v[46:47], v[44:45] op_sel:[0,1]
	v_mov_b32_e32 v35, v20
	ds_write_b64 v82, v[60:61] offset:8704
	v_fma_f32 v60, v46, v52, -v59
	v_pk_fma_f32 v[58:59], v[46:47], v[52:53], v[58:59] op_sel:[0,0,1] op_sel_hi:[1,0,0]
	v_sub_f32_e32 v20, v74, v75
	v_sub_f32_e32 v21, v0, v35
	v_sub_f32_e32 v28, 0, v21
	v_mov_b32_e32 v63, v59
	v_mul_f32_e32 v29, v28, v60
	v_mul_f32_e32 v28, v28, v59
	v_fma_f32 v40, v30, v60, -v28
	v_fma_f32 v41, v30, v63, v29
	v_fma_f32 v22, v46, v72, v22
	v_sub_f32_e32 v28, v2, v35
	v_sub_f32_e32 v29, v74, v75
	v_mov_b32_e32 v30, v22
	v_mul_f32_e32 v23, v28, v22
	v_mul_f32_e32 v22, v30, v21
	v_add_f32_e32 v24, v2, v38
	v_add_f32_e32 v25, v25, v39
	v_fma_f32 v30, v20, v28, -v22
	v_fma_f32 v31, v21, v29, v23
	v_pk_mul_f32 v[28:29], v[44:45], v[70:71] op_sel:[1,0]
	ds_write_b64 v82, v[30:31] offset:21760
	v_fma_f32 v30, v52, v70, -v29
	v_fma_f32 v29, v52, v71, v28
	v_mov_b32_e32 v35, v29
	v_mul_f32_e32 v46, v67, v54
	v_mul_f32_e32 v78, v70, v25
	v_mul_f32_e32 v28, v18, v29
	v_mul_f32_e32 v29, v18, v30
	v_fma_f32 v30, v2, v30, -v28
	v_fma_f32 v31, v2, v35, v29
	v_sub_f32_e32 v28, v78, v46
	v_sub_f32_e32 v29, v0, v36
	ds_write_b64 v82, v[30:31] offset:26112
	v_sub_f32_e32 v30, 0, v29
	v_mov_b32_e32 v31, v24
	v_pk_mul_f32 v[34:35], v[30:31], v[54:55] op_sel_hi:[1,0]
	v_pk_mov_b32 v[30:31], v[24:25], v[30:31] op_sel:[1,0]
	v_mul_f32_e32 v66, v67, v25
	v_fma_f32 v36, v24, v30, -v34
	v_fma_f32 v37, v25, v31, v35
	v_fma_f32 v80, v70, v54, v66
	v_sub_f32_e32 v24, v2, v38
	v_sub_f32_e32 v25, v78, v46
	v_readlane_b32 s4, v245, 26
	v_mul_f32_e32 v30, v80, v29
	v_mul_f32_e32 v31, v24, v80
	v_pk_fma_f32 v[50:51], v[16:17], v[178:179], v[0:1] neg_lo:[1,0,0] neg_hi:[1,0,0]
	v_fma_f32 v34, v28, v24, -v30
	v_fma_f32 v35, v29, v25, v31
	v_pk_mul_f32 v[24:25], v[72:73], v[58:59] op_sel:[0,1]
	v_fma_f32 v18, v16, s4, 0
	v_fma_f32 v28, v70, v60, -v24
	v_fma_f32 v25, v71, v60, v25
	v_mov_b32_e32 v31, v25
	v_pk_mul_f32 v[56:57], v[56:57], v[50:51] op_sel:[0,1]
	v_mul_f32_e32 v20, v21, v25
	v_mul_f32_e32 v21, v21, v28
	v_mul_f32_e32 v77, v51, v71
	v_fma_f32 v24, v32, v28, -v20
	v_fma_f32 v25, v32, v31, v21
	v_add_f32_e32 v20, v2, v18
	v_add_f32_e32 v21, v27, v19
	ds_write_b64 v82, v[24:25] offset:30464
	v_fma_f32 v24, v48, v21, -v56
	v_fma_f32 v27, v49, v21, v57
	v_mov_b32_e32 v28, v24
	v_mov_b32_e32 v29, v27
	v_pk_mul_f32 v[32:33], v[70:71], v[28:29]
	ds_write_b64 v82, v[34:35] offset:28288
	v_mul_f32_e64 v17, -v5, s4
	v_mul_f32_e32 v30, v21, v70
	ds_write_b64 v82, v[36:37] offset:10880
	v_sub_f32_e32 v34, v32, v33
	v_sub_f32_e32 v35, v0, v17
	v_sub_f32_e32 v22, v30, v77
	v_sub_f32_e32 v23, v0, v50
	v_sub_f32_e32 v16, 0, v35
	v_mul_f32_e32 v36, v50, v51
	v_mul_f32_e32 v37, v51, v20
	v_pk_mov_b32 v[38:39], v[20:21], v[50:51] op_sel:[1,0]
	ds_write_b64 v82, v[40:41] offset:13056
	v_mov_b32_e32 v1, v4
	v_mov_b32_e32 v4, v17
	v_fma_f32 v40, v20, v38, -v36
	v_fma_f32 v41, v21, v39, v37
	v_mul_f32_e32 v17, v16, v24
	v_mul_f32_e32 v16, v16, v27
	v_mul_f32_e32 v26, v21, v67
	v_fma_f32 v14, v15, v14, v23
	v_fma_f32 v20, v51, v70, v26
	v_fma_f32 v24, v14, v24, -v16
	v_fma_f32 v25, v14, v29, v17
	v_sub_f32_e32 v2, v2, v18
	v_sub_f32_e32 v3, v30, v77
	v_mul_f32_e32 v14, v20, v23
	v_mul_f32_e32 v15, v2, v20
	v_pk_mul_f32 v[26:27], v[72:73], v[28:29]
	v_fma_f32 v16, v22, v2, -v14
	v_fma_f32 v17, v23, v3, v15
	v_sub_f32_e32 v4, v0, v4
	v_sub_f32_e32 v5, v1, v23
	v_pk_mov_b32 v[36:37], v[0:1], v[32:33] op_sel:[1,0]
	v_pk_add_f32 v[2:3], v[26:27], v[26:27] op_sel:[0,1] op_sel_hi:[0,1]
	v_sub_f32_e32 v32, v36, v23
	v_sub_f32_e32 v33, v37, v33
	v_pk_mul_f32 v[2:3], v[4:5], v[2:3]
	v_mov_b32_e32 v1, v12
	v_fma_f32 v4, v34, v32, -v2
	v_fma_f32 v5, v35, v33, v3
	ds_write_b64 v82, v[42:43] offset:19584
	ds_write_b64 v82, v[40:41] offset:6528
	ds_write_b64 v82, v[24:25] offset:15232
	ds_write_b64 v82, v[16:17] offset:23936
	ds_write_b64 v82, v[4:5] offset:32640
	s_waitcnt lgkmcnt(0)
	s_barrier
	s_mov_b32 s54, s71
	v_ashrrev_i32_e32 v2, 31, v1
	v_lshrrev_b32_e32 v2, 28, v2
	v_and_b32_e32 v70, 15, v1
	v_add_u32_e32 v1, v1, v2
	v_ashrrev_i32_e32 v1, 4, v1
	v_lshlrev_b32_e32 v2, 11, v1
	v_lshl_add_u32 v1, v1, 7, v2
	v_lshl_or_b32 v1, v70, 3, v1
	ds_read2_b64 v[20:23], v1 offset1:17
	ds_read2_b64 v[24:27], v1 offset0:68 offset1:85
	ds_read2_b64 v[28:31], v1 offset0:136 offset1:153
	ds_read2_b64 v[32:35], v1 offset0:170 offset1:187
	ds_read2_b64 v[36:39], v1 offset0:204 offset1:221
	ds_read2_b64 v[40:43], v1 offset0:238 offset1:255
	ds_read2_b64 v[44:47], v1 offset0:34 offset1:51
	ds_read2_b64 v[48:51], v1 offset0:102 offset1:119
	s_waitcnt lgkmcnt(5)
	v_pk_add_f32 v[18:19], v[28:29], v[20:21]
	s_waitcnt lgkmcnt(2)
	v_pk_mov_b32 v[68:69], v[34:35], v[42:43] op_sel:[1,0]
	s_waitcnt lgkmcnt(1)
	v_pk_add_f32 v[64:65], v[46:47], v[34:35]
	s_waitcnt lgkmcnt(0)
	v_pk_add_f32 v[66:67], v[50:51], v[42:43]
	v_mov_b32_e32 v35, v43
	v_pk_add_f32 v[42:43], v[64:65], v[66:67] neg_lo:[0,1] neg_hi:[0,1]
	v_sub_f32_e32 v68, v47, v68
	v_sub_f32_e32 v69, v50, v69
	v_pk_add_f32 v[16:17], v[64:65], v[66:67]
	v_mul_f32_e32 v64, 0x3f3504f3, v43
	v_mul_f32_e32 v67, 0xbf3504f3, v43
	v_cvt_f32_i32_e32 v43, v70
	v_sub_f32_e32 v34, v46, v34
	v_sub_f32_e32 v35, v51, v35
	v_pk_add_f32 v[28:29], v[20:21], v[28:29] neg_lo:[0,1] neg_hi:[0,1]
	v_add_f32_e32 v43, v43, v43
	v_pk_add_f32 v[20:21], v[24:25], v[36:37] neg_lo:[0,1] neg_hi:[0,1]
	v_pk_add_f32 v[52:53], v[36:37], v[24:25]
	v_pk_add_f32 v[54:55], v[22:23], v[30:31]
	v_pk_add_f32 v[56:57], v[26:27], v[38:39]
	v_sub_f32_e32 v46, v34, v35
	v_mul_f32_e32 v43, 0x3b800000, v43
	v_pk_mov_b32 v[24:25], v[20:21], v[20:21] op_sel:[1,0]
	v_add_f32_e32 v36, v28, v21
	v_sub_f32_e32 v37, v29, v20
	v_pk_add_f32 v[34:35], v[34:35], v[34:35] op_sel:[0,1] op_sel_hi:[0,1]
	s_mov_b32 s55, s21
	v_pk_add_f32 v[4:5], v[54:55], v[56:57]
	v_pk_add_f32 v[58:59], v[44:45], v[32:33]
	v_pk_add_f32 v[60:61], v[48:49], v[40:41]
	v_pk_add_f32 v[54:55], v[54:55], v[56:57] neg_lo:[0,1] neg_hi:[0,1]
	v_mul_f32_e32 v43, 0.5, v43
	v_pk_add_f32 v[20:21], v[68:69], v[68:69] op_sel:[0,1] op_sel_hi:[0,1] neg_lo:[0,1] neg_hi:[0,1]
	s_mov_b32 s70, s21
	v_pk_mul_f32 v[34:35], v[34:35], s[54:55]
	v_pk_add_f32 v[14:15], v[58:59], v[60:61]
	v_pk_add_f32 v[62:63], v[58:59], v[60:61] neg_lo:[0,1] neg_hi:[0,1]
	v_add_f32_e32 v50, v68, v69
	v_pk_mul_f32 v[56:57], v[54:55], s[20:21] op_sel_hi:[1,0]
	v_mul_f32_e32 v42, 0x3f3504f3, v42
	v_sin_f32_e32 v58, v43
	s_nop 1
	v_cos_f32_e32 v76, v43
	s_nop 1
	v_fma_f32 v68, v20, s70, v34
	v_fma_f32 v69, v21, s71, -v35
	v_pk_add_f32 v[2:3], v[18:19], v[52:53]
	v_mov_b32_e32 v20, v18
	v_sub_f32_e32 v18, v64, v42
	v_sub_f32_e32 v19, v19, v53
	v_sub_f32_e32 v20, v20, v52
	v_sub_f32_e32 v21, v57, v56
	v_mov_b32_e32 v35, v42
	v_pk_add_f32 v[42:43], v[18:19], v[62:63] op_sel:[1,0] op_sel_hi:[0,1]
	v_mov_b32_e32 v53, v62
	v_sub_f32_e32 v34, v59, v61
	v_sub_f32_e32 v35, v67, v35
	v_sub_f32_e32 v62, v44, v32
	v_sub_f32_e32 v63, v22, v30
	v_sub_f32_e32 v64, v49, v41
	v_sub_f32_e32 v65, v27, v39
	v_mul_f32_e32 v78, 0x3f6c835e, v50
	v_mul_f32_e32 v79, 0x3ec3ef15, v46
	v_sub_f32_e32 v22, v45, v33
	v_sub_f32_e32 v23, v23, v31
	v_sub_f32_e32 v27, v26, v38
	v_sub_f32_e32 v26, v48, v40
	v_pk_add_f32 v[32:33], v[62:63], v[64:65] neg_lo:[0,1] neg_hi:[0,1]
	v_readlane_b32 s5, v245, 27
	v_pk_fma_f32 v[54:55], v[54:55], s[20:21], v[56:57] op_sel:[0,0,1] op_sel_hi:[1,0,0]
	v_pk_add_f32 v[66:67], v[62:63], v[64:65]
	v_pk_add_f32 v[30:31], v[22:23], v[26:27] neg_lo:[0,1] neg_hi:[0,1]
	v_pk_add_f32 v[22:23], v[22:23], v[26:27]
	s_mov_b32 s56, s3
	s_mov_b32 s57, s76
	v_mov_b32_e32 v39, v29
	v_mov_b32_e32 v27, v25
	v_mov_b32_e32 v52, v54
	v_pk_add_f32 v[54:55], v[54:55], v[18:19] neg_lo:[0,1] neg_hi:[0,1]
	v_mul_f32_e32 v26, 0x3ec3ef15, v33
	v_pk_mul_f32 v[40:41], v[32:33], s[56:57]
	s_mov_b32 s56, s20
	s_mov_b32 s57, s71
	v_mul_f32_e32 v33, s5, v32
	v_mul_f32_e32 v32, s4, v50
	v_sub_f32_e32 v24, v28, v24
	v_sub_f32_e32 v25, v79, v78
	v_pk_mul_f32 v[28:29], v[66:67], s[70:71] op_sel:[1,0]
	v_add_f32_e32 v56, v18, v52
	v_sub_f32_e32 v53, v19, v53
	v_pk_add_f32 v[18:19], v[42:43], v[54:55]
	v_mul_f32_e32 v38, 0x3f6c835e, v23
	v_mul_f32_e32 v43, 0x3f3504f3, v66
	v_mul_f32_e32 v44, 0x3f3504f3, v30
	v_pk_fma_f32 v[40:41], v[22:23], s[56:57], v[40:41]
	v_fma_f32 v23, v22, s31, v33
	v_fma_f32 v22, v46, s30, v32
	v_fma_f32 v32, v31, s54, v28
	v_fma_f32 v33, v31, s55, -v29
	v_pk_add_f32 v[26:27], v[38:39], v[26:27]
	v_add_f32_e32 v28, v44, v43
	v_fma_f32 v29, v30, s20, -v43
	v_pk_add_f32 v[30:31], v[36:37], v[28:29]
	v_pk_add_f32 v[38:39], v[32:33], v[68:69]
	v_xor_b32_e32 v77, 0x80000000, v58
	v_pk_add_f32 v[44:45], v[38:39], v[30:31]
	v_pk_add_f32 v[70:71], v[2:3], v[14:15]
	v_pk_mul_f32 v[50:51], v[58:59], v[44:45] op_sel_hi:[0,1]
	v_fma_f32 v62, v76, v44, v51
	v_fma_f32 v63, v76, v45, -v50
	v_mov_b32_e32 v59, v76
	v_pk_add_f32 v[72:73], v[4:5], v[16:17]
	v_mul_f32_e32 v44, v58, v58
	v_mul_f32_e32 v45, v59, v77
	v_pk_add_f32 v[74:75], v[72:73], v[70:71]
	v_pk_fma_f32 v[50:51], v[76:77], v[76:77], v[44:45] op_sel_hi:[0,1,1] neg_lo:[0,0,1] neg_hi:[0,0,1]
	v_pk_fma_f32 v[44:45], v[76:77], v[76:77], v[44:45] op_sel_hi:[0,1,1]
	v_pk_add_f32 v[60:61], v[20:21], v[34:35]
	ds_write2_b64 v1, v[74:75], v[62:63] offset1:17
	v_pk_add_f32 v[20:21], v[20:21], v[34:35] neg_lo:[0,1] neg_hi:[0,1]
	v_add_f32_e32 v34, v60, v56
	v_add_f32_e32 v35, v61, v53
	v_mov_b32_e32 v62, v50
	v_mov_b32_e32 v63, v45
	v_mul_f32_e32 v74, v45, v45
	v_mul_f32_e32 v75, v45, v50
	v_pk_mul_f32 v[44:45], v[34:35], v[44:45] op_sel:[1,1] op_sel_hi:[0,1]
	v_pk_fma_f32 v[78:79], v[50:51], v[62:63], v[74:75] op_sel_hi:[0,1,1] neg_lo:[0,0,1] neg_hi:[0,0,1]
	v_pk_fma_f32 v[74:75], v[50:51], v[62:63], v[74:75] op_sel_hi:[0,1,1]
	v_fma_f32 v88, v34, v50, -v44
	v_fma_f32 v89, v35, v50, v45
	v_pk_mul_f32 v[44:45], v[62:63], v[74:75] op_sel:[0,1]
	v_pk_add_f32 v[32:33], v[32:33], v[68:69] neg_lo:[0,1] neg_hi:[0,1]
	v_fma_f32 v50, v62, v78, -v45
	v_fma_f32 v45, v63, v78, v44
	v_sub_f32_e32 v42, v42, v54
	v_mov_b32_e32 v69, v45
	v_mov_b32_e32 v77, v58
	v_mov_b32_e32 v80, v78
	v_mov_b32_e32 v81, v75
	v_pk_add_f32 v[90:91], v[20:21], v[20:21] op_sel:[0,1] op_sel_hi:[0,1]
	v_mul_f32_e32 v43, v42, v50
	v_mul_f32_e32 v42, v42, v45
	v_pk_mul_f32 v[64:65], v[76:77], v[62:63]
	v_pk_mul_f32 v[66:67], v[58:59], v[62:63]
	v_mov_b32_e32 v68, v50
	v_fma_f32 v44, v90, v50, -v42
	v_pk_mul_f32 v[50:51], v[80:81], v[74:75] op_sel:[0,1]
	v_pk_add_f32 v[30:31], v[30:31], v[38:39] neg_lo:[0,1] neg_hi:[0,1]
	v_pk_add_f32 v[38:39], v[40:41], v[24:25]
	v_pk_add_f32 v[46:47], v[26:27], v[22:23]
	v_fma_f32 v45, v91, v69, v43
	v_pk_fma_f32 v[54:55], v[78:79], v[80:81], v[50:51] op_sel:[0,0,1] op_sel_hi:[0,1,0] neg_lo:[0,0,1] neg_hi:[0,0,1]
	v_pk_fma_f32 v[50:51], v[78:79], v[80:81], v[50:51] op_sel:[0,0,1] op_sel_hi:[0,1,0]
	v_mov_b32_e32 v92, v64
	v_pk_mov_b32 v[64:65], v[64:65], v[66:67] op_sel:[1,0]
	v_pk_add_f32 v[48:49], v[38:39], v[46:47]
	v_pk_add_f32 v[42:43], v[70:71], v[72:73] neg_lo:[0,1] neg_hi:[0,1]
	v_pk_mov_b32 v[72:73], v[50:51], v[54:55] op_sel:[1,0]
	v_add_f32_e32 v66, v92, v64
	v_sub_f32_e32 v64, v92, v64
	v_sub_f32_e32 v65, v67, v65
	v_pk_mul_f32 v[82:83], v[76:77], v[80:81]
	v_pk_mul_f32 v[84:85], v[58:59], v[80:81]
	v_pk_add_f32 v[28:29], v[36:37], v[28:29] neg_lo:[0,1] neg_hi:[0,1]
	v_mov_b32_e32 v70, v54
	v_mov_b32_e32 v71, v51
	v_pk_mul_f32 v[58:59], v[58:59], v[72:73] op_sel_hi:[0,1]
	v_pk_mul_f32 v[94:95], v[48:49], v[64:65] op_sel:[0,1]
	v_pk_mov_b32 v[86:87], v[74:75], v[78:79] op_sel:[1,0]
	v_pk_add_f32 v[34:35], v[28:29], v[32:33] op_sel:[0,1] op_sel_hi:[1,0]
	v_pk_add_f32 v[28:29], v[28:29], v[32:33] op_sel:[0,1] op_sel_hi:[1,0] neg_lo:[0,1] neg_hi:[0,1]
	v_fma_f32 v74, v76, v70, v58
	v_fma_f32 v59, v76, v71, -v59
	v_fma_f32 v96, v48, v66, -v95
	v_fma_f32 v97, v49, v66, v94
	v_mov_b32_e32 v98, v82
	v_mov_b32_e32 v99, v85
	v_pk_mov_b32 v[82:83], v[82:83], v[84:85] op_sel:[1,0]
	v_mov_b32_e32 v77, v59
	v_pk_mul_f32 v[48:49], v[80:81], v[64:65] op_sel:[0,1]
	v_pk_add_f32 v[84:85], v[98:99], v[82:83]
	v_sub_f32_e32 v83, v99, v83
	v_mov_b32_e32 v33, v29
	v_mov_b32_e32 v93, v65
	v_fma_f32 v64, v80, v66, -v49
	v_fma_f32 v49, v81, v66, v48
	v_mul_f32_e32 v36, v29, v83
	v_mul_f32_e32 v37, v34, v83
	v_mul_f32_e32 v58, v31, v59
	v_mul_f32_e32 v59, v31, v74
	v_mov_b32_e32 v92, v66
	v_mov_b32_e32 v66, v64
	v_mov_b32_e32 v67, v49
	v_mov_b32_e32 v98, v84
	v_mov_b32_e32 v99, v83
	v_fma_f32 v82, v34, v84, -v36
	v_fma_f32 v83, v33, v84, v37
	v_fma_f32 v74, v30, v74, -v58
	v_fma_f32 v75, v30, v77, v59
	v_pk_mul_f32 v[50:51], v[42:43], v[50:51] op_sel:[1,1] op_sel_hi:[0,1]
	v_pk_mul_f32 v[90:91], v[62:63], v[70:71]
	v_pk_mul_f32 v[62:63], v[62:63], v[72:73]
	ds_write2_b64 v1, v[88:89], v[96:97] offset0:34 offset1:51
	v_pk_mul_f32 v[88:89], v[92:93], v[70:71]
	v_pk_mul_f32 v[92:93], v[92:93], v[72:73]
	v_pk_mul_f32 v[94:95], v[80:81], v[70:71]
	v_pk_mul_f32 v[96:97], v[80:81], v[72:73]
	v_pk_mul_f32 v[32:33], v[70:71], v[98:99]
	v_pk_mul_f32 v[36:37], v[72:73], v[98:99]
	v_pk_mul_f32 v[30:31], v[70:71], v[68:69]
	v_pk_mul_f32 v[58:59], v[72:73], v[68:69]
	v_pk_mul_f32 v[68:69], v[70:71], v[66:67]
	v_pk_mul_f32 v[70:71], v[72:73], v[66:67]
	v_fma_f32 v72, v42, v54, -v50
	v_fma_f32 v73, v43, v54, v51
	v_sub_f32_e32 v42, v60, v56
	v_sub_f32_e32 v43, v53, v61
	v_pk_add_f32 v[50:51], v[62:63], v[62:63] op_sel:[0,1] op_sel_hi:[0,1]
	v_pk_mul_f32 v[50:51], v[42:43], v[50:51] op_sel:[1,0] op_sel_hi:[0,1]
	v_pk_add_f32 v[52:53], v[90:91], v[90:91] op_sel:[0,1] op_sel_hi:[0,1] neg_lo:[0,1] neg_hi:[0,1]
	v_fma_f32 v54, v42, v52, -v50
	v_fma_f32 v55, v43, v53, v51
	v_pk_add_f32 v[2:3], v[2:3], v[14:15] neg_lo:[0,1] neg_hi:[0,1]
	v_mov_b32_e32 v43, v47
	v_sub_f32_e32 v38, v38, v46
	v_sub_f32_e32 v39, v43, v39
	v_pk_add_f32 v[42:43], v[92:93], v[92:93] op_sel:[0,1] op_sel_hi:[0,1]
	v_pk_add_f32 v[4:5], v[4:5], v[16:17] neg_lo:[0,1] neg_hi:[0,1]
	v_pk_mul_f32 v[42:43], v[38:39], v[42:43] op_sel:[1,0] op_sel_hi:[0,1]
	v_pk_add_f32 v[46:47], v[88:89], v[88:89] op_sel:[0,1] op_sel_hi:[0,1] neg_lo:[0,1] neg_hi:[0,1]
	v_pk_add_f32 v[14:15], v[2:3], v[4:5] op_sel:[0,1] op_sel_hi:[1,0]
	v_pk_add_f32 v[2:3], v[2:3], v[4:5] op_sel:[0,1] op_sel_hi:[1,0] neg_lo:[0,1] neg_hi:[0,1]
	v_fma_f32 v50, v38, v46, -v42
	v_fma_f32 v51, v39, v47, v43
	v_pk_mul_f32 v[16:17], v[2:3], v[86:87] op_sel:[1,0]
	v_fma_f32 v38, v14, v78, -v16
	v_fma_f32 v39, v14, v81, v17
	v_mov_b32_e32 v5, v15
	v_pk_add_f32 v[16:17], v[96:97], v[96:97] op_sel:[0,1] op_sel_hi:[0,1]
	v_mul_f32_e32 v14, v15, v16
	v_mul_f32_e32 v15, v2, v17
	v_pk_add_f32 v[16:17], v[94:95], v[94:95] op_sel:[0,1] op_sel_hi:[0,1] neg_lo:[0,1] neg_hi:[0,1]
	v_fma_f32 v2, v2, v16, -v14
	v_fma_f32 v3, v5, v17, v15
	v_pk_add_f32 v[16:17], v[36:37], v[36:37] op_sel:[0,1] op_sel_hi:[0,1]
	v_mov_b32_e32 v5, v35
	v_mul_f32_e32 v14, v35, v16
	v_mul_f32_e32 v15, v28, v17
	v_pk_add_f32 v[16:17], v[32:33], v[32:33] op_sel:[0,1] op_sel_hi:[0,1] neg_lo:[0,1] neg_hi:[0,1]
	v_fma_f32 v28, v28, v16, -v14
	v_fma_f32 v29, v5, v17, v15
	v_pk_add_f32 v[14:15], v[58:59], v[58:59] op_sel:[0,1] op_sel_hi:[0,1]
	ds_write2_b64 v1, v[2:3], v[28:29] offset0:204 offset1:221
	v_mov_b32_e32 v3, v30
	v_sub_f32_e32 v2, v20, v21
	v_sub_f32_e32 v3, v3, v31
	v_mul_f32_e32 v4, v18, v14
	v_mul_f32_e32 v5, v2, v15
	v_pk_mov_b32 v[14:15], v[2:3], v[18:19] op_sel:[1,0]
	v_fma_f32 v16, v2, v14, -v4
	v_fma_f32 v17, v3, v15, v5
	v_mov_b32_e32 v3, v26
	v_mov_b32_e32 v5, v22
	v_sub_f32_e32 v2, v24, v40
	v_sub_f32_e32 v3, v3, v5
	v_sub_f32_e32 v4, v41, v25
	v_sub_f32_e32 v5, v27, v23
	ds_write2_b64 v1, v[72:73], v[74:75] offset0:136 offset1:153
	v_pk_add_f32 v[14:15], v[4:5], v[2:3]
	v_sub_f32_e32 v18, v2, v4
	v_sub_f32_e32 v2, v5, v3
	v_mul_f32_e32 v3, v2, v64
	v_mul_f32_e32 v2, v2, v49
	v_fma_f32 v4, v14, v64, -v2
	v_fma_f32 v5, v14, v67, v3
	ds_write2_b64 v1, v[44:45], v[4:5] offset0:102 offset1:119
	v_pk_add_f32 v[4:5], v[70:71], v[70:71] op_sel:[0,1] op_sel_hi:[0,1]
	v_mov_b32_e32 v21, v15
	v_mul_f32_e32 v2, v15, v4
	v_mul_f32_e32 v3, v18, v5
	v_pk_add_f32 v[4:5], v[68:69], v[68:69] op_sel:[0,1] op_sel_hi:[0,1] neg_lo:[0,1] neg_hi:[0,1]
	v_fma_f32 v14, v18, v4, -v2
	v_fma_f32 v15, v21, v5, v3
	ds_write2_b64 v1, v[54:55], v[50:51] offset0:170 offset1:187
	ds_write2_b64 v1, v[38:39], v[82:83] offset0:68 offset1:85
	ds_write2_b64 v1, v[16:17], v[14:15] offset0:238 offset1:255
	v_mov_b32_e32 v1, v6
	s_waitcnt lgkmcnt(0)
	s_barrier
	v_readlane_b32 s56, v245, 46
	v_mul_lo_u32 v1, v1, s33
	ds_read2_b64 v[2:5], v1 offset1:1
	ds_read2_b64 v[14:17], v1 offset0:8 offset1:9
	ds_read2_b64 v[18:21], v1 offset0:10 offset1:11
	ds_read2_b64 v[22:25], v1 offset0:12 offset1:13
	ds_read2_b64 v[26:29], v1 offset0:14 offset1:15
	ds_read2_b64 v[30:33], v1 offset0:2 offset1:3
	ds_read2_b64 v[34:37], v1 offset0:4 offset1:5
	ds_read2_b64 v[38:41], v1 offset0:6 offset1:7
	s_waitcnt lgkmcnt(7)
	v_mov_b32_e32 v1, v4
	v_mov_b32_e32 v42, v2
	v_mov_b32_e32 v43, v4
	v_mov_b32_e32 v4, v5
	v_mov_b32_e32 v5, v3
	s_waitcnt lgkmcnt(6)
	v_mov_b32_e32 v44, v14
	v_mov_b32_e32 v45, v16
	v_mov_b32_e32 v16, v17
	v_mov_b32_e32 v17, v15
	v_pk_add_f32 v[46:47], v[2:3], v[14:15] neg_lo:[0,1] neg_hi:[0,1]
	v_pk_add_f32 v[2:3], v[2:3], v[14:15]
	s_waitcnt lgkmcnt(1)
	v_mov_b32_e32 v15, v36
	v_mov_b32_e32 v49, v36
	v_mov_b32_e32 v36, v37
	v_mov_b32_e32 v37, v35
	v_mov_b32_e32 v50, v22
	v_mov_b32_e32 v51, v24
	v_mov_b32_e32 v24, v25
	v_mov_b32_e32 v25, v23
	v_mov_b32_e32 v48, v34
	v_pk_add_f32 v[52:53], v[34:35], v[22:23] neg_lo:[0,1] neg_hi:[0,1]
	v_pk_add_f32 v[22:23], v[34:35], v[22:23]
	v_pk_mov_b32 v[34:35], v[0:1], v[4:5] op_sel:[1,0]
	v_pk_mov_b32 v[54:55], v[44:45], v[16:17] op_sel:[1,0]
	v_pk_add_f32 v[4:5], v[4:5], v[16:17]
	v_pk_mov_b32 v[14:15], v[14:15], v[36:37] op_sel:[1,0]
	v_pk_mov_b32 v[16:17], v[50:51], v[24:25] op_sel:[1,0]
	v_pk_add_f32 v[42:43], v[42:43], v[44:45]
	v_pk_add_f32 v[44:45], v[48:49], v[50:51]
	v_pk_add_f32 v[24:25], v[36:37], v[24:25]
	v_pk_add_f32 v[48:49], v[2:3], v[22:23] neg_lo:[0,1] neg_hi:[0,1]
	v_pk_add_f32 v[2:3], v[2:3], v[22:23]
	v_pk_add_f32 v[22:23], v[34:35], v[54:55]
	v_pk_add_f32 v[34:35], v[34:35], v[54:55] neg_lo:[0,1] neg_hi:[0,1]
	v_pk_add_f32 v[36:37], v[14:15], v[16:17]
	v_pk_add_f32 v[14:15], v[14:15], v[16:17] neg_lo:[0,1] neg_hi:[0,1]
	v_add_f32_e32 v1, v46, v53
	v_sub_f32_e32 v50, v47, v52
	v_sub_f32_e32 v51, v46, v53
	v_add_f32_e32 v53, v47, v52
	v_pk_add_f32 v[16:17], v[42:43], v[44:45]
	v_pk_add_f32 v[4:5], v[4:5], v[24:25]
	v_add_f32_e32 v52, v34, v15
	v_sub_f32_e32 v54, v35, v14
	v_sub_f32_e32 v55, v34, v15
	v_add_f32_e32 v56, v35, v14
	v_pk_add_f32 v[14:15], v[30:31], v[18:19] neg_lo:[0,1] neg_hi:[0,1]
	v_pk_add_f32 v[24:25], v[30:31], v[18:19]
	v_mov_b32_e32 v44, v30
	v_mov_b32_e32 v46, v18
	s_xor_b64 s[50:51], s[40:41], -1
	v_pk_add_f32 v[42:43], v[22:23], v[36:37]
	v_pk_add_f32 v[22:23], v[22:23], v[36:37] neg_lo:[0,1] neg_hi:[0,1]
	s_waitcnt lgkmcnt(0)
	v_pk_add_f32 v[34:35], v[38:39], v[26:27] neg_lo:[0,1] neg_hi:[0,1]
	v_pk_add_f32 v[36:37], v[38:39], v[26:27]
	v_add_f32_e32 v44, v44, v46
	v_add_f32_e32 v45, v32, v20
	v_add_f32_e32 v18, v33, v21
	v_add_f32_e32 v19, v31, v19
	v_mov_b32_e32 v30, v38
	v_mov_b32_e32 v46, v26
	v_readlane_b32 s62, v245, 52
	v_add_f32_e32 v30, v30, v46
	v_add_f32_e32 v31, v40, v28
	v_add_f32_e32 v26, v41, v29
	v_add_f32_e32 v27, v39, v27
	v_pk_add_f32 v[46:47], v[24:25], v[36:37] neg_lo:[0,1] neg_hi:[0,1]
	v_pk_add_f32 v[24:25], v[24:25], v[36:37]
	v_add_f32_e32 v36, v14, v35
	v_sub_f32_e32 v37, v15, v34
	v_sub_f32_e32 v38, v14, v35
	v_add_f32_e32 v39, v15, v34
	v_pk_add_f32 v[14:15], v[32:33], v[20:21]
	v_pk_add_f32 v[20:21], v[32:33], v[20:21] neg_lo:[0,1] neg_hi:[0,1]
	v_pk_add_f32 v[32:33], v[40:41], v[28:29]
	v_pk_add_f32 v[28:29], v[40:41], v[28:29] neg_lo:[0,1] neg_hi:[0,1]
	v_readlane_b32 s63, v245, 53
	s_add_u32 s52, s62, s52
	v_pk_add_f32 v[30:31], v[44:45], v[30:31]
	v_pk_add_f32 v[18:19], v[18:19], v[26:27]
	v_sub_f32_e32 v27, v21, v28
	v_add_f32_e32 v21, v21, v28
	v_mul_f32_e32 v22, 0x3f3504f3, v22
	v_mul_f32_e32 v41, 0x3ec3ef15, v55
	v_mul_f32_e32 v45, 0xbf6c835e, v55
	s_addc_u32 s53, s63, s53
	s_mov_b32 s96, s10
	s_add_i32 s24, s1, s10
	v_readlane_b32 s4, v245, 56
	v_pk_add_f32 v[34:35], v[14:15], v[32:33]
	v_pk_add_f32 v[14:15], v[14:15], v[32:33] neg_lo:[0,1] neg_hi:[0,1]
	v_add_f32_e32 v26, v20, v29
	v_sub_f32_e32 v20, v20, v29
	v_fmamk_f32 v33, v23, 0x3f3504f3, v22
	v_fma_f32 v40, v23, s20, -v22
	v_fmac_f32_e32 v41, 0x3f6c835e, v56
	v_fmac_f32_e32 v45, 0x3ec3ef15, v56
	v_mul_f32_e32 v22, 0x3f3504f3, v36
	v_mul_f32_e32 v56, 0xbec3ef15, v21
	v_mul_f32_e32 v57, 0xbf6c835e, v21
	s_lshl_b64 s[54:55], s[24:25], 2
	v_readlane_b32 s8, v245, 60
	v_fmamk_f32 v32, v37, 0x3f3504f3, v22
	v_fma_f32 v36, v37, s20, -v22
	v_mul_f32_e32 v44, 0xbf3504f3, v14
	v_fmac_f32_e32 v56, 0xbf6c835e, v20
	v_fmac_f32_e32 v57, 0x3ec3ef15, v20
	v_pk_add_f32 v[20:21], v[2:3], v[24:25]
	v_pk_add_f32 v[22:23], v[42:43], v[34:35]
	v_readlane_b32 s57, v245, 47
	v_readlane_b32 s9, v245, 61
	s_add_u32 s56, s8, s54
	v_mul_f32_e32 v28, 0x3f6c835e, v52
	v_mul_f32_e32 v29, 0xbec3ef15, v52
	v_fmamk_f32 v52, v15, 0x3f3504f3, v44
	v_fmac_f32_e32 v44, 0xbf3504f3, v15
	v_pk_add_f32 v[2:3], v[2:3], v[24:25] neg_lo:[0,1] neg_hi:[0,1]
	v_pk_add_f32 v[24:25], v[16:17], v[30:31] neg_lo:[0,1] neg_hi:[0,1]
	v_pk_add_f32 v[14:15], v[22:23], v[20:21]
	v_pk_add_f32 v[16:17], v[20:21], v[22:23] neg_lo:[0,1] neg_hi:[0,1]
	s_addc_u32 s57, s9, s55
	global_load_dword v148, v0, s[52:53]
	global_load_dword v22, v0, s[42:43]
	global_load_dword v149, v0, s[44:45]
	global_load_dword v23, v0, s[46:47]
	global_load_dword v150, v0, s[56:57]
	global_load_dword v151, v0, s[48:49]
	global_load_dword v152, v186, s[56:57]
	global_load_dword v153, v187, s[56:57]
	v_readlane_b32 s10, v245, 62
	v_readlane_b32 s11, v245, 63
	s_add_u32 s52, s10, s54
	s_addc_u32 s53, s11, s55
	global_load_dword v154, v0, s[52:53]
	v_mul_f32_e32 v37, 0xbf3504f3, v38
	v_fmamk_f32 v55, v39, 0x3f3504f3, v37
	v_fmac_f32_e32 v37, 0xbf3504f3, v39
	v_mul_f32_e32 v38, 0x3ec3ef15, v26
	v_mul_f32_e32 v39, 0xbf6c835e, v26
	v_fmac_f32_e32 v28, 0x3ec3ef15, v54
	v_fmac_f32_e32 v29, 0x3f6c835e, v54
	v_fmac_f32_e32 v38, 0x3f6c835e, v27
	v_fmac_f32_e32 v39, 0x3ec3ef15, v27
	v_pk_add_f32 v[26:27], v[42:43], v[34:35] neg_lo:[0,1] neg_hi:[0,1]
	v_pk_add_f32 v[4:5], v[4:5], v[18:19] neg_lo:[0,1] neg_hi:[0,1]
	v_pk_add_f32 v[72:73], v[2:3], v[26:27] op_sel:[0,1] op_sel_hi:[1,0]
	v_pk_add_f32 v[2:3], v[2:3], v[26:27] op_sel:[0,1] op_sel_hi:[1,0] neg_lo:[0,1] neg_hi:[0,1]
	v_pk_add_f32 v[74:75], v[24:25], v[4:5] neg_lo:[0,1] neg_hi:[0,1]
	v_pk_add_f32 v[4:5], v[24:25], v[4:5]
	v_add_f32_e32 v25, v1, v32
	v_add_f32_e32 v27, v50, v36
	v_sub_f32_e32 v1, v1, v32
	v_sub_f32_e32 v31, v50, v36
	v_add_f32_e32 v30, v28, v38
	v_add_f32_e32 v32, v29, v39
	v_sub_f32_e32 v35, v28, v38
	v_sub_f32_e32 v29, v29, v39
	v_add_f32_e32 v24, v30, v25
	v_add_f32_e32 v26, v32, v27
	v_sub_f32_e32 v28, v25, v30
	v_sub_f32_e32 v30, v27, v32
	v_add_f32_e32 v32, v29, v1
	v_sub_f32_e32 v34, v31, v35
	v_sub_f32_e32 v36, v1, v29
	v_add_f32_e32 v38, v35, v31
	v_add_f32_e32 v1, v48, v47
	v_sub_f32_e32 v25, v49, v46
	v_sub_f32_e32 v27, v48, v47
	v_add_f32_e32 v29, v49, v46
	v_add_f32_e32 v31, v33, v52
	v_add_f32_e32 v35, v40, v44
	v_sub_f32_e32 v33, v33, v52
	v_sub_f32_e32 v39, v40, v44
	s_and_b64 s[40:41], s[40:41], exec
	s_mov_b32 s1, 0x5000000
	v_add_f32_e32 v40, v1, v31
	v_add_f32_e32 v42, v25, v35
	v_sub_f32_e32 v44, v1, v31
	v_sub_f32_e32 v46, v25, v35
	v_add_f32_e32 v48, v27, v39
	v_sub_f32_e32 v50, v29, v33
	v_sub_f32_e32 v52, v27, v39
	v_add_f32_e32 v54, v29, v33
	v_add_f32_e32 v1, v51, v55
	v_add_f32_e32 v25, v53, v37
	v_sub_f32_e32 v27, v51, v55
	v_sub_f32_e32 v29, v53, v37
	v_add_f32_e32 v31, v41, v56
	v_add_f32_e32 v33, v45, v57
	v_sub_f32_e32 v35, v41, v56
	v_sub_f32_e32 v37, v45, v57
	s_cselect_b32 s1, s1, 0xa000000
	v_readlane_b32 s4, v244, 11
	s_mov_b32 s2, 0
	v_add_f32_e32 v56, v31, v1
	v_add_f32_e32 v58, v33, v25
	v_sub_f32_e32 v60, v1, v31
	v_sub_f32_e32 v62, v25, v33
	v_add_f32_e32 v64, v37, v27
	v_sub_f32_e32 v66, v29, v35
	v_sub_f32_e32 v68, v27, v37
	v_add_f32_e32 v70, v35, v29
	s_add_u32 s1, s4, s1
	v_mov_b32_e32 v18, v72
	v_mov_b32_e32 v19, v3
	v_mov_b32_e32 v20, v74
	v_mov_b32_e32 v21, v5
	s_addc_u32 s94, s97, 0
	v_pk_mov_b32 v[72:73], v[2:3], v[72:73] op_sel:[1,0]
	v_pk_mov_b32 v[74:75], v[4:5], v[74:75] op_sel:[1,0]
	v_mov_b32_e32 v41, v40
	v_mov_b32_e32 v45, v44
	v_mov_b32_e32 v49, v48
	v_mov_b32_e32 v51, v50
	v_mov_b32_e32 v53, v52
	v_mov_b32_e32 v55, v54
	v_mov_b32_e32 v25, v24
	v_mov_b32_e32 v29, v28
	v_mov_b32_e32 v33, v32
	v_mov_b32_e32 v35, v34
	v_mov_b32_e32 v37, v36
	v_mov_b32_e32 v39, v38
	v_mov_b32_e32 v57, v56
	v_mov_b32_e32 v61, v60
	v_mov_b32_e32 v65, v64
	v_mov_b32_e32 v67, v66
	v_mov_b32_e32 v69, v68
	v_mov_b32_e32 v71, v70
	v_pk_mov_b32 v[76:77], v[14:15], v[14:15] op_sel:[1,0]
	v_mov_b32_e32 v27, v26
	v_mov_b32_e32 v43, v42
	v_mov_b32_e32 v59, v58
	v_pk_mov_b32 v[78:79], v[16:17], v[16:17] op_sel:[1,0]
	v_mov_b32_e32 v31, v30
	v_mov_b32_e32 v47, v46
	v_mov_b32_e32 v63, v62
	s_mov_b64 s[40:41], -1
	s_mov_b32 s24, s2
	v_readlane_b32 s58, v245, 48
	v_readlane_b32 s59, v245, 49
	v_readlane_b32 s60, v245, 50
	v_readlane_b32 s61, v245, 51
	v_readlane_b32 s5, v245, 57
	v_readlane_b32 s6, v245, 58
	v_readlane_b32 s7, v245, 59
	v_readlane_b32 s12, v244, 0
	v_readlane_b32 s13, v244, 1
	v_readlane_b32 s14, v244, 2
	v_readlane_b32 s15, v244, 3
	v_readlane_b32 s16, v244, 4
	v_readlane_b32 s17, v244, 5
	v_readlane_b32 s18, v244, 6
	v_readlane_b32 s19, v244, 7
	s_branch .LBB0_118

.LBB0_214:
	v_mov_b32_e32 v1, v12
	s_barrier
	v_pk_add_f32 v[118:119], v[2:3], v[4:5]
	v_ashrrev_i32_e32 v114, 31, v1
	v_lshrrev_b32_e32 v114, 24, v114
	v_and_b32_e32 v126, 0xff, v1
	v_add_lshl_u32 v1, v1, v114, 4
	v_pk_mov_b32 v[122:123], v[2:3], v[104:105] op_sel:[1,0]
	v_and_or_b32 v1, v1, s87, v126
	v_sub_f32_e32 v2, v2, v4
	v_sub_f32_e32 v3, v105, v89
	v_ashrrev_i32_e32 v114, 4, v1
	v_cvt_f32_i32_e32 v4, v126
	v_lshlrev_b32_e32 v1, 3, v1
	v_lshl_add_u32 v155, v114, 3, v1
	v_pk_add_f32 v[114:115], v[112:113], v[100:101]
	v_pk_add_f32 v[116:117], v[108:109], v[92:93]
	v_pk_add_f32 v[120:121], v[104:105], v[88:89]
	v_add_f32_e32 v1, v2, v3
	v_sub_f32_e32 v2, v2, v3
	v_add_f32_e32 v3, v4, v4
	v_mul_f32_e32 v3, 0x39800000, v3
	v_pk_add_f32 v[128:129], v[114:115], v[116:117]
	v_pk_add_f32 v[130:131], v[118:119], v[120:121]
	v_mul_f32_e32 v3, 0.5, v3
	v_pk_add_f32 v[132:133], v[128:129], v[130:131]
	v_sub_f32_e32 v122, v122, v5
	v_sub_f32_e32 v123, v123, v88
	v_sin_f32_e32 v4, v3
	v_mul_f32_e32 v124, 0x3f3504f3, v2
	v_cos_f32_e32 v126, v3
	v_pk_add_f32 v[2:3], v[132:133], 0 op_sel_hi:[1,0]
	v_sub_f32_e32 v5, v122, v123
	ds_write_b64 v155, v[2:3]
	v_pk_add_f32 v[2:3], v[112:113], v[100:101] neg_lo:[0,1] neg_hi:[0,1]
	v_pk_add_f32 v[136:137], v[108:109], v[92:93] neg_lo:[0,1] neg_hi:[0,1]
	v_mul_f32_e32 v1, 0x3f3504f3, v1
	v_mul_f32_e32 v125, 0x3f3504f3, v5
	v_pk_add_f32 v[138:139], v[2:3], v[136:137] op_sel:[0,1] op_sel_hi:[1,0]
	v_pk_add_f32 v[2:3], v[2:3], v[136:137] op_sel:[0,1] op_sel_hi:[1,0] neg_lo:[0,1] neg_hi:[0,1]
	v_mov_b32_e32 v136, v138
	v_add_f32_e32 v140, v125, v1
	v_fma_f32 v141, v5, s20, -v1
	v_add_f32_e32 v142, v136, v140
	v_add_f32_e32 v143, v3, v141
	v_xor_b32_e32 v127, 0x80000000, v4
	v_pk_add_f32 v[144:145], v[142:143], 0 op_sel_hi:[1,0]
	v_pk_mul_f32 v[146:147], v[144:145], v[4:5] op_sel:[1,0] op_sel_hi:[0,0]
	v_mov_b32_e32 v5, v126
	v_mul_f32_e32 v158, v4, v4
	v_mul_f32_e32 v159, v5, v127
	v_pk_add_f32 v[114:115], v[114:115], v[116:117] neg_lo:[0,1] neg_hi:[0,1]
	v_pk_add_f32 v[116:117], v[118:119], v[120:121] neg_lo:[0,1] neg_hi:[0,1]
	v_pk_fma_f32 v[160:161], v[126:127], v[126:127], v[158:159] op_sel_hi:[0,1,1] neg_lo:[0,0,1] neg_hi:[0,0,1]
	v_pk_fma_f32 v[158:159], v[126:127], v[126:127], v[158:159] op_sel_hi:[0,1,1]
	v_fma_f32 v156, v144, v126, v146
	v_fma_f32 v157, v145, v126, -v147
	v_pk_add_f32 v[118:119], v[114:115], v[116:117] op_sel:[0,1] op_sel_hi:[1,0]
	v_pk_add_f32 v[120:121], v[114:115], v[116:117] op_sel:[0,1] op_sel_hi:[1,0] neg_lo:[0,1] neg_hi:[0,1]
	v_pk_mov_b32 v[168:169], v[158:159], v[160:161] op_sel:[1,0]
	v_mov_b32_e32 v144, v118
	v_mov_b32_e32 v145, v121
	v_pk_add_f32 v[122:123], v[122:123], v[122:123] op_sel:[0,1] op_sel_hi:[0,1]
	s_mov_b32 s2, s20
	v_mov_b32_e32 v162, v160
	v_mov_b32_e32 v163, v159
	v_mov_b32_e32 v127, v4
	v_pk_mul_f32 v[170:171], v[158:159], v[168:169] op_sel:[1,0]
	v_pk_add_f32 v[146:147], v[144:145], 0 op_sel_hi:[1,0]
	v_pk_fma_f32 v[122:123], v[122:123], s[2:3], v[124:125] op_sel_hi:[1,1,0] neg_lo:[0,0,1] neg_hi:[0,0,1]
	v_pk_mul_f32 v[164:165], v[126:127], v[162:163]
	v_pk_mul_f32 v[166:167], v[4:5], v[162:163]
	v_pk_fma_f32 v[172:173], v[160:161], v[162:163], v[170:171] op_sel_hi:[0,1,1] neg_lo:[0,0,1] neg_hi:[0,0,1]
	v_pk_fma_f32 v[170:171], v[160:161], v[162:163], v[170:171] op_sel_hi:[0,1,1]
	v_add_f32_e32 v124, v2, v122
	v_add_f32_e32 v125, v139, v123
	v_mov_b32_e32 v174, v172
	v_mov_b32_e32 v175, v171
	v_mov_b32_e32 v214, v164
	v_pk_mov_b32 v[164:165], v[164:165], v[166:167] op_sel:[1,0]
	v_pk_mul_f32 v[158:159], v[146:147], v[158:159] op_sel:[1,1] op_sel_hi:[0,1]
	ds_write_b64 v155, v[156:157] offset:2176
	v_pk_add_f32 v[156:157], v[124:125], 0 op_sel_hi:[1,0]
	v_pk_mul_f32 v[202:203], v[174:175], v[174:175]
	v_pk_mul_f32 v[204:205], v[174:175], v[170:171] op_sel:[0,1] op_sel_hi:[1,0]
	v_add_f32_e32 v166, v214, v164
	v_sub_f32_e32 v164, v214, v164
	v_sub_f32_e32 v165, v167, v165
	v_fma_f32 v224, v146, v160, -v158
	v_fma_f32 v225, v147, v160, v159
	v_mov_b32_e32 v206, v202
	v_mov_b32_e32 v207, v204
	v_pk_mov_b32 v[202:203], v[202:203], v[204:205] op_sel:[1,0]
	v_pk_mul_f32 v[146:147], v[156:157], v[164:165] op_sel:[0,1]
	v_pk_add_f32 v[204:205], v[206:207], v[202:203] neg_lo:[0,1] neg_hi:[0,1]
	v_pk_add_f32 v[202:203], v[206:207], v[202:203]
	v_fma_f32 v158, v156, v166, -v147
	v_fma_f32 v159, v157, v166, v146
	v_mul_f32_e32 v181, v126, v171
	v_mul_f32_e32 v183, v4, v172
	v_mov_b32_e32 v206, v204
	v_mov_b32_e32 v207, v203
	v_mov_b32_e32 v215, v165
	v_pk_mul_f32 v[156:157], v[168:169], v[170:171] op_sel:[0,1]
	v_pk_mul_f32 v[164:165], v[174:175], v[164:165] op_sel:[0,1]
	v_mul_f32_e32 v1, v4, v171
	v_pk_mul_f32 v[4:5], v[4:5], v[206:207]
	ds_write_b64 v155, v[158:159] offset:6528
	v_sub_f32_e32 v146, v3, v141
	v_sub_f32_e32 v147, v181, v183
	v_fma_f32 v158, v162, v172, -v156
	v_fma_f32 v180, v174, v166, -v165
	v_mul_f32_e32 v177, v126, v172
	v_pk_mov_b32 v[208:209], v[202:203], v[204:205] op_sel:[1,0]
	v_pk_mul_f32 v[126:127], v[126:127], v[206:207]
	v_mul_f32_e32 v219, v171, v204
	v_mul_f32_e32 v221, v172, v203
	v_pk_mov_b32 v[222:223], v[170:171], v[172:173] op_sel:[1,0]
	v_mul_f32_e32 v171, v203, v158
	v_mul_f32_e32 v227, v203, v180
	v_pk_mul_f32 v[202:203], v[132:133], v[202:203] op_sel:[1,1] op_sel_hi:[0,1]
	v_pk_add_f32 v[4:5], v[4:5], v[4:5] op_sel:[1,0] op_sel_hi:[1,0] neg_lo:[0,1] neg_hi:[0,1]
	v_fma_f32 v228, v132, v204, -v202
	v_fma_f32 v229, v133, v204, v203
	v_pk_mul_f32 v[4:5], v[142:143], v[4:5] op_sel:[1,0] op_sel_hi:[0,1]
	v_pk_add_f32 v[126:127], v[126:127], v[126:127] op_sel:[0,1] op_sel_hi:[0,1]
	v_pk_mul_f32 v[212:213], v[162:163], v[208:209]
	v_fma_f32 v132, v142, v126, -v4
	v_fma_f32 v133, v143, v127, v5
	v_pk_mul_f32 v[210:211], v[162:163], v[206:207]
	v_pk_mov_b32 v[4:5], v[120:121], v[118:119] op_sel:[1,0]
	v_pk_add_f32 v[120:121], v[212:213], v[212:213] op_sel:[0,1] op_sel_hi:[0,1]
	v_mov_b32_e32 v214, v166
	v_pk_mul_f32 v[4:5], v[4:5], v[120:121]
	v_pk_add_f32 v[120:121], v[210:211], v[210:211] op_sel:[0,1] op_sel_hi:[0,1] neg_lo:[0,1] neg_hi:[0,1]
	v_pk_mul_f32 v[208:209], v[214:215], v[208:209]
	v_fma_f32 v126, v118, v120, -v4
	v_fma_f32 v127, v145, v121, v5
	v_pk_mul_f32 v[216:217], v[214:215], v[206:207]
	v_pk_add_f32 v[4:5], v[208:209], v[208:209] op_sel:[0,1] op_sel_hi:[0,1]
	v_pk_mul_f32 v[214:215], v[174:175], v[206:207]
	v_pk_mul_f32 v[4:5], v[124:125], v[4:5] op_sel:[1,0] op_sel_hi:[0,1]
	v_pk_add_f32 v[120:121], v[216:217], v[216:217] op_sel:[0,1] op_sel_hi:[0,1] neg_lo:[0,1] neg_hi:[0,1]
	v_pk_add_f32 v[134:135], v[128:129], v[130:131] neg_lo:[0,1] neg_hi:[0,1]
	ds_write_b64 v155, v[126:127] offset:21760
	v_fma_f32 v126, v124, v120, -v4
	v_fma_f32 v127, v125, v121, v5
	v_sub_f32_e32 v4, v128, v130
	v_sub_f32_e32 v5, v214, v215
	v_pk_mul_f32 v[222:223], v[134:135], v[222:223] op_sel:[1,0]
	v_add_f32_e32 v116, 0, v4
	ds_write_b64 v155, v[126:127] offset:23936
	v_add_f32_e32 v120, v135, v0
	v_add_f32_e32 v121, v221, v219
	v_fma_f32 v124, v116, v172, -v222
	v_fma_f32 v125, v116, v175, v223
	ds_write_b64 v155, v[224:225] offset:4352
	v_mul_f32_e32 v126, v120, v121
	v_mul_f32_e32 v127, v121, v4
	v_pk_mov_b32 v[120:121], v[4:5], v[120:121] op_sel:[1,0]
	ds_write_b64 v155, v[228:229] offset:17408
	v_fma_f32 v128, v4, v120, -v126
	v_fma_f32 v129, v5, v121, v127
	ds_write_b64 v155, v[132:133] offset:19584
	v_sub_f32_e32 v4, v136, v140
	ds_write_b64 v155, v[124:125] offset:8704
	ds_write_b64 v155, v[128:129] offset:26112
	v_add_f32_e32 v120, v4, v0
	v_add_f32_e32 v121, v177, v1
	v_mul_f32_e32 v128, v146, v147
	v_mul_f32_e32 v129, v147, v120
	v_pk_mov_b32 v[130:131], v[120:121], v[146:147] op_sel:[1,0]
	v_mul_f32_e32 v116, v204, v121
	v_mul_f32_e32 v126, v206, v147
	v_mul_f32_e32 v127, v207, v121
	v_fma_f32 v132, v120, v130, -v128
	v_fma_f32 v133, v121, v131, v129
	v_add_f32_e32 v134, 0, v146
	v_fma_f32 v157, v163, v172, v157
	v_fma_f32 v124, -v206, v121, v116
	v_fma_f32 v125, -v207, v147, v116
	v_mov_b32_e32 v135, v4
	v_pk_add_f32 v[120:121], v[126:127], v[126:127] op_sel:[1,0] op_sel_hi:[1,0]
	v_mov_b32_e32 v161, v157
	v_pk_mul_f32 v[120:121], v[134:135], v[120:121]
	v_mov_b32_e32 v127, v125
	v_pk_mov_b32 v[124:125], v[124:125], v[134:135] op_sel:[1,0]
	v_mul_f32_e32 v115, v206, v158
	v_mul_f32_e32 v163, v207, v161
	v_fma_f32 v4, v4, v124, -v120
	v_fma_f32 v5, v127, v125, v121
	v_mul_f32_e32 v1, v204, v157
	ds_write_b64 v155, v[132:133] offset:10880
	ds_write_b64 v155, v[4:5] offset:28288
	v_sub_f32_e32 v4, v114, v117
	v_sub_f32_e32 v5, v115, v163
	v_mul_f32_e32 v156, v119, v157
	v_mul_f32_e32 v157, v119, v158
	v_fma_f32 v165, v175, v166, v164
	v_add_f32_e32 v114, 0, v4
	v_mov_b32_e32 v167, v165
	v_add_f32_e32 v116, v119, v0
	v_add_f32_e32 v117, v171, v1
	v_fma_f32 v118, v114, v158, -v156
	v_fma_f32 v119, v114, v161, v157
	v_mul_f32_e32 v182, v206, v180
	v_mul_f32_e32 v183, v207, v167
	v_sub_f32_e32 v139, v139, v123
	v_mul_f32_e32 v114, v116, v117
	v_mul_f32_e32 v115, v117, v4
	v_pk_mov_b32 v[116:117], v[4:5], v[116:117] op_sel:[1,0]
	v_mul_f32_e32 v1, v204, v165
	v_fma_f32 v120, v4, v116, -v114
	v_fma_f32 v121, v5, v117, v115
	v_sub_f32_e32 v2, v2, v122
	v_sub_f32_e32 v3, v182, v183
	v_mul_f32_e32 v164, v139, v165
	v_mul_f32_e32 v165, v139, v180
	v_add_f32_e32 v4, 0, v2
	v_add_f32_e32 v114, v139, v0
	v_add_f32_e32 v115, v227, v1
	v_fma_f32 v116, v4, v180, -v164
	v_fma_f32 v117, v4, v167, v165
	ds_write_b64 v155, v[118:119] offset:13056
	ds_write_b64 v155, v[120:121] offset:30464
	v_mul_f32_e32 v4, v114, v115
	v_mul_f32_e32 v5, v115, v2
	v_pk_mov_b32 v[114:115], v[2:3], v[114:115] op_sel:[1,0]
	v_mov_b32_e32 v1, v6
	v_fma_f32 v118, v2, v114, -v4
	v_fma_f32 v119, v3, v115, v5
	s_mov_b32 s88, s71
	ds_write_b64 v155, v[116:117] offset:15232
	ds_write_b64 v155, v[118:119] offset:32640
	s_waitcnt lgkmcnt(0)
	s_barrier
	s_mov_b32 s89, s21
	v_ashrrev_i32_e32 v2, 31, v1
	v_lshrrev_b32_e32 v2, 28, v2
	v_and_b32_e32 v155, 15, v1
	v_add_u32_e32 v1, v1, v2
	v_ashrrev_i32_e32 v1, 4, v1
	v_lshlrev_b32_e32 v2, 11, v1
	v_lshl_add_u32 v1, v1, 7, v2
	v_lshl_or_b32 v1, v155, 3, v1
	ds_read2_b64 v[120:123], v1 offset1:17
	ds_read2_b64 v[124:127], v1 offset0:68 offset1:85
	ds_read2_b64 v[128:131], v1 offset0:136 offset1:153
	ds_read2_b64 v[132:135], v1 offset0:170 offset1:187
	ds_read2_b64 v[136:139], v1 offset0:204 offset1:221
	ds_read2_b64 v[140:143], v1 offset0:238 offset1:255
	ds_read2_b64 v[144:147], v1 offset0:34 offset1:51
	ds_read2_b64 v[156:159], v1 offset0:102 offset1:119
	s_waitcnt lgkmcnt(5)
	v_pk_add_f32 v[118:119], v[128:129], v[120:121]
	s_waitcnt lgkmcnt(2)
	v_pk_mov_b32 v[176:177], v[134:135], v[142:143] op_sel:[1,0]
	s_waitcnt lgkmcnt(1)
	v_pk_add_f32 v[172:173], v[146:147], v[134:135]
	s_waitcnt lgkmcnt(0)
	v_pk_add_f32 v[174:175], v[158:159], v[142:143]
	v_mov_b32_e32 v135, v143
	v_pk_add_f32 v[142:143], v[172:173], v[174:175] neg_lo:[0,1] neg_hi:[0,1]
	v_sub_f32_e32 v176, v147, v176
	v_sub_f32_e32 v177, v158, v177
	v_pk_add_f32 v[116:117], v[172:173], v[174:175]
	v_mul_f32_e32 v172, 0x3f3504f3, v143
	v_mul_f32_e32 v175, 0xbf3504f3, v143
	v_cvt_f32_i32_e32 v143, v155
	v_sub_f32_e32 v134, v146, v134
	v_sub_f32_e32 v135, v159, v135
	v_pk_add_f32 v[128:129], v[120:121], v[128:129] neg_lo:[0,1] neg_hi:[0,1]
	v_add_f32_e32 v143, v143, v143
	v_pk_add_f32 v[120:121], v[124:125], v[136:137] neg_lo:[0,1] neg_hi:[0,1]
	v_pk_add_f32 v[160:161], v[136:137], v[124:125]
	v_pk_add_f32 v[162:163], v[122:123], v[130:131]
	v_pk_add_f32 v[164:165], v[126:127], v[138:139]
	v_sub_f32_e32 v146, v134, v135
	v_mul_f32_e32 v143, 0x3b800000, v143
	v_pk_mov_b32 v[124:125], v[120:121], v[120:121] op_sel:[1,0]
	v_add_f32_e32 v136, v128, v121
	v_sub_f32_e32 v137, v129, v120
	v_pk_add_f32 v[134:135], v[134:135], v[134:135] op_sel:[0,1] op_sel_hi:[0,1]
	v_pk_add_f32 v[4:5], v[162:163], v[164:165]
	v_pk_add_f32 v[166:167], v[144:145], v[132:133]
	v_pk_add_f32 v[168:169], v[156:157], v[140:141]
	v_pk_add_f32 v[162:163], v[162:163], v[164:165] neg_lo:[0,1] neg_hi:[0,1]
	v_mul_f32_e32 v143, 0.5, v143
	v_pk_add_f32 v[120:121], v[176:177], v[176:177] op_sel:[0,1] op_sel_hi:[0,1] neg_lo:[0,1] neg_hi:[0,1]
	s_mov_b32 s70, s21
	v_pk_mul_f32 v[134:135], v[134:135], s[88:89]
	v_pk_add_f32 v[114:115], v[166:167], v[168:169]
	v_pk_add_f32 v[170:171], v[166:167], v[168:169] neg_lo:[0,1] neg_hi:[0,1]
	v_add_f32_e32 v158, v176, v177
	v_pk_mul_f32 v[164:165], v[162:163], s[20:21] op_sel_hi:[1,0]
	v_mul_f32_e32 v142, 0x3f3504f3, v142
	v_sin_f32_e32 v166, v143
	s_nop 1
	v_cos_f32_e32 v204, v143
	s_nop 1
	v_fma_f32 v176, v120, s70, v134
	v_fma_f32 v177, v121, s71, -v135
	v_pk_add_f32 v[2:3], v[118:119], v[160:161]
	v_mov_b32_e32 v120, v118
	v_sub_f32_e32 v118, v172, v142
	v_sub_f32_e32 v119, v119, v161
	v_sub_f32_e32 v120, v120, v160
	v_sub_f32_e32 v121, v165, v164
	v_mov_b32_e32 v135, v142
	v_pk_add_f32 v[142:143], v[118:119], v[170:171] op_sel:[1,0] op_sel_hi:[0,1]
	v_mov_b32_e32 v161, v170
	v_sub_f32_e32 v134, v167, v169
	v_sub_f32_e32 v135, v175, v135
	v_sub_f32_e32 v170, v144, v132
	v_sub_f32_e32 v171, v122, v130
	v_sub_f32_e32 v172, v157, v141
	v_sub_f32_e32 v173, v127, v139
	v_mul_f32_e32 v155, 0x3f6c835e, v158
	v_mul_f32_e32 v179, 0x3ec3ef15, v146
	v_sub_f32_e32 v122, v145, v133
	v_sub_f32_e32 v123, v123, v131
	v_sub_f32_e32 v127, v126, v138
	v_sub_f32_e32 v126, v156, v140
	v_pk_add_f32 v[132:133], v[170:171], v[172:173] neg_lo:[0,1] neg_hi:[0,1]
	v_pk_fma_f32 v[162:163], v[162:163], s[20:21], v[164:165] op_sel:[0,0,1] op_sel_hi:[1,0,0]
	v_pk_add_f32 v[174:175], v[170:171], v[172:173]
	v_pk_add_f32 v[130:131], v[122:123], v[126:127] neg_lo:[0,1] neg_hi:[0,1]
	v_pk_add_f32 v[122:123], v[122:123], v[126:127]
	v_mov_b32_e32 v139, v129
	v_mov_b32_e32 v127, v125
	v_mov_b32_e32 v160, v162
	v_pk_add_f32 v[162:163], v[162:163], v[118:119] neg_lo:[0,1] neg_hi:[0,1]
	v_mul_f32_e32 v126, 0x3ec3ef15, v133
	v_pk_mul_f32 v[140:141], v[132:133], s[20:21]
	s_mov_b32 s90, s20
	s_mov_b32 s91, s71
	v_mul_f32_e32 v133, s73, v132
	v_mul_f32_e32 v132, s72, v158
	v_sub_f32_e32 v124, v128, v124
	v_sub_f32_e32 v125, v179, v155
	v_pk_mul_f32 v[128:129], v[174:175], s[70:71] op_sel:[1,0]
	v_add_f32_e32 v164, v118, v160
	v_sub_f32_e32 v161, v119, v161
	v_pk_add_f32 v[118:119], v[142:143], v[162:163]
	v_mul_f32_e32 v138, 0x3f6c835e, v123
	v_mul_f32_e32 v143, 0x3f3504f3, v174
	v_mul_f32_e32 v144, 0x3f3504f3, v130
	v_pk_fma_f32 v[140:141], v[122:123], s[90:91], v[140:141] neg_lo:[0,0,1] neg_hi:[0,0,1]
	v_fma_f32 v123, v122, s31, -v133
	v_fma_f32 v122, v146, s30, -v132
	v_fma_f32 v132, v131, s88, v128
	v_fma_f32 v133, v131, s89, -v129
	v_pk_add_f32 v[126:127], v[138:139], v[126:127]
	v_add_f32_e32 v128, v144, v143
	v_fma_f32 v129, v130, s20, -v143
	v_pk_add_f32 v[130:131], v[136:137], v[128:129]
	v_pk_add_f32 v[138:139], v[132:133], v[176:177]
	v_xor_b32_e32 v205, 0x80000000, v166
	v_pk_add_f32 v[144:145], v[138:139], v[130:131]
	v_pk_add_f32 v[180:181], v[2:3], v[114:115]
	v_pk_mul_f32 v[158:159], v[166:167], v[144:145] op_sel_hi:[0,1]
	v_fma_f32 v170, v204, v144, v159
	v_fma_f32 v171, v204, v145, -v158
	v_mov_b32_e32 v167, v204
	v_pk_add_f32 v[182:183], v[4:5], v[116:117]
	v_mul_f32_e32 v144, v166, v166
	v_mul_f32_e32 v145, v167, v205
	v_pk_add_f32 v[202:203], v[182:183], v[180:181]
	v_pk_fma_f32 v[158:159], v[204:205], v[204:205], v[144:145] op_sel_hi:[0,1,1] neg_lo:[0,0,1] neg_hi:[0,0,1]
	v_pk_fma_f32 v[144:145], v[204:205], v[204:205], v[144:145] op_sel_hi:[0,1,1]
	v_pk_add_f32 v[168:169], v[120:121], v[134:135]
	ds_write2_b64 v1, v[202:203], v[170:171] offset1:17
	v_pk_add_f32 v[120:121], v[120:121], v[134:135] neg_lo:[0,1] neg_hi:[0,1]
	v_add_f32_e32 v134, v168, v164
	v_add_f32_e32 v135, v169, v161
	v_mov_b32_e32 v170, v158
	v_mov_b32_e32 v171, v145
	v_mul_f32_e32 v202, v145, v145
	v_mul_f32_e32 v203, v145, v158
	v_pk_mul_f32 v[144:145], v[134:135], v[144:145] op_sel:[1,1] op_sel_hi:[0,1]
	v_pk_fma_f32 v[206:207], v[158:159], v[170:171], v[202:203] op_sel_hi:[0,1,1] neg_lo:[0,0,1] neg_hi:[0,0,1]
	v_pk_fma_f32 v[202:203], v[158:159], v[170:171], v[202:203] op_sel_hi:[0,1,1]
	v_fma_f32 v216, v134, v158, -v144
	v_fma_f32 v217, v135, v158, v145
	v_pk_mul_f32 v[144:145], v[170:171], v[202:203] op_sel:[0,1]
	v_pk_add_f32 v[132:133], v[132:133], v[176:177] neg_lo:[0,1] neg_hi:[0,1]
	v_fma_f32 v158, v170, v206, -v145
	v_fma_f32 v145, v171, v206, v144
	v_sub_f32_e32 v142, v142, v162
	v_mov_b32_e32 v177, v145
	v_mov_b32_e32 v205, v166
	v_mov_b32_e32 v208, v206
	v_mov_b32_e32 v209, v203
	v_pk_add_f32 v[218:219], v[120:121], v[120:121] op_sel:[0,1] op_sel_hi:[0,1]
	v_mul_f32_e32 v143, v142, v158
	v_mul_f32_e32 v142, v142, v145
	v_pk_mul_f32 v[172:173], v[204:205], v[170:171]
	v_pk_mul_f32 v[174:175], v[166:167], v[170:171]
	v_mov_b32_e32 v176, v158
	v_fma_f32 v144, v218, v158, -v142
	v_pk_mul_f32 v[158:159], v[208:209], v[202:203] op_sel:[0,1]
	v_pk_add_f32 v[130:131], v[130:131], v[138:139] neg_lo:[0,1] neg_hi:[0,1]
	v_pk_add_f32 v[138:139], v[140:141], v[124:125]
	v_pk_add_f32 v[146:147], v[126:127], v[122:123]
	v_fma_f32 v145, v219, v177, v143
	v_pk_fma_f32 v[162:163], v[206:207], v[208:209], v[158:159] op_sel:[0,0,1] op_sel_hi:[0,1,0] neg_lo:[0,0,1] neg_hi:[0,0,1]
	v_pk_fma_f32 v[158:159], v[206:207], v[208:209], v[158:159] op_sel:[0,0,1] op_sel_hi:[0,1,0]
	v_mov_b32_e32 v220, v172
	v_pk_mov_b32 v[172:173], v[172:173], v[174:175] op_sel:[1,0]
	v_pk_add_f32 v[156:157], v[138:139], v[146:147]
	v_pk_add_f32 v[142:143], v[180:181], v[182:183] neg_lo:[0,1] neg_hi:[0,1]
	v_pk_mov_b32 v[182:183], v[158:159], v[162:163] op_sel:[1,0]
	v_add_f32_e32 v174, v220, v172
	v_sub_f32_e32 v172, v220, v172
	v_sub_f32_e32 v173, v175, v173
	v_pk_mul_f32 v[210:211], v[204:205], v[208:209]
	v_pk_mul_f32 v[212:213], v[166:167], v[208:209]
	v_pk_add_f32 v[128:129], v[136:137], v[128:129] neg_lo:[0,1] neg_hi:[0,1]
	v_mov_b32_e32 v180, v162
	v_mov_b32_e32 v181, v159
	v_pk_mul_f32 v[166:167], v[166:167], v[182:183] op_sel_hi:[0,1]
	v_pk_mul_f32 v[222:223], v[156:157], v[172:173] op_sel:[0,1]
	v_pk_mov_b32 v[214:215], v[202:203], v[206:207] op_sel:[1,0]
	v_pk_add_f32 v[134:135], v[128:129], v[132:133] op_sel:[0,1] op_sel_hi:[1,0]
	v_pk_add_f32 v[128:129], v[128:129], v[132:133] op_sel:[0,1] op_sel_hi:[1,0] neg_lo:[0,1] neg_hi:[0,1]
	v_fma_f32 v202, v204, v180, v166
	v_fma_f32 v167, v204, v181, -v167
	v_fma_f32 v224, v156, v174, -v223
	v_fma_f32 v225, v157, v174, v222
	v_mov_b32_e32 v226, v210
	v_mov_b32_e32 v227, v213
	v_pk_mov_b32 v[210:211], v[210:211], v[212:213] op_sel:[1,0]
	v_mov_b32_e32 v205, v167
	v_pk_mul_f32 v[156:157], v[208:209], v[172:173] op_sel:[0,1]
	v_add_f32_e32 v212, v226, v210
	v_sub_f32_e32 v211, v227, v211
	v_mov_b32_e32 v133, v129
	v_mov_b32_e32 v221, v173
	v_fma_f32 v172, v208, v174, -v157
	v_fma_f32 v157, v209, v174, v156
	v_mul_f32_e32 v136, v129, v211
	v_mul_f32_e32 v137, v134, v211
	v_mul_f32_e32 v166, v131, v167
	v_mul_f32_e32 v167, v131, v202
	v_mov_b32_e32 v220, v174
	v_mov_b32_e32 v174, v172
	v_mov_b32_e32 v175, v157
	v_mov_b32_e32 v226, v212
	v_mov_b32_e32 v227, v211
	v_fma_f32 v210, v134, v212, -v136
	v_fma_f32 v211, v133, v212, v137
	v_fma_f32 v202, v130, v202, -v166
	v_fma_f32 v203, v130, v205, v167
	v_pk_mul_f32 v[158:159], v[142:143], v[158:159] op_sel:[1,1] op_sel_hi:[0,1]
	v_pk_mul_f32 v[218:219], v[170:171], v[180:181]
	v_pk_mul_f32 v[170:171], v[170:171], v[182:183]
	ds_write2_b64 v1, v[216:217], v[224:225] offset0:34 offset1:51
	v_pk_mul_f32 v[216:217], v[220:221], v[180:181]
	v_pk_mul_f32 v[220:221], v[220:221], v[182:183]
	v_pk_mul_f32 v[222:223], v[208:209], v[180:181]
	v_pk_mul_f32 v[224:225], v[208:209], v[182:183]
	v_pk_mul_f32 v[132:133], v[180:181], v[226:227]
	v_pk_mul_f32 v[136:137], v[182:183], v[226:227]
	v_pk_mul_f32 v[130:131], v[180:181], v[176:177]
	v_pk_mul_f32 v[166:167], v[182:183], v[176:177]
	v_pk_mul_f32 v[176:177], v[180:181], v[174:175]
	v_pk_mul_f32 v[180:181], v[182:183], v[174:175]
	v_fma_f32 v182, v142, v162, -v158
	v_fma_f32 v183, v143, v162, v159
	v_sub_f32_e32 v142, v168, v164
	v_sub_f32_e32 v143, v161, v169
	v_pk_add_f32 v[158:159], v[170:171], v[170:171] op_sel:[0,1] op_sel_hi:[0,1]
	v_pk_mul_f32 v[158:159], v[142:143], v[158:159] op_sel:[1,0] op_sel_hi:[0,1]
	v_pk_add_f32 v[160:161], v[218:219], v[218:219] op_sel:[0,1] op_sel_hi:[0,1] neg_lo:[0,1] neg_hi:[0,1]
	v_fma_f32 v162, v142, v160, -v158
	v_fma_f32 v163, v143, v161, v159
	v_pk_add_f32 v[2:3], v[2:3], v[114:115] neg_lo:[0,1] neg_hi:[0,1]
	v_mov_b32_e32 v143, v147
	v_sub_f32_e32 v138, v138, v146
	v_sub_f32_e32 v139, v143, v139
	v_pk_add_f32 v[142:143], v[220:221], v[220:221] op_sel:[0,1] op_sel_hi:[0,1]
	v_pk_add_f32 v[4:5], v[4:5], v[116:117] neg_lo:[0,1] neg_hi:[0,1]
	v_pk_mul_f32 v[142:143], v[138:139], v[142:143] op_sel:[1,0] op_sel_hi:[0,1]
	v_pk_add_f32 v[146:147], v[216:217], v[216:217] op_sel:[0,1] op_sel_hi:[0,1] neg_lo:[0,1] neg_hi:[0,1]
	v_pk_add_f32 v[114:115], v[2:3], v[4:5] op_sel:[0,1] op_sel_hi:[1,0]
	v_pk_add_f32 v[2:3], v[2:3], v[4:5] op_sel:[0,1] op_sel_hi:[1,0] neg_lo:[0,1] neg_hi:[0,1]
	v_fma_f32 v158, v138, v146, -v142
	v_fma_f32 v159, v139, v147, v143
	v_pk_mul_f32 v[116:117], v[2:3], v[214:215] op_sel:[1,0]
	v_fma_f32 v138, v114, v206, -v116
	v_fma_f32 v139, v114, v209, v117
	v_mov_b32_e32 v5, v115
	v_pk_add_f32 v[116:117], v[224:225], v[224:225] op_sel:[0,1] op_sel_hi:[0,1]
	v_mul_f32_e32 v114, v115, v116
	v_mul_f32_e32 v115, v2, v117
	v_pk_add_f32 v[116:117], v[222:223], v[222:223] op_sel:[0,1] op_sel_hi:[0,1] neg_lo:[0,1] neg_hi:[0,1]
	v_fma_f32 v2, v2, v116, -v114
	v_fma_f32 v3, v5, v117, v115
	v_pk_add_f32 v[116:117], v[136:137], v[136:137] op_sel:[0,1] op_sel_hi:[0,1]
	v_mov_b32_e32 v5, v135
	v_mul_f32_e32 v114, v135, v116
	v_mul_f32_e32 v115, v128, v117
	v_pk_add_f32 v[116:117], v[132:133], v[132:133] op_sel:[0,1] op_sel_hi:[0,1] neg_lo:[0,1] neg_hi:[0,1]
	v_fma_f32 v128, v128, v116, -v114
	v_fma_f32 v129, v5, v117, v115
	v_pk_add_f32 v[114:115], v[166:167], v[166:167] op_sel:[0,1] op_sel_hi:[0,1]
	ds_write2_b64 v1, v[2:3], v[128:129] offset0:204 offset1:221
	v_mov_b32_e32 v3, v130
	v_sub_f32_e32 v2, v120, v121
	v_sub_f32_e32 v3, v3, v131
	v_mul_f32_e32 v4, v118, v114
	v_mul_f32_e32 v5, v2, v115
	v_pk_mov_b32 v[114:115], v[2:3], v[118:119] op_sel:[1,0]
	v_fma_f32 v116, v2, v114, -v4
	v_fma_f32 v117, v3, v115, v5
	v_mov_b32_e32 v3, v126
	v_mov_b32_e32 v5, v122
	v_sub_f32_e32 v2, v124, v140
	v_sub_f32_e32 v3, v3, v5
	v_sub_f32_e32 v4, v141, v125
	v_sub_f32_e32 v5, v127, v123
	ds_write2_b64 v1, v[182:183], v[202:203] offset0:136 offset1:153
	v_pk_add_f32 v[114:115], v[4:5], v[2:3]
	v_sub_f32_e32 v118, v2, v4
	v_sub_f32_e32 v2, v5, v3
	v_mul_f32_e32 v3, v2, v172
	v_mul_f32_e32 v2, v2, v157
	v_fma_f32 v4, v114, v172, -v2
	v_fma_f32 v5, v114, v175, v3
	ds_write2_b64 v1, v[144:145], v[4:5] offset0:102 offset1:119
	v_pk_add_f32 v[4:5], v[180:181], v[180:181] op_sel:[0,1] op_sel_hi:[0,1]
	v_mov_b32_e32 v121, v115
	v_mul_f32_e32 v2, v115, v4
	v_mul_f32_e32 v3, v118, v5
	v_pk_add_f32 v[4:5], v[176:177], v[176:177] op_sel:[0,1] op_sel_hi:[0,1] neg_lo:[0,1] neg_hi:[0,1]
	v_fma_f32 v114, v118, v4, -v2
	v_fma_f32 v115, v121, v5, v3
	ds_write2_b64 v1, v[162:163], v[158:159] offset0:170 offset1:187
	ds_write2_b64 v1, v[138:139], v[210:211] offset0:68 offset1:85
	ds_write2_b64 v1, v[116:117], v[114:115] offset0:238 offset1:255
	v_mov_b32_e32 v1, v12
	s_waitcnt lgkmcnt(0)
	s_barrier
	s_mov_b32 s77, s71
	v_mul_lo_u32 v1, v1, s33
	ds_read2_b64 v[2:5], v1 offset1:1
	ds_read2_b64 v[114:117], v1 offset0:2 offset1:3
	ds_read2_b64 v[118:121], v1 offset0:9 offset1:10
	ds_read2_b64 v[122:125], v1 offset0:4 offset1:5
	ds_read2_b64 v[126:129], v1 offset0:6 offset1:7
	ds_read2_b64 v[130:133], v1 offset0:13 offset1:14
	ds_read2_b64 v[134:137], v1 offset0:8 offset1:15
	ds_read2_b64 v[138:141], v1 offset0:11 offset1:12
	s_waitcnt lgkmcnt(5)
	v_add_f32_e32 v1, v4, v118
	s_waitcnt lgkmcnt(3)
	s_waitcnt lgkmcnt(2)
	v_add_f32_e32 v144, v124, v130
	s_waitcnt lgkmcnt(1)
	v_pk_add_f32 v[168:169], v[2:3], v[134:135]
	v_pk_add_f32 v[2:3], v[2:3], v[134:135] neg_lo:[0,1] neg_hi:[0,1]
	s_waitcnt lgkmcnt(0)
	v_pk_add_f32 v[134:135], v[122:123], v[140:141]
	v_pk_add_f32 v[122:123], v[122:123], v[140:141] neg_lo:[0,1] neg_hi:[0,1]
	v_add_f32_e32 v143, v1, v144
	v_sub_f32_e32 v1, v1, v144
	v_mov_b32_e32 v164, v115
	v_add_f32_e32 v170, v2, v123
	v_sub_f32_e32 v171, v3, v122
	v_add_f32_e32 v144, v116, v138
	v_add_f32_e32 v145, v128, v136
	v_mov_b32_e32 v166, v127
	v_mov_b32_e32 v177, v118
	v_add_f32_e32 v142, v5, v119
	v_add_f32_e32 v146, v117, v139
	v_add_f32_e32 v147, v129, v137
	v_mov_b32_e32 v156, v117
	v_mov_b32_e32 v158, v139
	v_add_f32_e32 v172, v115, v121
	v_add_f32_e32 v173, v114, v120
	v_mov_b32_e32 v115, v4
	v_sub_f32_e32 v4, v164, v121
	v_sub_f32_e32 v5, v5, v119
	v_mov_b32_e32 v121, v130
	v_add_f32_e32 v155, v125, v131
	v_sub_f32_e32 v116, v116, v138
	v_sub_f32_e32 v117, v129, v137
	v_sub_f32_e32 v114, v114, v120
	v_sub_f32_e32 v115, v115, v177
	v_add_f32_e32 v118, v127, v133
	v_add_f32_e32 v119, v126, v132
	v_mov_b32_e32 v127, v124
	v_sub_f32_e32 v124, v166, v133
	v_sub_f32_e32 v125, v125, v131
	v_mov_b32_e32 v159, v136
	v_pk_add_f32 v[136:137], v[116:117], v[116:117] op_sel_hi:[0,1] neg_lo:[0,1] neg_hi:[0,1]
	v_sub_f32_e32 v120, v126, v132
	v_sub_f32_e32 v121, v127, v121
	v_mov_b32_e32 v166, v116
	v_sub_f32_e32 v156, v156, v158
	v_sub_f32_e32 v157, v128, v159
	v_pk_add_f32 v[132:133], v[114:115], v[124:125] neg_lo:[0,1] neg_hi:[0,1]
	v_pk_add_f32 v[164:165], v[4:5], v[120:121]
	v_add_f32_e32 v116, v166, v117
	v_add_f32_e32 v117, v114, v124
	v_mov_b32_e32 v167, v4
	v_sub_f32_e32 v4, v5, v121
	v_add_f32_e32 v114, v115, v125
	v_pk_add_f32 v[138:139], v[156:157], v[156:157] op_sel:[0,1] op_sel_hi:[1,0]
	v_mov_b32_e32 v166, v156
	v_pk_mov_b32 v[156:157], v[156:157], v[120:121] op_sel:[1,0]
	v_pk_mul_f32 v[120:121], v[4:5], s[88:89] op_sel_hi:[0,1]
	v_pk_mul_f32 v[114:115], v[114:115], s[70:71] op_sel_hi:[0,1]
	v_pk_add_f32 v[156:157], v[166:167], v[156:157] neg_lo:[0,1] neg_hi:[0,1]
	v_sub_f32_e32 v160, v142, v155
	v_pk_add_f32 v[128:129], v[144:145], v[144:145] op_sel:[0,1] op_sel_hi:[1,0]
	v_sub_f32_e32 v144, v144, v145
	v_add_f32_e32 v124, v2, v123
	v_add_f32_e32 v125, v120, v114
	v_fma_f32 v166, v4, s88, v114
	v_fma_f32 v167, v4, s89, -v115
	v_mul_f32_e32 v145, 0x3f3504f3, v1
	v_mul_f32_e32 v159, 0x3f3504f3, v160
	v_mul_f32_e32 v162, 0x3f3504f3, v144
	v_mov_b32_e32 v4, v121
	v_mul_f32_e32 v140, 0x3ec3ef15, v133
	v_mul_f32_e32 v120, 0x3f6c835e, v165
	v_sub_f32_e32 v4, v4, v115
	v_sub_f32_e32 v5, v3, v122
	v_sub_f32_e32 v114, v168, v134
	v_sub_f32_e32 v115, v159, v145
	v_add_f32_e32 v120, v120, v140
	v_add_f32_e32 v121, v3, v122
	v_pk_mul_f32 v[140:141], v[116:117], s[72:73]
	v_pk_mul_f32 v[144:145], v[116:117], s[74:75]
	v_pk_mul_f32 v[116:117], v[116:117], s[88:89] op_sel_hi:[0,1]
	v_fma_f32 v206, v156, s70, v116
	v_fma_f32 v207, v156, s71, -v117
	v_pk_add_f32 v[116:117], v[146:147], v[146:147] op_sel:[0,1] op_sel_hi:[0,1] neg_lo:[0,1] neg_hi:[0,1]
	v_pk_fma_f32 v[176:177], v[156:157], s[72:73], v[144:145] neg_lo:[0,0,1] neg_hi:[0,0,1]
	v_fmac_f32_e32 v145, 0x3f3504f3, v157
	v_pk_fma_f32 v[140:141], v[156:157], s[74:75], v[140:141]
	v_pk_mul_f32 v[156:157], v[116:117], s[2:3]
	v_mov_b32_e32 v163, v135
	v_mov_b32_e32 v182, v138
	v_sub_f32_e32 v208, v156, v162
	v_sub_f32_e32 v209, v169, v163
	v_pk_fma_f32 v[116:117], v[116:117], s[2:3], v[162:163] op_sel_hi:[1,1,0] neg_lo:[0,0,1] neg_hi:[0,0,1]
	v_pk_mul_f32 v[138:139], v[138:139], s[88:89] op_sel_hi:[0,1]
	v_mul_f32_e32 v3, s77, v137
	v_mov_b32_e32 v122, v123
	v_pk_add_f32 v[174:175], v[168:169], v[134:135] neg_lo:[0,1] neg_hi:[0,1]
	v_add_f32_e32 v126, v169, v135
	v_add_f32_e32 v127, v172, v118
	v_pk_add_f32 v[130:131], v[172:173], v[118:119] neg_lo:[0,1] neg_hi:[0,1]
	v_mov_b32_e32 v181, v137
	v_pk_mov_b32 v[204:205], v[136:137], v[164:165] op_sel:[1,0]
	v_sub_f32_e32 v2, v2, v122
	v_sub_f32_e32 v3, v3, v139
	v_pk_fma_f32 v[122:123], v[136:137], s[76:77], v[138:139] op_sel:[1,0,0] neg_lo:[0,0,1] neg_hi:[0,0,1]
	v_pk_mov_b32 v[136:137], v[172:173], v[146:147] op_sel:[1,0]
	v_fmamk_f32 v160, v1, 0x3f3504f3, v159
	v_mov_b32_e32 v183, v132
	v_mov_b32_e32 v210, v118
	v_add_f32_e32 v134, v168, v134
	v_add_f32_e32 v135, v142, v155
	v_add_f32_e32 v118, v136, v119
	v_add_f32_e32 v119, v137, v147
	v_sub_f32_e32 v146, v174, v130
	v_add_f32_e32 v147, v175, v131
	v_mov_b32_e32 v161, v131
	v_pk_mul_f32 v[158:159], v[132:133], s[20:21]
	v_pk_mul_f32 v[132:133], v[182:183], s[74:75]
	v_pk_mul_f32 v[182:183], v[182:183], s[72:73]
	v_sub_f32_e32 v156, v172, v210
	v_sub_f32_e32 v157, v157, v162
	v_add_f32_e32 v130, v208, v160
	v_sub_f32_e32 v163, v209, v161
	v_mov_b32_e32 v180, v164
	v_pk_fma_f32 v[202:203], v[164:165], s[90:91], v[158:159] neg_lo:[0,0,1] neg_hi:[0,0,1]
	v_pk_fma_f32 v[164:165], v[164:165], s[2:3], v[158:159] op_sel_hi:[0,1,0] neg_lo:[0,0,1] neg_hi:[0,0,1]
	v_add_f32_e32 v136, v126, v127
	v_add_f32_e32 v137, v135, v119
	v_mov_b32_e32 v142, v134
	v_mov_b32_e32 v138, v118
	v_pk_add_f32 v[118:119], v[134:135], v[118:119] neg_lo:[0,1] neg_hi:[0,1]
	v_pk_add_f32 v[134:135], v[166:167], v[206:207]
	v_pk_add_f32 v[166:167], v[114:115], v[156:157]
	s_mov_b32 s92, s71
	s_mov_b32 s93, s3
	v_fma_f32 v158, v180, s78, -v158
	v_fma_f32 v159, v181, s79, -v182
	v_pk_fma_f32 v[180:181], v[204:205], s[30:31], v[182:183] neg_lo:[0,0,1] neg_hi:[0,0,1]
	v_add_f32_e32 v116, v160, v116
	v_add_f32_e32 v117, v115, v117
	v_add_f32_e32 v130, v166, v130
	v_add_f32_e32 v131, v167, v163
	v_mov_b32_e32 v144, v145
	v_pk_fma_f32 v[132:133], v[204:205], s[92:93], v[132:133] neg_lo:[0,0,1] neg_hi:[0,0,1]
	v_add_f32_e32 v138, v142, v138
	v_add_f32_e32 v139, v143, v128
	v_sub_f32_e32 v116, v166, v116
	v_sub_f32_e32 v117, v163, v117
	v_add_f32_e32 v162, v2, v164
	v_add_f32_e32 v163, v121, v165
	v_pk_add_f32 v[164:165], v[120:121], v[180:181]
	v_pk_add_f32 v[166:167], v[202:203], v[2:3]
	v_mov_b32_e32 v202, v120
	v_mov_b32_e32 v3, v120
	v_pk_add_f32 v[168:169], v[136:137], v[136:137] op_sel:[1,0] op_sel_hi:[1,0]
	v_mov_b32_e32 v142, v126
	v_pk_mov_b32 v[126:127], v[126:127], v[128:129] op_sel:[1,0]
	v_add_f32_e32 v128, v170, v144
	v_add_f32_e32 v129, v171, v177
	v_sub_f32_e32 v120, v203, v132
	v_sub_f32_e32 v121, v121, v133
	v_pk_add_f32 v[132:133], v[166:167], v[164:165]
	v_pk_add_f32 v[166:167], v[138:139], v[138:139] op_sel:[1,0] op_sel_hi:[1,0]
	v_pk_mul_f32 v[168:169], v[76:77], v[168:169]
	v_pk_add_f32 v[124:125], v[124:125], v[140:141] op_sel:[0,1] op_sel_hi:[1,0] neg_lo:[0,1] neg_hi:[0,1]
	v_pk_add_f32 v[140:141], v[134:135], v[128:129]
	v_fma_f32 v170, v14, v166, -v168
	v_fma_f32 v171, v15, v167, v169
	v_pk_add_f32 v[126:127], v[142:143], v[126:127] neg_lo:[0,1] neg_hi:[0,1]
	v_pk_mul_f32 v[166:167], v[26:27], v[140:141] op_sel:[0,1] op_sel_hi:[1,0]
	v_pk_add_f32 v[4:5], v[4:5], v[176:177] neg_lo:[0,1] neg_hi:[0,1]
	v_fma_f32 v168, v24, v140, -v166
	v_fma_f32 v141, v25, v141, v167
	v_pk_mul_f32 v[166:167], v[42:43], v[130:131] op_sel:[0,1] op_sel_hi:[1,0]
	v_pk_add_f32 v[128:129], v[128:129], v[134:135] neg_lo:[0,1] neg_hi:[0,1]
	v_pk_add_f32 v[134:135], v[4:5], v[124:125]
	v_sub_f32_e32 v143, v5, v125
	v_fma_f32 v172, v40, v130, -v166
	v_fma_f32 v131, v41, v131, v167
	v_pk_mul_f32 v[166:167], v[58:59], v[132:133] op_sel:[0,1] op_sel_hi:[1,0]
	v_pk_add_f32 v[176:177], v[126:127], v[126:127] op_sel:[0,1] op_sel_hi:[0,1] neg_lo:[0,1] neg_hi:[0,1]
	v_mov_b32_e32 v145, v143
	v_sub_f32_e32 v114, v115, v157
	v_sub_f32_e32 v115, v160, v208
	v_fma_f32 v174, v56, v132, -v166
	v_fma_f32 v133, v57, v133, v167
	v_pk_add_f32 v[166:167], v[118:119], v[118:119] op_sel:[0,1] op_sel_hi:[0,1]
	v_pk_mul_f32 v[176:177], v[72:73], v[176:177]
	v_mov_b32_e32 v144, v134
	v_pk_add_f32 v[156:157], v[146:147], v[114:115]
	v_pk_add_f32 v[114:115], v[146:147], v[114:115] neg_lo:[0,1] neg_hi:[0,1]
	v_fma_f32 v180, v18, v166, -v176
	v_fma_f32 v181, v19, v167, v177
	v_mul_f32_e32 v142, v34, v143
	v_mul_f32_e32 v143, v35, v134
	v_pk_add_f32 v[122:123], v[202:203], v[122:123]
	v_pk_add_f32 v[2:3], v[2:3], v[158:159] neg_lo:[0,1] neg_hi:[0,1]
	v_fma_f32 v166, v32, v144, -v142
	v_fma_f32 v143, v33, v145, v143
	v_mov_b32_e32 v147, v115
	v_pk_add_f32 v[122:123], v[162:163], v[122:123] neg_lo:[0,1] neg_hi:[0,1]
	v_pk_add_f32 v[158:159], v[120:121], v[2:3]
	v_sub_f32_e32 v163, v121, v3
	v_mul_f32_e32 v144, v50, v115
	v_mul_f32_e32 v145, v51, v156
	v_pk_add_f32 v[136:137], v[136:137], v[136:137] op_sel:[0,1] op_sel_hi:[0,1] neg_lo:[0,1] neg_hi:[0,1]
	v_fma_f32 v176, v48, v156, -v144
	v_fma_f32 v145, v49, v147, v145
	v_mov_b32_e32 v164, v158
	v_mul_f32_e32 v146, v66, v163
	v_mul_f32_e32 v147, v67, v158
	v_pk_add_f32 v[138:139], v[138:139], v[138:139] op_sel:[0,1] op_sel_hi:[0,1] neg_lo:[0,1] neg_hi:[0,1]
	v_pk_mul_f32 v[136:137], v[78:79], v[136:137]
	v_fma_f32 v162, v64, v164, -v146
	v_fma_f32 v147, v65, v163, v147
	v_fma_f32 v164, v16, v138, -v136
	v_fma_f32 v165, v17, v139, v137
	v_sub_f32_e32 v4, v124, v4
	v_pk_mul_f32 v[136:137], v[30:31], v[128:129] op_sel:[0,1] op_sel_hi:[1,0]
	v_sub_f32_e32 v2, v2, v120
	v_fma_f32 v138, v28, v128, -v136
	v_fma_f32 v129, v29, v129, v137
	v_pk_mul_f32 v[136:137], v[46:47], v[116:117] op_sel:[0,1] op_sel_hi:[1,0]
	v_pk_add_f32 v[126:127], v[126:127], v[126:127] op_sel:[1,0] op_sel_hi:[1,0]
	v_mov_b32_e32 v124, v4
	v_mov_b32_e32 v160, v114
	v_mov_b32_e32 v120, v2
	v_fma_f32 v182, v44, v116, -v136
	v_fma_f32 v117, v45, v117, v137
	v_pk_mul_f32 v[136:137], v[62:63], v[122:123] op_sel:[0,1] op_sel_hi:[1,0]
	v_pk_add_f32 v[118:119], v[118:119], v[118:119] op_sel:[0,1] op_sel_hi:[0,1] neg_lo:[0,1] neg_hi:[0,1]
	v_pk_mul_f32 v[126:127], v[74:75], v[126:127]
	v_mov_b32_e32 v125, v135
	v_mov_b32_e32 v161, v157
	v_fma_f32 v202, v60, v122, -v136
	v_fma_f32 v123, v61, v123, v137
	v_fma_f32 v136, v20, v118, -v126
	v_fma_f32 v137, v21, v119, v127
	v_mul_f32_e32 v5, v39, v4
	v_mul_f32_e32 v4, v38, v135
	v_mul_f32_e32 v115, v55, v114
	v_mul_f32_e32 v114, v54, v157
	v_mul_f32_e32 v3, v71, v2
	v_mul_f32_e32 v2, v70, v159
	v_fma_f32 v118, v36, v124, -v4
	v_fma_f32 v5, v37, v125, v5
	v_fma_f32 v124, v52, v160, -v114
	v_fma_f32 v126, v68, v120, -v2
	v_fma_f32 v3, v69, v159, v3
	v_fma_f32 v115, v53, v161, v115
	v_mov_b32_e32 v127, v3
	v_add_f32_e32 v206, v172, v182
	v_add_f32_e32 v207, v131, v117
	v_add_f32_e32 v212, v174, v202
	v_add_f32_e32 v213, v133, v123
	v_mov_b32_e32 v175, v131
	v_add_f32_e32 v214, v162, v126
	v_add_f32_e32 v215, v147, v127
	v_mov_b32_e32 v128, v117
	v_sub_f32_e32 v116, v174, v202
	v_sub_f32_e32 v117, v175, v117
	v_sub_f32_e32 v2, v147, v3
	v_sub_f32_e32 v3, v176, v124
	v_mov_b32_e32 v119, v5
	v_add_f32_e32 v158, v168, v138
	v_add_f32_e32 v159, v141, v129
	v_add_f32_e32 v208, v176, v124
	v_add_f32_e32 v209, v145, v115
	v_mov_b32_e32 v225, v168
	v_sub_f32_e32 v4, v145, v115
	v_sub_f32_e32 v5, v143, v5
	v_mov_b32_e32 v142, v124
	v_sub_f32_e32 v122, v133, v123
	v_sub_f32_e32 v123, v172, v182
	v_sub_f32_e32 v114, v162, v126
	v_sub_f32_e32 v115, v145, v115
	v_pk_add_f32 v[124:125], v[116:117], v[2:3]
	v_pk_add_f32 v[2:3], v[116:117], v[2:3] neg_lo:[0,1] neg_hi:[0,1]
	v_sub_f32_e32 v139, v225, v138
	v_sub_f32_e32 v138, v172, v182
	v_sub_f32_e32 v128, v131, v128
	v_sub_f32_e32 v129, v141, v129
	v_pk_add_f32 v[126:127], v[122:123], v[114:115] neg_lo:[0,1] neg_hi:[0,1]
	v_pk_add_f32 v[114:115], v[122:123], v[114:115]
	v_pk_add_f32 v[120:121], v[170:171], v[164:165]
	v_pk_add_f32 v[134:135], v[180:181], v[136:137]
	v_add_f32_e32 v160, v166, v118
	v_add_f32_e32 v161, v143, v119
	v_sub_f32_e32 v119, v166, v118
	v_sub_f32_e32 v118, v176, v142
	v_pk_add_f32 v[130:131], v[138:139], v[4:5]
	v_mul_f32_e32 v141, 0x3f3504f3, v125
	v_mul_f32_e32 v116, s74, v124
	v_mul_f32_e32 v117, s75, v3
	v_mul_f32_e32 v4, 0x3f6c835e, v126
	v_pk_add_f32 v[156:157], v[120:121], v[134:135]
	v_pk_add_f32 v[210:211], v[206:207], v[208:209]
	v_pk_add_f32 v[216:217], v[212:213], v[214:215]
	v_pk_add_f32 v[120:121], v[120:121], v[134:135] neg_lo:[0,1] neg_hi:[0,1]
	v_pk_add_f32 v[134:135], v[206:207], v[208:209] neg_lo:[0,1] neg_hi:[0,1]
	v_mov_b32_e32 v207, v212
	v_mov_b32_e32 v209, v214
	v_fma_f32 v116, v126, s72, -v116
	v_fma_f32 v117, v115, s73, -v117
	v_fma_f32 v122, v124, s80, -v4
	v_add_f32_e32 v4, v129, v119
	v_pk_add_f32 v[204:205], v[158:159], v[160:161]
	v_pk_add_f32 v[136:137], v[180:181], v[136:137] neg_lo:[0,1] neg_hi:[0,1]
	v_mov_b32_e32 v206, v158
	v_sub_f32_e32 v158, v159, v161
	v_sub_f32_e32 v159, v213, v215
	v_pk_add_f32 v[132:133], v[128:129], v[118:119] neg_lo:[0,1] neg_hi:[0,1]
	v_pk_mul_f32 v[118:119], v[4:5], s[88:89] op_sel_hi:[0,1]
	v_sub_f32_e32 v4, v139, v5
	v_pk_add_f32 v[164:165], v[170:171], v[164:165] neg_lo:[0,1] neg_hi:[0,1]
	v_mov_b32_e32 v171, v136
	v_sub_f32_e32 v206, v206, v160
	v_sub_f32_e32 v207, v207, v209
	v_pk_mul_f32 v[158:159], v[158:159], s[20:21] op_sel_hi:[1,0]
	v_fma_f32 v128, v4, s70, -v118
	v_fma_f32 v129, v4, s71, v119
	v_fma_f32 v161, v207, s3, -v159
	v_fma_f32 v208, v206, s2, v158
	v_pk_fma_f32 v[158:159], v[206:207], s[20:21], v[158:159] op_sel_hi:[1,0,1] neg_lo:[0,0,1] neg_hi:[0,0,1]
	v_pk_add_f32 v[206:207], v[120:121], v[134:135] op_sel:[0,1] op_sel_hi:[1,0] neg_lo:[0,1] neg_hi:[0,1]
	v_pk_add_f32 v[120:121], v[120:121], v[134:135] op_sel:[0,1] op_sel_hi:[1,0]
	v_mul_f32_e32 v170, 0x3f6c835e, v133
	s_mov_b32 s92, s3
	s_mov_b32 s93, s21
	v_pk_mul_f32 v[132:133], v[132:133], s[90:91]
	v_pk_mul_f32 v[4:5], v[114:115], s[70:71] op_sel_hi:[0,1]
	v_sub_f32_e32 v180, v164, v137
	v_pk_add_f32 v[136:137], v[164:165], v[136:137] op_sel:[0,1] op_sel_hi:[1,0]
	v_mov_b32_e32 v135, v121
	v_mul_f32_e32 v164, 0x3ec3ef15, v131
	v_mul_f32_e32 v121, 0x3f3504f3, v127
	v_fma_f32 v142, v130, s92, -v132
	v_fma_f32 v131, v131, s93, v133
	v_fma_f32 v114, v2, s88, -v4
	v_fma_f32 v115, v2, s89, v5
	v_mov_b32_e32 v1, v6
	v_mov_b32_e32 v181, v137
	v_pk_add_f32 v[124:125], v[164:165], v[170:171] neg_lo:[0,1] neg_hi:[0,1]
	v_sub_f32_e32 v140, v121, v141
	v_fmac_f32_e32 v141, 0x3f3504f3, v127
	s_barrier
	v_pk_add_f32 v[218:219], v[156:157], v[210:211]
	v_pk_add_f32 v[220:221], v[204:205], v[216:217]
	v_pk_add_f32 v[2:3], v[180:181], v[140:141]
	v_pk_add_f32 v[4:5], v[128:129], v[114:115]
	v_add_f32_e32 v126, v142, v136
	v_add_f32_e32 v127, v131, v122
	v_pk_add_f32 v[132:133], v[124:125], v[116:117]
	v_mul_lo_u32 v1, v1, s33
	v_pk_add_f32 v[222:223], v[218:219], v[220:221]
	v_mov_b32_e32 v134, v206
	v_add_f32_e32 v212, v158, v161
	v_add_f32_e32 v213, v159, v208
	v_pk_add_f32 v[118:119], v[2:3], v[4:5]
	v_pk_add_f32 v[138:139], v[132:133], v[126:127]
	v_pk_add_f32 v[214:215], v[134:135], v[212:213]
	ds_write2_b64 v1, v[222:223], v[118:119] offset1:1
	ds_write2_b64 v1, v[214:215], v[138:139] offset0:2 offset1:3
	v_pk_add_f32 v[118:119], v[156:157], v[210:211] neg_lo:[0,1] neg_hi:[0,1]
	v_pk_add_f32 v[138:139], v[204:205], v[216:217] neg_lo:[0,1] neg_hi:[0,1]
	v_pk_add_f32 v[114:115], v[128:129], v[114:115] neg_lo:[0,1] neg_hi:[0,1]
	v_pk_add_f32 v[144:145], v[118:119], v[138:139] op_sel:[0,1] op_sel_hi:[1,0] neg_lo:[0,1] neg_hi:[0,1]
	v_pk_add_f32 v[118:119], v[118:119], v[138:139] op_sel:[0,1] op_sel_hi:[1,0]
	v_pk_add_f32 v[138:139], v[180:181], v[140:141] neg_lo:[0,1] neg_hi:[0,1]
	v_pk_add_f32 v[128:129], v[138:139], v[114:115] op_sel:[0,1] op_sel_hi:[1,0] neg_lo:[0,1] neg_hi:[0,1]
	v_pk_add_f32 v[114:115], v[138:139], v[114:115] op_sel:[0,1] op_sel_hi:[1,0]
	v_mov_b32_e32 v138, v144
	v_mov_b32_e32 v139, v119
	v_mov_b32_e32 v140, v128
	v_mov_b32_e32 v141, v115
	ds_write2_b64 v1, v[138:139], v[140:141] offset0:4 offset1:5
	v_mov_b32_e32 v121, v207
	v_sub_f32_e32 v138, v208, v159
	v_sub_f32_e32 v139, v158, v161
	v_sub_f32_e32 v122, v131, v122
	v_sub_f32_e32 v123, v124, v116
	v_sub_f32_e32 v116, v136, v142
	v_sub_f32_e32 v117, v125, v117
	v_pk_add_f32 v[140:141], v[120:121], v[138:139] neg_lo:[0,1] neg_hi:[0,1]
	v_pk_add_f32 v[120:121], v[120:121], v[138:139]
	v_pk_add_f32 v[124:125], v[116:117], v[122:123] neg_lo:[0,1] neg_hi:[0,1]
	v_pk_add_f32 v[116:117], v[116:117], v[122:123]
	v_mov_b32_e32 v122, v140
	v_mov_b32_e32 v123, v121
	v_mov_b32_e32 v130, v124
	v_mov_b32_e32 v131, v117
	ds_write2_b64 v1, v[122:123], v[130:131] offset0:6 offset1:7
	v_pk_add_f32 v[122:123], v[218:219], v[220:221] neg_lo:[0,1] neg_hi:[0,1]
	v_pk_add_f32 v[2:3], v[2:3], v[4:5] neg_lo:[0,1] neg_hi:[0,1]
	v_mov_b32_e32 v5, v133
	ds_write2_b64 v1, v[122:123], v[2:3] offset0:8 offset1:9
	v_pk_add_f32 v[2:3], v[134:135], v[212:213] neg_lo:[0,1] neg_hi:[0,1]
	v_sub_f32_e32 v4, v126, v132
	v_sub_f32_e32 v5, v5, v127
	v_mov_b32_e32 v119, v145
	v_mov_b32_e32 v115, v129
	v_mov_b32_e32 v121, v141
	v_mov_b32_e32 v117, v125
	ds_write2_b64 v1, v[2:3], v[4:5] offset0:10 offset1:11
	ds_write2_b64 v1, v[118:119], v[114:115] offset0:12 offset1:13
	ds_write2_b64 v1, v[120:121], v[116:117] offset0:14 offset1:15
	v_mov_b32_e32 v1, v12
	s_waitcnt lgkmcnt(0)
	s_barrier
	v_mov_b32_e32 v155, 0
	v_ashrrev_i32_e32 v2, 31, v1
	v_lshrrev_b32_e32 v2, 28, v2
	v_and_b32_e32 v142, 15, v1
	v_add_u32_e32 v1, v1, v2
	v_ashrrev_i32_e32 v1, 4, v1
	v_lshlrev_b32_e32 v2, 11, v1
	v_lshl_add_u32 v1, v1, 7, v2
	v_lshl_or_b32 v1, v142, 3, v1
	ds_read2_b64 v[2:5], v1 offset1:17
	ds_read2_b64 v[114:117], v1 offset0:34 offset1:51
	ds_read2_b64 v[118:121], v1 offset0:68 offset1:85
	ds_read2_b64 v[122:125], v1 offset0:102 offset1:119
	ds_read2_b64 v[126:129], v1 offset0:136 offset1:153
	ds_read2_b64 v[130:133], v1 offset0:170 offset1:187
	ds_read2_b64 v[134:137], v1 offset0:204 offset1:221
	ds_read2_b64 v[138:141], v1 offset0:238 offset1:255
	s_waitcnt lgkmcnt(4)
	v_mov_b32_e32 v214, v122
	v_cvt_f32_i32_e32 v142, v142
	v_mov_b32_e32 v215, v121
	v_pk_mov_b32 v[120:121], v[122:123], v[120:121] op_sel:[1,0]
	v_add_f32_e32 v142, v142, v142
	v_mul_f32_e32 v142, 0x3b800000, v142
	v_mul_f32_e32 v142, 0.5, v142
	v_sin_f32_e32 v143, v142
	v_cos_f32_e32 v142, v142
	v_mul_f32_e32 v146, v143, v143
	v_mul_f32_e32 v144, v142, v143
	v_pk_fma_f32 v[146:147], v[142:143], v[142:143], v[146:147] op_sel_hi:[1,1,0] neg_lo:[0,0,1] neg_hi:[0,0,1]
	v_add_f32_e32 v144, v144, v144
	v_mov_b32_e32 v156, v146
	v_mov_b32_e32 v157, v142
	v_mov_b32_e32 v145, v143
	v_pk_mul_f32 v[158:159], v[156:157], v[146:147] op_sel_hi:[1,0]
	v_pk_mul_f32 v[162:163], v[144:145], v[146:147] op_sel_hi:[1,0]
	v_pk_fma_f32 v[170:171], v[144:145], v[144:145], v[158:159] op_sel_hi:[1,0,1] neg_lo:[1,0,0] neg_hi:[1,0,0]
	v_pk_fma_f32 v[164:165], v[156:157], v[144:145], v[162:163] op_sel_hi:[1,0,1]
	v_mov_b32_e32 v172, v170
	v_mov_b32_e32 v173, v142
	v_mov_b32_e32 v180, v144
	v_mov_b32_e32 v181, v164
	v_mul_f32_e32 v161, v157, v144
	v_mov_b32_e32 v166, v164
	v_mov_b32_e32 v167, v143
	v_pk_mul_f32 v[174:175], v[172:173], v[170:171] op_sel_hi:[1,0]
	v_mov_b32_e32 v147, v170
	v_pk_mul_f32 v[202:203], v[180:181], v[170:171] op_sel_hi:[1,0]
	v_pk_mul_f32 v[204:205], v[166:167], v[146:147]
	v_pk_mul_f32 v[182:183], v[164:165], v[180:181] op_sel_hi:[0,1]
	v_add_f32_e32 v160, v203, v203
	v_add_f32_e32 v161, v161, v163
	v_pk_fma_f32 v[162:163], v[172:173], v[180:181], v[204:205]
	v_fma_f32 v158, -v166, v164, v174
	v_fma_f32 v159, -v167, v144, v159
	v_mul_f32_e32 v168, v170, v165
	v_mul_f32_e32 v204, v164, v171
	v_pk_mul_f32 v[206:207], v[166:167], v[170:171] op_sel_hi:[1,0]
	v_pk_fma_f32 v[166:167], v[166:167], v[164:165], v[174:175] op_sel_hi:[1,0,1] neg_lo:[1,0,0] neg_hi:[1,0,0]
	v_pk_fma_f32 v[174:175], v[170:171], v[146:147], v[182:183] op_sel_hi:[0,1,1] neg_lo:[0,0,1] neg_hi:[0,0,1]
	v_pk_fma_f32 v[182:183], v[146:147], v[164:165], v[202:203] op_sel_hi:[1,0,1]
	v_add_f32_e32 v168, v168, v204
	v_add_f32_e32 v169, v203, v203
	v_mov_b32_e32 v205, v142
	v_pk_mul_f32 v[180:181], v[164:165], v[164:165] op_sel_hi:[0,1]
	v_pk_fma_f32 v[172:173], v[172:173], v[164:165], v[206:207] op_sel_hi:[1,0,1]
	v_mov_b32_e32 v204, v166
	v_mul_f32_e32 v142, v183, v146
	v_mul_f32_e32 v143, v143, v166
	v_pk_fma_f32 v[180:181], v[170:171], v[170:171], v[180:181] op_sel_hi:[0,1,1] neg_lo:[0,0,1] neg_hi:[0,0,1]
	v_fma_f32 v142, v204, v144, v142
	v_fma_f32 v143, v205, v183, v143
	v_pk_mov_b32 v[206:207], v[182:183], v[164:165] op_sel:[1,0]
	v_mov_b32_e32 v205, v170
	v_pk_mul_f32 v[208:209], v[206:207], v[168:169]
	v_pk_mul_f32 v[206:207], v[206:207], v[180:181] op_sel:[0,1] op_sel_hi:[1,0]
	v_pk_mul_f32 v[172:173], v[172:173], v[174:175]
	v_pk_fma_f32 v[174:175], v[204:205], v[180:181], v[208:209] op_sel:[0,1,0] op_sel_hi:[1,0,1] neg_lo:[0,0,1] neg_hi:[0,0,1]
	v_pk_fma_f32 v[204:205], v[204:205], v[168:169], v[206:207]
	v_mov_b32_e32 v206, v114
	v_mov_b32_e32 v207, v5
	v_pk_mov_b32 v[4:5], v[114:115], v[4:5] op_sel:[1,0]
	v_pk_mul_f32 v[176:177], v[144:145], v[164:165] op_sel_hi:[1,0]
	v_pk_mul_f32 v[202:203], v[144:145], v[182:183] op_sel:[0,1]
	v_pk_mul_f32 v[114:115], v[4:5], v[144:145]
	v_pk_mul_f32 v[144:145], v[206:207], v[144:145]
	v_mul_f32_e32 v160, v170, v160
	v_mul_f32_e32 v161, v166, v161
	v_pk_fma_f32 v[208:209], v[206:207], v[156:157], v[114:115] neg_lo:[0,0,1] neg_hi:[0,0,1]
	v_fma_f32 v115, v207, v157, v115
	v_fma_f32 v207, v5, v157, -v145
	v_fma_f32 v4, v4, v156, v144
	v_pk_fma_f32 v[176:177], v[156:157], v[170:171], v[176:177] op_sel_hi:[1,0,1] neg_lo:[0,0,1] neg_hi:[0,0,1]
	v_pk_fma_f32 v[202:203], v[156:157], v[166:167], v[202:203] op_sel_hi:[1,0,1] neg_lo:[0,0,1] neg_hi:[0,0,1]
	v_fma_f32 v158, v164, v158, v160
	v_fma_f32 v159, v183, v159, v161
	v_pk_mul_f32 v[160:161], v[182:183], v[162:163] op_sel:[1,0]
	v_mov_b32_e32 v156, v171
	v_mul_f32_e32 v206, v117, v165
	v_pk_mul_f32 v[122:123], v[120:121], v[162:163]
	v_pk_mul_f32 v[162:163], v[214:215], v[162:163]
	v_pk_fma_f32 v[160:161], v[166:167], v[176:177], v[160:161] op_sel_hi:[0,1,1] neg_lo:[0,0,1] neg_hi:[0,0,1]
	v_fma_f32 v156, v116, v156, -v206
	v_mov_b32_e32 v210, v118
	v_mov_b32_e32 v211, v117
	v_pk_mov_b32 v[116:117], v[118:119], v[116:117] op_sel:[1,0]
	v_fma_f32 v216, v214, v176, -v122
	v_fma_f32 v123, v215, v177, v123
	v_pk_fma_f32 v[214:215], v[120:121], v[176:177], v[162:163] neg_lo:[0,0,1] neg_hi:[0,0,1]
	v_fma_f32 v120, v120, v176, v162
	v_mov_b32_e32 v177, v119
	v_mul_f32_e32 v119, v118, v164
	v_mul_f32_e32 v118, v125, v168
	v_mul_f32_e32 v122, v125, v181
	v_pk_mul_f32 v[146:147], v[164:165], v[182:183] op_sel:[0,1]
	v_pk_mul_f32 v[116:117], v[116:117], v[164:165]
	v_mov_b32_e32 v176, v124
	v_fma_f32 v124, v124, v168, v122
	s_waitcnt lgkmcnt(2)
	v_mov_b32_e32 v168, v130
	v_mov_b32_e32 v169, v129
	v_pk_mov_b32 v[128:129], v[130:131], v[128:129] op_sel:[1,0]
	v_pk_fma_f32 v[146:147], v[170:171], v[166:167], v[146:147] op_sel_hi:[1,0,1] neg_lo:[0,0,1] neg_hi:[0,0,1]
	v_fma_f32 v212, v210, v170, -v116
	v_fma_f32 v117, v211, v171, v117
	v_pk_mov_b32 v[170:171], v[180:181], v[170:171] op_sel:[1,0]
	v_pk_mul_f32 v[130:131], v[128:129], v[142:143]
	v_pk_mul_f32 v[142:143], v[168:169], v[142:143]
	v_fma_f32 v164, v176, v170, -v118
	v_fma_f32 v119, v177, v171, v119
	v_pk_fma_f32 v[170:171], v[168:169], v[202:203], v[130:131] neg_lo:[0,0,1] neg_hi:[0,0,1]
	v_fma_f32 v131, v169, v203, v131
	v_fma_f32 v169, v129, v203, -v143
	v_fma_f32 v128, v128, v202, v142
	v_mov_b32_e32 v176, v132
	v_mov_b32_e32 v177, v127
	v_pk_mov_b32 v[180:181], v[146:147], v[166:167] op_sel:[1,0]
	v_mul_f32_e32 v202, v133, v159
	v_mul_f32_e32 v203, v126, v183
	v_pk_fma_f32 v[172:173], v[166:167], v[182:183], v[172:173]
	v_fma_f32 v218, v176, v180, -v202
	v_fma_f32 v177, v177, v181, v203
	v_mov_b32_e32 v181, v133
	s_waitcnt lgkmcnt(1)
	v_mov_b32_e32 v180, v134
	v_mul_f32_e32 v133, v132, v159
	v_mul_f32_e32 v132, v135, v158
	v_fma_f32 v158, v180, v146, -v132
	v_fma_f32 v133, v181, v147, v133
	s_waitcnt lgkmcnt(0)
	v_mov_b32_e32 v180, v138
	v_mov_b32_e32 v181, v137
	v_pk_mov_b32 v[136:137], v[138:139], v[136:137] op_sel:[1,0]
	v_pk_mul_f32 v[138:139], v[136:137], v[172:173]
	v_pk_mul_f32 v[172:173], v[180:181], v[172:173]
	v_pk_fma_f32 v[202:203], v[180:181], v[160:161], v[138:139] neg_lo:[0,0,1] neg_hi:[0,0,1]
	v_fma_f32 v139, v181, v161, v139
	v_fma_f32 v181, v137, v161, -v173
	v_fma_f32 v136, v136, v160, v172
	v_mov_b32_e32 v173, v135
	v_mov_b32_e32 v172, v140
	v_mul_f32_e32 v135, v134, v205
	v_mul_f32_e32 v134, v141, v204
	v_fma_f32 v220, v172, v174, -v134
	v_fma_f32 v135, v173, v175, v135
	v_pk_mov_b32 v[172:173], v[126:127], v[140:141] op_sel:[1,0]
	v_mul_f32_e32 v172, v172, v183
	v_mul_f32_e32 v173, v173, v204
	v_fma_f32 v140, v126, v166, -v172
	v_fma_f32 v127, v141, v174, v173
	v_mov_b32_e32 v141, v127
	v_add_f32_e32 v172, v156, v218
	v_add_f32_e32 v173, v3, v177
	v_mov_b32_e32 v219, v128
	v_mov_b32_e32 v211, v117
	v_mov_b32_e32 v147, v133
	v_mov_b32_e32 v167, v124
	v_add_f32_e32 v174, v164, v220
	v_add_f32_e32 v175, v119, v135
	v_add_f32_e32 v142, v207, v169
	v_add_f32_e32 v143, v4, v128
	v_add_f32_e32 v144, v215, v181
	v_add_f32_e32 v145, v120, v136
	v_add_f32_e32 v160, v208, v170
	v_add_f32_e32 v161, v115, v131
	v_sub_f32_e32 v114, v4, v128
	v_sub_f32_e32 v115, v115, v131
	v_mov_b32_e32 v221, v136
	v_sub_f32_e32 v5, v4, v219
	v_sub_f32_e32 v4, v156, v218
	v_sub_f32_e32 v124, v124, v127
	v_sub_f32_e32 v125, v216, v202
	v_add_f32_e32 v162, v216, v202
	v_add_f32_e32 v163, v123, v139
	v_mov_b32_e32 v206, v208
	v_sub_f32_e32 v122, v120, v136
	v_sub_f32_e32 v123, v123, v139
	v_mov_b32_e32 v217, v215
	v_mov_b32_e32 v180, v202
	v_sub_f32_e32 v116, v117, v133
	v_sub_f32_e32 v117, v208, v170
	v_sub_f32_e32 v121, v120, v221
	v_sub_f32_e32 v120, v164, v220
	v_pk_add_f32 v[126:127], v[4:5], v[124:125]
	v_pk_add_f32 v[4:5], v[4:5], v[124:125] neg_lo:[0,1] neg_hi:[0,1]
	v_add_f32_e32 v166, v2, v140
	v_add_f32_e32 v167, v167, v141
	v_sub_f32_e32 v168, v206, v170
	v_sub_f32_e32 v169, v207, v169
	v_pk_add_f32 v[130:131], v[216:217], v[180:181] neg_lo:[0,1] neg_hi:[0,1]
	v_pk_add_f32 v[132:133], v[116:117], v[120:121] neg_lo:[0,1] neg_hi:[0,1]
	v_pk_add_f32 v[116:117], v[116:117], v[120:121]
	v_sub_f32_e32 v2, v2, v140
	v_sub_f32_e32 v3, v3, v177
	v_sub_f32_e32 v118, v119, v135
	v_sub_f32_e32 v119, v212, v158
	v_pk_add_f32 v[128:129], v[168:169], v[122:123]
	v_pk_add_f32 v[136:137], v[114:115], v[130:131] neg_lo:[0,1] neg_hi:[0,1]
	v_mul_f32_e32 v139, 0x3f3504f3, v127
	v_mul_f32_e32 v120, s74, v126
	v_mul_f32_e32 v121, s75, v5
	v_mul_f32_e32 v114, 0x3f6c835e, v132
	v_add_f32_e32 v146, v212, v158
	v_add_f32_e32 v147, v211, v147
	v_sub_f32_e32 v134, v2, v118
	v_pk_add_f32 v[140:141], v[2:3], v[118:119]
	v_mul_f32_e32 v2, 0x3ec3ef15, v129
	v_mul_f32_e32 v118, 0x3f6c835e, v137
	v_fma_f32 v120, v132, s72, -v120
	v_fma_f32 v121, v117, s73, -v121
	v_fma_f32 v124, v126, s80, -v114
	v_add_f32_e32 v114, v115, v131
	v_pk_add_f32 v[2:3], v[2:3], v[118:119] neg_lo:[0,1] neg_hi:[0,1]
	v_pk_mul_f32 v[114:115], v[114:115], s[88:89] op_sel_hi:[0,1]
	v_sub_f32_e32 v118, v169, v123
	v_pk_add_f32 v[204:205], v[142:143], v[144:145]
	v_pk_add_f32 v[222:223], v[146:147], v[166:167]
	v_sub_f32_e32 v158, v166, v146
	v_sub_f32_e32 v159, v160, v162
	v_mov_b32_e32 v176, v143
	v_mov_b32_e32 v212, v145
	v_fma_f32 v122, v118, s70, -v114
	v_fma_f32 v123, v118, s71, v115
	v_sub_f32_e32 v142, v142, v144
	v_sub_f32_e32 v143, v172, v174
	v_sub_f32_e32 v144, v161, v163
	v_sub_f32_e32 v145, v147, v167
	v_pk_mul_f32 v[136:137], v[136:137], s[90:91]
	v_pk_mul_f32 v[114:115], v[116:117], s[70:71] op_sel_hi:[0,1]
	v_mov_b32_e32 v213, v175
	v_pk_mul_f32 v[144:145], v[144:145], s[20:21] op_sel_hi:[1,0]
	v_mul_f32_e32 v130, 0x3f3504f3, v133
	v_fma_f32 v156, v128, s92, -v136
	v_fma_f32 v129, v129, s93, v137
	v_fma_f32 v116, v4, s88, -v114
	v_fma_f32 v117, v4, s89, v115
	v_pk_add_f32 v[182:183], v[160:161], v[162:163]
	v_pk_add_f32 v[210:211], v[172:173], v[174:175]
	v_mov_b32_e32 v135, v141
	v_sub_f32_e32 v176, v176, v212
	v_sub_f32_e32 v177, v173, v213
	v_fma_f32 v147, v143, s3, -v145
	v_fma_f32 v160, v142, s2, v144
	v_sub_f32_e32 v138, v130, v139
	v_fmac_f32_e32 v139, 0x3f3504f3, v133
	v_pk_add_f32 v[224:225], v[204:205], v[210:211]
	v_pk_add_f32 v[226:227], v[182:183], v[222:223]
	v_pk_fma_f32 v[142:143], v[142:143], s[20:21], v[144:145] op_sel_hi:[1,0,1] neg_lo:[0,0,1] neg_hi:[0,0,1]
	v_sub_f32_e32 v144, v158, v176
	v_pk_add_f32 v[166:167], v[158:159], v[176:177]
	v_pk_add_f32 v[4:5], v[134:135], v[138:139]
	v_pk_add_f32 v[114:115], v[122:123], v[116:117]
	v_add_f32_e32 v126, v156, v140
	v_add_f32_e32 v127, v129, v124
	v_pk_add_f32 v[130:131], v[2:3], v[120:121]
	v_pk_add_f32 v[228:229], v[226:227], v[224:225]
	v_mov_b32_e32 v145, v167
	v_add_f32_e32 v162, v142, v147
	v_add_f32_e32 v163, v143, v160
	v_pk_add_f32 v[118:119], v[4:5], v[114:115]
	v_pk_add_f32 v[132:133], v[130:131], v[126:127]
	v_pk_add_f32 v[172:173], v[144:145], v[162:163]
	ds_write2_b64 v1, v[228:229], v[118:119] offset1:17
	ds_write2_b64 v1, v[172:173], v[132:133] offset0:34 offset1:51
	v_mov_b32_e32 v119, v204
	v_mov_b32_e32 v133, v210
	v_mov_b32_e32 v210, v183
	v_mov_b32_e32 v204, v223
	v_sub_f32_e32 v118, v222, v182
	v_sub_f32_e32 v119, v119, v133
	v_pk_add_f32 v[132:133], v[210:211], v[204:205] neg_lo:[0,1] neg_hi:[0,1]
	v_pk_add_f32 v[134:135], v[134:135], v[138:139] neg_lo:[0,1] neg_hi:[0,1]
	v_pk_add_f32 v[116:117], v[122:123], v[116:117] neg_lo:[0,1] neg_hi:[0,1]
	v_sub_f32_e32 v136, v118, v132
	v_pk_add_f32 v[164:165], v[118:119], v[132:133]
	v_pk_add_f32 v[122:123], v[134:135], v[116:117] op_sel:[0,1] op_sel_hi:[1,0] neg_lo:[0,1] neg_hi:[0,1]
	v_pk_add_f32 v[116:117], v[134:135], v[116:117] op_sel:[0,1] op_sel_hi:[1,0]
	v_mov_b32_e32 v137, v165
	v_mov_b32_e32 v134, v122
	v_mov_b32_e32 v135, v117
	ds_write2_b64 v1, v[136:137], v[134:135] offset0:68 offset1:85
	v_sub_f32_e32 v167, v177, v159
	v_mov_b32_e32 v161, v142
	v_mov_b32_e32 v146, v143
	v_mov_b32_e32 v157, v121
	v_pk_add_f32 v[134:135], v[160:161], v[146:147] neg_lo:[0,1] neg_hi:[0,1]
	v_sub_f32_e32 v124, v129, v124
	v_sub_f32_e32 v125, v2, v120
	v_sub_f32_e32 v2, v140, v156
	v_sub_f32_e32 v3, v3, v157
	v_pk_add_f32 v[136:137], v[166:167], v[134:135] neg_lo:[0,1] neg_hi:[0,1]
	v_pk_add_f32 v[134:135], v[166:167], v[134:135]
	v_pk_add_f32 v[120:121], v[2:3], v[124:125] neg_lo:[0,1] neg_hi:[0,1]
	v_pk_add_f32 v[2:3], v[2:3], v[124:125]
	v_mov_b32_e32 v138, v136
	v_mov_b32_e32 v139, v135
	v_mov_b32_e32 v124, v120
	v_mov_b32_e32 v125, v3
	ds_write2_b64 v1, v[138:139], v[124:125] offset0:102 offset1:119
	v_mov_b32_e32 v125, v225
	v_mov_b32_e32 v225, v227
	v_sub_f32_e32 v124, v226, v224
	v_sub_f32_e32 v125, v125, v225
	v_pk_add_f32 v[4:5], v[4:5], v[114:115] neg_lo:[0,1] neg_hi:[0,1]
	v_mov_b32_e32 v115, v131
	ds_write2_b64 v1, v[124:125], v[4:5] offset0:136 offset1:153
	v_pk_add_f32 v[4:5], v[144:145], v[162:163] neg_lo:[0,1] neg_hi:[0,1]
	v_sub_f32_e32 v114, v126, v130
	v_sub_f32_e32 v115, v115, v127
	ds_write2_b64 v1, v[4:5], v[114:115] offset0:170 offset1:187
	v_sub_f32_e32 v165, v133, v119
	v_mov_b32_e32 v135, v137
	v_mov_b32_e32 v3, v121
	v_mov_b32_e32 v117, v123
	ds_write2_b64 v1, v[134:135], v[2:3] offset0:238 offset1:255
	v_mov_b32_e32 v2, v6
	ds_write2_b64 v1, v[164:165], v[116:117] offset0:204 offset1:221
	s_waitcnt lgkmcnt(0)
	s_barrier
	s_lshl_b64 s[88:89], s[24:25], 1
	v_ashrrev_i32_e32 v3, 31, v2
	v_lshrrev_b32_e32 v3, 24, v3
	v_and_b32_e32 v1, 0xff, v2
	v_add_lshl_u32 v2, v2, v3, 4
	v_and_or_b32 v2, v2, s87, v1
	v_ashrrev_i32_e32 v3, 4, v2
	v_lshlrev_b32_e32 v2, 3, v2
	v_lshl_add_u32 v2, v3, 3, v2
	ds_read_b64 v[114:115], v2
	ds_read_b64 v[144:145], v2 offset:2176
	ds_read_b64 v[142:143], v2 offset:4352
	ds_read_b64 v[140:141], v2 offset:6528
	ds_read_b64 v[138:139], v2 offset:8704
	ds_read_b64 v[136:137], v2 offset:10880
	ds_read_b64 v[134:135], v2 offset:13056
	ds_read_b64 v[132:133], v2 offset:15232
	ds_read_b64 v[130:131], v2 offset:17408
	ds_read_b64 v[128:129], v2 offset:19584
	ds_read_b64 v[126:127], v2 offset:21760
	ds_read_b64 v[124:125], v2 offset:23936
	ds_read_b64 v[122:123], v2 offset:26112
	ds_read_b64 v[120:121], v2 offset:28288
	ds_read_b64 v[118:119], v2 offset:30464
	ds_read_b64 v[116:117], v2 offset:32640
	s_add_u32 s88, s1, s88
	s_addc_u32 s89, s94, s89
	v_lshl_add_u64 v[4:5], v[12:13], 1, s[88:89]
	v_mov_b32_e32 v158, 0
	s_and_saveexec_b64 s[90:91], s[36:37]
	s_cbranch_execz .LBB0_216
	global_load_ushort v2, v[4:5], off offset:-2
	s_waitcnt vmcnt(0)
	v_lshlrev_b32_e32 v158, 16, v2

.LBB0_346:
	s_or_b64 exec, exec, s[92:93]
	v_cndmask_b32_e64 v2, 0, v114, s[60:61]
	s_waitcnt vmcnt(1)
	v_fmac_f32_e32 v2, v1, v36
	v_add_f32_e32 v36, v2, v37
	v_cndmask_b32_e64 v37, 0, v114, s[58:59]
	v_fmac_f32_e32 v37, v1, v35
	v_add_f32_e32 v37, v37, v34
	v_cndmask_b32_e64 v34, 0, v114, s[56:57]
	v_fmac_f32_e32 v34, v1, v31
	v_add_f32_e32 v31, v34, v33
	v_cndmask_b32_e64 v33, 0, v114, s[54:55]
	v_fmac_f32_e32 v33, v1, v30
	v_cndmask_b32_e64 v30, 0, v114, s[52:53]
	v_fmac_f32_e32 v30, v1, v27
	v_cndmask_b32_e64 v27, 0, v114, s[50:51]
	v_fmac_f32_e32 v27, v1, v26
	v_add_f32_e32 v34, v30, v28
	v_add_f32_e32 v28, v27, v25
	v_cndmask_b32_e64 v25, 0, v114, s[0:1]
	v_fmac_f32_e32 v25, v1, v23
	v_cndmask_b32_e64 v23, 0, v114, s[48:49]
	v_fmac_f32_e32 v23, v1, v22
	v_cndmask_b32_e64 v22, 0, v114, s[46:47]
	v_fmac_f32_e32 v22, v1, v19
	v_cndmask_b32_e64 v19, 0, v114, s[44:45]
	v_fmac_f32_e32 v19, v1, v18
	v_add_f32_e32 v21, v23, v21
	v_add_f32_e32 v23, v19, v17
	v_cndmask_b32_e64 v17, 0, v114, s[42:43]
	v_fmac_f32_e32 v17, v1, v15
	v_cndmask_b32_e64 v15, 0, v114, s[40:41]
	v_fmac_f32_e32 v15, v1, v14
	v_add_f32_e32 v15, v15, v13
	v_cndmask_b32_e64 v13, 0, v114, s[38:39]
	v_fmac_f32_e32 v13, v1, v9
	v_cndmask_b32_e64 v9, 0, v114, s[36:37]
	v_fmac_f32_e32 v9, v1, v7
	v_cndmask_b32_e64 v2, 0, v114, s[62:63]
	v_add_f32_e32 v14, v9, v4
	v_cndmask_b32_e32 v4, 0, v114, vcc
	s_waitcnt vmcnt(0)
	v_fmac_f32_e32 v2, v1, v38
	v_fmac_f32_e32 v4, v1, v3
	v_mov_b32_e32 v1, v122
	v_add_f32_e32 v19, v2, v32
	s_barrier
	v_add_f32_e32 v30, v25, v24
	v_ashrrev_i32_e32 v2, 31, v1
	v_lshrrev_b32_e32 v2, 24, v2
	v_and_b32_e32 v7, 0xff, v1
	v_add_lshl_u32 v1, v1, v2, 4
	v_add_f32_e32 v25, v17, v16
	v_add_f32_e32 v16, v13, v11
	v_and_or_b32 v1, v1, s87, v7
	v_ashrrev_i32_e32 v2, 4, v1
	v_lshlrev_b32_e32 v1, 3, v1
	v_sub_f32_e32 v42, v16, v34
	v_sub_f32_e32 v43, v14, v28
	v_lshl_add_u32 v9, v2, 3, v1
	v_add_f32_e32 v1, 0, v42
	v_mul_f32_e32 v11, 0x3f3504f3, v1
	v_add_f32_e32 v22, v22, v20
	v_cvt_f32_i32_e32 v1, v7
	v_add_f32_e32 v24, v4, v5
	v_add_f32_e32 v29, v33, v29
	v_pk_add_f32 v[26:27], v[24:25], v[30:31]
	v_add_f32_e32 v1, v1, v1
	v_add_f32_e32 v2, v26, v27
	v_pk_add_f32 v[40:41], v[14:15], v[28:29]
	v_pk_add_f32 v[44:45], v[22:23], v[36:37] neg_lo:[0,1] neg_hi:[0,1]
	v_add_f32_e32 v34, v16, v34
	v_add_f32_e32 v35, v22, v36
	v_sub_f32_e32 v36, v15, v29
	v_add_f32_e32 v14, v23, v37
	v_add_f32_e32 v15, v21, v19
	v_mul_f32_e32 v1, 0x39800000, v1
	v_add_f32_e32 v4, v34, v35
	v_sub_f32_e32 v3, v21, v19
	v_pk_add_f32 v[18:19], v[40:41], v[14:15] neg_lo:[0,1] neg_hi:[0,1]
	v_pk_add_f32 v[14:15], v[40:41], v[14:15]
	v_mul_f32_e32 v1, 0.5, v1
	s_xor_b64 s[92:93], s[96:97], -1
	v_sub_f32_e32 v20, 0, v3
	v_add_f32_e32 v40, 0, v3
	v_sin_f32_e32 v50, v1
	s_and_b64 s[0:1], s[96:97], exec
	v_sub_f32_e32 v33, v25, v31
	v_add_f32_e32 v28, 0, v43
	v_add_f32_e32 v48, v2, v4
	v_add_f32_e32 v49, v14, v15
	v_cos_f32_e32 v56, v1
	s_mov_b32 s70, s21
	v_sub_f32_e32 v39, 0, v33
	v_sub_f32_e32 v38, 0, v45
	v_add_f32_e32 v52, v48, v49
	v_mov_b32_e32 v53, v0
	s_mov_b32 s0, s71
	s_mov_b32 s1, s21
	v_pk_mul_f32 v[28:29], v[28:29], s[70:71] op_sel_hi:[0,1]
	v_add_f32_e32 v16, 0, v36
	v_mul_f32_e32 v17, 0x3f3504f3, v18
	ds_write_b64 v9, v[52:53]
	v_fma_f32 v52, v38, s0, v28
	v_fma_f32 v53, v38, s1, -v29
	v_xor_b32_e32 v57, 0x80000000, v50
	v_pk_mul_f32 v[28:29], v[16:17], s[0:1] op_sel_hi:[0,1]
	v_fma_f32 v58, v20, s70, v28
	v_fma_f32 v59, v20, s71, -v29
	v_mov_b32_e32 v51, v56
	v_mul_f32_e32 v46, 0x3f3504f3, v19
	v_mul_f32_e32 v68, v50, v50
	v_mul_f32_e32 v69, v51, v57
	v_fma_f32 v22, v18, s20, 0
	v_sub_f32_e32 v16, v26, v27
	v_sub_f32_e32 v17, v0, v17
	v_sub_f32_e32 v20, v0, v46
	v_sub_f32_e32 v21, v34, v35
	v_mov_b32_e32 v1, v46
	v_pk_fma_f32 v[70:71], v[56:57], v[56:57], v[68:69] op_sel_hi:[0,1,1] neg_lo:[0,0,1] neg_hi:[0,0,1]
	v_pk_fma_f32 v[68:69], v[56:57], v[56:57], v[68:69] op_sel_hi:[0,1,1]
	v_add_f32_e32 v26, v22, v20
	v_sub_f32_e32 v34, v22, v20
	v_sub_f32_e32 v35, v0, v21
	v_add_f32_e32 v46, v16, v0
	v_sub_f32_e32 v61, v17, v1
	v_mov_b32_e32 v72, v70
	v_mov_b32_e32 v73, v69
	v_mul_f32_e32 v78, v69, v69
	v_mul_f32_e32 v79, v69, v70
	v_sub_f32_e32 v14, v14, v15
	v_add_f32_e32 v62, v46, v26
	v_add_f32_e32 v63, v61, v35
	v_pk_fma_f32 v[80:81], v[70:71], v[72:73], v[78:79] op_sel_hi:[0,1,1] neg_lo:[0,0,1] neg_hi:[0,0,1]
	v_pk_fma_f32 v[78:79], v[70:71], v[72:73], v[78:79] op_sel_hi:[0,1,1]
	v_mul_f32_e32 v31, 0x3f6c835e, v40
	v_mul_f32_e32 v25, 0x3ec3ef15, v36
	v_sub_f32_e32 v54, 0, v14
	v_pk_mul_f32 v[68:69], v[62:63], v[68:69] op_sel:[1,1] op_sel_hi:[0,1]
	v_mul_f32_e64 v13, -v44, s20
	v_add_f32_e32 v18, 0, v21
	v_sub_f32_e32 v22, v22, v20
	v_pk_add_f32 v[20:21], v[24:25], v[30:31] neg_lo:[0,1] neg_hi:[0,1]
	v_mul_f32_e32 v55, v54, v80
	v_mul_f32_e32 v54, v54, v79
	v_fma_f32 v88, v62, v70, -v68
	v_fma_f32 v89, v63, v70, v69
	v_add_f32_e32 v24, 0, v20
	v_add_f32_e32 v62, v13, v11
	v_fma_f32 v63, -v44, s20, -v11
	v_pk_add_f32 v[28:29], v[52:53], v[58:59]
	v_pk_add_f32 v[30:31], v[44:45], 0 op_sel_hi:[1,0]
	v_pk_add_f32 v[44:45], v[52:53], v[58:59] neg_lo:[0,1] neg_hi:[0,1]
	v_sub_f32_e32 v52, v24, v62
	v_sub_f32_e32 v53, v39, v63
	v_add_f32_e32 v24, v24, v62
	v_add_f32_e32 v25, v63, v39
	v_mov_b32_e32 v57, v50
	v_pk_add_f32 v[38:39], v[24:25], v[28:29]
	v_fmamk_f32 v34, v19, 0x3f3504f3, v17
	v_pk_mul_f32 v[58:59], v[38:39], v[50:51] op_sel_hi:[1,0]
	v_sub_f32_e32 v64, v18, v22
	v_fma_f32 v62, v38, v56, v59
	v_fma_f32 v63, v39, v56, -v58
	v_pk_mul_f32 v[58:59], v[72:73], v[78:79] op_sel:[0,1]
	ds_write_b64 v9, v[62:63] offset:2176
	v_fma_f32 v62, v72, v80, -v59
	v_fma_f32 v59, v73, v80, v58
	v_mov_b32_e32 v82, v80
	v_mov_b32_e32 v83, v79
	v_add_f32_e32 v60, v16, v34
	v_pk_mul_f32 v[84:85], v[56:57], v[82:83]
	v_pk_mul_f32 v[86:87], v[50:51], v[82:83]
	v_mov_b32_e32 v69, v59
	v_mul_f32_e32 v65, v64, v62
	v_mul_f32_e32 v64, v64, v59
	v_pk_add_f32 v[24:25], v[24:25], v[28:29] neg_lo:[0,1] neg_hi:[0,1]
	v_pk_add_f32 v[28:29], v[52:53], v[44:45] op_sel:[0,1] op_sel_hi:[1,0]
	v_pk_add_f32 v[44:45], v[52:53], v[44:45] op_sel:[0,1] op_sel_hi:[1,0] neg_lo:[0,1] neg_hi:[0,1]
	v_fma_f32 v70, v60, v62, -v64
	v_fma_f32 v71, v60, v69, v65
	v_pk_mov_b32 v[102:103], v[86:87], v[84:85] op_sel:[1,0]
	v_mov_b32_e32 v87, v85
	v_pk_mul_f32 v[64:65], v[82:83], v[78:79] op_sel:[0,1]
	v_pk_add_f32 v[84:85], v[102:103], v[86:87]
	v_pk_add_f32 v[86:87], v[102:103], v[86:87] neg_lo:[0,1] neg_hi:[0,1]
	v_mov_b32_e32 v53, v45
	ds_write_b64 v9, v[70:71] offset:13056
	v_pk_fma_f32 v[70:71], v[80:81], v[82:83], v[64:65] op_sel:[0,0,1] op_sel_hi:[0,1,0] neg_lo:[0,0,1] neg_hi:[0,0,1]
	v_pk_fma_f32 v[64:65], v[80:81], v[82:83], v[64:65] op_sel:[0,0,1] op_sel_hi:[0,1,0]
	v_mul_f32_e32 v38, v45, v86
	v_mul_f32_e32 v39, v28, v86
	ds_write_b64 v9, v[88:89] offset:4352
	v_mov_b32_e32 v88, v70
	v_mov_b32_e32 v89, v65
	v_pk_mov_b32 v[90:91], v[64:65], v[70:71] op_sel:[1,0]
	v_mov_b32_e32 v102, v86
	v_pk_mov_b32 v[104:105], v[84:85], v[86:87] op_sel:[1,0]
	v_fma_f32 v86, v28, v85, -v38
	v_fma_f32 v87, v53, v85, v39
	v_mul_f32_e32 v32, 0x3ec3ef15, v43
	v_mul_f32_e32 v66, 0x3f6c835e, v31
	v_pk_mul_f32 v[76:77], v[50:51], v[72:73]
	v_mov_b32_e32 v103, v85
	v_pk_add_f32 v[48:49], v[48:49], v[48:49] op_sel:[0,1] op_sel_hi:[0,1] neg_lo:[0,1] neg_hi:[0,1]
	v_pk_mul_f32 v[84:85], v[90:91], 0 op_sel_hi:[1,0]
	v_pk_mul_f32 v[50:51], v[50:51], v[88:89] op_sel_hi:[0,1]
	v_add_f32_e32 v32, v32, v66
	v_add_f32_e32 v33, v33, v0
	v_pk_mul_f32 v[66:67], v[42:43], s[20:21]
	s_mov_b32 s36, s20
	s_mov_b32 s37, s71
	v_mul_f32_e32 v40, s72, v40
	v_mul_f32_e32 v41, s73, v42
	v_mul_f32_e32 v1, v79, v70
	ds_write_b64 v9, v[86:87] offset:10880
	v_fma_f32 v86, v48, v70, -v84
	v_mul_f32_e32 v23, v70, v59
	v_fma_f32 v70, v56, v88, v51
	v_fma_f32 v51, v56, v89, -v50
	v_pk_fma_f32 v[42:43], v[30:31], s[36:37], v[66:67] neg_lo:[0,0,1] neg_hi:[0,0,1]
	v_fma_f32 v31, v30, s31, -v41
	v_fma_f32 v30, v36, s30, -v40
	v_pk_mul_f32 v[74:75], v[56:57], v[72:73]
	v_mov_b32_e32 v57, v51
	v_pk_add_f32 v[36:37], v[32:33], v[30:31]
	v_pk_add_f32 v[40:41], v[42:43], v[20:21]
	v_mov_b32_e32 v94, v74
	v_pk_mov_b32 v[74:75], v[74:75], v[76:77] op_sel:[1,0]
	v_mul_f32_e32 v50, v25, v51
	v_mul_f32_e32 v51, v25, v70
	v_pk_add_f32 v[66:67], v[36:37], v[40:41]
	v_pk_mul_f32 v[92:93], v[72:73], v[88:89]
	v_pk_mul_f32 v[72:73], v[72:73], v[90:91]
	v_add_f32_e32 v76, v94, v74
	v_sub_f32_e32 v74, v94, v74
	v_sub_f32_e32 v75, v77, v75
	v_fma_f32 v70, v24, v70, -v50
	v_fma_f32 v71, v24, v57, v51
	v_pk_mul_f32 v[96:97], v[66:67], v[74:75] op_sel:[0,1]
	v_sub_f32_e32 v24, v46, v26
	v_sub_f32_e32 v25, v35, v61
	v_pk_add_f32 v[26:27], v[72:73], v[72:73] op_sel:[0,1] op_sel_hi:[0,1]
	v_fma_f32 v98, v66, v76, -v97
	v_fma_f32 v99, v67, v76, v96
	v_pk_mul_f32 v[26:27], v[24:25], v[26:27] op_sel:[1,0] op_sel_hi:[0,1]
	v_pk_add_f32 v[46:47], v[92:93], v[92:93] op_sel:[0,1] op_sel_hi:[0,1] neg_lo:[0,1] neg_hi:[0,1]
	v_fma_f32 v50, v24, v46, -v26
	v_fma_f32 v51, v25, v47, v27
	ds_write_b64 v9, v[98:99] offset:6528
	v_mul_f32_e32 v96, v76, v88
	v_mul_f32_e32 v97, v75, v89
	v_mul_f32_e32 v94, v76, v90
	v_mul_f32_e32 v95, v75, v91
	v_pk_mul_f32 v[98:99], v[82:83], v[88:89]
	v_mov_b32_e32 v25, v37
	v_sub_f32_e32 v24, v40, v36
	v_sub_f32_e32 v25, v25, v41
	v_pk_add_f32 v[26:27], v[94:95], v[94:95] op_sel:[0,1] op_sel_hi:[0,1]
	v_pk_mul_f32 v[26:27], v[24:25], v[26:27] op_sel:[1,0] op_sel_hi:[0,1]
	v_pk_add_f32 v[36:37], v[96:97], v[96:97] op_sel:[0,1] op_sel_hi:[0,1] neg_lo:[0,1] neg_hi:[0,1]
	v_sub_f32_e32 v2, v2, v4
	v_sub_f32_e32 v3, v98, v99
	v_pk_mul_f32 v[100:101], v[80:81], v[64:65] op_sel_hi:[0,1]
	v_fma_f32 v40, v24, v36, -v26
	v_fma_f32 v41, v25, v37, v27
	v_add_f32_e32 v4, 0, v2
	v_fma_f32 v24, v4, v80, -v54
	v_fma_f32 v25, v4, v83, v55
	v_add_f32_e32 v4, v14, v0
	v_add_f32_e32 v5, v101, v1
	ds_write_b64 v9, v[24:25] offset:8704
	v_pk_mul_f32 v[52:53], v[88:89], v[102:103]
	v_mul_f32_e32 v14, v4, v5
	v_mul_f32_e32 v15, v5, v2
	v_pk_mov_b32 v[4:5], v[2:3], v[4:5] op_sel:[1,0]
	v_pk_mul_f32 v[38:39], v[88:89], v[104:105]
	v_fma_f32 v24, v2, v4, -v14
	v_fma_f32 v25, v3, v5, v15
	v_fma_f32 v87, v49, v89, v85
	ds_write_b64 v9, v[24:25] offset:26112
	v_pk_add_f32 v[24:25], v[52:53], v[52:53] op_sel:[1,0] op_sel_hi:[1,0]
	v_mul_f32_e32 v48, v88, v62
	v_mul_f32_e32 v49, v89, v69
	v_mul_f32_e32 v19, v65, v62
	v_mov_b32_e32 v3, v29
	v_pk_add_f32 v[4:5], v[38:39], v[38:39] op_sel:[0,1] op_sel_hi:[0,1] neg_lo:[0,1] neg_hi:[0,1]
	v_mul_f32_e32 v14, v29, v24
	v_mul_f32_e32 v15, v44, v25
	v_fma_f32 v24, v44, v4, -v14
	v_fma_f32 v25, v3, v5, v15
	v_sub_f32_e32 v2, v16, v34
	v_sub_f32_e32 v3, v48, v49
	v_pk_add_f32 v[4:5], v[18:19], v[22:23]
	v_pk_mul_f32 v[66:67], v[82:83], v[74:75] op_sel:[0,1]
	v_fma_f32 v74, v82, v76, -v67
	v_mul_f32_e32 v14, v4, v5
	v_mul_f32_e32 v15, v5, v2
	v_pk_mov_b32 v[4:5], v[2:3], v[4:5] op_sel:[1,0]
	v_fma_f32 v67, v83, v76, v66
	v_fma_f32 v16, v2, v4, -v14
	v_fma_f32 v17, v3, v5, v15
	v_sub_f32_e32 v2, v20, v42
	v_sub_f32_e32 v3, v33, v31
	v_mov_b32_e32 v77, v67
	v_sub_f32_e32 v4, v43, v21
	v_sub_f32_e32 v5, v32, v30
	v_pk_add_f32 v[14:15], v[2:3], v[4:5]
	v_pk_add_f32 v[2:3], v[2:3], v[4:5] neg_lo:[0,1] neg_hi:[0,1]
	v_mov_b32_e32 v76, v74
	ds_write_b64 v9, v[16:17] offset:30464
	v_mul_f32_e32 v16, v3, v67
	v_mul_f32_e32 v17, v3, v74
	v_pk_mul_f32 v[68:69], v[90:91], v[76:77]
	v_fma_f32 v18, v14, v74, -v16
	v_fma_f32 v19, v14, v77, v17
	v_pk_mul_f32 v[64:65], v[88:89], v[76:77]
	v_mov_b32_e32 v5, v15
	v_pk_add_f32 v[16:17], v[68:69], v[68:69] op_sel:[0,1] op_sel_hi:[0,1]
	v_mul_f32_e32 v14, v15, v16
	v_mul_f32_e32 v15, v2, v17
	v_pk_add_f32 v[16:17], v[64:65], v[64:65] op_sel:[0,1] op_sel_hi:[0,1] neg_lo:[0,1] neg_hi:[0,1]
	v_fma_f32 v2, v2, v16, -v14
	v_fma_f32 v3, v5, v17, v15
	v_mov_b32_e32 v1, v122
	ds_write_b64 v9, v[86:87] offset:17408
	ds_write_b64 v9, v[70:71] offset:19584
	ds_write_b64 v9, v[50:51] offset:21760
	ds_write_b64 v9, v[40:41] offset:23936
	ds_write_b64 v9, v[24:25] offset:28288
	ds_write_b64 v9, v[18:19] offset:15232
	ds_write_b64 v9, v[2:3] offset:32640
	s_waitcnt lgkmcnt(0)
	s_barrier
	s_cselect_b32 s95, s28, s88
	v_ashrrev_i32_e32 v2, 31, v1
	v_lshrrev_b32_e32 v2, 28, v2
	v_and_b32_e32 v7, 15, v1
	v_add_u32_e32 v1, v1, v2
	v_ashrrev_i32_e32 v1, 4, v1
	v_lshlrev_b32_e32 v2, 11, v1
	v_lshl_add_u32 v1, v1, 7, v2
	v_lshl_or_b32 v1, v7, 3, v1
	ds_read2_b64 v[20:23], v1 offset1:17
	ds_read2_b64 v[24:27], v1 offset0:68 offset1:85
	ds_read2_b64 v[28:31], v1 offset0:136 offset1:153
	ds_read2_b64 v[32:35], v1 offset0:170 offset1:187
	ds_read2_b64 v[36:39], v1 offset0:204 offset1:221
	ds_read2_b64 v[40:43], v1 offset0:238 offset1:255
	ds_read2_b64 v[44:47], v1 offset0:34 offset1:51
	ds_read2_b64 v[48:51], v1 offset0:102 offset1:119
	s_waitcnt lgkmcnt(5)
	v_pk_add_f32 v[18:19], v[28:29], v[20:21]
	v_pk_add_f32 v[28:29], v[20:21], v[28:29] neg_lo:[0,1] neg_hi:[0,1]
	s_waitcnt lgkmcnt(2)
	v_pk_mov_b32 v[68:69], v[34:35], v[42:43] op_sel:[1,0]
	s_waitcnt lgkmcnt(1)
	v_pk_add_f32 v[64:65], v[46:47], v[34:35]
	s_waitcnt lgkmcnt(0)
	v_sub_f32_e32 v34, v46, v34
	v_sub_f32_e32 v35, v51, v43
	v_pk_add_f32 v[20:21], v[24:25], v[36:37] neg_lo:[0,1] neg_hi:[0,1]
	v_pk_add_f32 v[52:53], v[36:37], v[24:25]
	v_pk_add_f32 v[54:55], v[22:23], v[30:31]
	v_pk_add_f32 v[56:57], v[26:27], v[38:39]
	v_pk_add_f32 v[66:67], v[50:51], v[42:43]
	v_sub_f32_e32 v68, v47, v68
	v_sub_f32_e32 v69, v50, v69
	v_sub_f32_e32 v46, v34, v35
	v_pk_mov_b32 v[24:25], v[20:21], v[20:21] op_sel:[1,0]
	v_add_f32_e32 v36, v28, v21
	v_sub_f32_e32 v37, v29, v20
	v_pk_add_f32 v[34:35], v[34:35], v[34:35] op_sel:[0,1] op_sel_hi:[0,1]
	v_pk_add_f32 v[4:5], v[54:55], v[56:57]
	v_pk_add_f32 v[42:43], v[64:65], v[66:67] neg_lo:[0,1] neg_hi:[0,1]
	v_pk_add_f32 v[54:55], v[54:55], v[56:57] neg_lo:[0,1] neg_hi:[0,1]
	v_pk_add_f32 v[20:21], v[68:69], v[68:69] op_sel:[0,1] op_sel_hi:[0,1] neg_lo:[0,1] neg_hi:[0,1]
	v_pk_mul_f32 v[34:35], v[34:35], s[0:1]
	v_pk_add_f32 v[58:59], v[44:45], v[32:33]
	v_pk_add_f32 v[60:61], v[48:49], v[40:41]
	v_pk_add_f32 v[16:17], v[64:65], v[66:67]
	v_add_f32_e32 v50, v68, v69
	v_pk_mul_f32 v[56:57], v[54:55], s[20:21] op_sel_hi:[1,0]
	v_mul_f32_e32 v42, 0x3f3504f3, v42
	v_mul_f32_e32 v64, 0x3f3504f3, v43
	v_mul_f32_e32 v67, 0xbf3504f3, v43
	v_fma_f32 v68, v20, s70, v34
	v_fma_f32 v69, v21, s71, -v35
	v_pk_add_f32 v[2:3], v[18:19], v[52:53]
	v_pk_add_f32 v[62:63], v[58:59], v[60:61] neg_lo:[0,1] neg_hi:[0,1]
	v_cvt_f32_i32_e32 v7, v7
	v_mov_b32_e32 v20, v18
	v_sub_f32_e32 v18, v64, v42
	v_sub_f32_e32 v19, v19, v53
	v_sub_f32_e32 v20, v20, v52
	v_sub_f32_e32 v21, v57, v56
	v_mov_b32_e32 v35, v42
	v_pk_add_f32 v[42:43], v[18:19], v[62:63] op_sel:[1,0] op_sel_hi:[0,1]
	v_mov_b32_e32 v53, v62
	v_sub_f32_e32 v34, v59, v61
	v_sub_f32_e32 v35, v67, v35
	v_sub_f32_e32 v62, v44, v32
	v_sub_f32_e32 v63, v22, v30
	v_sub_f32_e32 v64, v49, v41
	v_sub_f32_e32 v65, v27, v39
	v_mul_f32_e32 v9, 0x3f6c835e, v50
	v_mul_f32_e32 v11, 0x3ec3ef15, v46
	v_add_f32_e32 v7, v7, v7
	v_sub_f32_e32 v22, v45, v33
	v_sub_f32_e32 v23, v23, v31
	v_sub_f32_e32 v27, v26, v38
	v_sub_f32_e32 v26, v48, v40
	v_pk_add_f32 v[32:33], v[62:63], v[64:65] neg_lo:[0,1] neg_hi:[0,1]
	v_mul_f32_e32 v7, 0x3b800000, v7
	v_pk_add_f32 v[66:67], v[62:63], v[64:65]
	v_pk_add_f32 v[30:31], v[22:23], v[26:27] neg_lo:[0,1] neg_hi:[0,1]
	v_pk_add_f32 v[22:23], v[22:23], v[26:27]
	v_mov_b32_e32 v39, v29
	v_mov_b32_e32 v27, v25
	v_mul_f32_e32 v7, 0.5, v7
	v_mul_f32_e32 v26, 0x3ec3ef15, v33
	v_pk_mul_f32 v[40:41], v[32:33], s[20:21]
	v_mul_f32_e32 v33, s73, v32
	v_mul_f32_e32 v32, s72, v50
	v_sub_f32_e32 v24, v28, v24
	v_sub_f32_e32 v25, v11, v9
	v_pk_mul_f32 v[28:29], v[66:67], s[70:71] op_sel:[1,0]
	v_pk_add_f32 v[14:15], v[58:59], v[60:61]
	v_sin_f32_e32 v58, v7
	v_cos_f32_e32 v76, v7
	v_mul_f32_e32 v38, 0x3f6c835e, v23
	v_mul_f32_e32 v7, 0x3f3504f3, v66
	v_mul_f32_e32 v13, 0x3f3504f3, v30
	v_pk_fma_f32 v[40:41], v[22:23], s[36:37], v[40:41] neg_lo:[0,0,1] neg_hi:[0,0,1]
	v_fma_f32 v23, v22, s31, -v33
	v_fma_f32 v22, v46, s30, -v32
	v_fma_f32 v32, v31, s0, v28
	v_fma_f32 v33, v31, s1, -v29
	v_pk_add_f32 v[26:27], v[38:39], v[26:27]
	v_add_f32_e32 v28, v13, v7
	v_fma_f32 v29, v30, s20, -v7
	v_pk_add_f32 v[30:31], v[36:37], v[28:29]
	v_pk_add_f32 v[38:39], v[32:33], v[68:69]
	v_xor_b32_e32 v77, 0x80000000, v58
	v_pk_add_f32 v[44:45], v[38:39], v[30:31]
	v_pk_fma_f32 v[54:55], v[54:55], s[20:21], v[56:57] op_sel:[0,0,1] op_sel_hi:[1,0,0]
	v_pk_mul_f32 v[50:51], v[58:59], v[44:45] op_sel_hi:[0,1]
	v_fma_f32 v62, v76, v44, v51
	v_fma_f32 v63, v76, v45, -v50
	v_mov_b32_e32 v59, v76
	v_pk_add_f32 v[70:71], v[2:3], v[14:15]
	v_pk_add_f32 v[72:73], v[4:5], v[16:17]
	v_mov_b32_e32 v52, v54
	v_mul_f32_e32 v44, v58, v58
	v_mul_f32_e32 v45, v59, v77
	v_pk_add_f32 v[74:75], v[72:73], v[70:71]
	v_add_f32_e32 v56, v18, v52
	v_sub_f32_e32 v53, v19, v53
	v_pk_fma_f32 v[50:51], v[76:77], v[76:77], v[44:45] op_sel_hi:[0,1,1] neg_lo:[0,0,1] neg_hi:[0,0,1]
	v_pk_fma_f32 v[44:45], v[76:77], v[76:77], v[44:45] op_sel_hi:[0,1,1]
	v_pk_add_f32 v[60:61], v[20:21], v[34:35]
	ds_write2_b64 v1, v[74:75], v[62:63] offset1:17
	v_pk_add_f32 v[20:21], v[20:21], v[34:35] neg_lo:[0,1] neg_hi:[0,1]
	v_add_f32_e32 v34, v60, v56
	v_add_f32_e32 v35, v61, v53
	v_mov_b32_e32 v62, v50
	v_mov_b32_e32 v63, v45
	v_mul_f32_e32 v74, v45, v45
	v_mul_f32_e32 v75, v45, v50
	v_pk_mul_f32 v[44:45], v[34:35], v[44:45] op_sel:[1,1] op_sel_hi:[0,1]
	v_pk_fma_f32 v[78:79], v[50:51], v[62:63], v[74:75] op_sel_hi:[0,1,1] neg_lo:[0,0,1] neg_hi:[0,0,1]
	v_pk_fma_f32 v[74:75], v[50:51], v[62:63], v[74:75] op_sel_hi:[0,1,1]
	v_fma_f32 v88, v34, v50, -v44
	v_fma_f32 v89, v35, v50, v45
	v_pk_mul_f32 v[44:45], v[62:63], v[74:75] op_sel:[0,1]
	v_pk_add_f32 v[54:55], v[54:55], v[18:19] neg_lo:[0,1] neg_hi:[0,1]
	v_fma_f32 v50, v62, v78, -v45
	v_fma_f32 v45, v63, v78, v44
	v_pk_add_f32 v[18:19], v[42:43], v[54:55]
	v_pk_add_f32 v[32:33], v[32:33], v[68:69] neg_lo:[0,1] neg_hi:[0,1]
	v_mov_b32_e32 v69, v45
	v_sub_f32_e32 v42, v42, v54
	v_mov_b32_e32 v77, v58
	v_mov_b32_e32 v80, v78
	v_mov_b32_e32 v81, v75
	v_pk_add_f32 v[90:91], v[20:21], v[20:21] op_sel:[0,1] op_sel_hi:[0,1]
	v_mul_f32_e32 v43, v42, v50
	v_mul_f32_e32 v42, v42, v45
	v_pk_mul_f32 v[64:65], v[76:77], v[62:63]
	v_pk_mul_f32 v[66:67], v[58:59], v[62:63]
	v_mov_b32_e32 v68, v50
	v_fma_f32 v44, v90, v50, -v42
	v_pk_mul_f32 v[50:51], v[80:81], v[74:75] op_sel:[0,1]
	v_pk_add_f32 v[30:31], v[30:31], v[38:39] neg_lo:[0,1] neg_hi:[0,1]
	v_pk_add_f32 v[38:39], v[40:41], v[24:25]
	v_pk_add_f32 v[46:47], v[26:27], v[22:23]
	v_fma_f32 v45, v91, v69, v43
	v_pk_fma_f32 v[54:55], v[78:79], v[80:81], v[50:51] op_sel:[0,0,1] op_sel_hi:[0,1,0] neg_lo:[0,0,1] neg_hi:[0,0,1]
	v_pk_fma_f32 v[50:51], v[78:79], v[80:81], v[50:51] op_sel:[0,0,1] op_sel_hi:[0,1,0]
	v_mov_b32_e32 v92, v64
	v_pk_mov_b32 v[64:65], v[64:65], v[66:67] op_sel:[1,0]
	v_pk_add_f32 v[48:49], v[38:39], v[46:47]
	v_pk_add_f32 v[42:43], v[70:71], v[72:73] neg_lo:[0,1] neg_hi:[0,1]
	v_pk_mov_b32 v[72:73], v[50:51], v[54:55] op_sel:[1,0]
	v_add_f32_e32 v66, v92, v64
	v_sub_f32_e32 v64, v92, v64
	v_sub_f32_e32 v65, v67, v65
	v_pk_mul_f32 v[82:83], v[76:77], v[80:81]
	v_pk_mul_f32 v[84:85], v[58:59], v[80:81]
	v_pk_add_f32 v[28:29], v[36:37], v[28:29] neg_lo:[0,1] neg_hi:[0,1]
	v_mov_b32_e32 v70, v54
	v_mov_b32_e32 v71, v51
	v_pk_mul_f32 v[58:59], v[58:59], v[72:73] op_sel_hi:[0,1]
	v_pk_mul_f32 v[94:95], v[48:49], v[64:65] op_sel:[0,1]
	v_pk_mov_b32 v[86:87], v[74:75], v[78:79] op_sel:[1,0]
	v_pk_add_f32 v[34:35], v[28:29], v[32:33] op_sel:[0,1] op_sel_hi:[1,0]
	v_pk_add_f32 v[28:29], v[28:29], v[32:33] op_sel:[0,1] op_sel_hi:[1,0] neg_lo:[0,1] neg_hi:[0,1]
	v_fma_f32 v74, v76, v70, v58
	v_fma_f32 v59, v76, v71, -v59
	v_fma_f32 v96, v48, v66, -v95
	v_fma_f32 v97, v49, v66, v94
	v_mov_b32_e32 v98, v82
	v_mov_b32_e32 v99, v85
	v_pk_mov_b32 v[82:83], v[82:83], v[84:85] op_sel:[1,0]
	v_mov_b32_e32 v77, v59
	v_pk_mul_f32 v[48:49], v[80:81], v[64:65] op_sel:[0,1]
	v_pk_add_f32 v[84:85], v[98:99], v[82:83]
	v_sub_f32_e32 v83, v99, v83
	v_mov_b32_e32 v33, v29
	v_mov_b32_e32 v93, v65
	v_fma_f32 v64, v80, v66, -v49
	v_fma_f32 v49, v81, v66, v48
	v_mul_f32_e32 v36, v29, v83
	v_mul_f32_e32 v37, v34, v83
	v_mul_f32_e32 v58, v31, v59
	v_mul_f32_e32 v59, v31, v74
	v_mov_b32_e32 v92, v66
	v_mov_b32_e32 v66, v64
	v_mov_b32_e32 v67, v49
	v_mov_b32_e32 v98, v84
	v_mov_b32_e32 v99, v83
	v_fma_f32 v82, v34, v84, -v36
	v_fma_f32 v83, v33, v84, v37
	v_fma_f32 v74, v30, v74, -v58
	v_fma_f32 v75, v30, v77, v59
	v_pk_mul_f32 v[50:51], v[42:43], v[50:51] op_sel:[1,1] op_sel_hi:[0,1]
	v_pk_mul_f32 v[90:91], v[62:63], v[70:71]
	v_pk_mul_f32 v[62:63], v[62:63], v[72:73]
	ds_write2_b64 v1, v[88:89], v[96:97] offset0:34 offset1:51
	v_pk_mul_f32 v[88:89], v[92:93], v[70:71]
	v_pk_mul_f32 v[92:93], v[92:93], v[72:73]
	v_pk_mul_f32 v[94:95], v[80:81], v[70:71]
	v_pk_mul_f32 v[96:97], v[80:81], v[72:73]
	v_pk_mul_f32 v[32:33], v[70:71], v[98:99]
	v_pk_mul_f32 v[36:37], v[72:73], v[98:99]
	v_pk_mul_f32 v[30:31], v[70:71], v[68:69]
	v_pk_mul_f32 v[58:59], v[72:73], v[68:69]
	v_pk_mul_f32 v[68:69], v[70:71], v[66:67]
	v_pk_mul_f32 v[70:71], v[72:73], v[66:67]
	v_fma_f32 v72, v42, v54, -v50
	v_fma_f32 v73, v43, v54, v51
	v_sub_f32_e32 v42, v60, v56
	v_sub_f32_e32 v43, v53, v61
	v_pk_add_f32 v[50:51], v[62:63], v[62:63] op_sel:[0,1] op_sel_hi:[0,1]
	v_pk_mul_f32 v[50:51], v[42:43], v[50:51] op_sel:[1,0] op_sel_hi:[0,1]
	v_pk_add_f32 v[52:53], v[90:91], v[90:91] op_sel:[0,1] op_sel_hi:[0,1] neg_lo:[0,1] neg_hi:[0,1]
	v_fma_f32 v54, v42, v52, -v50
	v_fma_f32 v55, v43, v53, v51
	v_pk_add_f32 v[2:3], v[2:3], v[14:15] neg_lo:[0,1] neg_hi:[0,1]
	v_mov_b32_e32 v43, v47
	v_sub_f32_e32 v38, v38, v46
	v_sub_f32_e32 v39, v43, v39
	v_pk_add_f32 v[42:43], v[92:93], v[92:93] op_sel:[0,1] op_sel_hi:[0,1]
	v_pk_add_f32 v[4:5], v[4:5], v[16:17] neg_lo:[0,1] neg_hi:[0,1]
	v_pk_mul_f32 v[42:43], v[38:39], v[42:43] op_sel:[1,0] op_sel_hi:[0,1]
	v_pk_add_f32 v[46:47], v[88:89], v[88:89] op_sel:[0,1] op_sel_hi:[0,1] neg_lo:[0,1] neg_hi:[0,1]
	v_pk_add_f32 v[14:15], v[2:3], v[4:5] op_sel:[0,1] op_sel_hi:[1,0]
	v_pk_add_f32 v[2:3], v[2:3], v[4:5] op_sel:[0,1] op_sel_hi:[1,0] neg_lo:[0,1] neg_hi:[0,1]
	v_fma_f32 v50, v38, v46, -v42
	v_fma_f32 v51, v39, v47, v43
	v_pk_mul_f32 v[16:17], v[2:3], v[86:87] op_sel:[1,0]
	v_fma_f32 v38, v14, v78, -v16
	v_fma_f32 v39, v14, v81, v17
	v_mov_b32_e32 v5, v15
	v_pk_add_f32 v[16:17], v[96:97], v[96:97] op_sel:[0,1] op_sel_hi:[0,1]
	v_mul_f32_e32 v14, v15, v16
	v_mul_f32_e32 v15, v2, v17
	v_pk_add_f32 v[16:17], v[94:95], v[94:95] op_sel:[0,1] op_sel_hi:[0,1] neg_lo:[0,1] neg_hi:[0,1]
	v_fma_f32 v2, v2, v16, -v14
	v_fma_f32 v3, v5, v17, v15
	v_pk_add_f32 v[16:17], v[36:37], v[36:37] op_sel:[0,1] op_sel_hi:[0,1]
	v_mov_b32_e32 v5, v35
	v_mul_f32_e32 v14, v35, v16
	v_mul_f32_e32 v15, v28, v17
	v_pk_add_f32 v[16:17], v[32:33], v[32:33] op_sel:[0,1] op_sel_hi:[0,1] neg_lo:[0,1] neg_hi:[0,1]
	v_fma_f32 v28, v28, v16, -v14
	v_fma_f32 v29, v5, v17, v15
	v_pk_add_f32 v[14:15], v[58:59], v[58:59] op_sel:[0,1] op_sel_hi:[0,1]
	ds_write2_b64 v1, v[2:3], v[28:29] offset0:204 offset1:221
	v_mov_b32_e32 v3, v30
	v_sub_f32_e32 v2, v20, v21
	v_sub_f32_e32 v3, v3, v31
	v_mul_f32_e32 v4, v18, v14
	v_mul_f32_e32 v5, v2, v15
	v_pk_mov_b32 v[14:15], v[2:3], v[18:19] op_sel:[1,0]
	v_fma_f32 v16, v2, v14, -v4
	v_fma_f32 v17, v3, v15, v5
	v_mov_b32_e32 v3, v26
	v_mov_b32_e32 v5, v22
	v_sub_f32_e32 v2, v24, v40
	v_sub_f32_e32 v3, v3, v5
	v_sub_f32_e32 v4, v41, v25
	v_sub_f32_e32 v5, v27, v23
	ds_write2_b64 v1, v[72:73], v[74:75] offset0:136 offset1:153
	v_pk_add_f32 v[14:15], v[4:5], v[2:3]
	v_sub_f32_e32 v18, v2, v4
	v_sub_f32_e32 v2, v5, v3
	v_mul_f32_e32 v3, v2, v64
	v_mul_f32_e32 v2, v2, v49
	v_fma_f32 v4, v14, v64, -v2
	v_fma_f32 v5, v14, v67, v3
	ds_write2_b64 v1, v[44:45], v[4:5] offset0:102 offset1:119
	v_pk_add_f32 v[4:5], v[70:71], v[70:71] op_sel:[0,1] op_sel_hi:[0,1]
	v_mov_b32_e32 v21, v15
	v_mul_f32_e32 v2, v15, v4
	v_mul_f32_e32 v3, v18, v5
	v_pk_add_f32 v[4:5], v[68:69], v[68:69] op_sel:[0,1] op_sel_hi:[0,1] neg_lo:[0,1] neg_hi:[0,1]
	v_fma_f32 v14, v18, v4, -v2
	v_fma_f32 v15, v21, v5, v3
	ds_write2_b64 v1, v[54:55], v[50:51] offset0:170 offset1:187
	ds_write2_b64 v1, v[38:39], v[82:83] offset0:68 offset1:85
	ds_write2_b64 v1, v[16:17], v[14:15] offset0:238 offset1:255
	v_mov_b32_e32 v1, v122
	s_waitcnt lgkmcnt(0)
	s_barrier
	s_cselect_b32 s94, s89, s24
	v_mul_lo_u32 v1, v1, s33
	ds_read2_b64 v[2:5], v1 offset1:1
	ds_read2_b64 v[14:17], v1 offset0:8 offset1:9
	ds_read2_b64 v[18:21], v1 offset0:10 offset1:11
	ds_read2_b64 v[22:25], v1 offset0:12 offset1:13
	ds_read2_b64 v[26:29], v1 offset0:14 offset1:15
	ds_read2_b64 v[30:33], v1 offset0:2 offset1:3
	ds_read2_b64 v[34:37], v1 offset0:4 offset1:5
	ds_read2_b64 v[38:41], v1 offset0:6 offset1:7
	s_waitcnt lgkmcnt(7)
	v_mov_b32_e32 v1, v4
	v_mov_b32_e32 v42, v2
	v_mov_b32_e32 v43, v4
	v_mov_b32_e32 v4, v5
	v_mov_b32_e32 v5, v3
	s_waitcnt lgkmcnt(6)
	v_mov_b32_e32 v44, v14
	v_mov_b32_e32 v45, v16
	v_mov_b32_e32 v16, v17
	v_mov_b32_e32 v17, v15
	v_pk_add_f32 v[46:47], v[2:3], v[14:15] neg_lo:[0,1] neg_hi:[0,1]
	v_pk_add_f32 v[2:3], v[2:3], v[14:15]
	s_waitcnt lgkmcnt(1)
	v_mov_b32_e32 v7, v36
	v_mov_b32_e32 v15, v36
	v_mov_b32_e32 v36, v37
	v_mov_b32_e32 v37, v35
	v_mov_b32_e32 v48, v22
	v_mov_b32_e32 v49, v24
	v_mov_b32_e32 v24, v25
	v_mov_b32_e32 v25, v23
	v_mov_b32_e32 v14, v34
	v_pk_add_f32 v[50:51], v[34:35], v[22:23] neg_lo:[0,1] neg_hi:[0,1]
	v_pk_add_f32 v[22:23], v[34:35], v[22:23]
	v_pk_mov_b32 v[34:35], v[0:1], v[4:5] op_sel:[1,0]
	v_pk_mov_b32 v[52:53], v[44:45], v[16:17] op_sel:[1,0]
	v_pk_add_f32 v[42:43], v[42:43], v[44:45]
	v_pk_add_f32 v[4:5], v[4:5], v[16:17]
	v_pk_mov_b32 v[16:17], v[6:7], v[36:37] op_sel:[1,0]
	v_pk_mov_b32 v[44:45], v[48:49], v[24:25] op_sel:[1,0]
	v_pk_add_f32 v[14:15], v[14:15], v[48:49]
	v_pk_add_f32 v[24:25], v[36:37], v[24:25]
	v_pk_add_f32 v[48:49], v[2:3], v[22:23] neg_lo:[0,1] neg_hi:[0,1]
	v_pk_add_f32 v[2:3], v[2:3], v[22:23]
	v_pk_add_f32 v[22:23], v[34:35], v[52:53]
	v_pk_add_f32 v[34:35], v[34:35], v[52:53] neg_lo:[0,1] neg_hi:[0,1]
	v_pk_add_f32 v[36:37], v[16:17], v[44:45]
	v_pk_add_f32 v[16:17], v[16:17], v[44:45] neg_lo:[0,1] neg_hi:[0,1]
	v_add_f32_e32 v1, v46, v51
	v_sub_f32_e32 v7, v47, v50
	v_sub_f32_e32 v9, v46, v51
	v_add_f32_e32 v11, v47, v50
	v_pk_add_f32 v[4:5], v[4:5], v[24:25]
	v_add_f32_e32 v13, v34, v17
	v_sub_f32_e32 v50, v35, v16
	v_sub_f32_e32 v51, v34, v17
	v_add_f32_e32 v52, v35, v16
	v_pk_add_f32 v[16:17], v[30:31], v[18:19] neg_lo:[0,1] neg_hi:[0,1]
	v_pk_add_f32 v[24:25], v[30:31], v[18:19]
	v_mov_b32_e32 v44, v30
	v_mov_b32_e32 v46, v18
	v_pk_add_f32 v[14:15], v[42:43], v[14:15]
	v_pk_add_f32 v[42:43], v[22:23], v[36:37]
	v_pk_add_f32 v[22:23], v[22:23], v[36:37] neg_lo:[0,1] neg_hi:[0,1]
	s_waitcnt lgkmcnt(0)
	v_pk_add_f32 v[34:35], v[38:39], v[26:27] neg_lo:[0,1] neg_hi:[0,1]
	v_pk_add_f32 v[36:37], v[38:39], v[26:27]
	v_add_f32_e32 v44, v44, v46
	v_add_f32_e32 v45, v32, v20
	v_add_f32_e32 v18, v33, v21
	v_add_f32_e32 v19, v31, v19
	v_mov_b32_e32 v30, v38
	v_mov_b32_e32 v46, v26
	v_add_f32_e32 v30, v30, v46
	v_add_f32_e32 v31, v40, v28
	v_add_f32_e32 v26, v41, v29
	v_add_f32_e32 v27, v39, v27
	v_pk_add_f32 v[38:39], v[24:25], v[36:37] neg_lo:[0,1] neg_hi:[0,1]
	v_pk_add_f32 v[24:25], v[24:25], v[36:37]
	v_add_f32_e32 v36, v16, v35
	v_sub_f32_e32 v37, v17, v34
	v_sub_f32_e32 v46, v16, v35
	v_add_f32_e32 v47, v17, v34
	v_pk_add_f32 v[16:17], v[32:33], v[20:21]
	v_pk_add_f32 v[20:21], v[32:33], v[20:21] neg_lo:[0,1] neg_hi:[0,1]
	v_pk_add_f32 v[32:33], v[40:41], v[28:29]
	v_pk_add_f32 v[28:29], v[40:41], v[28:29] neg_lo:[0,1] neg_hi:[0,1]
	v_pk_add_f32 v[18:19], v[18:19], v[26:27]
	v_add_f32_e32 v26, v20, v29
	v_mul_f32_e32 v22, 0x3f3504f3, v22
	v_pk_add_f32 v[34:35], v[16:17], v[32:33]
	v_pk_add_f32 v[16:17], v[16:17], v[32:33] neg_lo:[0,1] neg_hi:[0,1]
	v_sub_f32_e32 v27, v21, v28
	v_sub_f32_e32 v20, v20, v29
	v_add_f32_e32 v21, v21, v28
	v_fmamk_f32 v29, v23, 0x3f3504f3, v22
	v_fma_f32 v33, v23, s20, -v22
	v_mul_f32_e32 v22, 0x3f3504f3, v36
	v_mul_f32_e32 v40, 0x3ec3ef15, v26
	v_mul_f32_e32 v26, 0xbf6c835e, v26
	v_pk_add_f32 v[30:31], v[44:45], v[30:31]
	v_mul_f32_e32 v28, 0x3f6c835e, v13
	v_mul_f32_e32 v13, 0x3ec3ef15, v13
	v_fmamk_f32 v32, v37, 0x3f3504f3, v22
	v_fma_f32 v36, v37, s20, -v22
	v_mul_f32_e32 v37, 0xbf3504f3, v46
	v_fmac_f32_e32 v40, 0x3f6c835e, v27
	v_fmac_f32_e32 v26, 0x3ec3ef15, v27
	v_mul_f32_e32 v27, 0xbf3504f3, v16
	v_mul_f32_e32 v16, 0x3ec3ef15, v21
	v_fmac_f32_e32 v28, 0x3ec3ef15, v50
	v_fma_f32 v13, v50, s21, -v13
	v_mul_f32_e32 v41, 0x3ec3ef15, v51
	v_mul_f32_e32 v45, 0xbf6c835e, v51
	v_fmamk_f32 v51, v47, 0x3f3504f3, v37
	v_fmac_f32_e32 v37, 0xbf3504f3, v47
	v_fmamk_f32 v44, v17, 0x3f3504f3, v27
	v_fmac_f32_e32 v27, 0xbf3504f3, v17
	v_fma_f32 v47, v20, s76, -v16
	v_mul_f32_e32 v53, 0xbf6c835e, v21
	v_pk_add_f32 v[16:17], v[2:3], v[24:25]
	v_pk_add_f32 v[2:3], v[2:3], v[24:25] neg_lo:[0,1] neg_hi:[0,1]
	v_pk_add_f32 v[22:23], v[14:15], v[30:31] neg_lo:[0,1] neg_hi:[0,1]
	v_pk_add_f32 v[24:25], v[42:43], v[34:35] neg_lo:[0,1] neg_hi:[0,1]
	v_pk_add_f32 v[4:5], v[4:5], v[18:19] neg_lo:[0,1] neg_hi:[0,1]
	v_fmac_f32_e32 v53, 0x3ec3ef15, v20
	v_pk_add_f32 v[20:21], v[42:43], v[34:35]
	v_pk_add_f32 v[70:71], v[2:3], v[24:25] op_sel:[0,1] op_sel_hi:[1,0]
	v_pk_add_f32 v[2:3], v[2:3], v[24:25] op_sel:[0,1] op_sel_hi:[1,0] neg_lo:[0,1] neg_hi:[0,1]
	v_pk_add_f32 v[72:73], v[22:23], v[4:5] neg_lo:[0,1] neg_hi:[0,1]
	v_pk_add_f32 v[4:5], v[22:23], v[4:5]
	v_add_f32_e32 v23, v1, v32
	v_add_f32_e32 v25, v7, v36
	v_sub_f32_e32 v1, v1, v32
	v_sub_f32_e32 v7, v7, v36
	v_add_f32_e32 v30, v28, v40
	v_add_f32_e32 v31, v13, v26
	v_sub_f32_e32 v35, v28, v40
	v_sub_f32_e32 v13, v13, v26
	v_fmac_f32_e32 v41, 0x3f6c835e, v52
	v_fmac_f32_e32 v45, 0x3ec3ef15, v52
	v_add_f32_e32 v22, v30, v23
	v_add_f32_e32 v24, v31, v25
	v_sub_f32_e32 v26, v23, v30
	v_sub_f32_e32 v28, v25, v31
	v_add_f32_e32 v30, v13, v1
	v_sub_f32_e32 v32, v7, v35
	v_sub_f32_e32 v34, v1, v13
	v_add_f32_e32 v36, v35, v7
	v_add_f32_e32 v1, v48, v39
	v_sub_f32_e32 v7, v49, v38
	v_sub_f32_e32 v13, v48, v39
	v_add_f32_e32 v23, v49, v38
	v_add_f32_e32 v25, v29, v44
	v_add_f32_e32 v31, v33, v27
	v_sub_f32_e32 v29, v29, v44
	v_sub_f32_e32 v27, v33, v27
	v_add_f32_e32 v38, v1, v25
	v_add_f32_e32 v40, v7, v31
	v_sub_f32_e32 v42, v1, v25
	v_sub_f32_e32 v44, v7, v31
	v_add_f32_e32 v46, v13, v27
	v_sub_f32_e32 v48, v23, v29
	v_sub_f32_e32 v50, v13, v27
	v_add_f32_e32 v52, v23, v29
	v_add_f32_e32 v1, v9, v51
	v_add_f32_e32 v7, v11, v37
	v_sub_f32_e32 v9, v9, v51
	v_sub_f32_e32 v11, v11, v37
	v_add_f32_e32 v13, v41, v47
	v_add_f32_e32 v23, v45, v53
	v_sub_f32_e32 v25, v41, v47
	v_sub_f32_e32 v27, v45, v53
	v_pk_add_f32 v[14:15], v[20:21], v[16:17]
	v_pk_add_f32 v[16:17], v[16:17], v[20:21] neg_lo:[0,1] neg_hi:[0,1]
	v_add_f32_e32 v54, v13, v1
	v_add_f32_e32 v56, v23, v7
	v_sub_f32_e32 v58, v1, v13
	v_sub_f32_e32 v60, v7, v23
	v_add_f32_e32 v62, v27, v9
	v_sub_f32_e32 v64, v11, v25
	v_sub_f32_e32 v66, v9, v27
	v_add_f32_e32 v68, v25, v11
	s_mov_b32 s29, 0
	v_mov_b32_e32 v18, v70
	v_mov_b32_e32 v19, v3
	v_mov_b32_e32 v20, v72
	v_mov_b32_e32 v21, v5
	v_pk_mov_b32 v[70:71], v[2:3], v[70:71] op_sel:[1,0]
	v_pk_mov_b32 v[72:73], v[4:5], v[72:73] op_sel:[1,0]
	v_mov_b32_e32 v39, v38
	v_mov_b32_e32 v43, v42
	v_mov_b32_e32 v47, v46
	v_mov_b32_e32 v49, v48
	v_mov_b32_e32 v51, v50
	v_mov_b32_e32 v53, v52
	v_mov_b32_e32 v23, v22
	v_mov_b32_e32 v27, v26
	v_mov_b32_e32 v31, v30
	v_mov_b32_e32 v33, v32
	v_mov_b32_e32 v35, v34
	v_mov_b32_e32 v37, v36
	v_mov_b32_e32 v55, v54
	v_mov_b32_e32 v59, v58
	v_mov_b32_e32 v63, v62
	v_mov_b32_e32 v65, v64
	v_mov_b32_e32 v67, v66
	v_mov_b32_e32 v69, v68
	v_mov_b32_e32 v13, v12
	v_mov_b32_e32 v7, v6
	v_mov_b32_e32 v9, v8
	v_mov_b32_e32 v11, v10
	v_pk_mov_b32 v[74:75], v[14:15], v[14:15] op_sel:[1,0]
	v_mov_b32_e32 v25, v24
	v_mov_b32_e32 v41, v40
	v_mov_b32_e32 v57, v56
	v_pk_mov_b32 v[76:77], v[16:17], v[16:17] op_sel:[1,0]
	v_mov_b32_e32 v29, v28
	v_mov_b32_e32 v45, v44
	v_mov_b32_e32 v61, v60
	s_mov_b64 s[0:1], 0
	s_branch .LBB0_348
.LBB0_347:
	v_mov_b32_e32 v102, v1
	s_barrier
	v_pk_add_f32 v[108:109], v[80:81], v[96:97]
	v_ashrrev_i32_e32 v103, 31, v102
	v_lshrrev_b32_e32 v103, 24, v103
	v_and_b32_e32 v115, 0xff, v102
	v_add_lshl_u32 v102, v102, v103, 4
	v_and_or_b32 v102, v102, s87, v115
	v_ashrrev_i32_e32 v103, 4, v102
	v_cvt_f32_i32_e32 v115, v115
	v_lshlrev_b32_e32 v102, 3, v102
	v_pk_add_f32 v[132:133], v[88:89], v[112:113]
	v_lshl_add_u32 v127, v103, 3, v102
	v_pk_add_f32 v[102:103], v[108:109], v[132:133] neg_lo:[0,1] neg_hi:[0,1]
	v_pk_add_f32 v[116:117], v[2:3], v[90:91]
	v_mul_f32_e32 v138, 0x3f3504f3, v102
	v_add_f32_e32 v102, v115, v115
	v_mul_f32_e32 v102, 0x39800000, v102
	v_pk_add_f32 v[118:119], v[82:83], v[98:99]
	v_pk_add_f32 v[104:105], v[4:5], v[92:93]
	v_pk_add_f32 v[106:107], v[84:85], v[100:101]
	v_pk_add_f32 v[120:121], v[78:79], v[94:95]
	v_pk_add_f32 v[128:129], v[86:87], v[110:111]
	v_mul_f32_e32 v102, 0.5, v102
	v_pk_add_f32 v[134:135], v[104:105], v[106:107] neg_lo:[0,1] neg_hi:[0,1]
	v_sin_f32_e32 v140, v102
	v_mul_f32_e32 v142, 0x3f3504f3, v103
	v_mul_f32_e32 v145, 0xbf3504f3, v103
	v_cos_f32_e32 v146, v102
	v_pk_add_f32 v[102:103], v[116:117], v[118:119]
	v_pk_add_f32 v[104:105], v[104:105], v[106:107]
	v_pk_add_f32 v[106:107], v[120:121], v[128:129]
	v_pk_add_f32 v[108:109], v[108:109], v[132:133]
	v_pk_add_f32 v[132:133], v[102:103], v[106:107]
	v_pk_add_f32 v[148:149], v[104:105], v[108:109]
	v_pk_add_f32 v[90:91], v[2:3], v[90:91] neg_lo:[0,1] neg_hi:[0,1]
	v_pk_add_f32 v[150:151], v[132:133], v[148:149]
	v_pk_add_f32 v[2:3], v[82:83], v[98:99] neg_lo:[0,1] neg_hi:[0,1]
	v_pk_mul_f32 v[136:137], v[134:135], s[20:21] op_sel_hi:[1,0]
	ds_write_b64 v127, v[150:151]
	v_pk_mov_b32 v[98:99], v[2:3], v[2:3] op_sel:[1,0]
	v_add_f32_e32 v150, v90, v3
	v_sub_f32_e32 v151, v91, v2
	v_pk_fma_f32 v[134:135], v[134:135], s[20:21], v[136:137] op_sel:[0,0,1] op_sel_hi:[1,0,0]
	v_sub_f32_e32 v2, v116, v118
	v_sub_f32_e32 v3, v137, v136
	v_sub_f32_e32 v82, v142, v138
	v_sub_f32_e32 v83, v117, v119
	v_mov_b32_e32 v117, v138
	v_mov_b32_e32 v137, v4
	v_mov_b32_e32 v139, v92
	v_sub_f32_e32 v136, v78, v94
	v_sub_f32_e32 v137, v137, v139
	v_mov_b32_e32 v139, v85
	v_sub_f32_e32 v92, v79, v95
	v_sub_f32_e32 v93, v5, v93
	v_mov_b32_e32 v5, v84
	v_mov_b32_e32 v143, v101
	v_sub_f32_e32 v84, v86, v110
	v_sub_f32_e32 v85, v5, v100
	v_mov_b32_e32 v138, v87
	v_sub_f32_e32 v4, v81, v97
	v_sub_f32_e32 v5, v78, v94
	v_mov_b32_e32 v101, v87
	v_sub_f32_e32 v78, v80, v96
	v_sub_f32_e32 v79, v79, v95
	v_pk_mov_b32 v[80:81], v[88:89], v[86:87] op_sel:[1,0]
	v_sub_f32_e32 v138, v138, v111
	v_sub_f32_e32 v139, v139, v143
	v_sub_f32_e32 v80, v80, v113
	v_sub_f32_e32 v81, v81, v110
	v_sub_f32_e32 v100, v88, v112
	v_sub_f32_e32 v101, v101, v111
	v_pk_add_f32 v[86:87], v[78:79], v[80:81] neg_lo:[0,1] neg_hi:[0,1]
	v_pk_add_f32 v[142:143], v[4:5], v[100:101]
	v_pk_add_f32 v[80:81], v[78:79], v[80:81]
	v_mov_b32_e32 v78, v86
	v_mul_f32_e32 v86, 0x3ec3ef15, v86
	v_pk_add_f32 v[88:89], v[136:137], v[138:139] neg_lo:[0,1] neg_hi:[0,1]
	v_pk_add_f32 v[94:95], v[92:93], v[84:85]
	v_pk_add_f32 v[96:97], v[4:5], v[100:101] neg_lo:[0,1] neg_hi:[0,1]
	v_mul_f32_e32 v84, 0x3f6c835e, v142
	v_mov_b32_e32 v101, v91
	v_mov_b32_e32 v91, v86
	v_add_f32_e32 v86, v137, v139
	s_mov_b32 s40, s21
	s_mov_b32 s41, s71
	v_pk_add_f32 v[130:131], v[120:121], v[128:129] neg_lo:[0,1] neg_hi:[0,1]
	v_mul_f32_e32 v100, 0x3ec3ef15, v89
	v_pk_mul_f32 v[88:89], v[88:89], s[20:21]
	s_mov_b32 s70, s20
	v_mov_b32_e32 v111, v99
	v_mov_b32_e32 v99, v84
	v_sub_f32_e32 v84, v93, v85
	s_mov_b32 s38, s71
	s_mov_b32 s39, s21
	v_pk_mul_f32 v[92:93], v[86:87], s[40:41] op_sel_hi:[0,1]
	v_sub_f32_e32 v116, v121, v129
	v_sub_f32_e32 v117, v145, v117
	v_pk_add_f32 v[118:119], v[82:83], v[130:131] op_sel:[1,0] op_sel_hi:[0,1]
	v_mov_b32_e32 v120, v134
	v_mov_b32_e32 v121, v130
	v_pk_add_f32 v[134:135], v[134:135], v[82:83] neg_lo:[0,1] neg_hi:[0,1]
	v_mov_b32_e32 v79, v81
	v_mul_f32_e32 v110, 0x3f6c835e, v95
	v_mul_f32_e32 v115, 0x3f3504f3, v143
	v_mul_f32_e32 v112, s72, v142
	v_mul_f32_e32 v113, s73, v97
	v_pk_fma_f32 v[4:5], v[94:95], s[70:71], v[88:89] neg_lo:[0,0,1] neg_hi:[0,0,1]
	v_fma_f32 v94, v84, s38, v92
	v_fma_f32 v95, v84, s39, -v93
	v_pk_mul_f32 v[80:81], v[80:81], s[38:39] op_sel_hi:[0,1]
	v_add_f32_e32 v128, v82, v120
	v_sub_f32_e32 v121, v83, v121
	v_pk_add_f32 v[130:131], v[2:3], v[116:117]
	v_pk_add_f32 v[82:83], v[2:3], v[116:117] neg_lo:[0,1] neg_hi:[0,1]
	v_pk_add_f32 v[2:3], v[118:119], v[134:135]
	v_mul_f32_e32 v119, 0x3f3504f3, v87
	v_fma_f32 v85, v87, s20, -v115
	v_fma_f32 v86, v96, s40, v80
	v_fma_f32 v87, v96, s41, -v81
	v_add_f32_e32 v84, v119, v115
	v_pk_add_f32 v[80:81], v[150:151], v[84:85]
	v_pk_add_f32 v[92:93], v[94:95], v[86:87]
	v_xor_b32_e32 v147, 0x80000000, v140
	v_pk_add_f32 v[96:97], v[80:81], v[92:93]
	v_pk_add_f32 v[88:89], v[100:101], v[110:111]
	v_pk_mul_f32 v[110:111], v[96:97], v[140:141] op_sel_hi:[1,0]
	v_pk_fma_f32 v[78:79], v[78:79], s[30:31], v[112:113] neg_lo:[0,0,1] neg_hi:[0,0,1]
	v_fma_f32 v112, v96, v146, v111
	v_fma_f32 v113, v97, v146, -v110
	v_mov_b32_e32 v141, v146
	v_mul_f32_e32 v96, v140, v140
	v_mul_f32_e32 v97, v141, v147
	v_pk_fma_f32 v[110:111], v[146:147], v[146:147], v[96:97] op_sel_hi:[0,1,1] neg_lo:[0,0,1] neg_hi:[0,0,1]
	v_pk_fma_f32 v[96:97], v[146:147], v[146:147], v[96:97] op_sel_hi:[0,1,1]
	v_add_f32_e32 v116, v130, v128
	v_add_f32_e32 v117, v131, v121
	ds_write_b64 v127, v[112:113] offset:2176
	v_mov_b32_e32 v112, v110
	v_mov_b32_e32 v113, v97
	v_mul_f32_e32 v142, v97, v97
	v_mul_f32_e32 v143, v97, v110
	v_pk_mul_f32 v[96:97], v[116:117], v[96:97] op_sel:[1,1] op_sel_hi:[0,1]
	v_pk_fma_f32 v[144:145], v[110:111], v[112:113], v[142:143] op_sel_hi:[0,1,1] neg_lo:[0,0,1] neg_hi:[0,0,1]
	v_pk_fma_f32 v[142:143], v[110:111], v[112:113], v[142:143] op_sel_hi:[0,1,1]
	v_fma_f32 v160, v116, v110, -v96
	v_fma_f32 v161, v117, v110, v97
	v_pk_mul_f32 v[110:111], v[112:113], v[142:143] op_sel:[0,1]
	v_fma_f32 v116, v112, v144, -v111
	v_fma_f32 v111, v113, v144, v110
	v_pk_add_f32 v[84:85], v[150:151], v[84:85] neg_lo:[0,1] neg_hi:[0,1]
	v_mov_b32_e32 v151, v111
	v_sub_f32_e32 v118, v118, v134
	ds_write_b64 v127, v[160:161] offset:4352
	v_mov_b32_e32 v150, v116
	v_pk_add_f32 v[160:161], v[82:83], v[82:83] op_sel:[0,1] op_sel_hi:[0,1]
	v_mul_f32_e32 v110, v118, v111
	v_mul_f32_e32 v111, v118, v116
	v_fma_f32 v116, v160, v116, -v110
	v_fma_f32 v117, v161, v151, v111
	v_mov_b32_e32 v152, v144
	v_mov_b32_e32 v153, v143
	ds_write_b64 v127, v[116:117] offset:13056
	v_pk_mul_f32 v[116:117], v[152:153], v[142:143] op_sel:[0,1]
	v_mov_b32_e32 v147, v140
	v_pk_fma_f32 v[118:119], v[144:145], v[152:153], v[116:117] op_sel:[0,0,1] op_sel_hi:[0,1,0] neg_lo:[0,0,1] neg_hi:[0,0,1]
	v_pk_fma_f32 v[116:117], v[144:145], v[152:153], v[116:117] op_sel:[0,0,1] op_sel_hi:[0,1,0]
	v_pk_mov_b32 v[134:135], v[116:117], v[118:119] op_sel:[1,0]
	v_pk_mul_f32 v[138:139], v[140:141], v[112:113]
	v_pk_mul_f32 v[156:157], v[140:141], v[152:153]
	v_pk_add_f32 v[110:111], v[132:133], v[148:149] neg_lo:[0,1] neg_hi:[0,1]
	v_mov_b32_e32 v132, v118
	v_mov_b32_e32 v133, v117
	v_pk_mul_f32 v[140:141], v[140:141], v[134:135] op_sel_hi:[0,1]
	v_pk_mov_b32 v[158:159], v[142:143], v[144:145] op_sel:[1,0]
	v_fma_f32 v142, v146, v132, v140
	v_fma_f32 v141, v146, v133, -v141
	v_pk_add_f32 v[80:81], v[80:81], v[92:93] neg_lo:[0,1] neg_hi:[0,1]
	v_pk_mul_f32 v[136:137], v[146:147], v[112:113]
	v_pk_mul_f32 v[154:155], v[146:147], v[152:153]
	v_mov_b32_e32 v147, v141
	v_mul_f32_e32 v140, v81, v141
	v_mul_f32_e32 v141, v81, v142
	v_pk_mul_f32 v[116:117], v[110:111], v[116:117] op_sel:[1,1] op_sel_hi:[0,1]
	v_pk_add_f32 v[90:91], v[90:91], v[98:99] neg_lo:[0,1] neg_hi:[0,1]
	v_pk_mul_f32 v[148:149], v[112:113], v[132:133]
	v_pk_mul_f32 v[112:113], v[112:113], v[134:135]
	v_fma_f32 v142, v80, v142, -v140
	v_fma_f32 v143, v80, v147, v141
	v_fma_f32 v146, v110, v118, -v116
	v_fma_f32 v147, v111, v118, v117
	v_pk_add_f32 v[92:93], v[4:5], v[90:91]
	v_pk_add_f32 v[98:99], v[88:89], v[78:79]
	v_mov_b32_e32 v160, v136
	v_pk_mov_b32 v[136:137], v[136:137], v[138:139] op_sel:[1,0]
	v_sub_f32_e32 v110, v130, v128
	v_sub_f32_e32 v111, v121, v131
	v_pk_add_f32 v[112:113], v[112:113], v[112:113] op_sel:[0,1] op_sel_hi:[0,1]
	v_pk_add_f32 v[100:101], v[98:99], v[92:93]
	v_add_f32_e32 v138, v160, v136
	v_sub_f32_e32 v136, v160, v136
	v_sub_f32_e32 v137, v139, v137
	v_pk_mul_f32 v[112:113], v[110:111], v[112:113] op_sel:[1,0] op_sel_hi:[0,1]
	v_pk_add_f32 v[116:117], v[148:149], v[148:149] op_sel:[0,1] op_sel_hi:[0,1] neg_lo:[0,1] neg_hi:[0,1]
	v_pk_mul_f32 v[162:163], v[100:101], v[136:137] op_sel:[0,1]
	v_fma_f32 v118, v110, v116, -v112
	v_fma_f32 v119, v111, v117, v113
	v_fma_f32 v164, v100, v138, -v163
	v_fma_f32 v165, v101, v138, v162
	v_mul_f32_e32 v162, v138, v132
	v_mul_f32_e32 v163, v137, v133
	v_mul_f32_e32 v160, v138, v134
	v_mul_f32_e32 v161, v137, v135
	v_mov_b32_e32 v111, v99
	v_sub_f32_e32 v92, v92, v98
	v_sub_f32_e32 v93, v111, v93
	v_pk_add_f32 v[98:99], v[160:161], v[160:161] op_sel:[0,1] op_sel_hi:[0,1]
	v_pk_mul_f32 v[98:99], v[92:93], v[98:99] op_sel:[1,0] op_sel_hi:[0,1]
	v_pk_add_f32 v[110:111], v[162:163], v[162:163] op_sel:[0,1] op_sel_hi:[0,1] neg_lo:[0,1] neg_hi:[0,1]
	v_fma_f32 v112, v92, v110, -v98
	v_fma_f32 v113, v93, v111, v99
	v_pk_add_f32 v[98:99], v[104:105], v[108:109] neg_lo:[0,1] neg_hi:[0,1]
	v_pk_add_f32 v[92:93], v[102:103], v[106:107] neg_lo:[0,1] neg_hi:[0,1]
	v_pk_add_f32 v[86:87], v[94:95], v[86:87] neg_lo:[0,1] neg_hi:[0,1]
	v_pk_add_f32 v[102:103], v[92:93], v[98:99] op_sel:[0,1] op_sel_hi:[1,0]
	v_pk_add_f32 v[92:93], v[92:93], v[98:99] op_sel:[0,1] op_sel_hi:[1,0] neg_lo:[0,1] neg_hi:[0,1]
	v_pk_add_f32 v[94:95], v[84:85], v[86:87] op_sel:[0,1] op_sel_hi:[1,0]
	v_pk_mul_f32 v[104:105], v[92:93], v[158:159] op_sel:[1,0]
	v_pk_add_f32 v[84:85], v[84:85], v[86:87] op_sel:[0,1] op_sel_hi:[1,0] neg_lo:[0,1] neg_hi:[0,1]
	v_pk_mul_f32 v[166:167], v[152:153], v[134:135]
	v_mov_b32_e32 v168, v154
	v_mov_b32_e32 v169, v157
	v_pk_mov_b32 v[154:155], v[154:155], v[156:157] op_sel:[1,0]
	v_fma_f32 v106, v102, v144, -v104
	v_fma_f32 v107, v102, v153, v105
	ds_write_b64 v127, v[164:165] offset:6528
	v_pk_mul_f32 v[164:165], v[152:153], v[132:133]
	v_add_f32_e32 v156, v168, v154
	v_sub_f32_e32 v155, v169, v155
	v_mov_b32_e32 v99, v103
	v_pk_add_f32 v[104:105], v[166:167], v[166:167] op_sel:[0,1] op_sel_hi:[0,1]
	v_mov_b32_e32 v87, v85
	v_mul_f32_e32 v96, v85, v155
	v_mul_f32_e32 v97, v94, v155
	v_mul_f32_e32 v102, v103, v104
	v_mul_f32_e32 v103, v92, v105
	v_pk_add_f32 v[104:105], v[164:165], v[164:165] op_sel:[0,1] op_sel_hi:[0,1] neg_lo:[0,1] neg_hi:[0,1]
	v_mov_b32_e32 v168, v156
	v_mov_b32_e32 v169, v155
	v_fma_f32 v154, v94, v156, -v96
	v_fma_f32 v155, v87, v156, v97
	v_fma_f32 v92, v92, v104, -v102
	v_fma_f32 v93, v99, v105, v103
	v_pk_mul_f32 v[96:97], v[134:135], v[168:169]
	ds_write_b64 v127, v[154:155] offset:10880
	v_pk_mul_f32 v[86:87], v[132:133], v[168:169]
	ds_write_b64 v127, v[146:147] offset:17408
	ds_write_b64 v127, v[142:143] offset:19584
	ds_write_b64 v127, v[92:93] offset:26112
	v_mov_b32_e32 v93, v95
	v_pk_add_f32 v[96:97], v[96:97], v[96:97] op_sel:[0,1] op_sel_hi:[0,1]
	v_mul_f32_e32 v94, v95, v96
	v_mul_f32_e32 v95, v84, v97
	v_pk_add_f32 v[86:87], v[86:87], v[86:87] op_sel:[0,1] op_sel_hi:[0,1] neg_lo:[0,1] neg_hi:[0,1]
	v_fma_f32 v84, v84, v86, -v94
	v_fma_f32 v85, v93, v87, v95
	v_pk_mul_f32 v[80:81], v[132:133], v[150:151]
	ds_write_b64 v127, v[84:85] offset:28288
	v_mov_b32_e32 v85, v80
	v_pk_mul_f32 v[140:141], v[134:135], v[150:151]
	v_sub_f32_e32 v80, v82, v83
	v_sub_f32_e32 v81, v85, v81
	v_pk_add_f32 v[84:85], v[140:141], v[140:141] op_sel:[0,1] op_sel_hi:[0,1]
	v_mul_f32_e32 v82, v2, v84
	v_mul_f32_e32 v83, v80, v85
	v_pk_mov_b32 v[2:3], v[80:81], v[2:3] op_sel:[1,0]
	v_pk_mul_f32 v[100:101], v[152:153], v[136:137] op_sel:[0,1]
	v_fma_f32 v84, v80, v2, -v82
	v_fma_f32 v85, v81, v3, v83
	v_fma_f32 v136, v152, v138, -v101
	v_fma_f32 v101, v153, v138, v100
	v_sub_f32_e32 v2, v5, v91
	v_sub_f32_e32 v3, v88, v78
	v_sub_f32_e32 v4, v90, v4
	v_sub_f32_e32 v5, v89, v79
	v_mov_b32_e32 v139, v101
	v_pk_add_f32 v[78:79], v[4:5], v[2:3]
	v_pk_add_f32 v[2:3], v[4:5], v[2:3] neg_lo:[0,1] neg_hi:[0,1]
	v_mov_b32_e32 v138, v136
	v_mul_f32_e32 v80, v3, v101
	v_mul_f32_e32 v81, v3, v136
	v_pk_mul_f32 v[134:135], v[134:135], v[138:139]
	v_fma_f32 v82, v78, v136, -v80
	v_fma_f32 v83, v78, v139, v81
	v_pk_mul_f32 v[132:133], v[132:133], v[138:139]
	v_mov_b32_e32 v5, v79
	v_pk_add_f32 v[80:81], v[134:135], v[134:135] op_sel:[0,1] op_sel_hi:[0,1]
	v_mul_f32_e32 v78, v79, v80
	v_mul_f32_e32 v79, v2, v81
	v_pk_add_f32 v[80:81], v[132:133], v[132:133] op_sel:[0,1] op_sel_hi:[0,1] neg_lo:[0,1] neg_hi:[0,1]
	v_fma_f32 v2, v2, v80, -v78
	v_fma_f32 v3, v5, v81, v79
	ds_write_b64 v127, v[118:119] offset:21760
	ds_write_b64 v127, v[2:3] offset:32640
	v_mov_b32_e32 v2, v1
	ds_write_b64 v127, v[112:113] offset:23936
	ds_write_b64 v127, v[106:107] offset:8704
	ds_write_b64 v127, v[84:85] offset:30464
	ds_write_b64 v127, v[82:83] offset:15232
	s_waitcnt lgkmcnt(0)
	s_barrier
	s_mov_b32 s2, s20
	v_ashrrev_i32_e32 v3, 31, v2
	v_lshrrev_b32_e32 v3, 28, v3
	v_and_b32_e32 v115, 15, v2
	v_add_u32_e32 v2, v2, v3
	v_ashrrev_i32_e32 v2, 4, v2
	v_lshlrev_b32_e32 v3, 11, v2
	v_lshl_add_u32 v2, v2, 7, v3
	v_lshl_or_b32 v127, v115, 3, v2
	ds_read2_b64 v[84:87], v127 offset1:17
	ds_read2_b64 v[88:91], v127 offset0:68 offset1:85
	ds_read2_b64 v[92:95], v127 offset0:136 offset1:153
	ds_read2_b64 v[96:99], v127 offset0:170 offset1:187
	ds_read2_b64 v[100:103], v127 offset0:204 offset1:221
	ds_read2_b64 v[104:107], v127 offset0:238 offset1:255
	ds_read2_b64 v[108:111], v127 offset0:34 offset1:51
	ds_read2_b64 v[116:119], v127 offset0:102 offset1:119
	s_waitcnt lgkmcnt(5)
	v_pk_add_f32 v[82:83], v[92:93], v[84:85]
	s_waitcnt lgkmcnt(2)
	v_pk_mov_b32 v[140:141], v[98:99], v[106:107] op_sel:[1,0]
	s_waitcnt lgkmcnt(1)
	v_pk_add_f32 v[136:137], v[110:111], v[98:99]
	s_waitcnt lgkmcnt(0)
	v_pk_add_f32 v[138:139], v[118:119], v[106:107]
	v_mov_b32_e32 v99, v107
	v_pk_add_f32 v[106:107], v[136:137], v[138:139] neg_lo:[0,1] neg_hi:[0,1]
	v_sub_f32_e32 v140, v111, v140
	v_sub_f32_e32 v141, v118, v141
	v_pk_add_f32 v[80:81], v[136:137], v[138:139]
	v_mul_f32_e32 v136, 0x3f3504f3, v107
	v_mul_f32_e32 v139, 0xbf3504f3, v107
	v_cvt_f32_i32_e32 v107, v115
	v_sub_f32_e32 v98, v110, v98
	v_sub_f32_e32 v99, v119, v99
	v_pk_add_f32 v[92:93], v[84:85], v[92:93] neg_lo:[0,1] neg_hi:[0,1]
	v_add_f32_e32 v107, v107, v107
	v_pk_add_f32 v[84:85], v[88:89], v[100:101] neg_lo:[0,1] neg_hi:[0,1]
	v_pk_add_f32 v[112:113], v[100:101], v[88:89]
	v_pk_add_f32 v[120:121], v[86:87], v[94:95]
	v_pk_add_f32 v[128:129], v[90:91], v[102:103]
	v_sub_f32_e32 v110, v98, v99
	v_mul_f32_e32 v107, 0x3b800000, v107
	v_pk_mov_b32 v[88:89], v[84:85], v[84:85] op_sel:[1,0]
	v_add_f32_e32 v100, v92, v85
	v_sub_f32_e32 v101, v93, v84
	v_pk_add_f32 v[98:99], v[98:99], v[98:99] op_sel:[0,1] op_sel_hi:[0,1]
	v_pk_add_f32 v[4:5], v[120:121], v[128:129]
	v_pk_add_f32 v[130:131], v[108:109], v[96:97]
	v_pk_add_f32 v[132:133], v[116:117], v[104:105]
	v_pk_add_f32 v[120:121], v[120:121], v[128:129] neg_lo:[0,1] neg_hi:[0,1]
	v_mul_f32_e32 v107, 0.5, v107
	v_pk_add_f32 v[84:85], v[140:141], v[140:141] op_sel:[0,1] op_sel_hi:[0,1] neg_lo:[0,1] neg_hi:[0,1]
	v_pk_mul_f32 v[98:99], v[98:99], s[38:39]
	v_pk_add_f32 v[78:79], v[130:131], v[132:133]
	v_pk_add_f32 v[134:135], v[130:131], v[132:133] neg_lo:[0,1] neg_hi:[0,1]
	v_add_f32_e32 v118, v140, v141
	v_pk_mul_f32 v[128:129], v[120:121], s[20:21] op_sel_hi:[1,0]
	v_mul_f32_e32 v106, 0x3f3504f3, v106
	v_sin_f32_e32 v130, v107
	s_nop 1
	v_cos_f32_e32 v148, v107
	s_nop 1
	v_fma_f32 v140, v84, s40, v98
	v_fma_f32 v141, v85, s41, -v99
	v_pk_add_f32 v[2:3], v[82:83], v[112:113]
	v_mov_b32_e32 v84, v82
	v_sub_f32_e32 v82, v136, v106
	v_sub_f32_e32 v83, v83, v113
	v_sub_f32_e32 v84, v84, v112
	v_sub_f32_e32 v85, v129, v128
	v_mov_b32_e32 v99, v106
	v_pk_add_f32 v[106:107], v[82:83], v[134:135] op_sel:[1,0] op_sel_hi:[0,1]
	v_mov_b32_e32 v113, v134
	v_sub_f32_e32 v98, v131, v133
	v_sub_f32_e32 v99, v139, v99
	v_sub_f32_e32 v134, v108, v96
	v_sub_f32_e32 v135, v86, v94
	v_sub_f32_e32 v136, v117, v105
	v_sub_f32_e32 v137, v91, v103
	v_mul_f32_e32 v115, 0x3f6c835e, v118
	v_mul_f32_e32 v150, 0x3ec3ef15, v110
	v_sub_f32_e32 v86, v109, v97
	v_sub_f32_e32 v87, v87, v95
	v_sub_f32_e32 v91, v90, v102
	v_sub_f32_e32 v90, v116, v104
	v_pk_add_f32 v[96:97], v[134:135], v[136:137] neg_lo:[0,1] neg_hi:[0,1]
	v_pk_fma_f32 v[120:121], v[120:121], s[20:21], v[128:129] op_sel:[0,0,1] op_sel_hi:[1,0,0]
	v_pk_add_f32 v[138:139], v[134:135], v[136:137]
	v_pk_add_f32 v[94:95], v[86:87], v[90:91] neg_lo:[0,1] neg_hi:[0,1]
	v_pk_add_f32 v[86:87], v[86:87], v[90:91]
	v_mov_b32_e32 v103, v93
	v_mov_b32_e32 v91, v89
	v_mov_b32_e32 v112, v120
	v_pk_add_f32 v[120:121], v[120:121], v[82:83] neg_lo:[0,1] neg_hi:[0,1]
	v_mul_f32_e32 v90, 0x3ec3ef15, v97
	v_pk_mul_f32 v[104:105], v[96:97], s[20:21]
	v_mul_f32_e32 v97, s73, v96
	v_mul_f32_e32 v96, s72, v118
	v_sub_f32_e32 v88, v92, v88
	v_sub_f32_e32 v89, v150, v115
	v_pk_mul_f32 v[92:93], v[138:139], s[40:41] op_sel:[1,0]
	v_add_f32_e32 v128, v82, v112
	v_sub_f32_e32 v113, v83, v113
	v_pk_add_f32 v[82:83], v[106:107], v[120:121]
	v_mul_f32_e32 v102, 0x3f6c835e, v87
	v_mul_f32_e32 v107, 0x3f3504f3, v138
	v_mul_f32_e32 v108, 0x3f3504f3, v94
	v_pk_fma_f32 v[104:105], v[86:87], s[70:71], v[104:105] neg_lo:[0,0,1] neg_hi:[0,0,1]
	v_fma_f32 v87, v86, s31, -v97
	v_fma_f32 v86, v110, s30, -v96
	v_fma_f32 v96, v95, s38, v92
	v_fma_f32 v97, v95, s39, -v93
	v_pk_add_f32 v[90:91], v[102:103], v[90:91]
	v_add_f32_e32 v92, v108, v107
	v_fma_f32 v93, v94, s20, -v107
	v_pk_add_f32 v[94:95], v[100:101], v[92:93]
	v_pk_add_f32 v[102:103], v[96:97], v[140:141]
	v_xor_b32_e32 v149, 0x80000000, v130
	v_pk_add_f32 v[108:109], v[102:103], v[94:95]
	v_pk_add_f32 v[142:143], v[2:3], v[78:79]
	v_pk_mul_f32 v[118:119], v[130:131], v[108:109] op_sel_hi:[0,1]
	v_fma_f32 v134, v148, v108, v119
	v_fma_f32 v135, v148, v109, -v118
	v_mov_b32_e32 v131, v148
	v_pk_add_f32 v[144:145], v[4:5], v[80:81]
	v_mul_f32_e32 v108, v130, v130
	v_mul_f32_e32 v109, v131, v149
	v_pk_add_f32 v[146:147], v[144:145], v[142:143]
	v_pk_fma_f32 v[118:119], v[148:149], v[148:149], v[108:109] op_sel_hi:[0,1,1] neg_lo:[0,0,1] neg_hi:[0,0,1]
	v_pk_fma_f32 v[108:109], v[148:149], v[148:149], v[108:109] op_sel_hi:[0,1,1]
	v_pk_add_f32 v[132:133], v[84:85], v[98:99]
	ds_write2_b64 v127, v[146:147], v[134:135] offset1:17
	v_pk_add_f32 v[84:85], v[84:85], v[98:99] neg_lo:[0,1] neg_hi:[0,1]
	v_add_f32_e32 v98, v132, v128
	v_add_f32_e32 v99, v133, v113
	v_mov_b32_e32 v134, v118
	v_mov_b32_e32 v135, v109
	v_mul_f32_e32 v146, v109, v109
	v_mul_f32_e32 v147, v109, v118
	v_pk_mul_f32 v[108:109], v[98:99], v[108:109] op_sel:[1,1] op_sel_hi:[0,1]
	v_pk_fma_f32 v[150:151], v[118:119], v[134:135], v[146:147] op_sel_hi:[0,1,1] neg_lo:[0,0,1] neg_hi:[0,0,1]
	v_pk_fma_f32 v[146:147], v[118:119], v[134:135], v[146:147] op_sel_hi:[0,1,1]
	v_fma_f32 v160, v98, v118, -v108
	v_fma_f32 v161, v99, v118, v109
	v_pk_mul_f32 v[108:109], v[134:135], v[146:147] op_sel:[0,1]
	v_pk_add_f32 v[96:97], v[96:97], v[140:141] neg_lo:[0,1] neg_hi:[0,1]
	v_fma_f32 v118, v134, v150, -v109
	v_fma_f32 v109, v135, v150, v108
	v_sub_f32_e32 v106, v106, v120
	v_mov_b32_e32 v141, v109
	v_mov_b32_e32 v149, v130
	v_mov_b32_e32 v152, v150
	v_mov_b32_e32 v153, v147
	v_pk_add_f32 v[162:163], v[84:85], v[84:85] op_sel:[0,1] op_sel_hi:[0,1]
	v_mul_f32_e32 v107, v106, v118
	v_mul_f32_e32 v106, v106, v109
	v_pk_mul_f32 v[136:137], v[148:149], v[134:135]
	v_pk_mul_f32 v[138:139], v[130:131], v[134:135]
	v_mov_b32_e32 v140, v118
	v_fma_f32 v108, v162, v118, -v106
	v_pk_mul_f32 v[118:119], v[152:153], v[146:147] op_sel:[0,1]
	v_pk_add_f32 v[94:95], v[94:95], v[102:103] neg_lo:[0,1] neg_hi:[0,1]
	v_pk_add_f32 v[102:103], v[104:105], v[88:89]
	v_pk_add_f32 v[110:111], v[90:91], v[86:87]
	v_fma_f32 v109, v163, v141, v107
	v_pk_fma_f32 v[120:121], v[150:151], v[152:153], v[118:119] op_sel:[0,0,1] op_sel_hi:[0,1,0] neg_lo:[0,0,1] neg_hi:[0,0,1]
	v_pk_fma_f32 v[118:119], v[150:151], v[152:153], v[118:119] op_sel:[0,0,1] op_sel_hi:[0,1,0]
	v_mov_b32_e32 v164, v136
	v_pk_mov_b32 v[136:137], v[136:137], v[138:139] op_sel:[1,0]
	v_pk_add_f32 v[116:117], v[102:103], v[110:111]
	v_pk_add_f32 v[106:107], v[142:143], v[144:145] neg_lo:[0,1] neg_hi:[0,1]
	v_pk_mov_b32 v[144:145], v[118:119], v[120:121] op_sel:[1,0]
	v_add_f32_e32 v138, v164, v136
	v_sub_f32_e32 v136, v164, v136
	v_sub_f32_e32 v137, v139, v137
	v_pk_mul_f32 v[154:155], v[148:149], v[152:153]
	v_pk_mul_f32 v[156:157], v[130:131], v[152:153]
	v_pk_add_f32 v[92:93], v[100:101], v[92:93] neg_lo:[0,1] neg_hi:[0,1]
	v_mov_b32_e32 v142, v120
	v_mov_b32_e32 v143, v119
	v_pk_mul_f32 v[130:131], v[130:131], v[144:145] op_sel_hi:[0,1]
	v_pk_mul_f32 v[166:167], v[116:117], v[136:137] op_sel:[0,1]
	v_pk_mov_b32 v[158:159], v[146:147], v[150:151] op_sel:[1,0]
	v_pk_add_f32 v[98:99], v[92:93], v[96:97] op_sel:[0,1] op_sel_hi:[1,0]
	v_pk_add_f32 v[92:93], v[92:93], v[96:97] op_sel:[0,1] op_sel_hi:[1,0] neg_lo:[0,1] neg_hi:[0,1]
	v_fma_f32 v146, v148, v142, v130
	v_fma_f32 v131, v148, v143, -v131
	v_fma_f32 v168, v116, v138, -v167
	v_fma_f32 v169, v117, v138, v166
	v_mov_b32_e32 v170, v154
	v_mov_b32_e32 v171, v157
	v_pk_mov_b32 v[154:155], v[154:155], v[156:157] op_sel:[1,0]
	v_mov_b32_e32 v149, v131
	v_pk_mul_f32 v[116:117], v[152:153], v[136:137] op_sel:[0,1]
	v_add_f32_e32 v156, v170, v154
	v_sub_f32_e32 v155, v171, v155
	v_mov_b32_e32 v97, v93
	v_mov_b32_e32 v165, v137
	v_fma_f32 v136, v152, v138, -v117
	v_fma_f32 v117, v153, v138, v116
	v_mul_f32_e32 v100, v93, v155
	v_mul_f32_e32 v101, v98, v155
	v_mul_f32_e32 v130, v95, v131
	v_mul_f32_e32 v131, v95, v146
	v_mov_b32_e32 v164, v138
	v_mov_b32_e32 v138, v136
	v_mov_b32_e32 v139, v117
	v_mov_b32_e32 v170, v156
	v_mov_b32_e32 v171, v155
	v_fma_f32 v154, v98, v156, -v100
	v_fma_f32 v155, v97, v156, v101
	v_fma_f32 v146, v94, v146, -v130
	v_fma_f32 v147, v94, v149, v131
	v_pk_mul_f32 v[118:119], v[106:107], v[118:119] op_sel:[1,1] op_sel_hi:[0,1]
	v_pk_mul_f32 v[162:163], v[134:135], v[142:143]
	v_pk_mul_f32 v[134:135], v[134:135], v[144:145]
	ds_write2_b64 v127, v[160:161], v[168:169] offset0:34 offset1:51
	v_pk_mul_f32 v[160:161], v[164:165], v[142:143]
	v_pk_mul_f32 v[164:165], v[164:165], v[144:145]
	v_pk_mul_f32 v[166:167], v[152:153], v[142:143]
	v_pk_mul_f32 v[168:169], v[152:153], v[144:145]
	v_pk_mul_f32 v[96:97], v[142:143], v[170:171]
	v_pk_mul_f32 v[100:101], v[144:145], v[170:171]
	v_pk_mul_f32 v[94:95], v[142:143], v[140:141]
	v_pk_mul_f32 v[130:131], v[144:145], v[140:141]
	v_pk_mul_f32 v[140:141], v[142:143], v[138:139]
	v_pk_mul_f32 v[142:143], v[144:145], v[138:139]
	v_fma_f32 v144, v106, v120, -v118
	v_fma_f32 v145, v107, v120, v119
	v_sub_f32_e32 v106, v132, v128
	v_sub_f32_e32 v107, v113, v133
	v_pk_add_f32 v[112:113], v[134:135], v[134:135] op_sel:[0,1] op_sel_hi:[0,1]
	v_pk_mul_f32 v[112:113], v[106:107], v[112:113] op_sel:[1,0] op_sel_hi:[0,1]
	v_pk_add_f32 v[118:119], v[162:163], v[162:163] op_sel:[0,1] op_sel_hi:[0,1] neg_lo:[0,1] neg_hi:[0,1]
	v_fma_f32 v120, v106, v118, -v112
	v_fma_f32 v121, v107, v119, v113
	v_pk_add_f32 v[2:3], v[2:3], v[78:79] neg_lo:[0,1] neg_hi:[0,1]
	v_mov_b32_e32 v107, v111
	v_sub_f32_e32 v102, v102, v110
	v_sub_f32_e32 v103, v107, v103
	v_pk_add_f32 v[106:107], v[164:165], v[164:165] op_sel:[0,1] op_sel_hi:[0,1]
	v_pk_add_f32 v[4:5], v[4:5], v[80:81] neg_lo:[0,1] neg_hi:[0,1]
	v_pk_mul_f32 v[106:107], v[102:103], v[106:107] op_sel:[1,0] op_sel_hi:[0,1]
	v_pk_add_f32 v[110:111], v[160:161], v[160:161] op_sel:[0,1] op_sel_hi:[0,1] neg_lo:[0,1] neg_hi:[0,1]
	v_pk_add_f32 v[78:79], v[2:3], v[4:5] op_sel:[0,1] op_sel_hi:[1,0]
	v_pk_add_f32 v[2:3], v[2:3], v[4:5] op_sel:[0,1] op_sel_hi:[1,0] neg_lo:[0,1] neg_hi:[0,1]
	v_fma_f32 v112, v102, v110, -v106
	v_fma_f32 v113, v103, v111, v107
	v_pk_mul_f32 v[80:81], v[2:3], v[158:159] op_sel:[1,0]
	v_fma_f32 v102, v78, v150, -v80
	v_fma_f32 v103, v78, v153, v81
	v_mov_b32_e32 v5, v79
	v_pk_add_f32 v[80:81], v[168:169], v[168:169] op_sel:[0,1] op_sel_hi:[0,1]
	v_mul_f32_e32 v78, v79, v80
	v_mul_f32_e32 v79, v2, v81
	v_pk_add_f32 v[80:81], v[166:167], v[166:167] op_sel:[0,1] op_sel_hi:[0,1] neg_lo:[0,1] neg_hi:[0,1]
	v_fma_f32 v2, v2, v80, -v78
	v_fma_f32 v3, v5, v81, v79
	v_pk_add_f32 v[80:81], v[100:101], v[100:101] op_sel:[0,1] op_sel_hi:[0,1]
	v_mov_b32_e32 v5, v99
	v_mul_f32_e32 v78, v99, v80
	v_mul_f32_e32 v79, v92, v81
	v_pk_add_f32 v[80:81], v[96:97], v[96:97] op_sel:[0,1] op_sel_hi:[0,1] neg_lo:[0,1] neg_hi:[0,1]
	v_fma_f32 v92, v92, v80, -v78
	v_fma_f32 v93, v5, v81, v79
	v_pk_add_f32 v[78:79], v[130:131], v[130:131] op_sel:[0,1] op_sel_hi:[0,1]
	ds_write2_b64 v127, v[2:3], v[92:93] offset0:204 offset1:221
	v_mov_b32_e32 v3, v94
	v_sub_f32_e32 v2, v84, v85
	v_sub_f32_e32 v3, v3, v95
	v_mul_f32_e32 v4, v82, v78
	v_mul_f32_e32 v5, v2, v79
	v_pk_mov_b32 v[78:79], v[2:3], v[82:83] op_sel:[1,0]
	v_fma_f32 v80, v2, v78, -v4
	v_fma_f32 v81, v3, v79, v5
	v_mov_b32_e32 v3, v90
	v_mov_b32_e32 v5, v86
	v_sub_f32_e32 v2, v88, v104
	v_sub_f32_e32 v3, v3, v5
	v_sub_f32_e32 v4, v105, v89
	v_sub_f32_e32 v5, v91, v87
	ds_write2_b64 v127, v[144:145], v[146:147] offset0:136 offset1:153
	v_pk_add_f32 v[78:79], v[4:5], v[2:3]
	v_sub_f32_e32 v82, v2, v4
	v_sub_f32_e32 v2, v5, v3
	v_mul_f32_e32 v3, v2, v136
	v_mul_f32_e32 v2, v2, v117
	v_fma_f32 v4, v78, v136, -v2
	v_fma_f32 v5, v78, v139, v3
	ds_write2_b64 v127, v[108:109], v[4:5] offset0:102 offset1:119
	v_pk_add_f32 v[4:5], v[142:143], v[142:143] op_sel:[0,1] op_sel_hi:[0,1]
	v_mov_b32_e32 v85, v79
	v_mul_f32_e32 v2, v79, v4
	v_mul_f32_e32 v3, v82, v5
	v_pk_add_f32 v[4:5], v[140:141], v[140:141] op_sel:[0,1] op_sel_hi:[0,1] neg_lo:[0,1] neg_hi:[0,1]
	v_fma_f32 v78, v82, v4, -v2
	v_fma_f32 v79, v85, v5, v3
	ds_write2_b64 v127, v[120:121], v[112:113] offset0:170 offset1:187
	v_mov_b32_e32 v2, v1
	ds_write2_b64 v127, v[102:103], v[154:155] offset0:68 offset1:85
	ds_write2_b64 v127, v[80:81], v[78:79] offset0:238 offset1:255
	s_waitcnt lgkmcnt(0)
	s_barrier
	s_mov_b32 s77, s71
	v_mul_lo_u32 v102, v2, s33
	ds_read2_b64 v[2:5], v102 offset1:1
	ds_read2_b64 v[78:81], v102 offset0:2 offset1:3
	ds_read2_b64 v[82:85], v102 offset0:9 offset1:10
	ds_read2_b64 v[86:89], v102 offset0:4 offset1:5
	ds_read2_b64 v[90:93], v102 offset0:6 offset1:7
	ds_read2_b64 v[94:97], v102 offset0:13 offset1:14
	ds_read2_b64 v[98:101], v102 offset0:8 offset1:15
	ds_read2_b64 v[102:105], v102 offset0:11 offset1:12
	s_waitcnt lgkmcnt(5)
	v_add_f32_e32 v106, v4, v82
	s_waitcnt lgkmcnt(3)
	s_waitcnt lgkmcnt(2)
	v_add_f32_e32 v108, v88, v94
	s_waitcnt lgkmcnt(1)
	v_pk_add_f32 v[132:133], v[2:3], v[98:99]
	v_pk_add_f32 v[2:3], v[2:3], v[98:99] neg_lo:[0,1] neg_hi:[0,1]
	s_waitcnt lgkmcnt(0)
	v_pk_add_f32 v[98:99], v[86:87], v[104:105]
	v_pk_add_f32 v[86:87], v[86:87], v[104:105] neg_lo:[0,1] neg_hi:[0,1]
	v_add_f32_e32 v107, v106, v108
	v_sub_f32_e32 v106, v106, v108
	v_mov_b32_e32 v128, v79
	v_add_f32_e32 v134, v2, v87
	v_sub_f32_e32 v135, v3, v86
	v_add_f32_e32 v108, v80, v102
	v_add_f32_e32 v109, v92, v100
	v_mov_b32_e32 v130, v91
	v_mov_b32_e32 v141, v82
	v_add_f32_e32 v115, v5, v83
	v_add_f32_e32 v110, v81, v103
	v_add_f32_e32 v111, v93, v101
	v_mov_b32_e32 v112, v81
	v_mov_b32_e32 v116, v103
	v_add_f32_e32 v136, v79, v85
	v_add_f32_e32 v137, v78, v84
	v_mov_b32_e32 v79, v4
	v_sub_f32_e32 v4, v128, v85
	v_sub_f32_e32 v5, v5, v83
	v_mov_b32_e32 v85, v94
	v_add_f32_e32 v119, v89, v95
	v_sub_f32_e32 v80, v80, v102
	v_sub_f32_e32 v81, v93, v101
	v_sub_f32_e32 v78, v78, v84
	v_sub_f32_e32 v79, v79, v141
	v_add_f32_e32 v82, v91, v97
	v_add_f32_e32 v83, v90, v96
	v_mov_b32_e32 v91, v88
	v_sub_f32_e32 v88, v130, v97
	v_sub_f32_e32 v89, v89, v95
	v_mov_b32_e32 v117, v100
	v_pk_add_f32 v[100:101], v[80:81], v[80:81] op_sel_hi:[0,1] neg_lo:[0,1] neg_hi:[0,1]
	v_sub_f32_e32 v84, v90, v96
	v_sub_f32_e32 v85, v91, v85
	v_mov_b32_e32 v130, v80
	v_sub_f32_e32 v112, v112, v116
	v_sub_f32_e32 v113, v92, v117
	v_pk_add_f32 v[96:97], v[78:79], v[88:89] neg_lo:[0,1] neg_hi:[0,1]
	v_pk_add_f32 v[128:129], v[4:5], v[84:85]
	v_add_f32_e32 v80, v130, v81
	v_add_f32_e32 v81, v78, v88
	v_mov_b32_e32 v131, v4
	v_sub_f32_e32 v4, v5, v85
	v_add_f32_e32 v78, v79, v89
	v_pk_add_f32 v[102:103], v[112:113], v[112:113] op_sel:[0,1] op_sel_hi:[1,0]
	v_mov_b32_e32 v130, v112
	v_pk_mov_b32 v[112:113], v[112:113], v[84:85] op_sel:[1,0]
	v_pk_mul_f32 v[84:85], v[4:5], s[38:39] op_sel_hi:[0,1]
	v_pk_mul_f32 v[78:79], v[78:79], s[40:41] op_sel_hi:[0,1]
	v_pk_add_f32 v[112:113], v[130:131], v[112:113] neg_lo:[0,1] neg_hi:[0,1]
	v_sub_f32_e32 v118, v115, v119
	v_pk_add_f32 v[92:93], v[108:109], v[108:109] op_sel:[0,1] op_sel_hi:[1,0]
	v_sub_f32_e32 v108, v108, v109
	v_add_f32_e32 v88, v2, v87
	v_add_f32_e32 v89, v84, v78
	v_fma_f32 v130, v4, s38, v78
	v_fma_f32 v131, v4, s39, -v79
	v_mul_f32_e32 v109, 0x3f3504f3, v106
	v_mul_f32_e32 v117, 0x3f3504f3, v118
	v_mul_f32_e32 v120, 0x3f3504f3, v108
	v_mov_b32_e32 v4, v85
	v_mul_f32_e32 v104, 0x3ec3ef15, v97
	v_mul_f32_e32 v84, 0x3f6c835e, v129
	v_sub_f32_e32 v4, v4, v79
	v_sub_f32_e32 v5, v3, v86
	v_sub_f32_e32 v78, v132, v98
	v_sub_f32_e32 v79, v117, v109
	v_add_f32_e32 v84, v84, v104
	v_add_f32_e32 v85, v3, v86
	v_pk_mul_f32 v[104:105], v[80:81], s[72:73]
	v_pk_mul_f32 v[108:109], v[80:81], s[74:75]
	v_pk_mul_f32 v[80:81], v[80:81], s[38:39] op_sel_hi:[0,1]
	v_fma_f32 v150, v112, s40, v80
	v_fma_f32 v151, v112, s41, -v81
	v_pk_add_f32 v[80:81], v[110:111], v[110:111] op_sel:[0,1] op_sel_hi:[0,1] neg_lo:[0,1] neg_hi:[0,1]
	v_pk_fma_f32 v[140:141], v[112:113], s[72:73], v[108:109] neg_lo:[0,0,1] neg_hi:[0,0,1]
	v_fmac_f32_e32 v109, 0x3f3504f3, v113
	v_pk_fma_f32 v[104:105], v[112:113], s[74:75], v[104:105]
	v_pk_mul_f32 v[112:113], v[80:81], s[2:3]
	v_mov_b32_e32 v121, v99
	v_mov_b32_e32 v144, v102
	v_sub_f32_e32 v152, v112, v120
	v_sub_f32_e32 v153, v133, v121
	v_pk_fma_f32 v[80:81], v[80:81], s[2:3], v[120:121] op_sel_hi:[1,1,0] neg_lo:[0,0,1] neg_hi:[0,0,1]
	v_pk_mul_f32 v[102:103], v[102:103], s[38:39] op_sel_hi:[0,1]
	v_mul_f32_e32 v3, s77, v101
	v_mov_b32_e32 v86, v87
	v_pk_add_f32 v[138:139], v[132:133], v[98:99] neg_lo:[0,1] neg_hi:[0,1]
	v_add_f32_e32 v90, v133, v99
	v_add_f32_e32 v91, v136, v82
	v_pk_add_f32 v[94:95], v[136:137], v[82:83] neg_lo:[0,1] neg_hi:[0,1]
	v_mov_b32_e32 v143, v101
	v_pk_mov_b32 v[148:149], v[100:101], v[128:129] op_sel:[1,0]
	v_sub_f32_e32 v2, v2, v86
	v_sub_f32_e32 v3, v3, v103
	v_pk_fma_f32 v[86:87], v[100:101], s[76:77], v[102:103] op_sel:[1,0,0] neg_lo:[0,0,1] neg_hi:[0,0,1]
	v_pk_mov_b32 v[100:101], v[136:137], v[110:111] op_sel:[1,0]
	v_fmamk_f32 v118, v106, 0x3f3504f3, v117
	v_mov_b32_e32 v145, v96
	v_mov_b32_e32 v154, v82
	v_add_f32_e32 v98, v132, v98
	v_add_f32_e32 v99, v115, v119
	v_add_f32_e32 v82, v100, v83
	v_add_f32_e32 v83, v101, v111
	v_sub_f32_e32 v110, v138, v94
	v_add_f32_e32 v111, v139, v95
	v_mov_b32_e32 v119, v95
	v_pk_mul_f32 v[116:117], v[96:97], s[20:21]
	v_pk_mul_f32 v[96:97], v[144:145], s[74:75]
	v_pk_mul_f32 v[144:145], v[144:145], s[72:73]
	v_sub_f32_e32 v112, v136, v154
	v_sub_f32_e32 v113, v113, v120
	v_add_f32_e32 v94, v152, v118
	v_sub_f32_e32 v121, v153, v119
	v_mov_b32_e32 v142, v128
	v_pk_fma_f32 v[146:147], v[128:129], s[70:71], v[116:117] neg_lo:[0,0,1] neg_hi:[0,0,1]
	v_pk_fma_f32 v[128:129], v[128:129], s[2:3], v[116:117] op_sel_hi:[0,1,0] neg_lo:[0,0,1] neg_hi:[0,0,1]
	v_add_f32_e32 v100, v90, v91
	v_add_f32_e32 v101, v99, v83
	v_mov_b32_e32 v106, v98
	v_mov_b32_e32 v102, v82
	v_pk_add_f32 v[82:83], v[98:99], v[82:83] neg_lo:[0,1] neg_hi:[0,1]
	v_pk_add_f32 v[98:99], v[130:131], v[150:151]
	v_pk_add_f32 v[130:131], v[78:79], v[112:113]
	s_mov_b32 s42, s71
	s_mov_b32 s43, s3
	v_fma_f32 v116, v142, s78, -v116
	v_fma_f32 v117, v143, s79, -v144
	v_pk_fma_f32 v[142:143], v[148:149], s[30:31], v[144:145] neg_lo:[0,0,1] neg_hi:[0,0,1]
	v_add_f32_e32 v80, v118, v80
	v_add_f32_e32 v81, v79, v81
	v_add_f32_e32 v94, v130, v94
	v_add_f32_e32 v95, v131, v121
	v_mov_b32_e32 v108, v109
	v_pk_fma_f32 v[96:97], v[148:149], s[42:43], v[96:97] neg_lo:[0,0,1] neg_hi:[0,0,1]
	v_add_f32_e32 v102, v106, v102
	v_add_f32_e32 v103, v107, v92
	v_sub_f32_e32 v80, v130, v80
	v_sub_f32_e32 v81, v121, v81
	v_add_f32_e32 v120, v2, v128
	v_add_f32_e32 v121, v85, v129
	v_pk_add_f32 v[128:129], v[84:85], v[142:143]
	v_pk_add_f32 v[130:131], v[146:147], v[2:3]
	v_mov_b32_e32 v146, v84
	v_mov_b32_e32 v3, v84
	v_pk_add_f32 v[132:133], v[100:101], v[100:101] op_sel:[1,0] op_sel_hi:[1,0]
	v_mov_b32_e32 v106, v90
	v_pk_mov_b32 v[90:91], v[90:91], v[92:93] op_sel:[1,0]
	v_add_f32_e32 v92, v134, v108
	v_add_f32_e32 v93, v135, v141
	v_sub_f32_e32 v84, v147, v96
	v_sub_f32_e32 v85, v85, v97
	v_pk_add_f32 v[96:97], v[130:131], v[128:129]
	v_pk_add_f32 v[130:131], v[102:103], v[102:103] op_sel:[1,0] op_sel_hi:[1,0]
	v_pk_mul_f32 v[132:133], v[74:75], v[132:133]
	v_pk_add_f32 v[88:89], v[88:89], v[104:105] op_sel:[0,1] op_sel_hi:[1,0] neg_lo:[0,1] neg_hi:[0,1]
	v_pk_add_f32 v[104:105], v[98:99], v[92:93]
	v_fma_f32 v134, v14, v130, -v132
	v_fma_f32 v135, v15, v131, v133
	v_pk_add_f32 v[90:91], v[106:107], v[90:91] neg_lo:[0,1] neg_hi:[0,1]
	v_pk_mul_f32 v[130:131], v[24:25], v[104:105] op_sel:[0,1] op_sel_hi:[1,0]
	v_pk_add_f32 v[4:5], v[4:5], v[140:141] neg_lo:[0,1] neg_hi:[0,1]
	v_fma_f32 v132, v22, v104, -v130
	v_fma_f32 v105, v23, v105, v131
	v_pk_mul_f32 v[130:131], v[40:41], v[94:95] op_sel:[0,1] op_sel_hi:[1,0]
	v_pk_add_f32 v[92:93], v[92:93], v[98:99] neg_lo:[0,1] neg_hi:[0,1]
	v_pk_add_f32 v[98:99], v[4:5], v[88:89]
	v_sub_f32_e32 v107, v5, v89
	v_fma_f32 v136, v38, v94, -v130
	v_fma_f32 v95, v39, v95, v131
	v_pk_mul_f32 v[130:131], v[56:57], v[96:97] op_sel:[0,1] op_sel_hi:[1,0]
	v_pk_add_f32 v[140:141], v[90:91], v[90:91] op_sel:[0,1] op_sel_hi:[0,1] neg_lo:[0,1] neg_hi:[0,1]
	v_mov_b32_e32 v109, v107
	v_sub_f32_e32 v78, v79, v113
	v_sub_f32_e32 v79, v118, v152
	v_fma_f32 v138, v54, v96, -v130
	v_fma_f32 v97, v55, v97, v131
	v_pk_add_f32 v[130:131], v[82:83], v[82:83] op_sel:[0,1] op_sel_hi:[0,1]
	v_pk_mul_f32 v[140:141], v[70:71], v[140:141]
	v_mov_b32_e32 v108, v98
	v_pk_add_f32 v[112:113], v[110:111], v[78:79]
	v_pk_add_f32 v[78:79], v[110:111], v[78:79] neg_lo:[0,1] neg_hi:[0,1]
	v_fma_f32 v142, v18, v130, -v140
	v_fma_f32 v143, v19, v131, v141
	v_mul_f32_e32 v106, v32, v107
	v_mul_f32_e32 v107, v33, v98
	v_pk_add_f32 v[86:87], v[146:147], v[86:87]
	v_pk_add_f32 v[2:3], v[2:3], v[116:117] neg_lo:[0,1] neg_hi:[0,1]
	v_fma_f32 v130, v30, v108, -v106
	v_fma_f32 v107, v31, v109, v107
	v_mov_b32_e32 v111, v79
	v_pk_add_f32 v[86:87], v[120:121], v[86:87] neg_lo:[0,1] neg_hi:[0,1]
	v_pk_add_f32 v[116:117], v[84:85], v[2:3]
	v_sub_f32_e32 v121, v85, v3
	v_mul_f32_e32 v108, v48, v79
	v_mul_f32_e32 v109, v49, v112
	v_pk_add_f32 v[100:101], v[100:101], v[100:101] op_sel:[0,1] op_sel_hi:[0,1] neg_lo:[0,1] neg_hi:[0,1]
	v_fma_f32 v140, v46, v112, -v108
	v_fma_f32 v109, v47, v111, v109
	v_mov_b32_e32 v128, v116
	v_mul_f32_e32 v110, v64, v121
	v_mul_f32_e32 v111, v65, v116
	v_pk_add_f32 v[102:103], v[102:103], v[102:103] op_sel:[0,1] op_sel_hi:[0,1] neg_lo:[0,1] neg_hi:[0,1]
	v_pk_mul_f32 v[100:101], v[76:77], v[100:101]
	v_fma_f32 v120, v62, v128, -v110
	v_fma_f32 v111, v63, v121, v111
	v_fma_f32 v128, v16, v102, -v100
	v_fma_f32 v129, v17, v103, v101
	v_sub_f32_e32 v4, v88, v4
	v_pk_mul_f32 v[100:101], v[28:29], v[92:93] op_sel:[0,1] op_sel_hi:[1,0]
	v_pk_add_f32 v[90:91], v[90:91], v[90:91] op_sel:[1,0] op_sel_hi:[1,0]
	v_fma_f32 v102, v26, v92, -v100
	v_fma_f32 v93, v27, v93, v101
	v_pk_mul_f32 v[100:101], v[44:45], v[80:81] op_sel:[0,1] op_sel_hi:[1,0]
	v_mov_b32_e32 v88, v4
	v_sub_f32_e32 v2, v2, v84
	v_fma_f32 v144, v42, v80, -v100
	v_fma_f32 v81, v43, v81, v101
	v_pk_mul_f32 v[100:101], v[60:61], v[86:87] op_sel:[0,1] op_sel_hi:[1,0]
	v_pk_add_f32 v[82:83], v[82:83], v[82:83] op_sel:[0,1] op_sel_hi:[0,1] neg_lo:[0,1] neg_hi:[0,1]
	v_pk_mul_f32 v[90:91], v[72:73], v[90:91]
	v_mov_b32_e32 v89, v99
	v_mov_b32_e32 v118, v78
	v_mov_b32_e32 v84, v2
	v_fma_f32 v146, v58, v86, -v100
	v_fma_f32 v87, v59, v87, v101
	v_fma_f32 v100, v20, v82, -v90
	v_fma_f32 v101, v21, v83, v91
	v_mul_f32_e32 v5, v37, v4
	v_mul_f32_e32 v4, v36, v99
	v_mov_b32_e32 v119, v113
	v_fma_f32 v82, v34, v88, -v4
	v_fma_f32 v5, v35, v89, v5
	v_mul_f32_e32 v79, v53, v78
	v_mul_f32_e32 v78, v52, v113
	v_mul_f32_e32 v3, v69, v2
	v_mul_f32_e32 v2, v68, v117
	v_fma_f32 v88, v50, v118, -v78
	v_fma_f32 v90, v66, v84, -v2
	v_fma_f32 v3, v67, v117, v3
	v_mov_b32_e32 v4, v1
	v_fma_f32 v79, v51, v119, v79
	v_mov_b32_e32 v91, v3
	s_barrier
	v_add_f32_e32 v150, v136, v144
	v_add_f32_e32 v151, v95, v81
	v_add_f32_e32 v156, v138, v146
	v_add_f32_e32 v157, v97, v87
	v_mov_b32_e32 v139, v95
	v_mul_lo_u32 v115, v4, s33
	v_add_f32_e32 v158, v120, v90
	v_add_f32_e32 v159, v111, v91
	v_mov_b32_e32 v92, v81
	v_sub_f32_e32 v80, v138, v146
	v_sub_f32_e32 v81, v139, v81
	v_sub_f32_e32 v2, v111, v3
	v_sub_f32_e32 v3, v140, v88
	v_mov_b32_e32 v83, v5
	v_add_f32_e32 v116, v132, v102
	v_add_f32_e32 v117, v105, v93
	v_add_f32_e32 v152, v140, v88
	v_add_f32_e32 v153, v109, v79
	v_mov_b32_e32 v169, v132
	v_sub_f32_e32 v4, v109, v79
	v_sub_f32_e32 v5, v107, v5
	v_mov_b32_e32 v106, v88
	v_sub_f32_e32 v86, v97, v87
	v_sub_f32_e32 v87, v136, v144
	v_sub_f32_e32 v78, v120, v90
	v_sub_f32_e32 v79, v109, v79
	v_pk_add_f32 v[88:89], v[80:81], v[2:3]
	v_pk_add_f32 v[2:3], v[80:81], v[2:3] neg_lo:[0,1] neg_hi:[0,1]
	v_sub_f32_e32 v103, v169, v102
	v_sub_f32_e32 v102, v136, v144
	v_sub_f32_e32 v92, v95, v92
	v_sub_f32_e32 v93, v105, v93
	v_pk_add_f32 v[90:91], v[86:87], v[78:79] neg_lo:[0,1] neg_hi:[0,1]
	v_pk_add_f32 v[78:79], v[86:87], v[78:79]
	v_pk_add_f32 v[84:85], v[134:135], v[128:129]
	v_pk_add_f32 v[98:99], v[142:143], v[100:101]
	v_add_f32_e32 v118, v130, v82
	v_add_f32_e32 v119, v107, v83
	v_sub_f32_e32 v83, v130, v82
	v_sub_f32_e32 v82, v140, v106
	v_pk_add_f32 v[94:95], v[102:103], v[4:5]
	v_mul_f32_e32 v105, 0x3f3504f3, v89
	v_mul_f32_e32 v80, s74, v88
	v_mul_f32_e32 v81, s75, v3
	v_mul_f32_e32 v4, 0x3f6c835e, v90
	v_pk_add_f32 v[112:113], v[84:85], v[98:99]
	v_pk_add_f32 v[154:155], v[150:151], v[152:153]
	v_pk_add_f32 v[160:161], v[156:157], v[158:159]
	v_pk_add_f32 v[84:85], v[84:85], v[98:99] neg_lo:[0,1] neg_hi:[0,1]
	v_pk_add_f32 v[98:99], v[150:151], v[152:153] neg_lo:[0,1] neg_hi:[0,1]
	v_mov_b32_e32 v151, v156
	v_mov_b32_e32 v153, v158
	v_fma_f32 v80, v90, s72, -v80
	v_fma_f32 v81, v79, s73, -v81
	v_fma_f32 v86, v88, s80, -v4
	v_add_f32_e32 v4, v93, v83
	v_pk_add_f32 v[148:149], v[116:117], v[118:119]
	v_pk_add_f32 v[100:101], v[142:143], v[100:101] neg_lo:[0,1] neg_hi:[0,1]
	v_mov_b32_e32 v150, v116
	v_sub_f32_e32 v116, v117, v119
	v_sub_f32_e32 v117, v157, v159
	v_pk_add_f32 v[96:97], v[92:93], v[82:83] neg_lo:[0,1] neg_hi:[0,1]
	v_pk_mul_f32 v[82:83], v[4:5], s[38:39] op_sel_hi:[0,1]
	v_sub_f32_e32 v4, v103, v5
	v_pk_add_f32 v[128:129], v[134:135], v[128:129] neg_lo:[0,1] neg_hi:[0,1]
	v_mov_b32_e32 v135, v100
	v_sub_f32_e32 v150, v150, v118
	v_sub_f32_e32 v151, v151, v153
	v_pk_mul_f32 v[116:117], v[116:117], s[20:21] op_sel_hi:[1,0]
	v_fma_f32 v92, v4, s40, -v82
	v_fma_f32 v93, v4, s41, v83
	v_fma_f32 v119, v151, s3, -v117
	v_fma_f32 v152, v150, s2, v116
	v_pk_fma_f32 v[116:117], v[150:151], s[20:21], v[116:117] op_sel_hi:[1,0,1] neg_lo:[0,0,1] neg_hi:[0,0,1]
	v_pk_add_f32 v[150:151], v[84:85], v[98:99] op_sel:[0,1] op_sel_hi:[1,0] neg_lo:[0,1] neg_hi:[0,1]
	v_pk_add_f32 v[84:85], v[84:85], v[98:99] op_sel:[0,1] op_sel_hi:[1,0]
	v_mul_f32_e32 v134, 0x3f6c835e, v97
	s_mov_b32 s42, s3
	s_mov_b32 s43, s21
	v_pk_mul_f32 v[96:97], v[96:97], s[70:71]
	v_pk_mul_f32 v[4:5], v[78:79], s[40:41] op_sel_hi:[0,1]
	v_sub_f32_e32 v142, v128, v101
	v_pk_add_f32 v[100:101], v[128:129], v[100:101] op_sel:[0,1] op_sel_hi:[1,0]
	v_mov_b32_e32 v99, v85
	v_mul_f32_e32 v128, 0x3ec3ef15, v95
	v_mul_f32_e32 v85, 0x3f3504f3, v91
	v_fma_f32 v106, v94, s42, -v96
	v_fma_f32 v95, v95, s43, v97
	v_fma_f32 v78, v2, s38, -v4
	v_fma_f32 v79, v2, s39, v5
	v_mov_b32_e32 v143, v101
	v_pk_add_f32 v[88:89], v[128:129], v[134:135] neg_lo:[0,1] neg_hi:[0,1]
	v_sub_f32_e32 v104, v85, v105
	v_fmac_f32_e32 v105, 0x3f3504f3, v91
	v_pk_add_f32 v[162:163], v[112:113], v[154:155]
	v_pk_add_f32 v[164:165], v[148:149], v[160:161]
	v_pk_add_f32 v[2:3], v[142:143], v[104:105]
	v_pk_add_f32 v[4:5], v[92:93], v[78:79]
	v_add_f32_e32 v90, v106, v100
	v_add_f32_e32 v91, v95, v86
	v_pk_add_f32 v[96:97], v[88:89], v[80:81]
	v_pk_add_f32 v[166:167], v[162:163], v[164:165]
	v_mov_b32_e32 v98, v150
	v_add_f32_e32 v156, v116, v119
	v_add_f32_e32 v157, v117, v152
	v_pk_add_f32 v[82:83], v[2:3], v[4:5]
	v_pk_add_f32 v[102:103], v[96:97], v[90:91]
	v_pk_add_f32 v[158:159], v[98:99], v[156:157]
	ds_write2_b64 v115, v[166:167], v[82:83] offset1:1
	ds_write2_b64 v115, v[158:159], v[102:103] offset0:2 offset1:3
	v_pk_add_f32 v[82:83], v[112:113], v[154:155] neg_lo:[0,1] neg_hi:[0,1]
	v_pk_add_f32 v[102:103], v[148:149], v[160:161] neg_lo:[0,1] neg_hi:[0,1]
	v_pk_add_f32 v[78:79], v[92:93], v[78:79] neg_lo:[0,1] neg_hi:[0,1]
	v_pk_add_f32 v[108:109], v[82:83], v[102:103] op_sel:[0,1] op_sel_hi:[1,0] neg_lo:[0,1] neg_hi:[0,1]
	v_pk_add_f32 v[82:83], v[82:83], v[102:103] op_sel:[0,1] op_sel_hi:[1,0]
	v_pk_add_f32 v[102:103], v[142:143], v[104:105] neg_lo:[0,1] neg_hi:[0,1]
	v_pk_add_f32 v[92:93], v[102:103], v[78:79] op_sel:[0,1] op_sel_hi:[1,0] neg_lo:[0,1] neg_hi:[0,1]
	v_pk_add_f32 v[78:79], v[102:103], v[78:79] op_sel:[0,1] op_sel_hi:[1,0]
	v_mov_b32_e32 v102, v108
	v_mov_b32_e32 v103, v83
	v_mov_b32_e32 v104, v92
	v_mov_b32_e32 v105, v79
	ds_write2_b64 v115, v[102:103], v[104:105] offset0:4 offset1:5
	v_mov_b32_e32 v85, v151
	v_sub_f32_e32 v102, v152, v117
	v_sub_f32_e32 v103, v116, v119
	v_sub_f32_e32 v86, v95, v86
	v_sub_f32_e32 v87, v88, v80
	v_sub_f32_e32 v80, v100, v106
	v_sub_f32_e32 v81, v89, v81
	v_pk_add_f32 v[104:105], v[84:85], v[102:103] neg_lo:[0,1] neg_hi:[0,1]
	v_pk_add_f32 v[84:85], v[84:85], v[102:103]
	v_pk_add_f32 v[88:89], v[80:81], v[86:87] neg_lo:[0,1] neg_hi:[0,1]
	v_pk_add_f32 v[80:81], v[80:81], v[86:87]
	v_mov_b32_e32 v86, v104
	v_mov_b32_e32 v87, v85
	v_mov_b32_e32 v94, v88
	v_mov_b32_e32 v95, v81
	ds_write2_b64 v115, v[86:87], v[94:95] offset0:6 offset1:7
	v_pk_add_f32 v[86:87], v[162:163], v[164:165] neg_lo:[0,1] neg_hi:[0,1]
	v_pk_add_f32 v[2:3], v[2:3], v[4:5] neg_lo:[0,1] neg_hi:[0,1]
	v_mov_b32_e32 v5, v97
	ds_write2_b64 v115, v[86:87], v[2:3] offset0:8 offset1:9
	v_pk_add_f32 v[2:3], v[98:99], v[156:157] neg_lo:[0,1] neg_hi:[0,1]
	v_sub_f32_e32 v4, v90, v96
	v_sub_f32_e32 v5, v5, v91
	ds_write2_b64 v115, v[2:3], v[4:5] offset0:10 offset1:11
	v_mov_b32_e32 v83, v109
	v_mov_b32_e32 v79, v93
	v_mov_b32_e32 v85, v105
	v_mov_b32_e32 v81, v89
	v_mov_b32_e32 v2, v1
	ds_write2_b64 v115, v[82:83], v[78:79] offset0:12 offset1:13
	ds_write2_b64 v115, v[84:85], v[80:81] offset0:14 offset1:15
	s_waitcnt lgkmcnt(0)
	s_barrier
	s_nop 0
	v_ashrrev_i32_e32 v3, 31, v2
	v_lshrrev_b32_e32 v3, 28, v3
	v_and_b32_e32 v106, 15, v2
	v_add_u32_e32 v2, v2, v3
	v_ashrrev_i32_e32 v2, 4, v2
	v_lshlrev_b32_e32 v3, 11, v2
	v_lshl_add_u32 v2, v2, 7, v3
	v_lshl_or_b32 v115, v106, 3, v2
	ds_read2_b64 v[2:5], v115 offset1:17
	ds_read2_b64 v[78:81], v115 offset0:34 offset1:51
	ds_read2_b64 v[82:85], v115 offset0:68 offset1:85
	ds_read2_b64 v[86:89], v115 offset0:102 offset1:119
	ds_read2_b64 v[90:93], v115 offset0:136 offset1:153
	ds_read2_b64 v[94:97], v115 offset0:170 offset1:187
	ds_read2_b64 v[98:101], v115 offset0:204 offset1:221
	ds_read2_b64 v[102:105], v115 offset0:238 offset1:255
	s_waitcnt lgkmcnt(4)
	v_mov_b32_e32 v158, v86
	v_cvt_f32_i32_e32 v106, v106
	v_mov_b32_e32 v159, v85
	v_pk_mov_b32 v[84:85], v[86:87], v[84:85] op_sel:[1,0]
	v_add_f32_e32 v106, v106, v106
	v_mul_f32_e32 v106, 0x3b800000, v106
	v_mul_f32_e32 v106, 0.5, v106
	v_sin_f32_e32 v107, v106
	v_cos_f32_e32 v106, v106
	v_mul_f32_e32 v110, v107, v107
	v_mul_f32_e32 v108, v106, v107
	v_pk_fma_f32 v[110:111], v[106:107], v[106:107], v[110:111] op_sel_hi:[1,1,0] neg_lo:[0,0,1] neg_hi:[0,0,1]
	v_add_f32_e32 v108, v108, v108
	v_mov_b32_e32 v112, v110
	v_mov_b32_e32 v113, v106
	v_mov_b32_e32 v109, v107
	v_pk_mul_f32 v[116:117], v[112:113], v[110:111] op_sel_hi:[1,0]
	v_pk_mul_f32 v[120:121], v[108:109], v[110:111] op_sel_hi:[1,0]
	v_pk_fma_f32 v[134:135], v[108:109], v[108:109], v[116:117] op_sel_hi:[1,0,1] neg_lo:[1,0,0] neg_hi:[1,0,0]
	v_pk_fma_f32 v[128:129], v[112:113], v[108:109], v[120:121] op_sel_hi:[1,0,1]
	v_mov_b32_e32 v136, v134
	v_mov_b32_e32 v137, v106
	v_mov_b32_e32 v142, v108
	v_mov_b32_e32 v143, v128
	v_mul_f32_e32 v119, v113, v108
	v_mov_b32_e32 v130, v128
	v_mov_b32_e32 v131, v107
	v_pk_mul_f32 v[138:139], v[136:137], v[134:135] op_sel_hi:[1,0]
	v_mov_b32_e32 v111, v134
	v_pk_mul_f32 v[146:147], v[142:143], v[134:135] op_sel_hi:[1,0]
	v_pk_mul_f32 v[148:149], v[130:131], v[110:111]
	v_pk_mul_f32 v[144:145], v[128:129], v[142:143] op_sel_hi:[0,1]
	v_add_f32_e32 v118, v147, v147
	v_add_f32_e32 v119, v119, v121
	v_pk_fma_f32 v[120:121], v[136:137], v[142:143], v[148:149]
	v_fma_f32 v116, -v130, v128, v138
	v_fma_f32 v117, -v131, v108, v117
	v_mul_f32_e32 v132, v134, v129
	v_mul_f32_e32 v148, v128, v135
	v_pk_mul_f32 v[150:151], v[130:131], v[134:135] op_sel_hi:[1,0]
	v_pk_fma_f32 v[130:131], v[130:131], v[128:129], v[138:139] op_sel_hi:[1,0,1] neg_lo:[1,0,0] neg_hi:[1,0,0]
	v_pk_fma_f32 v[138:139], v[134:135], v[110:111], v[144:145] op_sel_hi:[0,1,1] neg_lo:[0,0,1] neg_hi:[0,0,1]
	v_pk_fma_f32 v[144:145], v[110:111], v[128:129], v[146:147] op_sel_hi:[1,0,1]
	v_add_f32_e32 v132, v132, v148
	v_add_f32_e32 v133, v147, v147
	v_mov_b32_e32 v149, v106
	v_pk_mul_f32 v[142:143], v[128:129], v[128:129] op_sel_hi:[0,1]
	v_pk_fma_f32 v[136:137], v[136:137], v[128:129], v[150:151] op_sel_hi:[1,0,1]
	v_mov_b32_e32 v148, v130
	v_mul_f32_e32 v106, v145, v110
	v_mul_f32_e32 v107, v107, v130
	v_pk_fma_f32 v[142:143], v[134:135], v[134:135], v[142:143] op_sel_hi:[0,1,1] neg_lo:[0,0,1] neg_hi:[0,0,1]
	v_fma_f32 v106, v148, v108, v106
	v_fma_f32 v107, v149, v145, v107
	v_pk_mov_b32 v[150:151], v[144:145], v[128:129] op_sel:[1,0]
	v_mov_b32_e32 v149, v134
	v_pk_mul_f32 v[152:153], v[150:151], v[132:133]
	v_pk_mul_f32 v[150:151], v[150:151], v[142:143] op_sel:[0,1] op_sel_hi:[1,0]
	v_pk_mul_f32 v[136:137], v[136:137], v[138:139]
	v_pk_fma_f32 v[138:139], v[148:149], v[142:143], v[152:153] op_sel:[0,1,0] op_sel_hi:[1,0,1] neg_lo:[0,0,1] neg_hi:[0,0,1]
	v_pk_fma_f32 v[148:149], v[148:149], v[132:133], v[150:151]
	v_mov_b32_e32 v150, v78
	v_mov_b32_e32 v151, v5
	v_pk_mov_b32 v[4:5], v[78:79], v[4:5] op_sel:[1,0]
	v_pk_mul_f32 v[140:141], v[108:109], v[128:129] op_sel_hi:[1,0]
	v_pk_mul_f32 v[146:147], v[108:109], v[144:145] op_sel:[0,1]
	v_pk_mul_f32 v[78:79], v[4:5], v[108:109]
	v_pk_mul_f32 v[108:109], v[150:151], v[108:109]
	v_mul_f32_e32 v118, v134, v118
	v_mul_f32_e32 v119, v130, v119
	v_fma_f32 v152, v150, v112, -v78
	v_fma_f32 v79, v151, v113, v79
	v_fma_f32 v151, v5, v113, -v109
	v_fma_f32 v4, v4, v112, v108
	v_pk_fma_f32 v[140:141], v[112:113], v[134:135], v[140:141] op_sel_hi:[1,0,1] neg_lo:[0,0,1] neg_hi:[0,0,1]
	v_pk_fma_f32 v[146:147], v[112:113], v[130:131], v[146:147] op_sel_hi:[1,0,1] neg_lo:[0,0,1] neg_hi:[0,0,1]
	v_fma_f32 v116, v128, v116, v118
	v_fma_f32 v117, v145, v117, v119
	v_pk_mul_f32 v[118:119], v[144:145], v[120:121] op_sel:[1,0]
	v_mov_b32_e32 v112, v135
	v_mul_f32_e32 v150, v81, v129
	v_pk_mul_f32 v[86:87], v[84:85], v[120:121]
	v_pk_mul_f32 v[120:121], v[158:159], v[120:121]
	v_pk_fma_f32 v[118:119], v[130:131], v[140:141], v[118:119] op_sel_hi:[0,1,1] neg_lo:[0,0,1] neg_hi:[0,0,1]
	v_fma_f32 v112, v80, v112, -v150
	v_mov_b32_e32 v154, v82
	v_mov_b32_e32 v155, v81
	v_pk_mov_b32 v[80:81], v[82:83], v[80:81] op_sel:[1,0]
	v_fma_f32 v160, v158, v140, -v86
	v_fma_f32 v87, v159, v141, v87
	v_fma_f32 v159, v85, v141, -v121
	v_fma_f32 v84, v84, v140, v120
	v_mov_b32_e32 v141, v83
	v_mul_f32_e32 v83, v82, v128
	v_mul_f32_e32 v82, v89, v132
	v_mul_f32_e32 v86, v89, v143
	v_pk_mul_f32 v[110:111], v[128:129], v[144:145] op_sel:[0,1]
	v_pk_mul_f32 v[80:81], v[80:81], v[128:129]
	v_mov_b32_e32 v140, v88
	v_fma_f32 v88, v88, v132, v86
	s_waitcnt lgkmcnt(2)
	v_mov_b32_e32 v132, v94
	v_mov_b32_e32 v133, v93
	v_pk_mov_b32 v[92:93], v[94:95], v[92:93] op_sel:[1,0]
	v_pk_fma_f32 v[110:111], v[134:135], v[130:131], v[110:111] op_sel_hi:[1,0,1] neg_lo:[0,0,1] neg_hi:[0,0,1]
	v_fma_f32 v156, v154, v134, -v80
	v_fma_f32 v81, v155, v135, v81
	v_pk_mov_b32 v[134:135], v[142:143], v[134:135] op_sel:[1,0]
	v_pk_mul_f32 v[94:95], v[92:93], v[106:107]
	v_pk_mul_f32 v[106:107], v[132:133], v[106:107]
	v_fma_f32 v128, v140, v134, -v82
	v_fma_f32 v83, v141, v135, v83
	v_fma_f32 v134, v132, v146, -v94
	v_fma_f32 v95, v133, v147, v95
	v_fma_f32 v133, v93, v147, -v107
	v_fma_f32 v92, v92, v146, v106
	v_mov_b32_e32 v140, v96
	v_mov_b32_e32 v141, v91
	v_pk_mov_b32 v[142:143], v[110:111], v[130:131] op_sel:[1,0]
	v_mul_f32_e32 v146, v97, v117
	v_mul_f32_e32 v147, v90, v145
	v_pk_fma_f32 v[136:137], v[130:131], v[144:145], v[136:137]
	v_fma_f32 v162, v140, v142, -v146
	v_fma_f32 v141, v141, v143, v147
	v_mov_b32_e32 v143, v97
	s_waitcnt lgkmcnt(1)
	v_mov_b32_e32 v142, v98
	v_mul_f32_e32 v97, v96, v117
	v_mul_f32_e32 v96, v99, v116
	v_fma_f32 v116, v142, v110, -v96
	v_fma_f32 v97, v143, v111, v97
	s_waitcnt lgkmcnt(0)
	v_mov_b32_e32 v142, v102
	v_mov_b32_e32 v143, v101
	v_pk_mov_b32 v[100:101], v[102:103], v[100:101] op_sel:[1,0]
	v_pk_mul_f32 v[102:103], v[100:101], v[136:137]
	v_pk_mul_f32 v[136:137], v[142:143], v[136:137]
	v_fma_f32 v146, v142, v118, -v102
	v_fma_f32 v103, v143, v119, v103
	v_fma_f32 v143, v101, v119, -v137
	v_fma_f32 v100, v100, v118, v136
	v_mov_b32_e32 v137, v99
	v_mov_b32_e32 v136, v104
	v_mul_f32_e32 v99, v98, v149
	v_mul_f32_e32 v98, v105, v148
	v_fma_f32 v164, v136, v138, -v98
	v_fma_f32 v99, v137, v139, v99
	v_pk_mov_b32 v[136:137], v[90:91], v[104:105] op_sel:[1,0]
	v_mul_f32_e32 v136, v136, v145
	v_mul_f32_e32 v137, v137, v148
	v_fma_f32 v104, v90, v130, -v136
	v_fma_f32 v91, v105, v138, v137
	v_mov_b32_e32 v105, v91
	v_add_f32_e32 v136, v112, v162
	v_add_f32_e32 v137, v3, v141
	v_mov_b32_e32 v155, v81
	v_mov_b32_e32 v111, v97
	v_mov_b32_e32 v131, v88
	v_add_f32_e32 v138, v128, v164
	v_add_f32_e32 v139, v83, v99
	v_add_f32_e32 v106, v151, v133
	v_add_f32_e32 v107, v4, v92
	v_add_f32_e32 v108, v159, v143
	v_add_f32_e32 v109, v84, v100
	v_add_f32_e32 v118, v152, v134
	v_add_f32_e32 v119, v79, v95
	v_sub_f32_e32 v78, v4, v92
	v_sub_f32_e32 v79, v79, v95
	v_sub_f32_e32 v5, v4, v92
	v_sub_f32_e32 v4, v112, v162
	v_sub_f32_e32 v88, v88, v91
	v_sub_f32_e32 v89, v160, v146
	v_add_f32_e32 v120, v160, v146
	v_add_f32_e32 v121, v87, v103
	v_sub_f32_e32 v86, v84, v100
	v_sub_f32_e32 v87, v87, v103
	v_sub_f32_e32 v80, v81, v97
	v_sub_f32_e32 v81, v152, v134
	v_sub_f32_e32 v85, v84, v100
	v_sub_f32_e32 v84, v128, v164
	v_pk_add_f32 v[90:91], v[4:5], v[88:89]
	v_pk_add_f32 v[4:5], v[4:5], v[88:89] neg_lo:[0,1] neg_hi:[0,1]
	v_add_f32_e32 v130, v2, v104
	v_add_f32_e32 v131, v131, v105
	v_sub_f32_e32 v132, v152, v134
	v_sub_f32_e32 v133, v151, v133
	v_sub_f32_e32 v94, v160, v146
	v_sub_f32_e32 v95, v159, v143
	v_pk_add_f32 v[96:97], v[80:81], v[84:85] neg_lo:[0,1] neg_hi:[0,1]
	v_pk_add_f32 v[80:81], v[80:81], v[84:85]
	v_sub_f32_e32 v2, v2, v104
	v_sub_f32_e32 v3, v3, v141
	v_sub_f32_e32 v82, v83, v99
	v_sub_f32_e32 v83, v156, v116
	v_pk_add_f32 v[92:93], v[132:133], v[86:87]
	v_pk_add_f32 v[100:101], v[78:79], v[94:95] neg_lo:[0,1] neg_hi:[0,1]
	v_mul_f32_e32 v103, 0x3f3504f3, v91
	v_mul_f32_e32 v84, s74, v90
	v_mul_f32_e32 v85, s75, v5
	v_mul_f32_e32 v78, 0x3f6c835e, v96
	v_add_f32_e32 v110, v156, v116
	v_add_f32_e32 v111, v155, v111
	v_sub_f32_e32 v98, v2, v82
	v_pk_add_f32 v[104:105], v[2:3], v[82:83]
	v_mul_f32_e32 v2, 0x3ec3ef15, v93
	v_mul_f32_e32 v82, 0x3f6c835e, v101
	v_fma_f32 v84, v96, s72, -v84
	v_fma_f32 v85, v81, s73, -v85
	v_fma_f32 v88, v90, s80, -v78
	v_add_f32_e32 v78, v79, v95
	v_pk_add_f32 v[2:3], v[2:3], v[82:83] neg_lo:[0,1] neg_hi:[0,1]
	v_pk_mul_f32 v[78:79], v[78:79], s[38:39] op_sel_hi:[0,1]
	v_sub_f32_e32 v82, v133, v87
	v_pk_add_f32 v[148:149], v[106:107], v[108:109]
	v_pk_add_f32 v[166:167], v[110:111], v[130:131]
	v_sub_f32_e32 v116, v130, v110
	v_sub_f32_e32 v117, v118, v120
	v_mov_b32_e32 v140, v107
	v_mov_b32_e32 v156, v109
	v_fma_f32 v86, v82, s40, -v78
	v_fma_f32 v87, v82, s41, v79
	v_sub_f32_e32 v106, v106, v108
	v_sub_f32_e32 v107, v136, v138
	v_sub_f32_e32 v108, v119, v121
	v_sub_f32_e32 v109, v111, v131
	v_pk_mul_f32 v[100:101], v[100:101], s[70:71]
	v_pk_mul_f32 v[78:79], v[80:81], s[40:41] op_sel_hi:[0,1]
	v_pk_mul_f32 v[108:109], v[108:109], s[20:21] op_sel_hi:[1,0]
	v_mul_f32_e32 v94, 0x3f3504f3, v97
	v_fma_f32 v112, v92, s42, -v100
	v_fma_f32 v93, v93, s43, v101
	v_fma_f32 v80, v4, s38, -v78
	v_fma_f32 v81, v4, s39, v79
	v_pk_add_f32 v[144:145], v[118:119], v[120:121]
	v_pk_add_f32 v[154:155], v[136:137], v[138:139]
	v_mov_b32_e32 v99, v105
	v_sub_f32_e32 v140, v140, v156
	v_sub_f32_e32 v141, v137, v139
	v_fma_f32 v111, v107, s3, -v109
	v_fma_f32 v118, v106, s2, v108
	v_sub_f32_e32 v102, v94, v103
	v_fmac_f32_e32 v103, 0x3f3504f3, v97
	v_pk_add_f32 v[168:169], v[148:149], v[154:155]
	v_pk_add_f32 v[170:171], v[144:145], v[166:167]
	v_pk_fma_f32 v[106:107], v[106:107], s[20:21], v[108:109] op_sel_hi:[1,0,1] neg_lo:[0,0,1] neg_hi:[0,0,1]
	v_sub_f32_e32 v108, v116, v140
	v_pk_add_f32 v[130:131], v[116:117], v[140:141]
	v_pk_add_f32 v[4:5], v[98:99], v[102:103]
	v_pk_add_f32 v[78:79], v[86:87], v[80:81]
	v_add_f32_e32 v90, v112, v104
	v_add_f32_e32 v91, v93, v88
	v_pk_add_f32 v[94:95], v[2:3], v[84:85]
	v_pk_add_f32 v[172:173], v[170:171], v[168:169]
	v_mov_b32_e32 v109, v131
	v_add_f32_e32 v120, v106, v111
	v_add_f32_e32 v121, v107, v118
	v_pk_add_f32 v[82:83], v[4:5], v[78:79]
	v_pk_add_f32 v[96:97], v[94:95], v[90:91]
	v_pk_add_f32 v[136:137], v[108:109], v[120:121]
	ds_write2_b64 v115, v[172:173], v[82:83] offset1:17
	ds_write2_b64 v115, v[136:137], v[96:97] offset0:34 offset1:51
	v_mov_b32_e32 v83, v148
	v_mov_b32_e32 v97, v154
	v_sub_f32_e32 v82, v166, v144
	v_sub_f32_e32 v83, v83, v97
	v_sub_f32_e32 v96, v145, v167
	v_sub_f32_e32 v97, v155, v149
	v_pk_add_f32 v[98:99], v[98:99], v[102:103] neg_lo:[0,1] neg_hi:[0,1]
	v_pk_add_f32 v[80:81], v[86:87], v[80:81] neg_lo:[0,1] neg_hi:[0,1]
	v_sub_f32_e32 v100, v82, v96
	v_pk_add_f32 v[128:129], v[82:83], v[96:97]
	v_pk_add_f32 v[86:87], v[98:99], v[80:81] op_sel:[0,1] op_sel_hi:[1,0] neg_lo:[0,1] neg_hi:[0,1]
	v_pk_add_f32 v[80:81], v[98:99], v[80:81] op_sel:[0,1] op_sel_hi:[1,0]
	v_mov_b32_e32 v101, v129
	v_mov_b32_e32 v98, v86
	v_mov_b32_e32 v99, v81
	ds_write2_b64 v115, v[100:101], v[98:99] offset0:68 offset1:85
	v_sub_f32_e32 v131, v141, v117
	v_mov_b32_e32 v113, v85
	v_sub_f32_e32 v98, v118, v107
	v_sub_f32_e32 v99, v106, v111
	v_sub_f32_e32 v88, v93, v88
	v_sub_f32_e32 v89, v2, v84
	v_sub_f32_e32 v2, v104, v112
	v_sub_f32_e32 v3, v3, v113
	v_pk_add_f32 v[100:101], v[130:131], v[98:99] neg_lo:[0,1] neg_hi:[0,1]
	v_pk_add_f32 v[98:99], v[130:131], v[98:99]
	v_pk_add_f32 v[84:85], v[2:3], v[88:89] neg_lo:[0,1] neg_hi:[0,1]
	v_pk_add_f32 v[2:3], v[2:3], v[88:89]
	v_mov_b32_e32 v102, v100
	v_mov_b32_e32 v103, v99
	v_mov_b32_e32 v88, v84
	v_mov_b32_e32 v89, v3
	ds_write2_b64 v115, v[102:103], v[88:89] offset0:102 offset1:119
	v_mov_b32_e32 v89, v169
	v_sub_f32_e32 v88, v170, v168
	v_sub_f32_e32 v89, v89, v171
	v_pk_add_f32 v[4:5], v[4:5], v[78:79] neg_lo:[0,1] neg_hi:[0,1]
	v_mov_b32_e32 v79, v95
	ds_write2_b64 v115, v[88:89], v[4:5] offset0:136 offset1:153
	v_pk_add_f32 v[4:5], v[108:109], v[120:121] neg_lo:[0,1] neg_hi:[0,1]
	v_sub_f32_e32 v78, v90, v94
	v_sub_f32_e32 v79, v79, v91
	ds_write2_b64 v115, v[4:5], v[78:79] offset0:170 offset1:187
	v_sub_f32_e32 v129, v97, v83
	v_mov_b32_e32 v99, v101
	v_mov_b32_e32 v3, v85
	v_mov_b32_e32 v81, v87
	ds_write2_b64 v115, v[98:99], v[2:3] offset0:238 offset1:255
	v_mov_b32_e32 v2, v1
	ds_write2_b64 v115, v[128:129], v[80:81] offset0:204 offset1:221
	s_waitcnt lgkmcnt(0)
	s_barrier
	s_nop 0
	v_ashrrev_i32_e32 v3, 31, v2
	v_lshrrev_b32_e32 v3, 24, v3
	v_and_b32_e32 v4, 0xff, v2
	v_add_lshl_u32 v2, v2, v3, 4
	v_and_or_b32 v2, v2, s87, v4
	v_ashrrev_i32_e32 v3, 4, v2
	v_lshlrev_b32_e32 v2, 3, v2
	v_lshl_add_u32 v5, v3, 3, v2
	ds_read_b64 v[2:3], v5
	ds_read_b64 v[82:83], v5 offset:2176
	ds_read_b64 v[84:85], v5 offset:4352
	ds_read_b64 v[78:79], v5 offset:6528
	ds_read_b64 v[86:87], v5 offset:8704
	ds_read_b64 v[88:89], v5 offset:10880
	ds_read_b64 v[90:91], v5 offset:13056
	ds_read_b64 v[92:93], v5 offset:15232
	ds_read_b64 v[80:81], v5 offset:17408
	ds_read_b64 v[94:95], v5 offset:19584
	ds_read_b64 v[96:97], v5 offset:21760
	ds_read_b64 v[98:99], v5 offset:23936
	ds_read_b64 v[100:101], v5 offset:26112
	ds_read_b64 v[102:103], v5 offset:28288
	ds_read_b64 v[104:105], v5 offset:30464
	ds_read_b64 v[106:107], v5 offset:32640
	s_waitcnt lgkmcnt(9)
	v_mov_b32_e32 v164, v90
	v_cvt_f32_i32_e32 v4, v4
	v_mov_b32_e32 v165, v89
	v_pk_mov_b32 v[88:89], v[90:91], v[88:89] op_sel:[1,0]
	v_add_f32_e32 v4, v4, v4
	v_mul_f32_e32 v4, 0x39800000, v4
	v_mul_f32_e32 v4, 0.5, v4
	v_sin_f32_e32 v109, v4
	s_nop 0
	v_cos_f32_e32 v108, v4
	s_nop 0
	v_add_u32_e32 v4, s29, v1
	s_waitcnt lgkmcnt(4)
	v_mul_f32_e32 v112, v109, v109
	v_mul_f32_e32 v1, v108, v109
	v_add_f32_e32 v110, v1, v1
	v_pk_fma_f32 v[112:113], v[108:109], v[108:109], v[112:113] op_sel_hi:[1,1,0] neg_lo:[0,0,1] neg_hi:[0,0,1]
	v_mov_b32_e32 v111, v109
	v_mov_b32_e32 v116, v112
	v_mov_b32_e32 v117, v108
	v_pk_mul_f32 v[120:121], v[110:111], v[110:111] op_sel_hi:[1,0]
	v_pk_mul_f32 v[132:133], v[110:111], v[112:113] op_sel_hi:[1,0]
	v_pk_fma_f32 v[128:129], v[116:117], v[112:113], v[120:121] op_sel_hi:[1,0,1] neg_lo:[0,0,1] neg_hi:[0,0,1]
	v_pk_fma_f32 v[134:135], v[116:117], v[110:111], v[132:133] op_sel_hi:[1,0,1]
	v_mul_f32_e32 v151, v117, v112
	v_mul_f32_e32 v153, v117, v110
	v_mul_f32_e32 v148, v134, v112
	v_mul_f32_e32 v149, v109, v128
	v_mul_f32_e32 v152, v128, v134
	v_mul_f32_e32 v144, v128, v110
	v_mul_f32_e32 v145, v108, v134
	v_mul_f32_e32 v150, v128, v128
	v_fma_f32 v140, v128, v110, v148
	v_fma_f32 v141, v108, v134, v149
	v_mul_f32_e32 v142, v134, v134
	v_pk_mul_f32 v[136:137], v[116:117], v[128:129] op_sel_hi:[1,0]
	v_pk_mul_f32 v[138:139], v[110:111], v[134:135] op_sel_hi:[1,0]
	v_mul_f32_e32 v120, v128, v129
	v_add_f32_e32 v130, v152, v152
	v_add_f32_e32 v131, v153, v133
	v_mul_f32_e32 v132, v134, v135
	v_pk_fma_f32 v[146:147], v[116:117], v[128:129], v[138:139] op_sel_hi:[1,0,1] neg_lo:[0,0,1] neg_hi:[0,0,1]
	v_sub_f32_e32 v118, v150, v142
	v_sub_f32_e32 v119, v151, v121
	v_mov_b32_e32 v151, v137
	v_sub_f32_e32 v136, v136, v138
	v_sub_f32_e32 v137, v150, v142
	v_sub_f32_e32 v120, v120, v132
	v_sub_f32_e32 v121, v150, v142
	v_mul_f32_e32 v154, v128, v135
	v_mul_f32_e32 v156, v134, v129
	v_sub_f32_e32 v158, v150, v142
	v_sub_f32_e32 v159, v151, v139
	v_add_f32_e32 v132, v144, v148
	v_add_f32_e32 v133, v152, v152
	v_add_f32_e32 v138, v152, v152
	v_add_f32_e32 v139, v145, v149
	v_mov_b32_e32 v149, v108
	v_add_f32_e32 v142, v154, v156
	v_add_f32_e32 v143, v152, v152
	v_mov_b32_e32 v148, v158
	v_mul_f32_e32 v108, v133, v112
	v_mul_f32_e32 v109, v109, v158
	v_fma_f32 v108, v148, v110, v108
	v_fma_f32 v109, v149, v133, v109
	v_pk_mov_b32 v[150:151], v[132:133], v[134:135] op_sel:[1,0]
	v_mul_f32_e32 v130, v128, v130
	v_mul_f32_e32 v131, v158, v131
	v_mov_b32_e32 v149, v128
	v_pk_mul_f32 v[152:153], v[150:151], v[142:143]
	v_pk_mul_f32 v[150:151], v[150:151], v[120:121]
	v_fma_f32 v118, v134, v118, v130
	v_fma_f32 v119, v133, v119, v131
	v_pk_mul_f32 v[130:131], v[132:133], v[140:141] op_sel:[1,0]
	v_pk_mul_f32 v[90:91], v[88:89], v[140:141]
	v_pk_mul_f32 v[140:141], v[164:165], v[140:141]
	v_pk_fma_f32 v[130:131], v[158:159], v[146:147], v[130:131] op_sel_hi:[0,1,1] neg_lo:[0,0,1] neg_hi:[0,0,1]
	v_pk_mul_f32 v[136:137], v[138:139], v[136:137]
	v_pk_fma_f32 v[138:139], v[148:149], v[120:121], v[152:153] neg_lo:[0,0,1] neg_hi:[0,0,1]
	v_pk_fma_f32 v[148:149], v[148:149], v[142:143], v[150:151]
	v_mov_b32_e32 v150, v84
	v_mov_b32_e32 v151, v83
	v_pk_mov_b32 v[82:83], v[84:85], v[82:83] op_sel:[1,0]
	v_mov_b32_e32 v156, v86
	v_fma_f32 v166, v164, v146, -v90
	v_fma_f32 v91, v165, v147, v91
	v_fma_f32 v165, v89, v147, -v141
	v_fma_f32 v88, v88, v146, v140
	v_mov_b32_e32 v147, v87
	v_pk_mul_f32 v[144:145], v[110:111], v[132:133] op_sel:[0,1]
	v_pk_mul_f32 v[112:113], v[134:135], v[132:133] op_sel:[0,1]
	v_pk_mul_f32 v[84:85], v[82:83], v[110:111]
	v_pk_mul_f32 v[110:111], v[150:151], v[110:111]
	v_mov_b32_e32 v157, v79
	v_mul_f32_e32 v160, v87, v134
	v_mul_f32_e32 v161, v78, v135
	v_mov_b32_e32 v146, v92
	v_mov_b32_e32 v121, v128
	v_mul_f32_e32 v87, v86, v134
	v_mul_f32_e32 v86, v93, v142
	v_pk_fma_f32 v[144:145], v[116:117], v[158:159], v[144:145] op_sel_hi:[1,0,1] neg_lo:[0,0,1] neg_hi:[0,0,1]
	v_pk_fma_f32 v[112:113], v[128:129], v[158:159], v[112:113] op_sel_hi:[1,0,1] neg_lo:[0,0,1] neg_hi:[0,0,1]
	v_fma_f32 v152, v150, v116, -v84
	v_fma_f32 v85, v151, v117, v85
	v_pk_fma_f32 v[150:151], v[82:83], v[116:117], v[110:111] neg_lo:[0,0,1] neg_hi:[0,0,1]
	v_fma_f32 v82, v82, v116, v110
	v_mov_b32_e32 v116, v129
	v_pk_fma_f32 v[162:163], v[156:157], v[128:129], v[160:161] neg_lo:[0,0,1] neg_hi:[0,0,1]
	v_pk_fma_f32 v[156:157], v[156:157], v[128:129], v[160:161]
	v_fma_f32 v128, v146, v120, -v86
	v_fma_f32 v87, v147, v121, v87
	v_mov_b32_e32 v143, v120
	v_mov_b32_e32 v120, v96
	v_mov_b32_e32 v121, v95
	v_pk_mov_b32 v[94:95], v[96:97], v[94:95] op_sel:[1,0]
	v_pk_mul_f32 v[96:97], v[94:95], v[108:109]
	v_pk_mul_f32 v[108:109], v[120:121], v[108:109]
	v_pk_mul_f32 v[92:93], v[92:93], v[142:143]
	v_fma_f32 v142, v120, v144, -v96
	v_fma_f32 v97, v121, v145, v97
	v_pk_fma_f32 v[120:121], v[94:95], v[144:145], v[108:109] neg_lo:[0,0,1] neg_hi:[0,0,1]
	v_pk_fma_f32 v[94:95], v[94:95], v[144:145], v[108:109]
	v_mov_b32_e32 v144, v98
	v_mov_b32_e32 v145, v81
	v_pk_mov_b32 v[146:147], v[112:113], v[158:159] op_sel:[1,0]
	v_mul_f32_e32 v168, v99, v119
	v_mul_f32_e32 v169, v80, v133
	v_pk_fma_f32 v[136:137], v[158:159], v[132:133], v[136:137]
	v_fma_f32 v170, v144, v146, -v168
	v_fma_f32 v145, v145, v147, v169
	v_mov_b32_e32 v147, v99
	s_waitcnt lgkmcnt(3)
	v_mul_f32_e32 v99, v98, v119
	v_mul_f32_e32 v98, v101, v118
	v_fma_f32 v118, v100, v112, -v98
	v_fma_f32 v119, v147, v113, -v99
	v_fma_f32 v99, v147, v113, v99
	s_waitcnt lgkmcnt(1)
	v_mov_b32_e32 v146, v104
	v_mov_b32_e32 v147, v103
	v_pk_mov_b32 v[102:103], v[104:105], v[102:103] op_sel:[1,0]
	v_mul_f32_e32 v154, v78, v116
	v_mul_f32_e32 v155, v79, v135
	v_pk_mul_f32 v[104:105], v[102:103], v[136:137]
	v_pk_mul_f32 v[136:137], v[146:147], v[136:137]
	v_fma_f32 v168, v146, v130, -v104
	v_fma_f32 v105, v147, v131, v105
	v_fma_f32 v147, v103, v131, -v137
	v_fma_f32 v102, v102, v130, v136
	v_mov_b32_e32 v137, v101
	s_waitcnt lgkmcnt(0)
	v_mov_b32_e32 v136, v106
	v_mul_f32_e32 v101, v100, v149
	v_mul_f32_e32 v100, v107, v148
	v_pk_mov_b32 v[108:109], v[120:121], v[94:95] op_sel:[1,0]
	v_pk_fma_f32 v[172:173], v[136:137], v[138:139], v[100:101] neg_lo:[0,0,1] neg_hi:[0,0,1]
	v_mov_b32_e32 v113, v99
	v_pk_mov_b32 v[174:175], v[80:81], v[106:107] op_sel:[1,0]
	v_mov_b32_e32 v104, v121
	v_mul_f32_e32 v132, v174, v133
	v_mul_f32_e32 v133, v175, v148
	v_mov_b32_e32 v81, v107
	v_mov_b32_e32 v159, v138
	v_sub_f32_e32 v98, v157, v99
	v_sub_f32_e32 v99, v128, v172
	v_mov_b32_e32 v121, v92
	v_mov_b32_e32 v92, v155
	v_pk_fma_f32 v[100:101], v[136:137], v[138:139], v[100:101]
	v_fma_f32 v106, v80, v158, -v132
	v_fma_f32 v81, v81, v159, v133
	v_fma_f32 v78, v78, v116, -v92
	v_add_f32_e32 v93, v121, v93
	v_mov_b32_e32 v160, v162
	v_mov_b32_e32 v161, v157
	v_mov_b32_e32 v167, v91
	v_mov_b32_e32 v143, v97
	v_mov_b32_e32 v169, v105
	v_add_f32_e32 v112, v160, v118
	v_add_f32_e32 v113, v161, v113
	v_add_f32_e32 v132, v128, v172
	v_add_f32_e32 v133, v87, v101
	v_mov_b32_e32 v146, v97
	v_sub_f32_e32 v90, v151, v104
	v_sub_f32_e32 v91, v91, v105
	v_add_f32_e32 v96, v151, v108
	v_add_f32_e32 v97, v82, v109
	v_add_f32_e32 v104, v165, v147
	v_add_f32_e32 v105, v88, v102
	v_add_f32_e32 v108, v152, v142
	v_add_f32_e32 v109, v85, v143
	v_pk_add_f32 v[110:111], v[166:167], v[168:169]
	v_mov_b32_e32 v79, v93
	v_add_f32_e32 v92, v2, v106
	v_add_f32_e32 v93, v93, v81
	v_add_f32_e32 v116, v78, v170
	v_add_f32_e32 v117, v3, v145
	v_sub_f32_e32 v82, v82, v94
	v_sub_f32_e32 v83, v166, v168
	v_mov_b32_e32 v143, v102
	v_pk_add_f32 v[94:95], v[108:109], v[110:111]
	v_pk_add_f32 v[102:103], v[96:97], v[104:105]
	v_mov_b32_e32 v171, v81
	v_pk_add_f32 v[80:81], v[116:117], v[132:133]
	v_pk_add_f32 v[120:121], v[112:113], v[92:93]
	v_mov_b32_e32 v153, v88
	v_pk_add_f32 v[138:139], v[102:103], v[80:81]
	v_pk_add_f32 v[140:141], v[94:95], v[120:121]
	v_mov_b32_e32 v164, v85
	v_pk_add_f32 v[88:89], v[152:153], v[142:143] neg_lo:[0,1] neg_hi:[0,1]
	v_add_f32_e32 v5, v82, v83
	v_pk_add_f32 v[142:143], v[140:141], v[138:139]
	v_pk_add_f32 v[84:85], v[164:165], v[146:147] neg_lo:[0,1] neg_hi:[0,1]
	v_mul_f32_e32 v129, 0x3f3504f3, v5
	v_pk_mul_f32 v[142:143], v[142:143], s[84:85] op_sel_hi:[1,0]
	v_ashrrev_i32_e32 v5, 31, v4
	v_pk_add_f32 v[78:79], v[78:79], v[170:171] neg_lo:[0,1] neg_hi:[0,1]
	v_cvt_pk_bf16_f32 v107, v142, v143
	v_lshl_add_u64 v[4:5], v[4:5], 2, s[94:95]
	v_pk_mov_b32 v[100:101], v[100:101], v[118:119] op_sel:[1,0]
	v_pk_add_f32 v[118:119], v[84:85], v[84:85] op_sel:[0,1] op_sel_hi:[0,1]
	v_mov_b32_e32 v130, v78
	v_mov_b32_e32 v131, v98
	v_mov_b32_e32 v134, v79
	v_mov_b32_e32 v135, v99
	global_store_dword v[4:5], v107, off
	v_pk_mul_f32 v[118:119], v[118:119], s[38:39]
	v_pk_add_f32 v[142:143], v[90:91], v[90:91] op_sel:[0,1] op_sel_hi:[0,1] neg_lo:[0,1] neg_hi:[0,1]
	v_pk_add_f32 v[98:99], v[98:99], v[98:99] op_sel:[0,1] op_sel_hi:[0,1]
	v_sub_f32_e32 v1, v88, v89
	v_add_f32_e32 v136, v130, v134
	v_sub_f32_e32 v131, v131, v135
	v_sub_f32_e32 v2, v2, v106
	v_sub_f32_e32 v3, v3, v145
	v_sub_f32_e32 v86, v87, v100
	v_sub_f32_e32 v87, v162, v101
	v_fma_f32 v144, v142, s40, -v118
	v_fma_f32 v145, v143, s41, v119
	v_pk_mul_f32 v[98:99], v[98:99], s[40:41]
	v_pk_add_f32 v[78:79], v[78:79], v[78:79] op_sel:[0,1] op_sel_hi:[0,1] neg_lo:[0,1] neg_hi:[0,1]
	v_mul_f32_e32 v115, 0x3f3504f3, v1
	v_mul_f32_e32 v128, 0x3f6c835e, v131
	v_sub_f32_e32 v100, v2, v86
	v_pk_add_f32 v[106:107], v[2:3], v[86:87]
	v_fma_f32 v118, v78, s38, -v98
	v_fma_f32 v119, v79, s39, v99
	v_fma_f32 v134, v136, s80, -v128
	v_mov_b32_e32 v101, v107
	v_sub_f32_e32 v128, v115, v129
	v_fmac_f32_e32 v129, 0x3f3504f3, v1
	v_pk_add_f32 v[78:79], v[100:101], v[128:129]
	v_pk_add_f32 v[98:99], v[144:145], v[118:119]
	v_mov_b32_e32 v146, v112
	v_pk_add_f32 v[142:143], v[78:79], v[98:99]
	v_pk_mul_f32 v[142:143], v[142:143], s[84:85] op_sel_hi:[1,0]
	v_cvt_pk_bf16_f32 v1, v142, v143
	v_mov_b32_e32 v142, v92
	v_sub_f32_e32 v142, v142, v146
	v_sub_f32_e32 v143, v108, v110
	v_mov_b32_e32 v146, v97
	v_mov_b32_e32 v148, v105
	v_sub_f32_e32 v92, v109, v111
	v_sub_f32_e32 v93, v113, v93
	v_mov_b32_e32 v149, v133
	v_sub_f32_e32 v96, v96, v104
	v_sub_f32_e32 v97, v116, v132
	v_pk_mul_f32 v[92:93], v[92:93], s[20:21] op_sel_hi:[1,0]
	v_sub_f32_e32 v146, v146, v148
	v_sub_f32_e32 v147, v117, v149
	v_fma_f32 v105, v97, s3, -v93
	v_fma_f32 v108, v96, s2, v92
	v_pk_fma_f32 v[92:93], v[96:97], s[20:21], v[92:93] op_sel_hi:[1,0,1] neg_lo:[0,0,1] neg_hi:[0,0,1]
	v_sub_f32_e32 v96, v142, v146
	v_pk_add_f32 v[112:113], v[142:143], v[146:147]
	v_add_f32_e32 v110, v92, v105
	v_add_f32_e32 v111, v93, v108
	v_mov_b32_e32 v97, v113
	v_pk_add_f32 v[116:117], v[96:97], v[110:111]
	global_store_dword v[4:5], v1, off offset:1024
	v_pk_mul_f32 v[116:117], v[116:117], s[84:85] op_sel_hi:[1,0]
	v_cvt_pk_bf16_f32 v1, v116, v117
	v_mov_b32_e32 v117, v90
	v_add_f32_e32 v88, v88, v89
	v_add_f32_e32 v89, v117, v91
	v_mov_b32_e32 v91, v84
	v_sub_f32_e32 v82, v82, v83
	v_sub_f32_e32 v83, v91, v85
	v_mul_f32_e32 v2, 0x3ec3ef15, v89
	v_pk_mul_f32 v[84:85], v[82:83], s[70:71]
	v_mov_b32_e32 v137, v82
	v_mul_f32_e32 v86, 0x3f6c835e, v83
	v_pk_mul_f32 v[82:83], v[136:137], s[74:75]
	v_fma_f32 v90, v88, s42, -v84
	v_fma_f32 v85, v89, s43, v85
	v_fma_f32 v82, v131, s72, -v82
	v_fma_f32 v83, v88, s73, -v83
	v_pk_add_f32 v[2:3], v[2:3], v[86:87] neg_lo:[0,1] neg_hi:[0,1]
	v_add_f32_e32 v86, v90, v106
	v_add_f32_e32 v87, v85, v134
	v_pk_add_f32 v[88:89], v[2:3], v[82:83]
	global_store_dword v[4:5], v1, off offset:2048
	v_pk_add_f32 v[116:117], v[88:89], v[86:87]
	v_mov_b32_e32 v130, v94
	v_pk_mul_f32 v[116:117], v[116:117], s[84:85] op_sel_hi:[1,0]
	v_mov_b32_e32 v131, v80
	v_cvt_pk_bf16_f32 v1, v116, v117
	v_mov_b32_e32 v117, v102
	v_sub_f32_e32 v116, v120, v130
	v_sub_f32_e32 v117, v117, v131
	v_sub_f32_e32 v80, v95, v121
	v_sub_f32_e32 v81, v81, v103
	global_store_dword v[4:5], v1, off offset:3072
	v_sub_f32_e32 v94, v116, v80
	v_pk_add_f32 v[102:103], v[116:117], v[80:81]
	v_sub_f32_e32 v1, v81, v117
	v_mul_f32_e32 v80, s84, v94
	v_mul_f32_e32 v81, s84, v103
	s_movk_i32 s2, 0x1000
	v_cvt_pk_bf16_f32 v91, v80, v81
	v_add_co_u32_e32 v80, vcc, s2, v4
	v_pk_add_f32 v[100:101], v[100:101], v[128:129] neg_lo:[0,1] neg_hi:[0,1]
	v_pk_add_f32 v[116:117], v[144:145], v[118:119] neg_lo:[0,1] neg_hi:[0,1]
	v_addc_co_u32_e32 v81, vcc, 0, v5, vcc
	s_nop 1
	v_pk_add_f32 v[118:119], v[100:101], v[116:117] op_sel:[0,1] op_sel_hi:[1,0] neg_lo:[0,1] neg_hi:[0,1]
	v_pk_add_f32 v[100:101], v[100:101], v[116:117] op_sel:[0,1] op_sel_hi:[1,0]
	v_add_co_u32_e32 v94, vcc, s27, v4
	s_nop 1
	v_addc_co_u32_e32 v95, vcc, 0, v5, vcc
	v_mul_f32_e32 v116, s84, v118
	v_mul_f32_e32 v117, s84, v101
	global_store_dword v[94:95], v91, off offset:-4096
	v_cvt_pk_bf16_f32 v91, v116, v117
	v_pk_add_f32 v[116:117], v[146:147], v[142:143] neg_lo:[0,1] neg_hi:[0,1]
	v_mov_b32_e32 v109, v92
	v_mov_b32_e32 v104, v93
	v_mov_b32_e32 v113, v117
	v_pk_add_f32 v[92:93], v[108:109], v[104:105] neg_lo:[0,1] neg_hi:[0,1]
	global_store_dword v[80:81], v91, off offset:1024
	v_pk_add_f32 v[104:105], v[112:113], v[92:93] neg_lo:[0,1] neg_hi:[0,1]
	v_pk_add_f32 v[92:93], v[112:113], v[92:93]
	v_mul_f32_e32 v108, s84, v104
	v_mul_f32_e32 v109, s84, v93
	v_cvt_pk_bf16_f32 v91, v108, v109
	global_store_dword v[80:81], v91, off offset:2048
	v_mov_b32_e32 v135, v82
	v_mov_b32_e32 v107, v3
	v_mov_b32_e32 v91, v83
	v_sub_f32_e32 v84, v85, v134
	v_sub_f32_e32 v85, v2, v135
	v_pk_add_f32 v[2:3], v[106:107], v[90:91] neg_lo:[0,1] neg_hi:[0,1]
	v_pk_add_f32 v[78:79], v[78:79], v[98:99] neg_lo:[0,1] neg_hi:[0,1]
	v_pk_add_f32 v[82:83], v[2:3], v[84:85] neg_lo:[0,1] neg_hi:[0,1]
	v_pk_add_f32 v[2:3], v[2:3], v[84:85]
	v_mul_f32_e32 v84, s84, v82
	v_mul_f32_e32 v85, s84, v3
	v_pk_mul_f32 v[78:79], v[78:79], s[84:85] op_sel_hi:[1,0]
	v_cvt_pk_bf16_f32 v3, v84, v85
	global_store_dword v[80:81], v3, off offset:3072
	v_mov_b32_e32 v81, v139
	v_mov_b32_e32 v139, v141
	v_sub_f32_e32 v80, v140, v138
	v_sub_f32_e32 v81, v81, v139
	v_mul_f32_e32 v1, 0x39000000, v1
	v_pk_mul_f32 v[80:81], v[80:81], s[84:85] op_sel_hi:[1,0]
	v_add_co_u32_e32 v4, vcc, s86, v4
	v_cvt_pk_bf16_f32 v3, v80, v81
	global_store_dword v[94:95], v3, off
	v_cvt_pk_bf16_f32 v3, v78, v79
	v_pk_add_f32 v[78:79], v[96:97], v[110:111] neg_lo:[0,1] neg_hi:[0,1]
	global_store_dword v[94:95], v3, off offset:1024
	v_pk_mul_f32 v[78:79], v[78:79], s[84:85] op_sel_hi:[1,0]
	v_addc_co_u32_e32 v5, vcc, 0, v5, vcc
	s_nop 0
	v_cvt_pk_bf16_f32 v3, v78, v79
	v_mov_b32_e32 v79, v89
	v_mov_b32_e32 v89, v87
	v_sub_f32_e32 v78, v86, v88
	v_sub_f32_e32 v79, v79, v89
	global_store_dword v[94:95], v3, off offset:2048
	v_pk_mul_f32 v[78:79], v[78:79], s[84:85] op_sel_hi:[1,0]
	s_addk_i32 s29, 0x1000
	v_cvt_pk_bf16_f32 v3, v78, v79
	global_store_dword v[94:95], v3, off offset:3072
	v_mul_f32_e32 v3, 0x39000000, v102
	v_cvt_pk_bf16_f32 v1, v3, v1
	global_store_dword v[4:5], v1, off
	v_mul_f32_e32 v1, 0x39000000, v100
	v_mul_f32_e32 v3, 0x39000000, v119
	v_cvt_pk_bf16_f32 v1, v1, v3
	global_store_dword v[4:5], v1, off offset:1024
	v_mul_f32_e32 v1, 0x39000000, v92
	v_mul_f32_e32 v3, 0x39000000, v105
	v_cvt_pk_bf16_f32 v1, v1, v3
	s_add_u32 s0, s0, 0x4000
	global_store_dword v[4:5], v1, off offset:2048
	v_mul_f32_e32 v1, 0x39000000, v2
	v_mul_f32_e32 v2, 0x39000000, v83
	s_addc_u32 s1, s1, 0
	v_cvt_pk_bf16_f32 v1, v1, v2
	s_cmp_eq_u32 s0, 0x10000
	global_store_dword v[4:5], v1, off offset:3072
	s_cbranch_scc1 .LBB0_412

.LBB0_444:
	s_or_b64 exec, exec, s[22:23]
	v_cvt_f32_u32_e32 v40, v40
	v_cndmask_b32_e64 v60, 0, v114, s[62:63]
	s_waitcnt vmcnt(1)
	v_fmac_f32_e32 v60, v1, v25
	v_cndmask_b32_e64 v71, 0, v114, s[64:65]
	v_mul_f32_e32 v40, 0x39800000, v40
	v_mul_f32_e32 v40, 0.5, v40
	v_sin_f32_e32 v59, v40
	v_cos_f32_e32 v58, v40
	v_cvt_f32_u32_e32 v40, v24
	v_sub_f32_e32 v24, v60, v57
	s_waitcnt vmcnt(0)
	v_fmac_f32_e32 v71, v1, v37
	v_pk_mul_f32 v[24:25], v[58:59], v[24:25] op_sel_hi:[1,0] neg_hi:[0,1]
	v_mul_f32_e32 v40, 0x39800000, v40
	v_mul_f32_e32 v40, 0.5, v40
	v_sin_f32_e32 v59, v40
	v_cos_f32_e32 v58, v40
	v_cvt_f32_u32_e32 v40, v26
	v_cndmask_b32_e64 v37, 0, v114, s[60:61]
	v_fmac_f32_e32 v37, v1, v56
	v_sub_f32_e32 v26, v37, v27
	v_mul_f32_e32 v40, 0x39800000, v40
	v_mul_f32_e32 v40, 0.5, v40
	v_sin_f32_e32 v57, v40
	v_cos_f32_e32 v56, v40
	v_cvt_f32_u32_e32 v40, v38
	v_cndmask_b32_e64 v37, 0, v114, s[58:59]
	v_fmac_f32_e32 v37, v1, v39
	v_sub_f32_e32 v38, v37, v55
	v_mul_f32_e32 v40, 0x39800000, v40
	v_mul_f32_e32 v40, 0.5, v40
	v_pk_mul_f32 v[38:39], v[56:57], v[38:39] op_sel_hi:[1,0] neg_hi:[0,1]
	v_sin_f32_e32 v57, v40
	v_cos_f32_e32 v56, v40
	v_cvt_f32_u32_e32 v40, v30
	v_cndmask_b32_e64 v37, 0, v114, s[56:57]
	v_fmac_f32_e32 v37, v1, v54
	v_sub_f32_e32 v30, v37, v31
	v_mul_f32_e32 v40, 0x39800000, v40
	v_mul_f32_e32 v40, 0.5, v40
	v_sin_f32_e32 v55, v40
	v_cos_f32_e32 v54, v40
	v_cvt_f32_u32_e32 v40, v32
	v_cndmask_b32_e64 v37, 0, v114, s[0:1]
	v_fmac_f32_e32 v37, v1, v33
	v_sub_f32_e32 v32, v37, v53
	v_mul_f32_e32 v40, 0x39800000, v40
	v_mul_f32_e32 v40, 0.5, v40
	v_pk_mul_f32 v[32:33], v[54:55], v[32:33] op_sel_hi:[1,0] neg_hi:[0,1]
	v_sin_f32_e32 v55, v40
	v_cos_f32_e32 v54, v40
	v_cvt_f32_u32_e32 v40, v34
	v_cndmask_b32_e64 v37, 0, v114, s[54:55]
	v_fmac_f32_e32 v37, v1, v52
	v_sub_f32_e32 v34, v37, v35
	v_mul_f32_e32 v40, 0x39800000, v40
	v_mul_f32_e32 v40, 0.5, v40
	v_sin_f32_e32 v53, v40
	v_cos_f32_e32 v52, v40
	v_cvt_f32_u32_e32 v40, v28
	v_cndmask_b32_e64 v37, 0, v114, s[52:53]
	v_fmac_f32_e32 v37, v1, v50
	v_sub_f32_e32 v28, v37, v51
	v_mul_f32_e32 v37, 0x39800000, v40
	v_pk_mul_f32 v[50:51], v[52:53], v[28:29] op_sel_hi:[1,0] neg_hi:[0,1]
	v_cndmask_b32_e64 v28, 0, v114, s[50:51]
	v_mul_f32_e32 v37, 0.5, v37
	v_sin_f32_e32 v53, v37
	v_cos_f32_e32 v52, v37
	v_fmac_f32_e32 v28, v1, v29
	v_cvt_f32_u32_e32 v29, v22
	v_cvt_f32_u32_e32 v16, v16
	v_sub_f32_e32 v28, v28, v23
	v_pk_mul_f32 v[34:35], v[54:55], v[34:35] op_sel_hi:[1,0] neg_hi:[0,1]
	v_pk_mul_f32 v[22:23], v[52:53], v[28:29] op_sel_hi:[1,0] neg_hi:[0,1]
	v_mul_f32_e32 v29, 0x39800000, v29
	v_mul_f32_e32 v29, 0.5, v29
	v_mul_f32_e32 v16, 0x39800000, v16
	v_sin_f32_e32 v55, v29
	v_cos_f32_e32 v54, v29
	v_cvt_f32_u32_e32 v18, v18
	v_mul_f32_e32 v16, 0.5, v16
	v_cndmask_b32_e64 v37, 0, v114, s[48:49]
	v_sin_f32_e32 v61, v16
	v_cos_f32_e32 v60, v16
	v_cvt_f32_u32_e32 v16, v14
	v_fmac_f32_e32 v37, v1, v48
	v_cvt_f32_u32_e32 v29, v20
	v_sub_f32_e32 v20, v37, v49
	v_cndmask_b32_e64 v37, 0, v114, s[46:47]
	v_pk_mul_f32 v[48:49], v[54:55], v[20:21] op_sel_hi:[1,0] neg_hi:[0,1]
	v_fmac_f32_e32 v37, v1, v21
	v_cndmask_b32_e64 v21, 0, v114, s[44:45]
	v_mul_f32_e32 v18, 0x39800000, v18
	v_fmac_f32_e32 v21, v1, v46
	v_mul_f32_e32 v18, 0.5, v18
	v_mul_f32_e32 v16, 0x39800000, v16
	v_sub_f32_e32 v40, v37, v47
	v_sin_f32_e32 v47, v18
	v_cos_f32_e32 v46, v18
	v_sub_f32_e32 v18, v21, v19
	v_cndmask_b32_e64 v19, 0, v114, s[42:43]
	v_mul_f32_e32 v16, 0.5, v16
	v_fmac_f32_e32 v19, v1, v17
	v_sin_f32_e32 v17, v16
	v_cos_f32_e32 v16, v16
	v_sub_f32_e32 v14, v19, v45
	v_cndmask_b32_e64 v19, 0, v114, s[40:41]
	v_cvt_f32_u32_e32 v2, v2
	v_fmac_f32_e32 v19, v1, v15
	v_pk_mul_f32 v[62:63], v[60:61], v[14:15] op_sel_hi:[1,0] neg_hi:[0,1]
	v_cvt_f32_u32_e32 v15, v4
	v_sub_f32_e32 v4, v19, v44
	v_cndmask_b32_e64 v19, 0, v114, s[38:39]
	v_pk_mul_f32 v[44:45], v[16:17], v[4:5] op_sel_hi:[1,0] neg_hi:[0,1]
	v_fmac_f32_e32 v19, v1, v5
	v_cndmask_b32_e32 v5, 0, v114, vcc
	v_fmac_f32_e32 v5, v1, v3
	v_mul_f32_e32 v1, 0x39800000, v2
	v_mul_f32_e32 v1, 0.5, v1
	v_sin_f32_e32 v69, v1
	v_cos_f32_e32 v68, v1
	v_cvt_f32_u32_e32 v1, v36
	v_mul_f32_e32 v15, 0x39800000, v15
	v_mul_f32_e32 v29, 0x39800000, v29
	v_mul_f32_e32 v15, 0.5, v15
	v_mul_f32_e32 v1, 0x39800000, v1
	v_mul_f32_e32 v1, 0.5, v1
	v_sin_f32_e32 v3, v1
	v_cos_f32_e32 v2, v1
	v_mov_b32_e32 v1, v122
	v_mul_f32_e32 v29, 0.5, v29
	v_sin_f32_e32 v65, v15
	v_cos_f32_e32 v64, v15
	s_barrier
	v_pk_mul_f32 v[30:31], v[56:57], v[30:31] op_sel_hi:[1,0] neg_hi:[0,1]
	v_ashrrev_i32_e32 v15, 31, v1
	v_sin_f32_e32 v57, v29
	v_cos_f32_e32 v56, v29
	v_lshrrev_b32_e32 v15, 24, v15
	v_sub_f32_e32 v70, v5, v43
	v_and_b32_e32 v5, 0xff, v1
	v_add_lshl_u32 v1, v1, v15, 4
	v_and_or_b32 v1, v1, s87, v5
	v_pk_mul_f32 v[26:27], v[58:59], v[26:27] op_sel_hi:[1,0] neg_hi:[0,1]
	v_ashrrev_i32_e32 v15, 4, v1
	v_lshlrev_b32_e32 v1, 3, v1
	v_pk_mul_f32 v[58:59], v[56:57], v[40:41] op_sel_hi:[1,0] neg_hi:[0,1]
	v_sub_f32_e32 v36, v71, v41
	v_lshl_add_u32 v1, v15, 3, v1
	v_pk_fma_f32 v[40:41], v[56:57], v[40:41], v[26:27] op_sel_hi:[1,0,1] neg_hi:[0,1,0]
	v_pk_fma_f32 v[56:57], v[16:17], v[4:5], v[32:33] op_sel_hi:[1,0,1] neg_hi:[0,1,0]
	v_sub_f32_e32 v42, v19, v42
	v_cvt_f32_i32_e32 v15, v5
	v_pk_mul_f32 v[66:67], v[64:65], v[42:43] op_sel_hi:[1,0] neg_hi:[0,1]
	v_pk_fma_f32 v[42:43], v[64:65], v[42:43], v[34:35] op_sel_hi:[1,0,1] neg_hi:[0,1,0]
	v_pk_mul_f32 v[36:37], v[2:3], v[36:37] op_sel_hi:[1,0] neg_hi:[0,1]
	v_pk_fma_f32 v[60:61], v[60:61], v[14:15], v[30:31] op_sel_hi:[1,0,1] neg_hi:[0,1,0]
	v_add_f32_e32 v14, v15, v15
	v_pk_add_f32 v[4:5], v[42:43], v[40:41] neg_lo:[0,1] neg_hi:[0,1]
	v_mul_f32_e32 v14, 0x39800000, v14
	v_pk_fma_f32 v[72:73], v[68:69], v[70:71], v[50:51] op_sel_hi:[1,0,1] neg_hi:[0,1,0]
	v_pk_fma_f32 v[74:75], v[46:47], v[18:19], v[38:39] op_sel_hi:[1,0,1] neg_hi:[0,1,0]
	v_pk_fma_f32 v[20:21], v[54:55], v[20:21], v[24:25] op_sel_hi:[1,0,1] neg_hi:[0,1,0]
	v_mul_f32_e32 v14, 0.5, v14
	v_pk_mul_f32 v[76:77], v[4:5], s[20:21] op_sel_hi:[1,0]
	v_pk_fma_f32 v[28:29], v[52:53], v[28:29], v[36:37] op_sel_hi:[1,0,1] neg_hi:[0,1,0]
	v_sin_f32_e32 v64, v14
	v_pk_fma_f32 v[78:79], v[4:5], s[20:21], v[76:77] op_sel:[0,0,1] op_sel_hi:[1,0,0]
	v_cos_f32_e32 v80, v14
	v_pk_add_f32 v[2:3], v[72:73], v[74:75]
	v_pk_add_f32 v[4:5], v[42:43], v[40:41]
	v_pk_add_f32 v[14:15], v[56:57], v[20:21]
	v_pk_add_f32 v[16:17], v[60:61], v[28:29]
	v_pk_add_f32 v[28:29], v[60:61], v[28:29] neg_lo:[0,1] neg_hi:[0,1]
	v_pk_add_f32 v[40:41], v[2:3], v[14:15]
	v_mul_f32_e32 v19, 0x3f3504f3, v28
	v_pk_add_f32 v[42:43], v[4:5], v[16:17]
	v_pk_fma_f32 v[50:51], v[68:69], v[70:71], v[50:51] op_sel_hi:[1,0,1] neg_lo:[0,0,1] neg_hi:[0,1,1]
	v_pk_add_f32 v[52:53], v[40:41], v[42:43]
	v_pk_fma_f32 v[38:39], v[46:47], v[18:19], v[38:39] op_sel_hi:[1,0,1] neg_lo:[0,0,1] neg_hi:[0,1,1]
	ds_write_b64 v1, v[52:53]
	v_pk_mov_b32 v[46:47], v[38:39], v[38:39] op_sel:[1,0]
	v_add_f32_e32 v52, v50, v39
	v_sub_f32_e32 v53, v51, v38
	v_pk_add_f32 v[54:55], v[56:57], v[20:21] neg_lo:[0,1] neg_hi:[0,1]
	v_mul_f32_e32 v20, 0x3f3504f3, v29
	v_mul_f32_e32 v29, 0xbf3504f3, v29
	v_mov_b32_e32 v60, v74
	v_mov_b32_e32 v18, v21
	v_sub_f32_e32 v38, v72, v60
	v_sub_f32_e32 v39, v77, v76
	v_sub_f32_e32 v28, v57, v18
	v_sub_f32_e32 v29, v29, v19
	v_sub_f32_e32 v18, v20, v19
	v_sub_f32_e32 v19, v73, v75
	v_mov_b32_e32 v20, v78
	v_mov_b32_e32 v21, v54
	v_pk_add_f32 v[56:57], v[18:19], v[54:55] op_sel:[1,0] op_sel_hi:[0,1]
	v_add_f32_e32 v54, v18, v20
	v_sub_f32_e32 v61, v19, v21
	v_pk_add_f32 v[68:69], v[38:39], v[28:29]
	v_pk_add_f32 v[20:21], v[38:39], v[28:29] neg_lo:[0,1] neg_hi:[0,1]
	v_mov_b32_e32 v39, v66
	v_mov_b32_e32 v73, v34
	v_sub_f32_e32 v38, v44, v32
	v_sub_f32_e32 v39, v39, v73
	v_mov_b32_e32 v73, v59
	v_sub_f32_e32 v34, v45, v33
	v_sub_f32_e32 v35, v67, v35
	v_mov_b32_e32 v67, v58
	v_mov_b32_e32 v75, v27
	v_sub_f32_e32 v27, v67, v26
	v_sub_f32_e32 v26, v48, v24
	v_sub_f32_e32 v72, v49, v25
	v_sub_f32_e32 v73, v73, v75
	v_sub_f32_e32 v58, v63, v31
	v_sub_f32_e32 v59, v44, v32
	v_mov_b32_e32 v66, v22
	v_mov_b32_e32 v75, v25
	s_and_b64 s[0:1], s[96:97], exec
	v_sub_f32_e32 v30, v62, v30
	v_sub_f32_e32 v31, v45, v33
	v_sub_f32_e32 v22, v23, v37
	v_sub_f32_e32 v23, v48, v24
	v_readlane_b32 s0, v244, 15
	v_sub_f32_e32 v66, v66, v36
	v_sub_f32_e32 v67, v49, v75
	v_pk_add_f32 v[32:33], v[30:31], v[22:23] neg_lo:[0,1] neg_hi:[0,1]
	s_cselect_b32 s41, s88, s0
	v_readlane_b32 s0, v244, 13
	v_pk_add_f32 v[74:75], v[58:59], v[66:67]
	v_mov_b32_e32 v62, v32
	v_mul_f32_e32 v32, 0x3ec3ef15, v32
	s_cselect_b32 s40, s24, s0
	v_pk_add_f32 v[24:25], v[38:39], v[72:73] neg_lo:[0,1] neg_hi:[0,1]
	v_pk_add_f32 v[36:37], v[34:35], v[26:27]
	v_pk_add_f32 v[30:31], v[30:31], v[22:23]
	v_mul_f32_e32 v26, 0x3f6c835e, v74
	v_mov_b32_e32 v49, v51
	v_mov_b32_e32 v51, v32
	s_mov_b32 s0, s71
	s_mov_b32 s1, s21
	v_add_f32_e32 v32, v39, v73
	s_mov_b32 s22, s21
	s_mov_b32 s23, s71
	v_pk_add_f32 v[70:71], v[78:79], v[18:19] neg_lo:[0,1] neg_hi:[0,1]
	v_mul_f32_e32 v44, 0x3ec3ef15, v25
	v_mul_f32_e32 v48, 0x3f6c835e, v37
	v_pk_add_f32 v[58:59], v[58:59], v[66:67] neg_lo:[0,1] neg_hi:[0,1]
	v_pk_mul_f32 v[24:25], v[24:25], s[20:21]
	v_mov_b32_e32 v63, v31
	s_mov_b32 s70, s20
	v_mov_b32_e32 v45, v47
	v_mov_b32_e32 v47, v26
	v_sub_f32_e32 v26, v35, v27
	v_pk_mul_f32 v[34:35], v[32:33], s[22:23] op_sel_hi:[0,1]
	v_pk_mul_f32 v[30:31], v[30:31], s[0:1] op_sel_hi:[0,1]
	v_add_f32_e32 v28, v68, v54
	v_add_f32_e32 v29, v69, v61
	v_pk_add_f32 v[18:19], v[56:57], v[70:71]
	v_mul_f32_e32 v55, 0x3f3504f3, v75
	v_mul_f32_e32 v57, 0x3f3504f3, v33
	v_pk_fma_f32 v[22:23], v[36:37], s[70:71], v[24:25] neg_lo:[0,0,1] neg_hi:[0,0,1]
	v_pk_add_f32 v[36:37], v[48:49], v[44:45]
	v_fma_f32 v38, v26, s0, v34
	v_fma_f32 v39, v26, s1, -v35
	v_fma_f32 v48, v58, s22, v30
	v_fma_f32 v49, v58, s23, -v31
	v_add_f32_e32 v26, v57, v55
	v_fma_f32 v27, v33, s20, -v55
	v_pk_add_f32 v[32:33], v[52:53], v[26:27]
	v_pk_add_f32 v[30:31], v[38:39], v[48:49]
	v_pk_add_f32 v[44:45], v[50:51], v[46:47] neg_lo:[0,1] neg_hi:[0,1]
	v_pk_add_f32 v[50:51], v[32:33], v[30:31]
	v_xor_b32_e32 v81, 0x80000000, v64
	v_mul_f32_e32 v66, s72, v74
	v_mul_f32_e32 v67, s73, v59
	v_pk_mul_f32 v[58:59], v[50:51], v[64:65] op_sel_hi:[1,0]
	v_pk_fma_f32 v[24:25], v[62:63], s[30:31], v[66:67] neg_lo:[0,0,1] neg_hi:[0,0,1]
	v_fma_f32 v62, v50, v80, v59
	v_fma_f32 v63, v51, v80, -v58
	v_mov_b32_e32 v65, v80
	v_mul_f32_e32 v50, v64, v64
	v_mul_f32_e32 v51, v65, v81
	ds_write_b64 v1, v[62:63] offset:2176
	v_pk_fma_f32 v[58:59], v[80:81], v[80:81], v[50:51] op_sel_hi:[0,1,1] neg_lo:[0,0,1] neg_hi:[0,0,1]
	v_pk_fma_f32 v[50:51], v[80:81], v[80:81], v[50:51] op_sel_hi:[0,1,1]
	v_mov_b32_e32 v62, v58
	v_mov_b32_e32 v63, v51
	v_mul_f32_e32 v74, v51, v51
	v_mul_f32_e32 v75, v51, v58
	v_pk_mul_f32 v[50:51], v[28:29], v[50:51] op_sel:[1,1] op_sel_hi:[0,1]
	v_pk_fma_f32 v[76:77], v[58:59], v[62:63], v[74:75] op_sel_hi:[0,1,1] neg_lo:[0,0,1] neg_hi:[0,0,1]
	v_pk_fma_f32 v[74:75], v[58:59], v[62:63], v[74:75] op_sel_hi:[0,1,1]
	v_fma_f32 v88, v28, v58, -v50
	v_fma_f32 v89, v29, v58, v51
	v_pk_mul_f32 v[50:51], v[62:63], v[74:75] op_sel:[0,1]
	v_pk_add_f32 v[26:27], v[52:53], v[26:27] neg_lo:[0,1] neg_hi:[0,1]
	v_fma_f32 v52, v62, v76, -v51
	v_fma_f32 v51, v63, v76, v50
	v_mov_b32_e32 v59, v51
	v_sub_f32_e32 v56, v56, v70
	v_mov_b32_e32 v78, v76
	v_mov_b32_e32 v79, v75
	ds_write_b64 v1, v[88:89] offset:4352
	v_mov_b32_e32 v58, v52
	v_pk_add_f32 v[88:89], v[20:21], v[20:21] op_sel:[0,1] op_sel_hi:[0,1]
	v_mul_f32_e32 v50, v56, v51
	v_mul_f32_e32 v51, v56, v52
	v_fma_f32 v52, v88, v52, -v50
	v_fma_f32 v53, v89, v59, v51
	v_pk_add_f32 v[40:41], v[40:41], v[42:43] neg_lo:[0,1] neg_hi:[0,1]
	v_pk_mul_f32 v[42:43], v[78:79], v[74:75] op_sel:[0,1]
	v_pk_fma_f32 v[50:51], v[76:77], v[78:79], v[42:43] op_sel:[0,0,1] op_sel_hi:[0,1,0] neg_lo:[0,0,1] neg_hi:[0,0,1]
	v_pk_fma_f32 v[42:43], v[76:77], v[78:79], v[42:43] op_sel:[0,0,1] op_sel_hi:[0,1,0]
	v_pk_mov_b32 v[56:57], v[42:43], v[50:51] op_sel:[1,0]
	v_mov_b32_e32 v81, v64
	v_pk_mul_f32 v[72:73], v[64:65], v[62:63]
	v_pk_mul_f32 v[84:85], v[64:65], v[78:79]
	ds_write_b64 v1, v[52:53] offset:13056
	v_mov_b32_e32 v52, v50
	v_mov_b32_e32 v53, v43
	v_pk_mul_f32 v[64:65], v[64:65], v[56:57] op_sel_hi:[0,1]
	v_fma_f32 v70, v80, v52, v64
	v_fma_f32 v65, v80, v53, -v65
	v_pk_add_f32 v[30:31], v[32:33], v[30:31] neg_lo:[0,1] neg_hi:[0,1]
	v_pk_mov_b32 v[86:87], v[74:75], v[76:77] op_sel:[1,0]
	v_mov_b32_e32 v75, v65
	v_mul_f32_e32 v64, v31, v65
	v_mul_f32_e32 v65, v31, v70
	v_pk_mul_f32 v[42:43], v[40:41], v[42:43] op_sel:[1,1] op_sel_hi:[0,1]
	v_pk_mul_f32 v[66:67], v[80:81], v[62:63]
	v_pk_mul_f32 v[82:83], v[80:81], v[78:79]
	v_pk_mul_f32 v[80:81], v[62:63], v[52:53]
	v_pk_mul_f32 v[62:63], v[62:63], v[56:57]
	v_fma_f32 v70, v30, v70, -v64
	v_fma_f32 v71, v30, v75, v65
	v_fma_f32 v64, v40, v50, -v42
	v_fma_f32 v65, v41, v50, v43
	v_pk_add_f32 v[34:35], v[22:23], v[44:45]
	v_pk_add_f32 v[46:47], v[36:37], v[24:25]
	v_mov_b32_e32 v88, v66
	v_pk_mov_b32 v[66:67], v[66:67], v[72:73] op_sel:[1,0]
	v_sub_f32_e32 v40, v68, v54
	v_sub_f32_e32 v41, v61, v69
	v_pk_add_f32 v[42:43], v[62:63], v[62:63] op_sel:[0,1] op_sel_hi:[0,1]
	v_pk_add_f32 v[32:33], v[46:47], v[34:35]
	v_add_f32_e32 v72, v88, v66
	v_sub_f32_e32 v66, v88, v66
	v_sub_f32_e32 v67, v73, v67
	v_pk_mul_f32 v[42:43], v[40:41], v[42:43] op_sel:[1,0] op_sel_hi:[0,1]
	v_pk_add_f32 v[50:51], v[80:81], v[80:81] op_sel:[0,1] op_sel_hi:[0,1] neg_lo:[0,1] neg_hi:[0,1]
	v_pk_mul_f32 v[90:91], v[32:33], v[66:67] op_sel:[0,1]
	v_fma_f32 v54, v40, v50, -v42
	v_fma_f32 v55, v41, v51, v43
	v_fma_f32 v92, v32, v72, -v91
	v_fma_f32 v93, v33, v72, v90
	v_mul_f32_e32 v90, v72, v52
	v_mul_f32_e32 v91, v67, v53
	v_mul_f32_e32 v88, v72, v56
	v_mul_f32_e32 v89, v67, v57
	v_mov_b32_e32 v41, v47
	v_sub_f32_e32 v34, v34, v46
	v_sub_f32_e32 v35, v41, v35
	v_pk_add_f32 v[40:41], v[88:89], v[88:89] op_sel:[0,1] op_sel_hi:[0,1]
	v_pk_add_f32 v[2:3], v[2:3], v[14:15] neg_lo:[0,1] neg_hi:[0,1]
	v_pk_add_f32 v[4:5], v[4:5], v[16:17] neg_lo:[0,1] neg_hi:[0,1]
	v_pk_mul_f32 v[40:41], v[34:35], v[40:41] op_sel:[1,0] op_sel_hi:[0,1]
	v_pk_add_f32 v[42:43], v[90:91], v[90:91] op_sel:[0,1] op_sel_hi:[0,1] neg_lo:[0,1] neg_hi:[0,1]
	v_pk_add_f32 v[14:15], v[2:3], v[4:5] op_sel:[0,1] op_sel_hi:[1,0]
	v_pk_add_f32 v[2:3], v[2:3], v[4:5] op_sel:[0,1] op_sel_hi:[1,0] neg_lo:[0,1] neg_hi:[0,1]
	v_pk_add_f32 v[28:29], v[38:39], v[48:49] neg_lo:[0,1] neg_hi:[0,1]
	v_fma_f32 v46, v34, v42, -v40
	v_fma_f32 v47, v35, v43, v41
	v_pk_mul_f32 v[16:17], v[2:3], v[86:87] op_sel:[1,0]
	v_pk_add_f32 v[38:39], v[26:27], v[28:29] op_sel:[0,1] op_sel_hi:[1,0]
	v_pk_add_f32 v[26:27], v[26:27], v[28:29] op_sel:[0,1] op_sel_hi:[1,0] neg_lo:[0,1] neg_hi:[0,1]
	v_pk_mul_f32 v[94:95], v[78:79], v[56:57]
	v_mov_b32_e32 v96, v82
	v_mov_b32_e32 v97, v85
	v_pk_mov_b32 v[82:83], v[82:83], v[84:85] op_sel:[1,0]
	v_fma_f32 v34, v14, v76, -v16
	v_fma_f32 v35, v14, v79, v17
	ds_write_b64 v1, v[92:93] offset:6528
	v_pk_mul_f32 v[92:93], v[78:79], v[52:53]
	v_add_f32_e32 v84, v96, v82
	v_sub_f32_e32 v83, v97, v83
	v_mov_b32_e32 v5, v15
	v_pk_add_f32 v[16:17], v[94:95], v[94:95] op_sel:[0,1] op_sel_hi:[0,1]
	v_mov_b32_e32 v29, v27
	v_mov_b32_e32 v96, v84
	v_mov_b32_e32 v97, v83
	v_mul_f32_e32 v48, v27, v83
	v_mul_f32_e32 v49, v38, v83
	v_mul_f32_e32 v14, v15, v16
	v_mul_f32_e32 v15, v2, v17
	v_pk_add_f32 v[16:17], v[92:93], v[92:93] op_sel:[0,1] op_sel_hi:[0,1] neg_lo:[0,1] neg_hi:[0,1]
	v_fma_f32 v82, v38, v84, -v48
	v_fma_f32 v83, v29, v84, v49
	v_pk_mul_f32 v[48:49], v[56:57], v[96:97]
	v_fma_f32 v2, v2, v16, -v14
	v_fma_f32 v3, v5, v17, v15
	v_pk_mul_f32 v[28:29], v[52:53], v[96:97]
	v_pk_add_f32 v[14:15], v[48:49], v[48:49] op_sel:[0,1] op_sel_hi:[0,1]
	ds_write_b64 v1, v[82:83] offset:10880
	ds_write_b64 v1, v[64:65] offset:17408
	ds_write_b64 v1, v[70:71] offset:19584
	ds_write_b64 v1, v[2:3] offset:26112
	v_mov_b32_e32 v3, v39
	v_mul_f32_e32 v4, v39, v14
	v_mul_f32_e32 v5, v26, v15
	v_pk_add_f32 v[14:15], v[28:29], v[28:29] op_sel:[0,1] op_sel_hi:[0,1] neg_lo:[0,1] neg_hi:[0,1]
	v_pk_mul_f32 v[30:31], v[52:53], v[58:59]
	v_fma_f32 v16, v26, v14, -v4
	v_fma_f32 v17, v3, v15, v5
	v_pk_mul_f32 v[58:59], v[56:57], v[58:59]
	v_mov_b32_e32 v3, v30
	v_sub_f32_e32 v2, v20, v21
	v_sub_f32_e32 v3, v3, v31
	v_pk_add_f32 v[14:15], v[58:59], v[58:59] op_sel:[0,1] op_sel_hi:[0,1]
	v_mul_f32_e32 v4, v18, v14
	v_mul_f32_e32 v5, v2, v15
	v_pk_mov_b32 v[14:15], v[2:3], v[18:19] op_sel:[1,0]
	ds_write_b64 v1, v[16:17] offset:28288
	v_fma_f32 v16, v2, v14, -v4
	v_fma_f32 v17, v3, v15, v5
	v_pk_mul_f32 v[32:33], v[78:79], v[66:67] op_sel:[0,1]
	v_fma_f32 v66, v78, v72, -v33
	v_fma_f32 v33, v79, v72, v32
	v_sub_f32_e32 v2, v23, v45
	v_sub_f32_e32 v3, v36, v24
	v_sub_f32_e32 v4, v44, v22
	v_sub_f32_e32 v5, v37, v25
	v_mov_b32_e32 v73, v33
	v_pk_add_f32 v[14:15], v[4:5], v[2:3]
	v_pk_add_f32 v[2:3], v[4:5], v[2:3] neg_lo:[0,1] neg_hi:[0,1]
	v_mov_b32_e32 v72, v66
	ds_write_b64 v1, v[16:17] offset:30464
	v_mul_f32_e32 v16, v3, v33
	v_mul_f32_e32 v17, v3, v66
	v_pk_mul_f32 v[56:57], v[56:57], v[72:73]
	v_fma_f32 v18, v14, v66, -v16
	v_fma_f32 v19, v14, v73, v17
	v_pk_mul_f32 v[52:53], v[52:53], v[72:73]
	v_mov_b32_e32 v5, v15
	v_pk_add_f32 v[16:17], v[56:57], v[56:57] op_sel:[0,1] op_sel_hi:[0,1]
	v_mul_f32_e32 v14, v15, v16
	v_mul_f32_e32 v15, v2, v17
	v_pk_add_f32 v[16:17], v[52:53], v[52:53] op_sel:[0,1] op_sel_hi:[0,1] neg_lo:[0,1] neg_hi:[0,1]
	v_fma_f32 v2, v2, v16, -v14
	v_fma_f32 v3, v5, v17, v15
	ds_write_b64 v1, v[54:55] offset:21760
	ds_write_b64 v1, v[46:47] offset:23936
	ds_write_b64 v1, v[34:35] offset:8704
	ds_write_b64 v1, v[18:19] offset:15232
	ds_write_b64 v1, v[2:3] offset:32640
	v_mov_b32_e32 v1, v122
	s_waitcnt lgkmcnt(0)
	s_barrier
	s_mov_b32 s43, 0
	v_ashrrev_i32_e32 v2, 31, v1
	v_lshrrev_b32_e32 v2, 28, v2
	v_and_b32_e32 v70, 15, v1
	v_add_u32_e32 v1, v1, v2
	v_ashrrev_i32_e32 v1, 4, v1
	v_lshlrev_b32_e32 v2, 11, v1
	v_lshl_add_u32 v1, v1, 7, v2
	v_lshl_or_b32 v1, v70, 3, v1
	ds_read2_b64 v[20:23], v1 offset1:17
	ds_read2_b64 v[24:27], v1 offset0:68 offset1:85
	ds_read2_b64 v[28:31], v1 offset0:136 offset1:153
	ds_read2_b64 v[32:35], v1 offset0:170 offset1:187
	ds_read2_b64 v[36:39], v1 offset0:204 offset1:221
	ds_read2_b64 v[40:43], v1 offset0:238 offset1:255
	ds_read2_b64 v[44:47], v1 offset0:34 offset1:51
	ds_read2_b64 v[48:51], v1 offset0:102 offset1:119
	s_waitcnt lgkmcnt(5)
	v_pk_add_f32 v[18:19], v[28:29], v[20:21]
	s_waitcnt lgkmcnt(2)
	v_pk_mov_b32 v[68:69], v[34:35], v[42:43] op_sel:[1,0]
	s_waitcnt lgkmcnt(1)
	v_pk_add_f32 v[64:65], v[46:47], v[34:35]
	s_waitcnt lgkmcnt(0)
	v_pk_add_f32 v[66:67], v[50:51], v[42:43]
	v_mov_b32_e32 v35, v43
	v_pk_add_f32 v[42:43], v[64:65], v[66:67] neg_lo:[0,1] neg_hi:[0,1]
	v_sub_f32_e32 v68, v47, v68
	v_sub_f32_e32 v69, v50, v69
	v_pk_add_f32 v[16:17], v[64:65], v[66:67]
	v_mul_f32_e32 v64, 0x3f3504f3, v43
	v_mul_f32_e32 v67, 0xbf3504f3, v43
	v_cvt_f32_i32_e32 v43, v70
	v_sub_f32_e32 v34, v46, v34
	v_sub_f32_e32 v35, v51, v35
	v_pk_add_f32 v[28:29], v[20:21], v[28:29] neg_lo:[0,1] neg_hi:[0,1]
	v_add_f32_e32 v43, v43, v43
	v_pk_add_f32 v[20:21], v[24:25], v[36:37] neg_lo:[0,1] neg_hi:[0,1]
	v_pk_add_f32 v[52:53], v[36:37], v[24:25]
	v_pk_add_f32 v[54:55], v[22:23], v[30:31]
	v_pk_add_f32 v[56:57], v[26:27], v[38:39]
	v_sub_f32_e32 v46, v34, v35
	v_mul_f32_e32 v43, 0x3b800000, v43
	v_pk_mov_b32 v[24:25], v[20:21], v[20:21] op_sel:[1,0]
	v_add_f32_e32 v36, v28, v21
	v_sub_f32_e32 v37, v29, v20
	v_pk_add_f32 v[34:35], v[34:35], v[34:35] op_sel:[0,1] op_sel_hi:[0,1]
	v_pk_add_f32 v[4:5], v[54:55], v[56:57]
	v_pk_add_f32 v[58:59], v[44:45], v[32:33]
	v_pk_add_f32 v[60:61], v[48:49], v[40:41]
	v_pk_add_f32 v[54:55], v[54:55], v[56:57] neg_lo:[0,1] neg_hi:[0,1]
	v_mul_f32_e32 v43, 0.5, v43
	v_pk_add_f32 v[20:21], v[68:69], v[68:69] op_sel:[0,1] op_sel_hi:[0,1] neg_lo:[0,1] neg_hi:[0,1]
	v_pk_mul_f32 v[34:35], v[34:35], s[0:1]
	v_pk_add_f32 v[14:15], v[58:59], v[60:61]
	v_pk_add_f32 v[62:63], v[58:59], v[60:61] neg_lo:[0,1] neg_hi:[0,1]
	v_add_f32_e32 v50, v68, v69
	v_pk_mul_f32 v[56:57], v[54:55], s[20:21] op_sel_hi:[1,0]
	v_mul_f32_e32 v42, 0x3f3504f3, v42
	v_sin_f32_e32 v58, v43
	s_nop 1
	v_cos_f32_e32 v76, v43
	s_nop 1
	v_fma_f32 v68, v20, s22, v34
	v_fma_f32 v69, v21, s23, -v35
	v_pk_add_f32 v[2:3], v[18:19], v[52:53]
	v_mov_b32_e32 v20, v18
	v_sub_f32_e32 v18, v64, v42
	v_sub_f32_e32 v19, v19, v53
	v_sub_f32_e32 v20, v20, v52
	v_sub_f32_e32 v21, v57, v56
	v_mov_b32_e32 v35, v42
	v_pk_add_f32 v[42:43], v[18:19], v[62:63] op_sel:[1,0] op_sel_hi:[0,1]
	v_mov_b32_e32 v53, v62
	v_sub_f32_e32 v34, v59, v61
	v_sub_f32_e32 v35, v67, v35
	v_sub_f32_e32 v62, v44, v32
	v_sub_f32_e32 v63, v22, v30
	v_sub_f32_e32 v64, v49, v41
	v_sub_f32_e32 v65, v27, v39
	v_mul_f32_e32 v78, 0x3f6c835e, v50
	v_mul_f32_e32 v79, 0x3ec3ef15, v46
	v_sub_f32_e32 v22, v45, v33
	v_sub_f32_e32 v23, v23, v31
	v_sub_f32_e32 v27, v26, v38
	v_sub_f32_e32 v26, v48, v40
	v_pk_add_f32 v[32:33], v[62:63], v[64:65] neg_lo:[0,1] neg_hi:[0,1]
	v_pk_fma_f32 v[54:55], v[54:55], s[20:21], v[56:57] op_sel:[0,0,1] op_sel_hi:[1,0,0]
	v_pk_add_f32 v[66:67], v[62:63], v[64:65]
	v_pk_add_f32 v[30:31], v[22:23], v[26:27] neg_lo:[0,1] neg_hi:[0,1]
	v_pk_add_f32 v[22:23], v[22:23], v[26:27]
	v_mov_b32_e32 v39, v29
	v_mov_b32_e32 v27, v25
	v_mov_b32_e32 v52, v54
	v_pk_add_f32 v[54:55], v[54:55], v[18:19] neg_lo:[0,1] neg_hi:[0,1]
	v_mul_f32_e32 v26, 0x3ec3ef15, v33
	v_pk_mul_f32 v[40:41], v[32:33], s[20:21]
	v_mul_f32_e32 v33, s73, v32
	v_mul_f32_e32 v32, s72, v50
	v_sub_f32_e32 v24, v28, v24
	v_sub_f32_e32 v25, v79, v78
	v_pk_mul_f32 v[28:29], v[66:67], s[22:23] op_sel:[1,0]
	v_add_f32_e32 v56, v18, v52
	v_sub_f32_e32 v53, v19, v53
	v_pk_add_f32 v[18:19], v[42:43], v[54:55]
	v_mul_f32_e32 v38, 0x3f6c835e, v23
	v_mul_f32_e32 v43, 0x3f3504f3, v66
	v_mul_f32_e32 v44, 0x3f3504f3, v30
	v_pk_fma_f32 v[40:41], v[22:23], s[70:71], v[40:41] neg_lo:[0,0,1] neg_hi:[0,0,1]
	v_fma_f32 v23, v22, s31, -v33
	v_fma_f32 v22, v46, s30, -v32
	v_fma_f32 v32, v31, s0, v28
	v_fma_f32 v33, v31, s1, -v29
	v_pk_add_f32 v[26:27], v[38:39], v[26:27]
	v_add_f32_e32 v28, v44, v43
	v_fma_f32 v29, v30, s20, -v43
	v_pk_add_f32 v[30:31], v[36:37], v[28:29]
	v_pk_add_f32 v[38:39], v[32:33], v[68:69]
	v_xor_b32_e32 v77, 0x80000000, v58
	v_pk_add_f32 v[44:45], v[38:39], v[30:31]
	v_pk_add_f32 v[70:71], v[2:3], v[14:15]
	v_pk_mul_f32 v[50:51], v[58:59], v[44:45] op_sel_hi:[0,1]
	v_fma_f32 v62, v76, v44, v51
	v_fma_f32 v63, v76, v45, -v50
	v_mov_b32_e32 v59, v76
	v_pk_add_f32 v[72:73], v[4:5], v[16:17]
	v_mul_f32_e32 v44, v58, v58
	v_mul_f32_e32 v45, v59, v77
	v_pk_add_f32 v[74:75], v[72:73], v[70:71]
	v_pk_fma_f32 v[50:51], v[76:77], v[76:77], v[44:45] op_sel_hi:[0,1,1] neg_lo:[0,0,1] neg_hi:[0,0,1]
	v_pk_fma_f32 v[44:45], v[76:77], v[76:77], v[44:45] op_sel_hi:[0,1,1]
	v_pk_add_f32 v[60:61], v[20:21], v[34:35]
	ds_write2_b64 v1, v[74:75], v[62:63] offset1:17
	v_pk_add_f32 v[20:21], v[20:21], v[34:35] neg_lo:[0,1] neg_hi:[0,1]
	v_add_f32_e32 v34, v60, v56
	v_add_f32_e32 v35, v61, v53
	v_mov_b32_e32 v62, v50
	v_mov_b32_e32 v63, v45
	v_mul_f32_e32 v74, v45, v45
	v_mul_f32_e32 v75, v45, v50
	v_pk_mul_f32 v[44:45], v[34:35], v[44:45] op_sel:[1,1] op_sel_hi:[0,1]
	v_pk_fma_f32 v[78:79], v[50:51], v[62:63], v[74:75] op_sel_hi:[0,1,1] neg_lo:[0,0,1] neg_hi:[0,0,1]
	v_pk_fma_f32 v[74:75], v[50:51], v[62:63], v[74:75] op_sel_hi:[0,1,1]
	v_fma_f32 v88, v34, v50, -v44
	v_fma_f32 v89, v35, v50, v45
	v_pk_mul_f32 v[44:45], v[62:63], v[74:75] op_sel:[0,1]
	v_pk_add_f32 v[32:33], v[32:33], v[68:69] neg_lo:[0,1] neg_hi:[0,1]
	v_fma_f32 v50, v62, v78, -v45
	v_fma_f32 v45, v63, v78, v44
	v_sub_f32_e32 v42, v42, v54
	v_mov_b32_e32 v69, v45
	v_mov_b32_e32 v77, v58
	v_mov_b32_e32 v80, v78
	v_mov_b32_e32 v81, v75
	v_pk_add_f32 v[90:91], v[20:21], v[20:21] op_sel:[0,1] op_sel_hi:[0,1]
	v_mul_f32_e32 v43, v42, v50
	v_mul_f32_e32 v42, v42, v45
	v_pk_mul_f32 v[64:65], v[76:77], v[62:63]
	v_pk_mul_f32 v[66:67], v[58:59], v[62:63]
	v_mov_b32_e32 v68, v50
	v_fma_f32 v44, v90, v50, -v42
	v_pk_mul_f32 v[50:51], v[80:81], v[74:75] op_sel:[0,1]
	v_pk_add_f32 v[30:31], v[30:31], v[38:39] neg_lo:[0,1] neg_hi:[0,1]
	v_pk_add_f32 v[38:39], v[40:41], v[24:25]
	v_pk_add_f32 v[46:47], v[26:27], v[22:23]
	v_fma_f32 v45, v91, v69, v43
	v_pk_fma_f32 v[54:55], v[78:79], v[80:81], v[50:51] op_sel:[0,0,1] op_sel_hi:[0,1,0] neg_lo:[0,0,1] neg_hi:[0,0,1]
	v_pk_fma_f32 v[50:51], v[78:79], v[80:81], v[50:51] op_sel:[0,0,1] op_sel_hi:[0,1,0]
	v_mov_b32_e32 v92, v64
	v_pk_mov_b32 v[64:65], v[64:65], v[66:67] op_sel:[1,0]
	v_pk_add_f32 v[48:49], v[38:39], v[46:47]
	v_pk_add_f32 v[42:43], v[70:71], v[72:73] neg_lo:[0,1] neg_hi:[0,1]
	v_pk_mov_b32 v[72:73], v[50:51], v[54:55] op_sel:[1,0]
	v_add_f32_e32 v66, v92, v64
	v_sub_f32_e32 v64, v92, v64
	v_sub_f32_e32 v65, v67, v65
	v_pk_mul_f32 v[82:83], v[76:77], v[80:81]
	v_pk_mul_f32 v[84:85], v[58:59], v[80:81]
	v_pk_add_f32 v[28:29], v[36:37], v[28:29] neg_lo:[0,1] neg_hi:[0,1]
	v_mov_b32_e32 v70, v54
	v_mov_b32_e32 v71, v51
	v_pk_mul_f32 v[58:59], v[58:59], v[72:73] op_sel_hi:[0,1]
	v_pk_mul_f32 v[94:95], v[48:49], v[64:65] op_sel:[0,1]
	v_pk_mov_b32 v[86:87], v[74:75], v[78:79] op_sel:[1,0]
	v_pk_add_f32 v[34:35], v[28:29], v[32:33] op_sel:[0,1] op_sel_hi:[1,0]
	v_pk_add_f32 v[28:29], v[28:29], v[32:33] op_sel:[0,1] op_sel_hi:[1,0] neg_lo:[0,1] neg_hi:[0,1]
	v_fma_f32 v74, v76, v70, v58
	v_fma_f32 v59, v76, v71, -v59
	v_fma_f32 v96, v48, v66, -v95
	v_fma_f32 v97, v49, v66, v94
	v_mov_b32_e32 v98, v82
	v_mov_b32_e32 v99, v85
	v_pk_mov_b32 v[82:83], v[82:83], v[84:85] op_sel:[1,0]
	v_mov_b32_e32 v77, v59
	v_pk_mul_f32 v[48:49], v[80:81], v[64:65] op_sel:[0,1]
	v_pk_add_f32 v[84:85], v[98:99], v[82:83]
	v_sub_f32_e32 v83, v99, v83
	v_mov_b32_e32 v33, v29
	v_mov_b32_e32 v93, v65
	v_fma_f32 v64, v80, v66, -v49
	v_fma_f32 v49, v81, v66, v48
	v_mul_f32_e32 v36, v29, v83
	v_mul_f32_e32 v37, v34, v83
	v_mul_f32_e32 v58, v31, v59
	v_mul_f32_e32 v59, v31, v74
	v_mov_b32_e32 v92, v66
	v_mov_b32_e32 v66, v64
	v_mov_b32_e32 v67, v49
	v_mov_b32_e32 v98, v84
	v_mov_b32_e32 v99, v83
	v_fma_f32 v82, v34, v84, -v36
	v_fma_f32 v83, v33, v84, v37
	v_fma_f32 v74, v30, v74, -v58
	v_fma_f32 v75, v30, v77, v59
	v_pk_mul_f32 v[50:51], v[42:43], v[50:51] op_sel:[1,1] op_sel_hi:[0,1]
	v_pk_mul_f32 v[90:91], v[62:63], v[70:71]
	v_pk_mul_f32 v[62:63], v[62:63], v[72:73]
	ds_write2_b64 v1, v[88:89], v[96:97] offset0:34 offset1:51
	v_pk_mul_f32 v[88:89], v[92:93], v[70:71]
	v_pk_mul_f32 v[92:93], v[92:93], v[72:73]
	v_pk_mul_f32 v[94:95], v[80:81], v[70:71]
	v_pk_mul_f32 v[96:97], v[80:81], v[72:73]
	v_pk_mul_f32 v[32:33], v[70:71], v[98:99]
	v_pk_mul_f32 v[36:37], v[72:73], v[98:99]
	v_pk_mul_f32 v[30:31], v[70:71], v[68:69]
	v_pk_mul_f32 v[58:59], v[72:73], v[68:69]
	v_pk_mul_f32 v[68:69], v[70:71], v[66:67]
	v_pk_mul_f32 v[70:71], v[72:73], v[66:67]
	v_fma_f32 v72, v42, v54, -v50
	v_fma_f32 v73, v43, v54, v51
	v_sub_f32_e32 v42, v60, v56
	v_sub_f32_e32 v43, v53, v61
	v_pk_add_f32 v[50:51], v[62:63], v[62:63] op_sel:[0,1] op_sel_hi:[0,1]
	v_pk_mul_f32 v[50:51], v[42:43], v[50:51] op_sel:[1,0] op_sel_hi:[0,1]
	v_pk_add_f32 v[52:53], v[90:91], v[90:91] op_sel:[0,1] op_sel_hi:[0,1] neg_lo:[0,1] neg_hi:[0,1]
	v_fma_f32 v54, v42, v52, -v50
	v_fma_f32 v55, v43, v53, v51
	v_pk_add_f32 v[2:3], v[2:3], v[14:15] neg_lo:[0,1] neg_hi:[0,1]
	v_mov_b32_e32 v43, v47
	v_sub_f32_e32 v38, v38, v46
	v_sub_f32_e32 v39, v43, v39
	v_pk_add_f32 v[42:43], v[92:93], v[92:93] op_sel:[0,1] op_sel_hi:[0,1]
	v_pk_add_f32 v[4:5], v[4:5], v[16:17] neg_lo:[0,1] neg_hi:[0,1]
	v_pk_mul_f32 v[42:43], v[38:39], v[42:43] op_sel:[1,0] op_sel_hi:[0,1]
	v_pk_add_f32 v[46:47], v[88:89], v[88:89] op_sel:[0,1] op_sel_hi:[0,1] neg_lo:[0,1] neg_hi:[0,1]
	v_pk_add_f32 v[14:15], v[2:3], v[4:5] op_sel:[0,1] op_sel_hi:[1,0]
	v_pk_add_f32 v[2:3], v[2:3], v[4:5] op_sel:[0,1] op_sel_hi:[1,0] neg_lo:[0,1] neg_hi:[0,1]
	v_fma_f32 v50, v38, v46, -v42
	v_fma_f32 v51, v39, v47, v43
	v_pk_mul_f32 v[16:17], v[2:3], v[86:87] op_sel:[1,0]
	v_fma_f32 v38, v14, v78, -v16
	v_fma_f32 v39, v14, v81, v17
	v_mov_b32_e32 v5, v15
	v_pk_add_f32 v[16:17], v[96:97], v[96:97] op_sel:[0,1] op_sel_hi:[0,1]
	v_mul_f32_e32 v14, v15, v16
	v_mul_f32_e32 v15, v2, v17
	v_pk_add_f32 v[16:17], v[94:95], v[94:95] op_sel:[0,1] op_sel_hi:[0,1] neg_lo:[0,1] neg_hi:[0,1]
	v_fma_f32 v2, v2, v16, -v14
	v_fma_f32 v3, v5, v17, v15
	v_pk_add_f32 v[16:17], v[36:37], v[36:37] op_sel:[0,1] op_sel_hi:[0,1]
	v_mov_b32_e32 v5, v35
	v_mul_f32_e32 v14, v35, v16
	v_mul_f32_e32 v15, v28, v17
	v_pk_add_f32 v[16:17], v[32:33], v[32:33] op_sel:[0,1] op_sel_hi:[0,1] neg_lo:[0,1] neg_hi:[0,1]
	v_fma_f32 v28, v28, v16, -v14
	v_fma_f32 v29, v5, v17, v15
	v_pk_add_f32 v[14:15], v[58:59], v[58:59] op_sel:[0,1] op_sel_hi:[0,1]
	ds_write2_b64 v1, v[2:3], v[28:29] offset0:204 offset1:221
	v_mov_b32_e32 v3, v30
	v_sub_f32_e32 v2, v20, v21
	v_sub_f32_e32 v3, v3, v31
	v_mul_f32_e32 v4, v18, v14
	v_mul_f32_e32 v5, v2, v15
	v_pk_mov_b32 v[14:15], v[2:3], v[18:19] op_sel:[1,0]
	v_fma_f32 v16, v2, v14, -v4
	v_fma_f32 v17, v3, v15, v5
	v_mov_b32_e32 v3, v26
	v_mov_b32_e32 v5, v22
	v_sub_f32_e32 v2, v24, v40
	v_sub_f32_e32 v3, v3, v5
	v_sub_f32_e32 v4, v41, v25
	v_sub_f32_e32 v5, v27, v23
	ds_write2_b64 v1, v[72:73], v[74:75] offset0:136 offset1:153
	v_pk_add_f32 v[14:15], v[4:5], v[2:3]
	v_sub_f32_e32 v18, v2, v4
	v_sub_f32_e32 v2, v5, v3
	v_mul_f32_e32 v3, v2, v64
	v_mul_f32_e32 v2, v2, v49
	v_fma_f32 v4, v14, v64, -v2
	v_fma_f32 v5, v14, v67, v3
	ds_write2_b64 v1, v[44:45], v[4:5] offset0:102 offset1:119
	v_pk_add_f32 v[4:5], v[70:71], v[70:71] op_sel:[0,1] op_sel_hi:[0,1]
	v_mov_b32_e32 v21, v15
	v_mul_f32_e32 v2, v15, v4
	v_mul_f32_e32 v3, v18, v5
	v_pk_add_f32 v[4:5], v[68:69], v[68:69] op_sel:[0,1] op_sel_hi:[0,1] neg_lo:[0,1] neg_hi:[0,1]
	v_fma_f32 v14, v18, v4, -v2
	v_fma_f32 v15, v21, v5, v3
	ds_write2_b64 v1, v[54:55], v[50:51] offset0:170 offset1:187
	ds_write2_b64 v1, v[38:39], v[82:83] offset0:68 offset1:85
	ds_write2_b64 v1, v[16:17], v[14:15] offset0:238 offset1:255
	v_mov_b32_e32 v1, v122
	s_waitcnt lgkmcnt(0)
	s_barrier
	s_and_b64 s[0:1], s[96:97], exec
	v_mul_lo_u32 v1, v1, s33
	ds_read2_b64 v[2:5], v1 offset1:1
	ds_read2_b64 v[14:17], v1 offset0:8 offset1:9
	ds_read2_b64 v[18:21], v1 offset0:10 offset1:11
	ds_read2_b64 v[22:25], v1 offset0:12 offset1:13
	ds_read2_b64 v[26:29], v1 offset0:14 offset1:15
	ds_read2_b64 v[30:33], v1 offset0:2 offset1:3
	ds_read2_b64 v[34:37], v1 offset0:4 offset1:5
	ds_read2_b64 v[38:41], v1 offset0:6 offset1:7
	s_waitcnt lgkmcnt(7)
	v_mov_b32_e32 v1, v4
	v_mov_b32_e32 v42, v2
	v_mov_b32_e32 v43, v4
	v_mov_b32_e32 v4, v5
	v_mov_b32_e32 v5, v3
	s_waitcnt lgkmcnt(6)
	v_mov_b32_e32 v44, v14
	v_mov_b32_e32 v45, v16
	v_mov_b32_e32 v16, v17
	v_mov_b32_e32 v17, v15
	v_pk_add_f32 v[46:47], v[2:3], v[14:15] neg_lo:[0,1] neg_hi:[0,1]
	v_pk_add_f32 v[2:3], v[2:3], v[14:15]
	s_waitcnt lgkmcnt(1)
	v_mov_b32_e32 v15, v36
	v_mov_b32_e32 v49, v36
	v_mov_b32_e32 v36, v37
	v_mov_b32_e32 v37, v35
	v_mov_b32_e32 v50, v22
	v_mov_b32_e32 v51, v24
	v_mov_b32_e32 v24, v25
	v_mov_b32_e32 v25, v23
	v_mov_b32_e32 v48, v34
	v_pk_add_f32 v[52:53], v[34:35], v[22:23] neg_lo:[0,1] neg_hi:[0,1]
	v_pk_add_f32 v[22:23], v[34:35], v[22:23]
	v_pk_mov_b32 v[34:35], v[0:1], v[4:5] op_sel:[1,0]
	v_pk_mov_b32 v[54:55], v[44:45], v[16:17] op_sel:[1,0]
	v_pk_add_f32 v[4:5], v[4:5], v[16:17]
	v_pk_mov_b32 v[14:15], v[14:15], v[36:37] op_sel:[1,0]
	v_pk_mov_b32 v[16:17], v[50:51], v[24:25] op_sel:[1,0]
	v_pk_add_f32 v[42:43], v[42:43], v[44:45]
	v_pk_add_f32 v[44:45], v[48:49], v[50:51]
	v_pk_add_f32 v[24:25], v[36:37], v[24:25]
	v_pk_add_f32 v[48:49], v[2:3], v[22:23] neg_lo:[0,1] neg_hi:[0,1]
	v_pk_add_f32 v[2:3], v[2:3], v[22:23]
	v_pk_add_f32 v[22:23], v[34:35], v[54:55]
	v_pk_add_f32 v[34:35], v[34:35], v[54:55] neg_lo:[0,1] neg_hi:[0,1]
	v_pk_add_f32 v[36:37], v[14:15], v[16:17]
	v_pk_add_f32 v[14:15], v[14:15], v[16:17] neg_lo:[0,1] neg_hi:[0,1]
	v_add_f32_e32 v1, v46, v53
	v_sub_f32_e32 v50, v47, v52
	v_sub_f32_e32 v51, v46, v53
	v_add_f32_e32 v53, v47, v52
	v_pk_add_f32 v[16:17], v[42:43], v[44:45]
	v_pk_add_f32 v[4:5], v[4:5], v[24:25]
	v_add_f32_e32 v52, v34, v15
	v_sub_f32_e32 v54, v35, v14
	v_sub_f32_e32 v55, v34, v15
	v_add_f32_e32 v56, v35, v14
	v_pk_add_f32 v[14:15], v[30:31], v[18:19] neg_lo:[0,1] neg_hi:[0,1]
	v_pk_add_f32 v[24:25], v[30:31], v[18:19]
	v_mov_b32_e32 v44, v30
	v_mov_b32_e32 v46, v18
	v_pk_add_f32 v[42:43], v[22:23], v[36:37]
	v_pk_add_f32 v[22:23], v[22:23], v[36:37] neg_lo:[0,1] neg_hi:[0,1]
	s_waitcnt lgkmcnt(0)
	v_pk_add_f32 v[34:35], v[38:39], v[26:27] neg_lo:[0,1] neg_hi:[0,1]
	v_pk_add_f32 v[36:37], v[38:39], v[26:27]
	v_add_f32_e32 v44, v44, v46
	v_add_f32_e32 v45, v32, v20
	v_add_f32_e32 v18, v33, v21
	v_add_f32_e32 v19, v31, v19
	v_mov_b32_e32 v30, v38
	v_mov_b32_e32 v46, v26
	v_add_f32_e32 v30, v30, v46
	v_add_f32_e32 v31, v40, v28
	v_add_f32_e32 v26, v41, v29
	v_add_f32_e32 v27, v39, v27
	v_pk_add_f32 v[38:39], v[24:25], v[36:37] neg_lo:[0,1] neg_hi:[0,1]
	v_pk_add_f32 v[24:25], v[24:25], v[36:37]
	v_add_f32_e32 v36, v14, v35
	v_sub_f32_e32 v37, v15, v34
	v_sub_f32_e32 v46, v14, v35
	v_add_f32_e32 v47, v15, v34
	v_pk_add_f32 v[14:15], v[32:33], v[20:21]
	v_pk_add_f32 v[20:21], v[32:33], v[20:21] neg_lo:[0,1] neg_hi:[0,1]
	v_pk_add_f32 v[32:33], v[40:41], v[28:29]
	v_mul_f32_e32 v22, 0x3f3504f3, v22
	v_pk_add_f32 v[28:29], v[40:41], v[28:29] neg_lo:[0,1] neg_hi:[0,1]
	v_pk_add_f32 v[34:35], v[14:15], v[32:33]
	v_pk_add_f32 v[14:15], v[14:15], v[32:33] neg_lo:[0,1] neg_hi:[0,1]
	v_fmamk_f32 v33, v23, 0x3f3504f3, v22
	v_fma_f32 v40, v23, s20, -v22
	v_mul_f32_e32 v22, 0x3f3504f3, v36
	v_pk_add_f32 v[30:31], v[44:45], v[30:31]
	v_pk_add_f32 v[18:19], v[18:19], v[26:27]
	v_add_f32_e32 v26, v20, v29
	v_sub_f32_e32 v27, v21, v28
	v_sub_f32_e32 v20, v20, v29
	v_add_f32_e32 v21, v21, v28
	v_mul_f32_e32 v28, 0x3f6c835e, v52
	v_mul_f32_e32 v29, 0x3ec3ef15, v52
	v_mul_f32_e32 v41, 0x3ec3ef15, v55
	v_mul_f32_e32 v45, 0xbf6c835e, v55
	v_fmamk_f32 v32, v37, 0x3f3504f3, v22
	v_fma_f32 v36, v37, s20, -v22
	v_mul_f32_e32 v37, 0xbf3504f3, v46
	v_fmac_f32_e32 v28, 0x3ec3ef15, v54
	v_fma_f32 v29, v54, s21, -v29
	v_fmac_f32_e32 v41, 0x3f6c835e, v56
	v_fmac_f32_e32 v45, 0x3ec3ef15, v56
	v_fmamk_f32 v54, v47, 0x3f3504f3, v37
	v_fmac_f32_e32 v37, 0xbf3504f3, v47
	v_mul_f32_e32 v44, 0x3ec3ef15, v26
	v_mul_f32_e32 v46, 0xbf6c835e, v26
	v_mul_f32_e32 v47, 0xbf3504f3, v14
	v_mul_f32_e32 v14, 0x3ec3ef15, v21
	v_mul_f32_e32 v56, 0xbf6c835e, v21
	v_fmac_f32_e32 v44, 0x3f6c835e, v27
	v_fmac_f32_e32 v46, 0x3ec3ef15, v27
	v_fma_f32 v55, v20, s76, -v14
	v_fmac_f32_e32 v56, 0x3ec3ef15, v20
	v_pk_add_f32 v[20:21], v[2:3], v[24:25]
	v_pk_add_f32 v[2:3], v[2:3], v[24:25] neg_lo:[0,1] neg_hi:[0,1]
	v_pk_add_f32 v[22:23], v[42:43], v[34:35]
	v_pk_add_f32 v[24:25], v[16:17], v[30:31] neg_lo:[0,1] neg_hi:[0,1]
	v_pk_add_f32 v[26:27], v[42:43], v[34:35] neg_lo:[0,1] neg_hi:[0,1]
	v_pk_add_f32 v[4:5], v[4:5], v[18:19] neg_lo:[0,1] neg_hi:[0,1]
	v_fmamk_f32 v52, v15, 0x3f3504f3, v47
	v_fmac_f32_e32 v47, 0xbf3504f3, v15
	v_pk_add_f32 v[14:15], v[22:23], v[20:21]
	v_pk_add_f32 v[16:17], v[20:21], v[22:23] neg_lo:[0,1] neg_hi:[0,1]
	v_pk_add_f32 v[70:71], v[2:3], v[26:27] op_sel:[0,1] op_sel_hi:[1,0]
	v_pk_add_f32 v[2:3], v[2:3], v[26:27] op_sel:[0,1] op_sel_hi:[1,0] neg_lo:[0,1] neg_hi:[0,1]
	v_pk_add_f32 v[72:73], v[24:25], v[4:5] neg_lo:[0,1] neg_hi:[0,1]
	v_pk_add_f32 v[4:5], v[24:25], v[4:5]
	v_add_f32_e32 v23, v1, v32
	v_add_f32_e32 v25, v50, v36
	v_sub_f32_e32 v1, v1, v32
	v_sub_f32_e32 v27, v50, v36
	v_add_f32_e32 v26, v28, v44
	v_add_f32_e32 v30, v29, v46
	v_sub_f32_e32 v31, v28, v44
	v_sub_f32_e32 v29, v29, v46
	v_add_f32_e32 v22, v26, v23
	v_add_f32_e32 v24, v30, v25
	v_sub_f32_e32 v26, v23, v26
	v_sub_f32_e32 v28, v25, v30
	v_add_f32_e32 v30, v29, v1
	v_sub_f32_e32 v32, v27, v31
	v_sub_f32_e32 v34, v1, v29
	v_add_f32_e32 v36, v31, v27
	v_add_f32_e32 v1, v48, v39
	v_sub_f32_e32 v23, v49, v38
	v_sub_f32_e32 v25, v48, v39
	v_add_f32_e32 v27, v49, v38
	v_add_f32_e32 v29, v33, v52
	v_add_f32_e32 v31, v40, v47
	v_sub_f32_e32 v33, v33, v52
	v_sub_f32_e32 v35, v40, v47
	v_add_f32_e32 v38, v1, v29
	v_add_f32_e32 v40, v23, v31
	v_sub_f32_e32 v42, v1, v29
	v_sub_f32_e32 v44, v23, v31
	v_add_f32_e32 v46, v25, v35
	v_sub_f32_e32 v48, v27, v33
	v_sub_f32_e32 v50, v25, v35
	v_add_f32_e32 v52, v27, v33
	v_add_f32_e32 v1, v51, v54
	v_add_f32_e32 v23, v53, v37
	v_sub_f32_e32 v25, v51, v54
	v_sub_f32_e32 v27, v53, v37
	v_add_f32_e32 v29, v41, v55
	v_add_f32_e32 v31, v45, v56
	v_sub_f32_e32 v33, v41, v55
	v_sub_f32_e32 v35, v45, v56
	v_add_f32_e32 v54, v29, v1
	v_add_f32_e32 v56, v31, v23
	v_sub_f32_e32 v58, v1, v29
	v_sub_f32_e32 v60, v23, v31
	v_add_f32_e32 v62, v35, v25
	v_sub_f32_e32 v64, v27, v33
	v_sub_f32_e32 v66, v25, v35
	v_add_f32_e32 v68, v33, v27
	v_readlane_b32 s0, v244, 11
	v_mov_b32_e32 v18, v70
	v_mov_b32_e32 v19, v3
	v_mov_b32_e32 v20, v72
	v_mov_b32_e32 v21, v5
	s_cselect_b32 s29, s12, s28
	s_cselect_b32 s42, s0, s89
	v_pk_mov_b32 v[70:71], v[2:3], v[70:71] op_sel:[1,0]
	v_pk_mov_b32 v[72:73], v[4:5], v[72:73] op_sel:[1,0]
	v_mov_b32_e32 v39, v38
	v_mov_b32_e32 v43, v42
	v_mov_b32_e32 v47, v46
	v_mov_b32_e32 v49, v48
	v_mov_b32_e32 v51, v50
	v_mov_b32_e32 v53, v52
	v_mov_b32_e32 v23, v22
	v_mov_b32_e32 v27, v26
	v_mov_b32_e32 v31, v30
	v_mov_b32_e32 v33, v32
	v_mov_b32_e32 v35, v34
	v_mov_b32_e32 v37, v36
	v_mov_b32_e32 v55, v54
	v_mov_b32_e32 v59, v58
	v_mov_b32_e32 v63, v62
	v_mov_b32_e32 v65, v64
	v_mov_b32_e32 v67, v66
	v_mov_b32_e32 v69, v68
	v_pk_mov_b32 v[74:75], v[14:15], v[14:15] op_sel:[1,0]
	v_mov_b32_e32 v25, v24
	v_mov_b32_e32 v41, v40
	v_mov_b32_e32 v57, v56
	v_pk_mov_b32 v[76:77], v[16:17], v[16:17] op_sel:[1,0]
	v_mov_b32_e32 v29, v28
	v_mov_b32_e32 v45, v44
	v_mov_b32_e32 v61, v60
	s_mov_b64 s[34:35], 0
	s_branch .LBB0_446

.LBB0_510:
	v_cvt_f32_i32_e32 v105, v105
	v_cvt_f32_i32_e32 v104, v104
	v_cvt_f32_i32_e32 v119, v108
	v_cvt_f32_i32_e32 v121, v118
	v_mul_f32_e32 v105, 0x39800000, v105
	v_mul_f32_e32 v105, 0.5, v105
	v_mul_f32_e32 v109, 0x39800000, v104
	v_sin_f32_e32 v104, v105
	v_cos_f32_e32 v202, v105
	v_mul_f32_e32 v109, 0.5, v109
	v_sin_f32_e32 v204, v109
	v_pk_mul_f32 v[206:207], v[106:107], v[104:105] op_sel:[1,0] op_sel_hi:[0,0]
	v_fma_f32 v104, v106, v202, v206
	v_fma_f32 v107, v107, v202, -v207
	v_cos_f32_e32 v202, v109
	v_pk_mul_f32 v[204:205], v[112:113], v[204:205] op_sel:[1,0] op_sel_hi:[0,0]
	v_cvt_f32_i32_e32 v117, v117
	v_cvt_f32_i32_e32 v183, v120
	v_fma_f32 v108, v112, v202, v204
	v_fma_f32 v113, v113, v202, -v205
	v_mul_f32_e32 v109, 0x39800000, v119
	v_mul_f32_e32 v109, 0.5, v109
	v_sin_f32_e32 v112, v109
	s_nop 0
	v_cos_f32_e32 v202, v109
	s_nop 0
	v_cvt_f32_i32_e32 v179, v179
	v_pk_mul_f32 v[204:205], v[114:115], v[112:113] op_sel:[1,0] op_sel_hi:[0,0]
	v_fma_f32 v118, v114, v202, v204
	v_fma_f32 v119, v115, v202, -v205
	v_mul_f32_e32 v112, 0x39800000, v121
	v_mul_f32_e32 v114, 0.5, v112
	v_sin_f32_e32 v112, v114
	s_nop 0
	v_cos_f32_e32 v202, v114
	s_nop 0
	v_cvt_f32_i32_e32 v121, v116
	v_pk_mul_f32 v[204:205], v[102:103], v[112:113] op_sel:[1,0] op_sel_hi:[0,0]
	v_fma_f32 v114, v102, v202, v204
	v_mul_f32_e32 v112, 0x39800000, v117
	v_mul_f32_e32 v115, 0.5, v112
	v_sin_f32_e32 v112, v115
	s_nop 0
	v_fma_f32 v103, v103, v202, -v205
	v_cos_f32_e32 v202, v115
	s_nop 0
	v_pk_mul_f32 v[204:205], v[100:101], v[112:113] op_sel:[1,0] op_sel_hi:[0,0]
	v_mov_b32_e32 v115, v103
	v_fma_f32 v116, v100, v202, v204
	v_fma_f32 v101, v101, v202, -v205
	v_mul_f32_e32 v100, 0x39800000, v121
	v_mul_f32_e32 v100, 0.5, v100
	v_sin_f32_e32 v112, v100
	s_nop 0
	v_cos_f32_e32 v202, v100
	s_nop 0
	s_mov_b32 s0, s71
	v_pk_mul_f32 v[204:205], v[98:99], v[112:113] op_sel:[1,0] op_sel_hi:[0,0]
	v_fma_f32 v120, v98, v202, v204
	v_fma_f32 v99, v99, v202, -v205
	v_cvt_f32_i32_e32 v204, v182
	v_mul_f32_e32 v98, 0x39800000, v183
	v_mul_f32_e32 v112, 0.5, v98
	v_sin_f32_e32 v98, v112
	s_nop 0
	v_cos_f32_e32 v112, v112
	s_nop 0
	s_mov_b32 s1, s21
	v_pk_mul_f32 v[182:183], v[96:97], v[98:99] op_sel:[1,0] op_sel_hi:[0,0]
	v_fma_f32 v202, v96, v112, v182
	v_fma_f32 v97, v97, v112, -v183
	v_cvt_f32_i32_e32 v112, v181
	v_mul_f32_e32 v96, 0x39800000, v204
	v_mul_f32_e32 v98, 0.5, v96
	v_sin_f32_e32 v96, v98
	v_cos_f32_e32 v98, v98
	v_mov_b32_e32 v203, v97
	v_cvt_f32_i32_e32 v204, v180
	v_pk_mul_f32 v[182:183], v[94:95], v[96:97] op_sel:[1,0] op_sel_hi:[0,0]
	v_fma_f32 v96, v94, v98, v182
	v_fma_f32 v95, v95, v98, -v183
	v_mul_f32_e32 v97, 0x39800000, v112
	v_mul_f32_e32 v97, 0.5, v97
	v_sin_f32_e32 v98, v97
	v_cos_f32_e32 v112, v97
	v_mov_b32_e32 v97, v95
	s_mov_b32 s22, s21
	v_pk_mul_f32 v[180:181], v[92:93], v[98:99] op_sel:[1,0] op_sel_hi:[0,0]
	v_fma_f32 v182, v92, v112, v180
	v_fma_f32 v93, v93, v112, -v181
	v_mul_f32_e32 v92, 0x39800000, v204
	v_mul_f32_e32 v92, 0.5, v92
	v_sin_f32_e32 v98, v92
	v_cos_f32_e32 v112, v92
	v_add_f32_e32 v220, v182, v104
	v_add_f32_e32 v221, v93, v107
	v_pk_mul_f32 v[180:181], v[90:91], v[98:99] op_sel:[1,0] op_sel_hi:[0,0]
	v_fma_f32 v204, v90, v112, v180
	v_fma_f32 v181, v91, v112, -v181
	v_mul_f32_e32 v90, 0x39800000, v179
	v_mul_f32_e32 v91, 0.5, v90
	v_sin_f32_e32 v90, v91
	s_nop 0
	v_cos_f32_e32 v98, v91
	s_nop 0
	v_cvt_f32_i32_e32 v112, v177
	v_pk_mul_f32 v[90:91], v[88:89], v[90:91] op_sel:[1,0] op_sel_hi:[0,0]
	v_fma_f32 v206, v88, v98, v90
	v_fma_f32 v89, v89, v98, -v91
	v_cvt_f32_i32_e32 v91, v176
	v_mul_f32_e32 v88, 0x39800000, v112
	v_mul_f32_e32 v90, 0.5, v88
	v_sin_f32_e32 v88, v90
	v_cos_f32_e32 v90, v90
	v_mov_b32_e32 v207, v89
	v_pk_add_f32 v[216:217], v[206:207], v[118:119]
	v_pk_mul_f32 v[88:89], v[86:87], v[88:89] op_sel:[1,0] op_sel_hi:[0,0]
	v_fma_f32 v176, v86, v90, v88
	v_fma_f32 v209, v87, v90, -v89
	v_mul_f32_e32 v86, 0x39800000, v91
	v_mul_f32_e32 v87, 0.5, v86
	v_sin_f32_e32 v86, v87
	s_nop 0
	v_cos_f32_e32 v88, v87
	s_nop 0
	v_cvt_f32_i32_e32 v89, v175
	v_pk_mul_f32 v[86:87], v[84:85], v[86:87] op_sel:[1,0] op_sel_hi:[0,0]
	v_add_f32_e32 v224, v176, v114
	v_add_f32_e32 v225, v209, v115
	v_fma_f32 v210, v84, v88, v86
	v_fma_f32 v213, v85, v88, -v87
	v_mul_f32_e32 v84, 0x39800000, v89
	v_mul_f32_e32 v85, 0.5, v84
	v_sin_f32_e32 v84, v85
	s_nop 0
	v_cos_f32_e32 v86, v85
	s_nop 0
	v_cvt_f32_i32_e32 v87, v174
	v_pk_mul_f32 v[84:85], v[4:5], v[84:85] op_sel:[1,0] op_sel_hi:[0,0]
	v_add_f32_e32 v218, v210, v116
	v_add_f32_e32 v219, v213, v101
	v_fma_f32 v174, v4, v86, v84
	v_mul_f32_e32 v87, 0x39800000, v87
	v_mul_f32_e32 v87, 0.5, v87
	v_fma_f32 v215, v5, v86, -v85
	v_mov_b32_e32 v5, v127
	v_sin_f32_e32 v88, v87
	v_cos_f32_e32 v4, v87
	v_cvt_f32_i32_e32 v5, v5
	v_pk_mul_f32 v[84:85], v[2:3], v[88:89] op_sel:[1,0] op_sel_hi:[0,0]
	s_barrier
	v_fma_f32 v88, v2, v4, v84
	v_fma_f32 v89, v3, v4, -v85
	s_nop 0
	v_mul_f32_e32 v2, 0x39800000, v5
	v_mul_f32_e32 v3, 0.5, v2
	v_sin_f32_e32 v2, v3
	s_nop 0
	v_cos_f32_e32 v4, v3
	s_nop 0
	v_mov_b32_e32 v3, v78
	v_ashrrev_i32_e32 v84, 31, v3
	v_lshrrev_b32_e32 v84, 24, v84
	v_and_b32_e32 v5, 0xff, v3
	v_add_lshl_u32 v3, v3, v84, 4
	v_and_or_b32 v3, v3, s87, v5
	v_ashrrev_i32_e32 v84, 4, v3
	v_lshlrev_b32_e32 v3, 3, v3
	v_lshl_add_u32 v179, v84, 3, v3
	v_pk_add_f32 v[90:91], v[88:89], v[202:203]
	v_cvt_f32_i32_e32 v3, v5
	v_add_f32_e32 v84, v174, v120
	v_add_f32_e32 v85, v215, v99
	v_add_f32_e32 v86, v204, v108
	v_add_f32_e32 v87, v181, v113
	v_pk_add_f32 v[202:203], v[88:89], v[202:203] neg_lo:[0,1] neg_hi:[0,1]
	v_add_f32_e32 v3, v3, v3
	v_mul_f32_e32 v3, 0x39800000, v3
	v_mul_f32_e32 v3, 0.5, v3
	v_sin_f32_e32 v100, v3
	v_cos_f32_e32 v230, v3
	v_pk_mul_f32 v[2:3], v[110:111], v[2:3] op_sel:[1,0] op_sel_hi:[0,0]
	v_fma_f32 v232, v110, v4, v2
	v_fma_f32 v111, v111, v4, -v3
	v_pk_add_f32 v[226:227], v[84:85], v[86:87] neg_lo:[0,1] neg_hi:[0,1]
	v_add_f32_e32 v234, v96, v232
	v_add_f32_e32 v235, v97, v111
	v_pk_add_f32 v[2:3], v[90:91], v[216:217]
	v_pk_add_f32 v[4:5], v[84:85], v[86:87]
	v_pk_add_f32 v[84:85], v[218:219], v[220:221]
	v_pk_add_f32 v[86:87], v[224:225], v[234:235]
	v_pk_add_f32 v[236:237], v[2:3], v[84:85]
	v_pk_add_f32 v[238:239], v[4:5], v[86:87]
	v_pk_add_f32 v[88:89], v[206:207], v[118:119] neg_lo:[0,1] neg_hi:[0,1]
	v_pk_mul_f32 v[228:229], v[226:227], s[20:21] op_sel_hi:[1,0]
	v_pk_add_f32 v[240:241], v[236:237], v[238:239]
	v_pk_mov_b32 v[118:119], v[88:89], v[88:89] op_sel:[1,0]
	v_add_f32_e32 v206, v202, v89
	v_sub_f32_e32 v207, v203, v88
	v_pk_fma_f32 v[226:227], v[226:227], s[20:21], v[228:229] op_sel:[0,0,1] op_sel_hi:[1,0,0]
	ds_write_b64 v179, v[240:241]
	v_mov_b32_e32 v89, v229
	v_mov_b32_e32 v229, v174
	v_sub_f32_e32 v121, v229, v120
	v_sub_f32_e32 v120, v210, v116
	v_sub_f32_e32 v112, v93, v107
	v_sub_f32_e32 v113, v181, v113
	v_mov_b32_e32 v180, v104
	v_sub_f32_e32 v109, v204, v108
	v_sub_f32_e32 v108, v182, v180
	v_mov_b32_e32 v233, v107
	v_sub_f32_e32 v106, v176, v114
	v_sub_f32_e32 v107, v213, v101
	v_sub_f32_e32 v94, v95, v111
	v_sub_f32_e32 v95, v182, v104
	v_sub_f32_e32 v102, v209, v103
	v_sub_f32_e32 v103, v210, v116
	v_sub_f32_e32 v92, v96, v232
	v_sub_f32_e32 v93, v93, v233
	v_pk_add_f32 v[104:105], v[106:107], v[94:95] neg_lo:[0,1] neg_hi:[0,1]
	v_sub_f32_e32 v98, v213, v101
	v_sub_f32_e32 v99, v215, v99
	v_pk_add_f32 v[96:97], v[102:103], v[92:93]
	v_pk_add_f32 v[106:107], v[106:107], v[94:95]
	v_mov_b32_e32 v94, v104
	v_mul_f32_e32 v104, 0x3ec3ef15, v104
	v_pk_add_f32 v[110:111], v[120:121], v[112:113] neg_lo:[0,1] neg_hi:[0,1]
	v_pk_add_f32 v[114:115], v[98:99], v[108:109]
	v_pk_add_f32 v[102:103], v[102:103], v[92:93] neg_lo:[0,1] neg_hi:[0,1]
	v_mul_f32_e32 v98, 0x3f6c835e, v96
	v_mov_b32_e32 v175, v203
	v_mov_b32_e32 v203, v104
	v_add_f32_e32 v104, v121, v113
	s_mov_b32 s23, s71
	v_mul_f32_e32 v116, 0x3ec3ef15, v111
	v_mul_f32_e32 v174, 0x3f6c835e, v115
	v_mul_f32_e32 v101, 0x3f3504f3, v97
	v_mov_b32_e32 v95, v107
	v_mov_b32_e32 v117, v119
	v_mov_b32_e32 v119, v98
	v_sub_f32_e32 v98, v99, v109
	v_pk_mul_f32 v[108:109], v[104:105], s[22:23] op_sel_hi:[0,1]
	v_pk_mul_f32 v[106:107], v[106:107], s[0:1] op_sel_hi:[0,1]
	v_mul_f32_e32 v120, 0x3f3504f3, v105
	v_pk_mul_f32 v[92:93], v[110:111], s[20:21]
	v_mul_f32_e32 v110, s72, v96
	v_mul_f32_e32 v111, s73, v103
	v_pk_add_f32 v[96:97], v[174:175], v[116:117]
	v_fma_f32 v112, v98, s0, v108
	v_fma_f32 v113, v98, s1, -v109
	v_fma_f32 v116, v102, s22, v106
	v_fma_f32 v117, v102, s23, -v107
	v_add_f32_e32 v98, v120, v101
	v_fma_f32 v99, v105, s20, -v101
	v_pk_add_f32 v[104:105], v[206:207], v[98:99]
	v_pk_add_f32 v[102:103], v[112:113], v[116:117]
	v_xor_b32_e32 v231, 0x80000000, v100
	v_pk_add_f32 v[106:107], v[104:105], v[102:103]
	v_pk_add_f32 v[224:225], v[224:225], v[234:235] neg_lo:[0,1] neg_hi:[0,1]
	v_pk_fma_f32 v[94:95], v[94:95], s[30:31], v[110:111] neg_lo:[0,0,1] neg_hi:[0,0,1]
	v_pk_add_f32 v[110:111], v[202:203], v[118:119] neg_lo:[0,1] neg_hi:[0,1]
	v_pk_mul_f32 v[118:119], v[100:101], v[106:107] op_sel_hi:[0,1]
	v_mul_f32_e32 v235, 0x3f3504f3, v224
	v_fma_f32 v120, v230, v106, v119
	v_fma_f32 v121, v230, v107, -v118
	v_pk_add_f32 v[222:223], v[218:219], v[220:221] neg_lo:[0,1] neg_hi:[0,1]
	v_mul_f32_e32 v218, 0x3f3504f3, v225
	v_mov_b32_e32 v224, v219
	v_mov_b32_e32 v101, v230
	v_mul_f32_e32 v225, 0xbf3504f3, v225
	v_mov_b32_e32 v88, v90
	v_sub_f32_e32 v90, v218, v235
	v_sub_f32_e32 v91, v91, v217
	v_mov_b32_e32 v218, v226
	v_mov_b32_e32 v219, v222
	v_mul_f32_e32 v106, v100, v100
	v_mul_f32_e32 v107, v101, v231
	v_sub_f32_e32 v88, v88, v216
	v_sub_f32_e32 v89, v89, v228
	v_sub_f32_e32 v220, v224, v221
	v_sub_f32_e32 v221, v225, v235
	v_pk_add_f32 v[216:217], v[90:91], v[222:223] op_sel:[1,0] op_sel_hi:[0,1]
	v_add_f32_e32 v222, v90, v218
	v_sub_f32_e32 v219, v91, v219
	v_pk_fma_f32 v[118:119], v[230:231], v[230:231], v[106:107] op_sel_hi:[0,1,1] neg_lo:[0,0,1] neg_hi:[0,0,1]
	v_pk_fma_f32 v[106:107], v[230:231], v[230:231], v[106:107] op_sel_hi:[0,1,1]
	v_pk_add_f32 v[224:225], v[88:89], v[220:221]
	v_pk_add_f32 v[226:227], v[226:227], v[90:91] neg_lo:[0,1] neg_hi:[0,1]
	v_pk_add_f32 v[90:91], v[88:89], v[220:221] neg_lo:[0,1] neg_hi:[0,1]
	v_add_f32_e32 v220, v224, v222
	v_add_f32_e32 v221, v225, v219
	ds_write_b64 v179, v[120:121] offset:2176
	v_mov_b32_e32 v120, v118
	v_mov_b32_e32 v121, v107
	v_mul_f32_e32 v180, v107, v107
	v_mul_f32_e32 v181, v107, v118
	v_pk_mul_f32 v[106:107], v[220:221], v[106:107] op_sel:[1,1] op_sel_hi:[0,1]
	v_pk_fma_f32 v[182:183], v[118:119], v[120:121], v[180:181] op_sel_hi:[0,1,1] neg_lo:[0,0,1] neg_hi:[0,0,1]
	v_pk_fma_f32 v[180:181], v[118:119], v[120:121], v[180:181] op_sel_hi:[0,1,1]
	v_fma_f32 v212, v220, v118, -v106
	v_fma_f32 v213, v221, v118, v107
	v_pk_mul_f32 v[118:119], v[120:121], v[180:181] op_sel:[0,1]
	v_pk_add_f32 v[98:99], v[206:207], v[98:99] neg_lo:[0,1] neg_hi:[0,1]
	v_fma_f32 v206, v120, v182, -v119
	v_fma_f32 v119, v121, v182, v118
	v_pk_add_f32 v[88:89], v[216:217], v[226:227]
	ds_write_b64 v179, v[212:213] offset:4352
	v_mov_b32_e32 v213, v119
	v_sub_f32_e32 v216, v216, v226
	v_mov_b32_e32 v212, v206
	v_pk_add_f32 v[214:215], v[90:91], v[90:91] op_sel:[0,1] op_sel_hi:[0,1]
	v_mul_f32_e32 v118, v216, v119
	v_mul_f32_e32 v119, v216, v206
	v_mov_b32_e32 v202, v182
	v_mov_b32_e32 v203, v181
	v_fma_f32 v206, v214, v206, -v118
	v_fma_f32 v207, v215, v213, v119
	v_pk_mov_b32 v[210:211], v[180:181], v[182:183] op_sel:[1,0]
	v_pk_mul_f32 v[180:181], v[202:203], v[180:181] op_sel:[0,1]
	ds_write_b64 v179, v[206:207] offset:13056
	v_pk_fma_f32 v[206:207], v[182:183], v[202:203], v[180:181] op_sel:[0,0,1] op_sel_hi:[0,1,0] neg_lo:[0,0,1] neg_hi:[0,0,1]
	v_pk_fma_f32 v[180:181], v[182:183], v[202:203], v[180:181] op_sel:[0,0,1] op_sel_hi:[0,1,0]
	s_mov_b32 s70, s20
	v_mov_b32_e32 v231, v100
	v_pk_mov_b32 v[216:217], v[180:181], v[206:207] op_sel:[1,0]
	v_pk_fma_f32 v[92:93], v[114:115], s[70:71], v[92:93] neg_lo:[0,0,1] neg_hi:[0,0,1]
	v_pk_mul_f32 v[174:175], v[230:231], v[120:121]
	v_pk_mul_f32 v[176:177], v[100:101], v[120:121]
	v_pk_mul_f32 v[208:209], v[100:101], v[202:203]
	v_mov_b32_e32 v214, v206
	v_mov_b32_e32 v215, v181
	v_pk_mul_f32 v[100:101], v[100:101], v[216:217] op_sel_hi:[0,1]
	v_pk_add_f32 v[108:109], v[92:93], v[110:111]
	v_pk_add_f32 v[114:115], v[96:97], v[94:95]
	v_pk_mul_f32 v[204:205], v[230:231], v[202:203]
	v_pk_add_f32 v[106:107], v[112:113], v[116:117] neg_lo:[0,1] neg_hi:[0,1]
	v_fma_f32 v220, v230, v214, v100
	v_fma_f32 v101, v230, v215, -v101
	v_mov_b32_e32 v230, v174
	v_pk_mov_b32 v[174:175], v[174:175], v[176:177] op_sel:[1,0]
	v_pk_add_f32 v[102:103], v[104:105], v[102:103] neg_lo:[0,1] neg_hi:[0,1]
	v_pk_add_f32 v[104:105], v[114:115], v[108:109]
	v_pk_add_f32 v[112:113], v[98:99], v[106:107] op_sel:[0,1] op_sel_hi:[1,0]
	v_pk_add_f32 v[98:99], v[98:99], v[106:107] op_sel:[0,1] op_sel_hi:[1,0] neg_lo:[0,1] neg_hi:[0,1]
	v_pk_add_f32 v[118:119], v[236:237], v[238:239] neg_lo:[0,1] neg_hi:[0,1]
	v_add_f32_e32 v176, v230, v174
	v_sub_f32_e32 v174, v230, v174
	v_sub_f32_e32 v175, v177, v175
	v_mov_b32_e32 v238, v204
	v_mov_b32_e32 v239, v209
	v_pk_mov_b32 v[204:205], v[204:205], v[208:209] op_sel:[1,0]
	v_pk_mul_f32 v[232:233], v[104:105], v[174:175] op_sel:[0,1]
	v_add_f32_e32 v208, v238, v204
	v_sub_f32_e32 v205, v239, v205
	v_mov_b32_e32 v107, v99
	v_fma_f32 v234, v104, v176, -v233
	v_fma_f32 v235, v105, v176, v232
	v_mul_f32_e32 v116, v99, v205
	v_mul_f32_e32 v117, v112, v205
	v_mov_b32_e32 v227, v101
	v_pk_mul_f32 v[104:105], v[202:203], v[174:175] op_sel:[0,1]
	v_mov_b32_e32 v239, v205
	v_fma_f32 v204, v112, v208, -v116
	v_fma_f32 v205, v107, v208, v117
	v_mov_b32_e32 v231, v175
	v_fma_f32 v174, v202, v176, -v105
	v_fma_f32 v105, v203, v176, v104
	v_mul_f32_e32 v100, v103, v101
	v_mul_f32_e32 v101, v103, v220
	v_mov_b32_e32 v230, v176
	v_mov_b32_e32 v176, v174
	v_mov_b32_e32 v177, v105
	v_mov_b32_e32 v238, v208
	ds_write_b64 v179, v[204:205] offset:10880
	v_fma_f32 v204, v102, v220, -v100
	v_fma_f32 v205, v102, v227, v101
	v_pk_mul_f32 v[180:181], v[118:119], v[180:181] op_sel:[1,1] op_sel_hi:[0,1]
	v_pk_mul_f32 v[228:229], v[120:121], v[214:215]
	v_pk_mul_f32 v[120:121], v[120:121], v[216:217]
	ds_write_b64 v179, v[234:235] offset:6528
	v_pk_mul_f32 v[232:233], v[230:231], v[214:215]
	v_pk_mul_f32 v[234:235], v[202:203], v[214:215]
	v_pk_mul_f32 v[106:107], v[214:215], v[238:239]
	v_pk_mul_f32 v[100:101], v[214:215], v[212:213]
	v_pk_mul_f32 v[208:209], v[214:215], v[176:177]
	v_fma_f32 v214, v118, v206, -v180
	v_fma_f32 v215, v119, v206, v181
	v_sub_f32_e32 v118, v224, v222
	v_sub_f32_e32 v119, v219, v225
	v_pk_add_f32 v[120:121], v[120:121], v[120:121] op_sel:[0,1] op_sel_hi:[0,1]
	v_pk_mul_f32 v[120:121], v[118:119], v[120:121] op_sel:[1,0] op_sel_hi:[0,1]
	v_pk_add_f32 v[180:181], v[228:229], v[228:229] op_sel:[0,1] op_sel_hi:[0,1] neg_lo:[0,1] neg_hi:[0,1]
	ds_write_b64 v179, v[214:215] offset:17408
	ds_write_b64 v179, v[204:205] offset:19584
	v_fma_f32 v204, v118, v180, -v120
	v_fma_f32 v205, v119, v181, v121
	v_pk_mul_f32 v[230:231], v[230:231], v[216:217]
	v_mov_b32_e32 v119, v115
	v_sub_f32_e32 v108, v108, v114
	v_sub_f32_e32 v109, v119, v109
	v_pk_add_f32 v[114:115], v[230:231], v[230:231] op_sel:[0,1] op_sel_hi:[0,1]
	v_pk_add_f32 v[2:3], v[2:3], v[84:85] neg_lo:[0,1] neg_hi:[0,1]
	v_pk_add_f32 v[4:5], v[4:5], v[86:87] neg_lo:[0,1] neg_hi:[0,1]
	v_pk_mul_f32 v[114:115], v[108:109], v[114:115] op_sel:[1,0] op_sel_hi:[0,1]
	v_pk_add_f32 v[118:119], v[232:233], v[232:233] op_sel:[0,1] op_sel_hi:[0,1] neg_lo:[0,1] neg_hi:[0,1]
	v_pk_add_f32 v[84:85], v[2:3], v[4:5] op_sel:[0,1] op_sel_hi:[1,0]
	v_pk_add_f32 v[2:3], v[2:3], v[4:5] op_sel:[0,1] op_sel_hi:[1,0] neg_lo:[0,1] neg_hi:[0,1]
	v_fma_f32 v120, v108, v118, -v114
	v_fma_f32 v121, v109, v119, v115
	v_pk_mul_f32 v[86:87], v[2:3], v[210:211] op_sel:[1,0]
	v_pk_mul_f32 v[236:237], v[202:203], v[216:217]
	v_fma_f32 v108, v84, v182, -v86
	v_fma_f32 v109, v84, v203, v87
	v_mov_b32_e32 v5, v85
	v_pk_add_f32 v[86:87], v[236:237], v[236:237] op_sel:[0,1] op_sel_hi:[0,1]
	v_mul_f32_e32 v84, v85, v86
	v_mul_f32_e32 v85, v2, v87
	v_pk_add_f32 v[86:87], v[234:235], v[234:235] op_sel:[0,1] op_sel_hi:[0,1] neg_lo:[0,1] neg_hi:[0,1]
	v_pk_mul_f32 v[116:117], v[216:217], v[238:239]
	v_fma_f32 v2, v2, v86, -v84
	v_fma_f32 v3, v5, v87, v85
	v_pk_add_f32 v[84:85], v[116:117], v[116:117] op_sel:[0,1] op_sel_hi:[0,1]
	ds_write_b64 v179, v[2:3] offset:26112
	v_mov_b32_e32 v3, v113
	v_mul_f32_e32 v4, v113, v84
	v_mul_f32_e32 v5, v98, v85
	v_pk_add_f32 v[84:85], v[106:107], v[106:107] op_sel:[0,1] op_sel_hi:[0,1] neg_lo:[0,1] neg_hi:[0,1]
	v_fma_f32 v86, v98, v84, -v4
	v_fma_f32 v87, v3, v85, v5
	v_pk_mul_f32 v[102:103], v[216:217], v[212:213]
	v_mov_b32_e32 v3, v100
	v_sub_f32_e32 v2, v90, v91
	v_sub_f32_e32 v3, v3, v101
	v_pk_add_f32 v[84:85], v[102:103], v[102:103] op_sel:[0,1] op_sel_hi:[0,1]
	v_mul_f32_e32 v4, v88, v84
	v_mul_f32_e32 v5, v2, v85
	v_pk_mov_b32 v[84:85], v[2:3], v[88:89] op_sel:[1,0]
	ds_write_b64 v179, v[86:87] offset:28288
	v_fma_f32 v86, v2, v84, -v4
	v_fma_f32 v87, v3, v85, v5
	v_sub_f32_e32 v2, v93, v111
	v_sub_f32_e32 v3, v96, v94
	v_sub_f32_e32 v4, v110, v92
	v_sub_f32_e32 v5, v97, v95
	v_pk_add_f32 v[84:85], v[4:5], v[2:3]
	v_pk_add_f32 v[2:3], v[4:5], v[2:3] neg_lo:[0,1] neg_hi:[0,1]
	ds_write_b64 v179, v[86:87] offset:30464
	v_mul_f32_e32 v86, v3, v105
	v_mul_f32_e32 v87, v3, v174
	v_pk_mul_f32 v[212:213], v[216:217], v[176:177]
	v_fma_f32 v88, v84, v174, -v86
	v_fma_f32 v89, v84, v177, v87
	v_mov_b32_e32 v5, v85
	v_pk_add_f32 v[86:87], v[212:213], v[212:213] op_sel:[0,1] op_sel_hi:[0,1]
	v_mul_f32_e32 v84, v85, v86
	v_mul_f32_e32 v85, v2, v87
	v_pk_add_f32 v[86:87], v[208:209], v[208:209] op_sel:[0,1] op_sel_hi:[0,1] neg_lo:[0,1] neg_hi:[0,1]
	v_fma_f32 v2, v2, v86, -v84
	v_fma_f32 v3, v5, v87, v85
	ds_write_b64 v179, v[204:205] offset:21760
	ds_write_b64 v179, v[2:3] offset:32640
	v_mov_b32_e32 v2, v78
	ds_write_b64 v179, v[120:121] offset:23936
	ds_write_b64 v179, v[108:109] offset:8704
	ds_write_b64 v179, v[88:89] offset:15232
	s_waitcnt lgkmcnt(0)
	s_barrier
	s_mov_b32 s2, s20
	v_ashrrev_i32_e32 v3, 31, v2
	v_lshrrev_b32_e32 v3, 28, v3
	v_and_b32_e32 v179, 15, v2
	v_add_u32_e32 v2, v2, v3
	v_ashrrev_i32_e32 v2, 4, v2
	v_lshlrev_b32_e32 v3, 11, v2
	v_lshl_add_u32 v2, v2, 7, v3
	v_lshl_or_b32 v242, v179, 3, v2
	ds_read2_b64 v[90:93], v242 offset1:17
	ds_read2_b64 v[94:97], v242 offset0:68 offset1:85
	ds_read2_b64 v[98:101], v242 offset0:136 offset1:153
	ds_read2_b64 v[102:105], v242 offset0:170 offset1:187
	ds_read2_b64 v[106:109], v242 offset0:204 offset1:221
	ds_read2_b64 v[110:113], v242 offset0:238 offset1:255
	ds_read2_b64 v[114:117], v242 offset0:34 offset1:51
	ds_read2_b64 v[118:121], v242 offset0:102 offset1:119
	s_waitcnt lgkmcnt(5)
	v_pk_add_f32 v[88:89], v[98:99], v[90:91]
	s_waitcnt lgkmcnt(2)
	v_pk_mov_b32 v[210:211], v[104:105], v[112:113] op_sel:[1,0]
	s_waitcnt lgkmcnt(1)
	v_pk_add_f32 v[206:207], v[116:117], v[104:105]
	s_waitcnt lgkmcnt(0)
	v_pk_add_f32 v[208:209], v[120:121], v[112:113]
	v_mov_b32_e32 v105, v113
	v_pk_add_f32 v[112:113], v[206:207], v[208:209] neg_lo:[0,1] neg_hi:[0,1]
	v_sub_f32_e32 v210, v117, v210
	v_sub_f32_e32 v211, v120, v211
	v_pk_add_f32 v[86:87], v[206:207], v[208:209]
	v_mul_f32_e32 v206, 0x3f3504f3, v113
	v_mul_f32_e32 v209, 0xbf3504f3, v113
	v_cvt_f32_i32_e32 v113, v179
	v_sub_f32_e32 v104, v116, v104
	v_sub_f32_e32 v105, v121, v105
	v_pk_add_f32 v[98:99], v[90:91], v[98:99] neg_lo:[0,1] neg_hi:[0,1]
	v_add_f32_e32 v113, v113, v113
	v_pk_add_f32 v[90:91], v[94:95], v[106:107] neg_lo:[0,1] neg_hi:[0,1]
	v_pk_add_f32 v[174:175], v[106:107], v[94:95]
	v_pk_add_f32 v[176:177], v[92:93], v[100:101]
	v_pk_add_f32 v[180:181], v[96:97], v[108:109]
	v_sub_f32_e32 v116, v104, v105
	v_mul_f32_e32 v113, 0x3b800000, v113
	v_pk_mov_b32 v[94:95], v[90:91], v[90:91] op_sel:[1,0]
	v_add_f32_e32 v106, v98, v91
	v_sub_f32_e32 v107, v99, v90
	v_pk_add_f32 v[104:105], v[104:105], v[104:105] op_sel:[0,1] op_sel_hi:[0,1]
	v_pk_add_f32 v[4:5], v[176:177], v[180:181]
	v_pk_add_f32 v[182:183], v[114:115], v[102:103]
	v_pk_add_f32 v[202:203], v[118:119], v[110:111]
	v_pk_add_f32 v[176:177], v[176:177], v[180:181] neg_lo:[0,1] neg_hi:[0,1]
	v_mul_f32_e32 v113, 0.5, v113
	v_pk_add_f32 v[90:91], v[210:211], v[210:211] op_sel:[0,1] op_sel_hi:[0,1] neg_lo:[0,1] neg_hi:[0,1]
	v_pk_mul_f32 v[104:105], v[104:105], s[0:1]
	v_pk_add_f32 v[84:85], v[182:183], v[202:203]
	v_pk_add_f32 v[204:205], v[182:183], v[202:203] neg_lo:[0,1] neg_hi:[0,1]
	v_add_f32_e32 v120, v210, v211
	v_pk_mul_f32 v[180:181], v[176:177], s[20:21] op_sel_hi:[1,0]
	v_mul_f32_e32 v112, 0x3f3504f3, v112
	v_sin_f32_e32 v182, v113
	s_nop 1
	v_cos_f32_e32 v218, v113
	s_nop 1
	v_fma_f32 v210, v90, s22, v104
	v_fma_f32 v211, v91, s23, -v105
	v_pk_add_f32 v[2:3], v[88:89], v[174:175]
	v_mov_b32_e32 v90, v88
	v_sub_f32_e32 v88, v206, v112
	v_sub_f32_e32 v89, v89, v175
	v_sub_f32_e32 v90, v90, v174
	v_sub_f32_e32 v91, v181, v180
	v_mov_b32_e32 v105, v112
	v_pk_add_f32 v[112:113], v[88:89], v[204:205] op_sel:[1,0] op_sel_hi:[0,1]
	v_mov_b32_e32 v175, v204
	v_sub_f32_e32 v104, v183, v203
	v_sub_f32_e32 v105, v209, v105
	v_sub_f32_e32 v204, v114, v102
	v_sub_f32_e32 v205, v92, v100
	v_sub_f32_e32 v206, v119, v111
	v_sub_f32_e32 v207, v97, v109
	v_mul_f32_e32 v179, 0x3f6c835e, v120
	v_mul_f32_e32 v220, 0x3ec3ef15, v116
	v_sub_f32_e32 v92, v115, v103
	v_sub_f32_e32 v93, v93, v101
	v_sub_f32_e32 v97, v96, v108
	v_sub_f32_e32 v96, v118, v110
	v_pk_add_f32 v[102:103], v[204:205], v[206:207] neg_lo:[0,1] neg_hi:[0,1]
	v_pk_fma_f32 v[176:177], v[176:177], s[20:21], v[180:181] op_sel:[0,0,1] op_sel_hi:[1,0,0]
	v_pk_add_f32 v[208:209], v[204:205], v[206:207]
	v_pk_add_f32 v[100:101], v[92:93], v[96:97] neg_lo:[0,1] neg_hi:[0,1]
	v_pk_add_f32 v[92:93], v[92:93], v[96:97]
	v_mov_b32_e32 v109, v99
	v_mov_b32_e32 v97, v95
	v_mov_b32_e32 v174, v176
	v_pk_add_f32 v[176:177], v[176:177], v[88:89] neg_lo:[0,1] neg_hi:[0,1]
	v_mul_f32_e32 v96, 0x3ec3ef15, v103
	v_pk_mul_f32 v[110:111], v[102:103], s[20:21]
	v_mul_f32_e32 v103, s73, v102
	v_mul_f32_e32 v102, s72, v120
	v_sub_f32_e32 v94, v98, v94
	v_sub_f32_e32 v95, v220, v179
	v_pk_mul_f32 v[98:99], v[208:209], s[22:23] op_sel:[1,0]
	v_add_f32_e32 v180, v88, v174
	v_sub_f32_e32 v175, v89, v175
	v_pk_add_f32 v[88:89], v[112:113], v[176:177]
	v_mul_f32_e32 v108, 0x3f6c835e, v93
	v_mul_f32_e32 v113, 0x3f3504f3, v208
	v_mul_f32_e32 v114, 0x3f3504f3, v100
	v_pk_fma_f32 v[110:111], v[92:93], s[70:71], v[110:111] neg_lo:[0,0,1] neg_hi:[0,0,1]
	v_fma_f32 v93, v92, s31, -v103
	v_fma_f32 v92, v116, s30, -v102
	v_fma_f32 v102, v101, s0, v98
	v_fma_f32 v103, v101, s1, -v99
	v_pk_add_f32 v[96:97], v[108:109], v[96:97]
	v_add_f32_e32 v98, v114, v113
	v_fma_f32 v99, v100, s20, -v113
	v_pk_add_f32 v[100:101], v[106:107], v[98:99]
	v_pk_add_f32 v[108:109], v[102:103], v[210:211]
	v_xor_b32_e32 v219, 0x80000000, v182
	v_pk_add_f32 v[114:115], v[108:109], v[100:101]
	v_pk_add_f32 v[212:213], v[2:3], v[84:85]
	v_pk_mul_f32 v[120:121], v[182:183], v[114:115] op_sel_hi:[0,1]
	v_fma_f32 v204, v218, v114, v121
	v_fma_f32 v205, v218, v115, -v120
	v_mov_b32_e32 v183, v218
	v_pk_add_f32 v[214:215], v[4:5], v[86:87]
	v_mul_f32_e32 v114, v182, v182
	v_mul_f32_e32 v115, v183, v219
	v_pk_add_f32 v[216:217], v[214:215], v[212:213]
	v_pk_fma_f32 v[120:121], v[218:219], v[218:219], v[114:115] op_sel_hi:[0,1,1] neg_lo:[0,0,1] neg_hi:[0,0,1]
	v_pk_fma_f32 v[114:115], v[218:219], v[218:219], v[114:115] op_sel_hi:[0,1,1]
	v_pk_add_f32 v[202:203], v[90:91], v[104:105]
	ds_write2_b64 v242, v[216:217], v[204:205] offset1:17
	v_pk_add_f32 v[90:91], v[90:91], v[104:105] neg_lo:[0,1] neg_hi:[0,1]
	v_add_f32_e32 v104, v202, v180
	v_add_f32_e32 v105, v203, v175
	v_mov_b32_e32 v204, v120
	v_mov_b32_e32 v205, v115
	v_mul_f32_e32 v216, v115, v115
	v_mul_f32_e32 v217, v115, v120
	v_pk_mul_f32 v[114:115], v[104:105], v[114:115] op_sel:[1,1] op_sel_hi:[0,1]
	v_pk_fma_f32 v[220:221], v[120:121], v[204:205], v[216:217] op_sel_hi:[0,1,1] neg_lo:[0,0,1] neg_hi:[0,0,1]
	v_pk_fma_f32 v[216:217], v[120:121], v[204:205], v[216:217] op_sel_hi:[0,1,1]
	v_fma_f32 v230, v104, v120, -v114
	v_fma_f32 v231, v105, v120, v115
	v_pk_mul_f32 v[114:115], v[204:205], v[216:217] op_sel:[0,1]
	v_pk_add_f32 v[102:103], v[102:103], v[210:211] neg_lo:[0,1] neg_hi:[0,1]
	v_fma_f32 v120, v204, v220, -v115
	v_fma_f32 v115, v205, v220, v114
	v_sub_f32_e32 v112, v112, v176
	v_mov_b32_e32 v211, v115
	v_mov_b32_e32 v219, v182
	v_mov_b32_e32 v222, v220
	v_mov_b32_e32 v223, v217
	v_pk_add_f32 v[232:233], v[90:91], v[90:91] op_sel:[0,1] op_sel_hi:[0,1]
	v_mul_f32_e32 v113, v112, v120
	v_mul_f32_e32 v112, v112, v115
	v_pk_mul_f32 v[206:207], v[218:219], v[204:205]
	v_pk_mul_f32 v[208:209], v[182:183], v[204:205]
	v_mov_b32_e32 v210, v120
	v_fma_f32 v114, v232, v120, -v112
	v_pk_mul_f32 v[120:121], v[222:223], v[216:217] op_sel:[0,1]
	v_pk_add_f32 v[100:101], v[100:101], v[108:109] neg_lo:[0,1] neg_hi:[0,1]
	v_pk_add_f32 v[108:109], v[110:111], v[94:95]
	v_pk_add_f32 v[116:117], v[96:97], v[92:93]
	v_fma_f32 v115, v233, v211, v113
	v_pk_fma_f32 v[176:177], v[220:221], v[222:223], v[120:121] op_sel:[0,0,1] op_sel_hi:[0,1,0] neg_lo:[0,0,1] neg_hi:[0,0,1]
	v_pk_fma_f32 v[120:121], v[220:221], v[222:223], v[120:121] op_sel:[0,0,1] op_sel_hi:[0,1,0]
	v_mov_b32_e32 v234, v206
	v_pk_mov_b32 v[206:207], v[206:207], v[208:209] op_sel:[1,0]
	v_pk_add_f32 v[118:119], v[108:109], v[116:117]
	v_pk_add_f32 v[112:113], v[212:213], v[214:215] neg_lo:[0,1] neg_hi:[0,1]
	v_pk_mov_b32 v[214:215], v[120:121], v[176:177] op_sel:[1,0]
	v_add_f32_e32 v208, v234, v206
	v_sub_f32_e32 v206, v234, v206
	v_sub_f32_e32 v207, v209, v207
	v_pk_mul_f32 v[224:225], v[218:219], v[222:223]
	v_pk_mul_f32 v[226:227], v[182:183], v[222:223]
	v_pk_add_f32 v[98:99], v[106:107], v[98:99] neg_lo:[0,1] neg_hi:[0,1]
	v_mov_b32_e32 v212, v176
	v_mov_b32_e32 v213, v121
	v_pk_mul_f32 v[182:183], v[182:183], v[214:215] op_sel_hi:[0,1]
	v_pk_mul_f32 v[236:237], v[118:119], v[206:207] op_sel:[0,1]
	v_pk_mov_b32 v[228:229], v[216:217], v[220:221] op_sel:[1,0]
	v_pk_add_f32 v[104:105], v[98:99], v[102:103] op_sel:[0,1] op_sel_hi:[1,0]
	v_pk_add_f32 v[98:99], v[98:99], v[102:103] op_sel:[0,1] op_sel_hi:[1,0] neg_lo:[0,1] neg_hi:[0,1]
	v_fma_f32 v216, v218, v212, v182
	v_fma_f32 v183, v218, v213, -v183
	v_fma_f32 v238, v118, v208, -v237
	v_fma_f32 v239, v119, v208, v236
	v_mov_b32_e32 v240, v224
	v_mov_b32_e32 v241, v227
	v_pk_mov_b32 v[224:225], v[224:225], v[226:227] op_sel:[1,0]
	v_mov_b32_e32 v219, v183
	v_pk_mul_f32 v[118:119], v[222:223], v[206:207] op_sel:[0,1]
	v_add_f32_e32 v226, v240, v224
	v_sub_f32_e32 v225, v241, v225
	v_mov_b32_e32 v103, v99
	v_mov_b32_e32 v235, v207
	v_fma_f32 v206, v222, v208, -v119
	v_fma_f32 v119, v223, v208, v118
	v_mul_f32_e32 v106, v99, v225
	v_mul_f32_e32 v107, v104, v225
	v_mul_f32_e32 v182, v101, v183
	v_mul_f32_e32 v183, v101, v216
	v_mov_b32_e32 v234, v208
	v_mov_b32_e32 v208, v206
	v_mov_b32_e32 v209, v119
	v_mov_b32_e32 v240, v226
	v_mov_b32_e32 v241, v225
	v_fma_f32 v224, v104, v226, -v106
	v_fma_f32 v225, v103, v226, v107
	v_fma_f32 v216, v100, v216, -v182
	v_fma_f32 v217, v100, v219, v183
	v_pk_mul_f32 v[120:121], v[112:113], v[120:121] op_sel:[1,1] op_sel_hi:[0,1]
	v_pk_mul_f32 v[232:233], v[204:205], v[212:213]
	v_pk_mul_f32 v[204:205], v[204:205], v[214:215]
	ds_write2_b64 v242, v[230:231], v[238:239] offset0:34 offset1:51
	v_pk_mul_f32 v[230:231], v[234:235], v[212:213]
	v_pk_mul_f32 v[234:235], v[234:235], v[214:215]
	v_pk_mul_f32 v[236:237], v[222:223], v[212:213]
	v_pk_mul_f32 v[238:239], v[222:223], v[214:215]
	v_pk_mul_f32 v[102:103], v[212:213], v[240:241]
	v_pk_mul_f32 v[106:107], v[214:215], v[240:241]
	v_pk_mul_f32 v[100:101], v[212:213], v[210:211]
	v_pk_mul_f32 v[182:183], v[214:215], v[210:211]
	v_pk_mul_f32 v[210:211], v[212:213], v[208:209]
	v_pk_mul_f32 v[212:213], v[214:215], v[208:209]
	v_fma_f32 v214, v112, v176, -v120
	v_fma_f32 v215, v113, v176, v121
	v_sub_f32_e32 v112, v202, v180
	v_sub_f32_e32 v113, v175, v203
	v_pk_add_f32 v[120:121], v[204:205], v[204:205] op_sel:[0,1] op_sel_hi:[0,1]
	v_pk_mul_f32 v[120:121], v[112:113], v[120:121] op_sel:[1,0] op_sel_hi:[0,1]
	v_pk_add_f32 v[174:175], v[232:233], v[232:233] op_sel:[0,1] op_sel_hi:[0,1] neg_lo:[0,1] neg_hi:[0,1]
	v_fma_f32 v176, v112, v174, -v120
	v_fma_f32 v177, v113, v175, v121
	v_pk_add_f32 v[2:3], v[2:3], v[84:85] neg_lo:[0,1] neg_hi:[0,1]
	v_mov_b32_e32 v113, v117
	v_sub_f32_e32 v108, v108, v116
	v_sub_f32_e32 v109, v113, v109
	v_pk_add_f32 v[112:113], v[234:235], v[234:235] op_sel:[0,1] op_sel_hi:[0,1]
	v_pk_add_f32 v[4:5], v[4:5], v[86:87] neg_lo:[0,1] neg_hi:[0,1]
	v_pk_mul_f32 v[112:113], v[108:109], v[112:113] op_sel:[1,0] op_sel_hi:[0,1]
	v_pk_add_f32 v[116:117], v[230:231], v[230:231] op_sel:[0,1] op_sel_hi:[0,1] neg_lo:[0,1] neg_hi:[0,1]
	v_pk_add_f32 v[84:85], v[2:3], v[4:5] op_sel:[0,1] op_sel_hi:[1,0]
	v_pk_add_f32 v[2:3], v[2:3], v[4:5] op_sel:[0,1] op_sel_hi:[1,0] neg_lo:[0,1] neg_hi:[0,1]
	v_fma_f32 v120, v108, v116, -v112
	v_fma_f32 v121, v109, v117, v113
	v_pk_mul_f32 v[86:87], v[2:3], v[228:229] op_sel:[1,0]
	v_fma_f32 v108, v84, v220, -v86
	v_fma_f32 v109, v84, v223, v87
	v_mov_b32_e32 v5, v85
	v_pk_add_f32 v[86:87], v[238:239], v[238:239] op_sel:[0,1] op_sel_hi:[0,1]
	v_mul_f32_e32 v84, v85, v86
	v_mul_f32_e32 v85, v2, v87
	v_pk_add_f32 v[86:87], v[236:237], v[236:237] op_sel:[0,1] op_sel_hi:[0,1] neg_lo:[0,1] neg_hi:[0,1]
	v_fma_f32 v2, v2, v86, -v84
	v_fma_f32 v3, v5, v87, v85
	v_pk_add_f32 v[86:87], v[106:107], v[106:107] op_sel:[0,1] op_sel_hi:[0,1]
	v_mov_b32_e32 v5, v105
	v_mul_f32_e32 v84, v105, v86
	v_mul_f32_e32 v85, v98, v87
	v_pk_add_f32 v[86:87], v[102:103], v[102:103] op_sel:[0,1] op_sel_hi:[0,1] neg_lo:[0,1] neg_hi:[0,1]
	v_fma_f32 v98, v98, v86, -v84
	v_fma_f32 v99, v5, v87, v85
	v_pk_add_f32 v[84:85], v[182:183], v[182:183] op_sel:[0,1] op_sel_hi:[0,1]
	ds_write2_b64 v242, v[2:3], v[98:99] offset0:204 offset1:221
	v_mov_b32_e32 v3, v100
	v_sub_f32_e32 v2, v90, v91
	v_sub_f32_e32 v3, v3, v101
	v_mul_f32_e32 v4, v88, v84
	v_mul_f32_e32 v5, v2, v85
	v_pk_mov_b32 v[84:85], v[2:3], v[88:89] op_sel:[1,0]
	v_fma_f32 v86, v2, v84, -v4
	v_fma_f32 v87, v3, v85, v5
	v_mov_b32_e32 v3, v96
	v_mov_b32_e32 v5, v92
	v_sub_f32_e32 v2, v94, v110
	v_sub_f32_e32 v3, v3, v5
	v_sub_f32_e32 v4, v111, v95
	v_sub_f32_e32 v5, v97, v93
	ds_write2_b64 v242, v[214:215], v[216:217] offset0:136 offset1:153
	v_pk_add_f32 v[84:85], v[4:5], v[2:3]
	v_sub_f32_e32 v88, v2, v4
	v_sub_f32_e32 v2, v5, v3
	v_mul_f32_e32 v3, v2, v206
	v_mul_f32_e32 v2, v2, v119
	v_fma_f32 v4, v84, v206, -v2
	v_fma_f32 v5, v84, v209, v3
	ds_write2_b64 v242, v[114:115], v[4:5] offset0:102 offset1:119
	v_pk_add_f32 v[4:5], v[212:213], v[212:213] op_sel:[0,1] op_sel_hi:[0,1]
	v_mov_b32_e32 v91, v85
	v_mul_f32_e32 v2, v85, v4
	v_mul_f32_e32 v3, v88, v5
	v_pk_add_f32 v[4:5], v[210:211], v[210:211] op_sel:[0,1] op_sel_hi:[0,1] neg_lo:[0,1] neg_hi:[0,1]
	v_fma_f32 v84, v88, v4, -v2
	v_fma_f32 v85, v91, v5, v3
	ds_write2_b64 v242, v[176:177], v[120:121] offset0:170 offset1:187
	v_mov_b32_e32 v2, v78
	ds_write2_b64 v242, v[108:109], v[224:225] offset0:68 offset1:85
	ds_write2_b64 v242, v[86:87], v[84:85] offset0:238 offset1:255
	s_waitcnt lgkmcnt(0)
	s_barrier
	s_mov_b32 s77, s71
	v_mul_lo_u32 v108, v2, s33
	ds_read2_b64 v[2:5], v108 offset1:1
	ds_read2_b64 v[84:87], v108 offset0:2 offset1:3
	ds_read2_b64 v[88:91], v108 offset0:9 offset1:10
	ds_read2_b64 v[92:95], v108 offset0:4 offset1:5
	ds_read2_b64 v[96:99], v108 offset0:6 offset1:7
	ds_read2_b64 v[100:103], v108 offset0:13 offset1:14
	ds_read2_b64 v[104:107], v108 offset0:8 offset1:15
	ds_read2_b64 v[108:111], v108 offset0:11 offset1:12
	s_waitcnt lgkmcnt(5)
	v_add_f32_e32 v112, v4, v88
	s_waitcnt lgkmcnt(3)
	s_waitcnt lgkmcnt(2)
	v_add_f32_e32 v114, v94, v100
	s_waitcnt lgkmcnt(1)
	v_pk_add_f32 v[202:203], v[2:3], v[104:105]
	v_pk_add_f32 v[2:3], v[2:3], v[104:105] neg_lo:[0,1] neg_hi:[0,1]
	s_waitcnt lgkmcnt(0)
	v_pk_add_f32 v[104:105], v[92:93], v[110:111]
	v_pk_add_f32 v[92:93], v[92:93], v[110:111] neg_lo:[0,1] neg_hi:[0,1]
	v_add_f32_e32 v113, v112, v114
	v_sub_f32_e32 v112, v112, v114
	v_mov_b32_e32 v180, v85
	v_add_f32_e32 v204, v2, v93
	v_sub_f32_e32 v205, v3, v92
	v_add_f32_e32 v114, v86, v108
	v_add_f32_e32 v115, v98, v106
	v_mov_b32_e32 v182, v97
	v_mov_b32_e32 v211, v88
	v_add_f32_e32 v175, v5, v89
	v_add_f32_e32 v116, v87, v109
	v_add_f32_e32 v117, v99, v107
	v_mov_b32_e32 v118, v87
	v_mov_b32_e32 v120, v109
	v_add_f32_e32 v206, v85, v91
	v_add_f32_e32 v207, v84, v90
	v_mov_b32_e32 v85, v4
	v_sub_f32_e32 v4, v180, v91
	v_sub_f32_e32 v5, v5, v89
	v_mov_b32_e32 v91, v100
	v_add_f32_e32 v179, v95, v101
	v_sub_f32_e32 v86, v86, v108
	v_sub_f32_e32 v87, v99, v107
	v_sub_f32_e32 v84, v84, v90
	v_sub_f32_e32 v85, v85, v211
	v_add_f32_e32 v88, v97, v103
	v_add_f32_e32 v89, v96, v102
	v_mov_b32_e32 v97, v94
	v_sub_f32_e32 v94, v182, v103
	v_sub_f32_e32 v95, v95, v101
	v_mov_b32_e32 v121, v106
	v_pk_add_f32 v[106:107], v[86:87], v[86:87] op_sel_hi:[0,1] neg_lo:[0,1] neg_hi:[0,1]
	v_sub_f32_e32 v90, v96, v102
	v_sub_f32_e32 v91, v97, v91
	v_mov_b32_e32 v182, v86
	v_sub_f32_e32 v118, v118, v120
	v_sub_f32_e32 v119, v98, v121
	v_pk_add_f32 v[102:103], v[84:85], v[94:95] neg_lo:[0,1] neg_hi:[0,1]
	v_pk_add_f32 v[180:181], v[4:5], v[90:91]
	v_add_f32_e32 v86, v182, v87
	v_add_f32_e32 v87, v84, v94
	v_mov_b32_e32 v183, v4
	v_sub_f32_e32 v4, v5, v91
	v_add_f32_e32 v84, v85, v95
	v_pk_add_f32 v[108:109], v[118:119], v[118:119] op_sel:[0,1] op_sel_hi:[1,0]
	v_mov_b32_e32 v182, v118
	v_pk_mov_b32 v[118:119], v[118:119], v[90:91] op_sel:[1,0]
	v_pk_mul_f32 v[90:91], v[4:5], s[0:1] op_sel_hi:[0,1]
	v_pk_mul_f32 v[84:85], v[84:85], s[22:23] op_sel_hi:[0,1]
	v_pk_add_f32 v[118:119], v[182:183], v[118:119] neg_lo:[0,1] neg_hi:[0,1]
	v_sub_f32_e32 v174, v175, v179
	v_pk_add_f32 v[98:99], v[114:115], v[114:115] op_sel:[0,1] op_sel_hi:[1,0]
	v_sub_f32_e32 v114, v114, v115
	v_add_f32_e32 v94, v2, v93
	v_add_f32_e32 v95, v90, v84
	v_fma_f32 v182, v4, s0, v84
	v_fma_f32 v183, v4, s1, -v85
	v_mul_f32_e32 v115, 0x3f3504f3, v112
	v_mul_f32_e32 v121, 0x3f3504f3, v174
	v_mul_f32_e32 v176, 0x3f3504f3, v114
	v_mov_b32_e32 v4, v91
	v_mul_f32_e32 v110, 0x3ec3ef15, v103
	v_mul_f32_e32 v90, 0x3f6c835e, v181
	v_sub_f32_e32 v4, v4, v85
	v_sub_f32_e32 v5, v3, v92
	v_sub_f32_e32 v84, v202, v104
	v_sub_f32_e32 v85, v121, v115
	v_add_f32_e32 v90, v90, v110
	v_add_f32_e32 v91, v3, v92
	v_pk_mul_f32 v[110:111], v[86:87], s[72:73]
	v_pk_mul_f32 v[114:115], v[86:87], s[74:75]
	v_pk_mul_f32 v[86:87], v[86:87], s[0:1] op_sel_hi:[0,1]
	v_fma_f32 v220, v118, s22, v86
	v_fma_f32 v221, v118, s23, -v87
	v_pk_add_f32 v[86:87], v[116:117], v[116:117] op_sel:[0,1] op_sel_hi:[0,1] neg_lo:[0,1] neg_hi:[0,1]
	v_pk_fma_f32 v[210:211], v[118:119], s[72:73], v[114:115] neg_lo:[0,0,1] neg_hi:[0,0,1]
	v_fmac_f32_e32 v115, 0x3f3504f3, v119
	v_pk_fma_f32 v[110:111], v[118:119], s[74:75], v[110:111]
	v_pk_mul_f32 v[118:119], v[86:87], s[2:3]
	v_mov_b32_e32 v177, v105
	v_mov_b32_e32 v214, v108
	v_sub_f32_e32 v222, v118, v176
	v_sub_f32_e32 v223, v203, v177
	v_pk_fma_f32 v[86:87], v[86:87], s[2:3], v[176:177] op_sel_hi:[1,1,0] neg_lo:[0,0,1] neg_hi:[0,0,1]
	v_pk_mul_f32 v[108:109], v[108:109], s[0:1] op_sel_hi:[0,1]
	v_mul_f32_e32 v3, s77, v107
	v_mov_b32_e32 v92, v93
	v_pk_add_f32 v[208:209], v[202:203], v[104:105] neg_lo:[0,1] neg_hi:[0,1]
	v_add_f32_e32 v96, v203, v105
	v_add_f32_e32 v97, v206, v88
	v_pk_add_f32 v[100:101], v[206:207], v[88:89] neg_lo:[0,1] neg_hi:[0,1]
	v_mov_b32_e32 v213, v107
	v_pk_mov_b32 v[218:219], v[106:107], v[180:181] op_sel:[1,0]
	v_sub_f32_e32 v2, v2, v92
	v_sub_f32_e32 v3, v3, v109
	v_pk_fma_f32 v[92:93], v[106:107], s[76:77], v[108:109] op_sel:[1,0,0] neg_lo:[0,0,1] neg_hi:[0,0,1]
	v_pk_mov_b32 v[106:107], v[206:207], v[116:117] op_sel:[1,0]
	v_fmamk_f32 v174, v112, 0x3f3504f3, v121
	v_mov_b32_e32 v215, v102
	v_mov_b32_e32 v224, v88
	v_add_f32_e32 v104, v202, v104
	v_add_f32_e32 v105, v175, v179
	v_add_f32_e32 v88, v106, v89
	v_add_f32_e32 v89, v107, v117
	v_sub_f32_e32 v116, v208, v100
	v_add_f32_e32 v117, v209, v101
	v_mov_b32_e32 v175, v101
	v_pk_mul_f32 v[120:121], v[102:103], s[20:21]
	v_pk_mul_f32 v[102:103], v[214:215], s[74:75]
	v_pk_mul_f32 v[214:215], v[214:215], s[72:73]
	v_sub_f32_e32 v118, v206, v224
	v_sub_f32_e32 v119, v119, v176
	v_add_f32_e32 v100, v222, v174
	v_sub_f32_e32 v177, v223, v175
	v_mov_b32_e32 v212, v180
	v_pk_fma_f32 v[216:217], v[180:181], s[70:71], v[120:121] neg_lo:[0,0,1] neg_hi:[0,0,1]
	v_pk_fma_f32 v[180:181], v[180:181], s[2:3], v[120:121] op_sel_hi:[0,1,0] neg_lo:[0,0,1] neg_hi:[0,0,1]
	v_add_f32_e32 v106, v96, v97
	v_add_f32_e32 v107, v105, v89
	v_mov_b32_e32 v112, v104
	v_mov_b32_e32 v108, v88
	v_pk_add_f32 v[88:89], v[104:105], v[88:89] neg_lo:[0,1] neg_hi:[0,1]
	v_pk_add_f32 v[104:105], v[182:183], v[220:221]
	v_pk_add_f32 v[182:183], v[84:85], v[118:119]
	s_mov_b32 s38, s71
	s_mov_b32 s39, s3
	v_fma_f32 v120, v212, s78, -v120
	v_fma_f32 v121, v213, s79, -v214
	v_pk_fma_f32 v[212:213], v[218:219], s[30:31], v[214:215] neg_lo:[0,0,1] neg_hi:[0,0,1]
	v_add_f32_e32 v86, v174, v86
	v_add_f32_e32 v87, v85, v87
	v_add_f32_e32 v100, v182, v100
	v_add_f32_e32 v101, v183, v177
	v_mov_b32_e32 v114, v115
	v_pk_fma_f32 v[102:103], v[218:219], s[38:39], v[102:103] neg_lo:[0,0,1] neg_hi:[0,0,1]
	v_add_f32_e32 v108, v112, v108
	v_add_f32_e32 v109, v113, v98
	v_sub_f32_e32 v86, v182, v86
	v_sub_f32_e32 v87, v177, v87
	v_add_f32_e32 v176, v2, v180
	v_add_f32_e32 v177, v91, v181
	v_pk_add_f32 v[180:181], v[90:91], v[212:213]
	v_pk_add_f32 v[182:183], v[216:217], v[2:3]
	v_mov_b32_e32 v216, v90
	v_mov_b32_e32 v3, v90
	v_pk_add_f32 v[202:203], v[106:107], v[106:107] op_sel:[1,0] op_sel_hi:[1,0]
	v_mov_b32_e32 v112, v96
	v_pk_mov_b32 v[96:97], v[96:97], v[98:99] op_sel:[1,0]
	v_add_f32_e32 v98, v204, v114
	v_add_f32_e32 v99, v205, v211
	v_sub_f32_e32 v90, v217, v102
	v_sub_f32_e32 v91, v91, v103
	v_pk_add_f32 v[102:103], v[182:183], v[180:181]
	v_pk_add_f32 v[182:183], v[108:109], v[108:109] op_sel:[1,0] op_sel_hi:[1,0]
	v_pk_mul_f32 v[202:203], v[74:75], v[202:203]
	v_pk_add_f32 v[94:95], v[94:95], v[110:111] op_sel:[0,1] op_sel_hi:[1,0] neg_lo:[0,1] neg_hi:[0,1]
	v_pk_add_f32 v[110:111], v[104:105], v[98:99]
	v_fma_f32 v204, v14, v182, -v202
	v_fma_f32 v205, v15, v183, v203
	v_pk_add_f32 v[96:97], v[112:113], v[96:97] neg_lo:[0,1] neg_hi:[0,1]
	v_pk_mul_f32 v[182:183], v[24:25], v[110:111] op_sel:[0,1] op_sel_hi:[1,0]
	v_pk_add_f32 v[4:5], v[4:5], v[210:211] neg_lo:[0,1] neg_hi:[0,1]
	v_fma_f32 v202, v22, v110, -v182
	v_fma_f32 v111, v23, v111, v183
	v_pk_mul_f32 v[182:183], v[40:41], v[100:101] op_sel:[0,1] op_sel_hi:[1,0]
	v_pk_add_f32 v[98:99], v[98:99], v[104:105] neg_lo:[0,1] neg_hi:[0,1]
	v_pk_add_f32 v[104:105], v[4:5], v[94:95]
	v_sub_f32_e32 v113, v5, v95
	v_fma_f32 v206, v38, v100, -v182
	v_fma_f32 v101, v39, v101, v183
	v_pk_mul_f32 v[182:183], v[56:57], v[102:103] op_sel:[0,1] op_sel_hi:[1,0]
	v_pk_add_f32 v[210:211], v[96:97], v[96:97] op_sel:[0,1] op_sel_hi:[0,1] neg_lo:[0,1] neg_hi:[0,1]
	v_mov_b32_e32 v115, v113
	v_sub_f32_e32 v84, v85, v119
	v_sub_f32_e32 v85, v174, v222
	v_fma_f32 v208, v54, v102, -v182
	v_fma_f32 v103, v55, v103, v183
	v_pk_add_f32 v[182:183], v[88:89], v[88:89] op_sel:[0,1] op_sel_hi:[0,1]
	v_pk_mul_f32 v[210:211], v[70:71], v[210:211]
	v_mov_b32_e32 v114, v104
	v_pk_add_f32 v[118:119], v[116:117], v[84:85]
	v_pk_add_f32 v[84:85], v[116:117], v[84:85] neg_lo:[0,1] neg_hi:[0,1]
	v_fma_f32 v212, v18, v182, -v210
	v_fma_f32 v213, v19, v183, v211
	v_mul_f32_e32 v112, v32, v113
	v_mul_f32_e32 v113, v33, v104
	v_pk_add_f32 v[92:93], v[216:217], v[92:93]
	v_pk_add_f32 v[2:3], v[2:3], v[120:121] neg_lo:[0,1] neg_hi:[0,1]
	v_fma_f32 v182, v30, v114, -v112
	v_fma_f32 v113, v31, v115, v113
	v_mov_b32_e32 v117, v85
	v_pk_add_f32 v[92:93], v[176:177], v[92:93] neg_lo:[0,1] neg_hi:[0,1]
	v_pk_add_f32 v[120:121], v[90:91], v[2:3]
	v_sub_f32_e32 v177, v91, v3
	v_mul_f32_e32 v114, v48, v85
	v_mul_f32_e32 v115, v49, v118
	v_pk_add_f32 v[106:107], v[106:107], v[106:107] op_sel:[0,1] op_sel_hi:[0,1] neg_lo:[0,1] neg_hi:[0,1]
	v_fma_f32 v210, v46, v118, -v114
	v_fma_f32 v115, v47, v117, v115
	v_mov_b32_e32 v180, v120
	v_mul_f32_e32 v116, v64, v177
	v_mul_f32_e32 v117, v65, v120
	v_pk_add_f32 v[108:109], v[108:109], v[108:109] op_sel:[0,1] op_sel_hi:[0,1] neg_lo:[0,1] neg_hi:[0,1]
	v_pk_mul_f32 v[106:107], v[76:77], v[106:107]
	v_fma_f32 v176, v62, v180, -v116
	v_fma_f32 v117, v63, v177, v117
	v_fma_f32 v180, v16, v108, -v106
	v_fma_f32 v181, v17, v109, v107
	v_sub_f32_e32 v4, v94, v4
	v_pk_mul_f32 v[106:107], v[28:29], v[98:99] op_sel:[0,1] op_sel_hi:[1,0]
	v_pk_add_f32 v[96:97], v[96:97], v[96:97] op_sel:[1,0] op_sel_hi:[1,0]
	v_fma_f32 v108, v26, v98, -v106
	v_fma_f32 v99, v27, v99, v107
	v_pk_mul_f32 v[106:107], v[44:45], v[86:87] op_sel:[0,1] op_sel_hi:[1,0]
	v_mov_b32_e32 v94, v4
	v_sub_f32_e32 v2, v2, v90
	v_fma_f32 v214, v42, v86, -v106
	v_fma_f32 v87, v43, v87, v107
	v_pk_mul_f32 v[106:107], v[60:61], v[92:93] op_sel:[0,1] op_sel_hi:[1,0]
	v_pk_add_f32 v[88:89], v[88:89], v[88:89] op_sel:[0,1] op_sel_hi:[0,1] neg_lo:[0,1] neg_hi:[0,1]
	v_pk_mul_f32 v[96:97], v[72:73], v[96:97]
	v_mov_b32_e32 v95, v105
	v_mov_b32_e32 v174, v84
	v_mov_b32_e32 v90, v2
	v_fma_f32 v216, v58, v92, -v106
	v_fma_f32 v93, v59, v93, v107
	v_fma_f32 v106, v20, v88, -v96
	v_fma_f32 v107, v21, v89, v97
	v_mul_f32_e32 v5, v37, v4
	v_mul_f32_e32 v4, v36, v105
	v_mov_b32_e32 v175, v119
	v_fma_f32 v88, v34, v94, -v4
	v_fma_f32 v5, v35, v95, v5
	v_mul_f32_e32 v85, v53, v84
	v_mul_f32_e32 v84, v52, v119
	v_mul_f32_e32 v3, v69, v2
	v_mul_f32_e32 v2, v68, v121
	v_fma_f32 v94, v50, v174, -v84
	v_fma_f32 v96, v66, v90, -v2
	v_fma_f32 v3, v67, v121, v3
	v_mov_b32_e32 v4, v78
	v_fma_f32 v85, v51, v175, v85
	v_mov_b32_e32 v97, v3
	s_barrier
	v_add_f32_e32 v220, v206, v214
	v_add_f32_e32 v221, v101, v87
	v_add_f32_e32 v226, v208, v216
	v_add_f32_e32 v227, v103, v93
	v_mov_b32_e32 v209, v101
	v_mul_lo_u32 v179, v4, s33
	v_add_f32_e32 v228, v176, v96
	v_add_f32_e32 v229, v117, v97
	v_mov_b32_e32 v98, v87
	v_sub_f32_e32 v86, v208, v216
	v_sub_f32_e32 v87, v209, v87
	v_sub_f32_e32 v2, v117, v3
	v_sub_f32_e32 v3, v210, v94
	v_mov_b32_e32 v89, v5
	v_add_f32_e32 v120, v202, v108
	v_add_f32_e32 v121, v111, v99
	v_add_f32_e32 v222, v210, v94
	v_add_f32_e32 v223, v115, v85
	v_mov_b32_e32 v239, v202
	v_sub_f32_e32 v4, v115, v85
	v_sub_f32_e32 v5, v113, v5
	v_mov_b32_e32 v112, v94
	v_sub_f32_e32 v92, v103, v93
	v_sub_f32_e32 v93, v206, v214
	v_sub_f32_e32 v84, v176, v96
	v_sub_f32_e32 v85, v115, v85
	v_pk_add_f32 v[94:95], v[86:87], v[2:3]
	v_pk_add_f32 v[2:3], v[86:87], v[2:3] neg_lo:[0,1] neg_hi:[0,1]
	v_sub_f32_e32 v109, v239, v108
	v_sub_f32_e32 v108, v206, v214
	v_sub_f32_e32 v98, v101, v98
	v_sub_f32_e32 v99, v111, v99
	v_pk_add_f32 v[96:97], v[92:93], v[84:85] neg_lo:[0,1] neg_hi:[0,1]
	v_pk_add_f32 v[84:85], v[92:93], v[84:85]
	v_pk_add_f32 v[90:91], v[204:205], v[180:181]
	v_pk_add_f32 v[104:105], v[212:213], v[106:107]
	v_add_f32_e32 v174, v182, v88
	v_add_f32_e32 v175, v113, v89
	v_sub_f32_e32 v89, v182, v88
	v_sub_f32_e32 v88, v210, v112
	v_pk_add_f32 v[100:101], v[108:109], v[4:5]
	v_mul_f32_e32 v111, 0x3f3504f3, v95
	v_mul_f32_e32 v86, s74, v94
	v_mul_f32_e32 v87, s75, v3
	v_mul_f32_e32 v4, 0x3f6c835e, v96
	v_pk_add_f32 v[118:119], v[90:91], v[104:105]
	v_pk_add_f32 v[224:225], v[220:221], v[222:223]
	v_pk_add_f32 v[230:231], v[226:227], v[228:229]
	v_pk_add_f32 v[90:91], v[90:91], v[104:105] neg_lo:[0,1] neg_hi:[0,1]
	v_pk_add_f32 v[104:105], v[220:221], v[222:223] neg_lo:[0,1] neg_hi:[0,1]
	v_mov_b32_e32 v221, v226
	v_mov_b32_e32 v223, v228
	v_fma_f32 v86, v96, s72, -v86
	v_fma_f32 v87, v85, s73, -v87
	v_fma_f32 v92, v94, s80, -v4
	v_add_f32_e32 v4, v99, v89
	v_pk_add_f32 v[218:219], v[120:121], v[174:175]
	v_pk_add_f32 v[106:107], v[212:213], v[106:107] neg_lo:[0,1] neg_hi:[0,1]
	v_mov_b32_e32 v220, v120
	v_sub_f32_e32 v120, v121, v175
	v_sub_f32_e32 v121, v227, v229
	v_pk_add_f32 v[102:103], v[98:99], v[88:89] neg_lo:[0,1] neg_hi:[0,1]
	v_pk_mul_f32 v[88:89], v[4:5], s[0:1] op_sel_hi:[0,1]
	v_sub_f32_e32 v4, v109, v5
	v_pk_add_f32 v[180:181], v[204:205], v[180:181] neg_lo:[0,1] neg_hi:[0,1]
	v_mov_b32_e32 v205, v106
	v_sub_f32_e32 v220, v220, v174
	v_sub_f32_e32 v221, v221, v223
	v_pk_mul_f32 v[120:121], v[120:121], s[20:21] op_sel_hi:[1,0]
	v_fma_f32 v98, v4, s22, -v88
	v_fma_f32 v99, v4, s23, v89
	v_fma_f32 v175, v221, s3, -v121
	v_fma_f32 v222, v220, s2, v120
	v_pk_fma_f32 v[120:121], v[220:221], s[20:21], v[120:121] op_sel_hi:[1,0,1] neg_lo:[0,0,1] neg_hi:[0,0,1]
	v_pk_add_f32 v[220:221], v[90:91], v[104:105] op_sel:[0,1] op_sel_hi:[1,0] neg_lo:[0,1] neg_hi:[0,1]
	v_pk_add_f32 v[90:91], v[90:91], v[104:105] op_sel:[0,1] op_sel_hi:[1,0]
	v_mul_f32_e32 v204, 0x3f6c835e, v103
	s_mov_b32 s38, s3
	s_mov_b32 s39, s21
	v_pk_mul_f32 v[102:103], v[102:103], s[70:71]
	v_pk_mul_f32 v[4:5], v[84:85], s[22:23] op_sel_hi:[0,1]
	v_sub_f32_e32 v212, v180, v107
	v_pk_add_f32 v[106:107], v[180:181], v[106:107] op_sel:[0,1] op_sel_hi:[1,0]
	v_mov_b32_e32 v105, v91
	v_mul_f32_e32 v180, 0x3ec3ef15, v101
	v_mul_f32_e32 v91, 0x3f3504f3, v97
	v_fma_f32 v112, v100, s38, -v102
	v_fma_f32 v101, v101, s39, v103
	v_fma_f32 v84, v2, s0, -v4
	v_fma_f32 v85, v2, s1, v5
	v_mov_b32_e32 v213, v107
	v_pk_add_f32 v[94:95], v[180:181], v[204:205] neg_lo:[0,1] neg_hi:[0,1]
	v_sub_f32_e32 v110, v91, v111
	v_fmac_f32_e32 v111, 0x3f3504f3, v97
	v_pk_add_f32 v[232:233], v[118:119], v[224:225]
	v_pk_add_f32 v[234:235], v[218:219], v[230:231]
	v_pk_add_f32 v[2:3], v[212:213], v[110:111]
	v_pk_add_f32 v[4:5], v[98:99], v[84:85]
	v_add_f32_e32 v96, v112, v106
	v_add_f32_e32 v97, v101, v92
	v_pk_add_f32 v[102:103], v[94:95], v[86:87]
	v_pk_add_f32 v[236:237], v[232:233], v[234:235]
	v_mov_b32_e32 v104, v220
	v_add_f32_e32 v226, v120, v175
	v_add_f32_e32 v227, v121, v222
	v_pk_add_f32 v[88:89], v[2:3], v[4:5]
	v_pk_add_f32 v[108:109], v[102:103], v[96:97]
	v_pk_add_f32 v[228:229], v[104:105], v[226:227]
	ds_write2_b64 v179, v[236:237], v[88:89] offset1:1
	ds_write2_b64 v179, v[228:229], v[108:109] offset0:2 offset1:3
	v_pk_add_f32 v[88:89], v[118:119], v[224:225] neg_lo:[0,1] neg_hi:[0,1]
	v_pk_add_f32 v[108:109], v[218:219], v[230:231] neg_lo:[0,1] neg_hi:[0,1]
	v_pk_add_f32 v[84:85], v[98:99], v[84:85] neg_lo:[0,1] neg_hi:[0,1]
	v_pk_add_f32 v[114:115], v[88:89], v[108:109] op_sel:[0,1] op_sel_hi:[1,0] neg_lo:[0,1] neg_hi:[0,1]
	v_pk_add_f32 v[88:89], v[88:89], v[108:109] op_sel:[0,1] op_sel_hi:[1,0]
	v_pk_add_f32 v[108:109], v[212:213], v[110:111] neg_lo:[0,1] neg_hi:[0,1]
	v_pk_add_f32 v[98:99], v[108:109], v[84:85] op_sel:[0,1] op_sel_hi:[1,0] neg_lo:[0,1] neg_hi:[0,1]
	v_pk_add_f32 v[84:85], v[108:109], v[84:85] op_sel:[0,1] op_sel_hi:[1,0]
	v_mov_b32_e32 v108, v114
	v_mov_b32_e32 v109, v89
	v_mov_b32_e32 v110, v98
	v_mov_b32_e32 v111, v85
	ds_write2_b64 v179, v[108:109], v[110:111] offset0:4 offset1:5
	v_mov_b32_e32 v91, v221
	v_sub_f32_e32 v108, v222, v121
	v_sub_f32_e32 v109, v120, v175
	v_sub_f32_e32 v92, v101, v92
	v_sub_f32_e32 v93, v94, v86
	v_sub_f32_e32 v86, v106, v112
	v_sub_f32_e32 v87, v95, v87
	v_pk_add_f32 v[110:111], v[90:91], v[108:109] neg_lo:[0,1] neg_hi:[0,1]
	v_pk_add_f32 v[90:91], v[90:91], v[108:109]
	v_pk_add_f32 v[94:95], v[86:87], v[92:93] neg_lo:[0,1] neg_hi:[0,1]
	v_pk_add_f32 v[86:87], v[86:87], v[92:93]
	v_mov_b32_e32 v92, v110
	v_mov_b32_e32 v93, v91
	v_mov_b32_e32 v100, v94
	v_mov_b32_e32 v101, v87
	ds_write2_b64 v179, v[92:93], v[100:101] offset0:6 offset1:7
	v_pk_add_f32 v[92:93], v[232:233], v[234:235] neg_lo:[0,1] neg_hi:[0,1]
	v_pk_add_f32 v[2:3], v[2:3], v[4:5] neg_lo:[0,1] neg_hi:[0,1]
	v_mov_b32_e32 v5, v103
	ds_write2_b64 v179, v[92:93], v[2:3] offset0:8 offset1:9
	v_pk_add_f32 v[2:3], v[104:105], v[226:227] neg_lo:[0,1] neg_hi:[0,1]
	v_sub_f32_e32 v4, v96, v102
	v_sub_f32_e32 v5, v5, v97
	ds_write2_b64 v179, v[2:3], v[4:5] offset0:10 offset1:11
	v_mov_b32_e32 v89, v115
	v_mov_b32_e32 v85, v99
	v_mov_b32_e32 v91, v111
	v_mov_b32_e32 v87, v95
	v_mov_b32_e32 v2, v78
	ds_write2_b64 v179, v[88:89], v[84:85] offset0:12 offset1:13
	ds_write2_b64 v179, v[90:91], v[86:87] offset0:14 offset1:15
	s_waitcnt lgkmcnt(0)
	s_barrier
	s_nop 0
	v_ashrrev_i32_e32 v3, 31, v2
	v_lshrrev_b32_e32 v3, 28, v3
	v_and_b32_e32 v112, 15, v2
	v_add_u32_e32 v2, v2, v3
	v_ashrrev_i32_e32 v2, 4, v2
	v_lshlrev_b32_e32 v3, 11, v2
	v_lshl_add_u32 v2, v2, 7, v3
	v_lshl_or_b32 v179, v112, 3, v2
	ds_read2_b64 v[2:5], v179 offset1:17
	ds_read2_b64 v[84:87], v179 offset0:34 offset1:51
	ds_read2_b64 v[88:91], v179 offset0:68 offset1:85
	ds_read2_b64 v[92:95], v179 offset0:102 offset1:119
	ds_read2_b64 v[96:99], v179 offset0:136 offset1:153
	ds_read2_b64 v[100:103], v179 offset0:170 offset1:187
	ds_read2_b64 v[104:107], v179 offset0:204 offset1:221
	ds_read2_b64 v[108:111], v179 offset0:238 offset1:255
	s_waitcnt lgkmcnt(4)
	v_mov_b32_e32 v228, v92
	v_cvt_f32_i32_e32 v112, v112
	v_mov_b32_e32 v229, v91
	v_pk_mov_b32 v[90:91], v[92:93], v[90:91] op_sel:[1,0]
	v_add_f32_e32 v112, v112, v112
	v_mul_f32_e32 v112, 0x3b800000, v112
	v_mul_f32_e32 v112, 0.5, v112
	v_sin_f32_e32 v113, v112
	v_cos_f32_e32 v112, v112
	v_mul_f32_e32 v116, v113, v113
	v_mul_f32_e32 v114, v112, v113
	v_pk_fma_f32 v[116:117], v[112:113], v[112:113], v[116:117] op_sel_hi:[1,1,0] neg_lo:[0,0,1] neg_hi:[0,0,1]
	v_add_f32_e32 v114, v114, v114
	v_mov_b32_e32 v118, v116
	v_mov_b32_e32 v119, v112
	v_mov_b32_e32 v115, v113
	v_pk_mul_f32 v[120:121], v[118:119], v[116:117] op_sel_hi:[1,0]
	v_pk_mul_f32 v[176:177], v[114:115], v[116:117] op_sel_hi:[1,0]
	v_pk_fma_f32 v[204:205], v[114:115], v[114:115], v[120:121] op_sel_hi:[1,0,1] neg_lo:[1,0,0] neg_hi:[1,0,0]
	v_pk_fma_f32 v[180:181], v[118:119], v[114:115], v[176:177] op_sel_hi:[1,0,1]
	v_mov_b32_e32 v206, v204
	v_mov_b32_e32 v207, v112
	v_mov_b32_e32 v212, v114
	v_mov_b32_e32 v213, v180
	v_mul_f32_e32 v175, v119, v114
	v_mov_b32_e32 v182, v180
	v_mov_b32_e32 v183, v113
	v_pk_mul_f32 v[208:209], v[206:207], v[204:205] op_sel_hi:[1,0]
	v_mov_b32_e32 v117, v204
	v_pk_mul_f32 v[216:217], v[212:213], v[204:205] op_sel_hi:[1,0]
	v_pk_mul_f32 v[218:219], v[182:183], v[116:117]
	v_pk_mul_f32 v[214:215], v[180:181], v[212:213] op_sel_hi:[0,1]
	v_add_f32_e32 v174, v217, v217
	v_add_f32_e32 v175, v175, v177
	v_pk_fma_f32 v[176:177], v[206:207], v[212:213], v[218:219]
	v_fma_f32 v120, -v182, v180, v208
	v_fma_f32 v121, -v183, v114, v121
	v_mul_f32_e32 v202, v204, v181
	v_mul_f32_e32 v218, v180, v205
	v_pk_mul_f32 v[220:221], v[182:183], v[204:205] op_sel_hi:[1,0]
	v_pk_fma_f32 v[182:183], v[182:183], v[180:181], v[208:209] op_sel_hi:[1,0,1] neg_lo:[1,0,0] neg_hi:[1,0,0]
	v_pk_fma_f32 v[208:209], v[204:205], v[116:117], v[214:215] op_sel_hi:[0,1,1] neg_lo:[0,0,1] neg_hi:[0,0,1]
	v_pk_fma_f32 v[214:215], v[116:117], v[180:181], v[216:217] op_sel_hi:[1,0,1]
	v_add_f32_e32 v202, v202, v218
	v_add_f32_e32 v203, v217, v217
	v_mov_b32_e32 v219, v112
	v_pk_mul_f32 v[212:213], v[180:181], v[180:181] op_sel_hi:[0,1]
	v_pk_fma_f32 v[206:207], v[206:207], v[180:181], v[220:221] op_sel_hi:[1,0,1]
	v_mov_b32_e32 v218, v182
	v_mul_f32_e32 v112, v215, v116
	v_mul_f32_e32 v113, v113, v182
	v_pk_fma_f32 v[212:213], v[204:205], v[204:205], v[212:213] op_sel_hi:[0,1,1] neg_lo:[0,0,1] neg_hi:[0,0,1]
	v_fma_f32 v112, v218, v114, v112
	v_fma_f32 v113, v219, v215, v113
	v_pk_mov_b32 v[220:221], v[214:215], v[180:181] op_sel:[1,0]
	v_mov_b32_e32 v219, v204
	v_pk_mul_f32 v[222:223], v[220:221], v[202:203]
	v_pk_mul_f32 v[220:221], v[220:221], v[212:213] op_sel:[0,1] op_sel_hi:[1,0]
	v_pk_mul_f32 v[206:207], v[206:207], v[208:209]
	v_pk_fma_f32 v[208:209], v[218:219], v[212:213], v[222:223] op_sel:[0,1,0] op_sel_hi:[1,0,1] neg_lo:[0,0,1] neg_hi:[0,0,1]
	v_pk_fma_f32 v[218:219], v[218:219], v[202:203], v[220:221]
	v_mov_b32_e32 v220, v84
	v_mov_b32_e32 v221, v5
	v_pk_mov_b32 v[4:5], v[84:85], v[4:5] op_sel:[1,0]
	v_pk_mul_f32 v[210:211], v[114:115], v[180:181] op_sel_hi:[1,0]
	v_pk_mul_f32 v[216:217], v[114:115], v[214:215] op_sel:[0,1]
	v_pk_mul_f32 v[84:85], v[4:5], v[114:115]
	v_pk_mul_f32 v[114:115], v[220:221], v[114:115]
	v_mul_f32_e32 v174, v204, v174
	v_mul_f32_e32 v175, v182, v175
	v_pk_fma_f32 v[222:223], v[220:221], v[118:119], v[84:85] neg_lo:[0,0,1] neg_hi:[0,0,1]
	v_fma_f32 v85, v221, v119, v85
	v_fma_f32 v221, v5, v119, -v115
	v_fma_f32 v4, v4, v118, v114
	v_pk_fma_f32 v[210:211], v[118:119], v[204:205], v[210:211] op_sel_hi:[1,0,1] neg_lo:[0,0,1] neg_hi:[0,0,1]
	v_pk_fma_f32 v[216:217], v[118:119], v[182:183], v[216:217] op_sel_hi:[1,0,1] neg_lo:[0,0,1] neg_hi:[0,0,1]
	v_fma_f32 v120, v180, v120, v174
	v_fma_f32 v121, v215, v121, v175
	v_pk_mul_f32 v[174:175], v[214:215], v[176:177] op_sel:[1,0]
	v_mov_b32_e32 v118, v205
	v_mul_f32_e32 v220, v87, v181
	v_pk_mul_f32 v[92:93], v[90:91], v[176:177]
	v_pk_mul_f32 v[176:177], v[228:229], v[176:177]
	v_pk_fma_f32 v[174:175], v[182:183], v[210:211], v[174:175] op_sel_hi:[0,1,1] neg_lo:[0,0,1] neg_hi:[0,0,1]
	v_fma_f32 v118, v86, v118, -v220
	v_mov_b32_e32 v224, v88
	v_mov_b32_e32 v225, v87
	v_pk_mov_b32 v[86:87], v[88:89], v[86:87] op_sel:[1,0]
	v_fma_f32 v230, v228, v210, -v92
	v_fma_f32 v93, v229, v211, v93
	v_pk_fma_f32 v[228:229], v[90:91], v[210:211], v[176:177] neg_lo:[0,0,1] neg_hi:[0,0,1]
	v_fma_f32 v90, v90, v210, v176
	v_mov_b32_e32 v211, v89
	v_mul_f32_e32 v89, v88, v180
	v_mul_f32_e32 v88, v95, v202
	v_mul_f32_e32 v92, v95, v213
	v_pk_mul_f32 v[116:117], v[180:181], v[214:215] op_sel:[0,1]
	v_pk_mul_f32 v[86:87], v[86:87], v[180:181]
	v_mov_b32_e32 v210, v94
	v_fma_f32 v94, v94, v202, v92
	s_waitcnt lgkmcnt(2)
	v_mov_b32_e32 v202, v100
	v_mov_b32_e32 v203, v99
	v_pk_mov_b32 v[98:99], v[100:101], v[98:99] op_sel:[1,0]
	v_pk_fma_f32 v[116:117], v[204:205], v[182:183], v[116:117] op_sel_hi:[1,0,1] neg_lo:[0,0,1] neg_hi:[0,0,1]
	v_fma_f32 v226, v224, v204, -v86
	v_fma_f32 v87, v225, v205, v87
	v_pk_mov_b32 v[204:205], v[212:213], v[204:205] op_sel:[1,0]
	v_pk_mul_f32 v[100:101], v[98:99], v[112:113]
	v_pk_mul_f32 v[112:113], v[202:203], v[112:113]
	v_fma_f32 v180, v210, v204, -v88
	v_fma_f32 v89, v211, v205, v89
	v_fma_f32 v204, v202, v216, -v100
	v_fma_f32 v101, v203, v217, v101
	v_fma_f32 v203, v99, v217, -v113
	v_fma_f32 v98, v98, v216, v112
	v_mov_b32_e32 v210, v102
	v_mov_b32_e32 v211, v97
	v_pk_mov_b32 v[212:213], v[116:117], v[182:183] op_sel:[1,0]
	v_mul_f32_e32 v216, v103, v121
	v_mul_f32_e32 v217, v96, v215
	v_pk_fma_f32 v[206:207], v[182:183], v[214:215], v[206:207]
	v_fma_f32 v232, v210, v212, -v216
	v_fma_f32 v211, v211, v213, v217
	v_mov_b32_e32 v213, v103
	s_waitcnt lgkmcnt(1)
	v_mov_b32_e32 v212, v104
	v_mul_f32_e32 v103, v102, v121
	v_mul_f32_e32 v102, v105, v120
	v_fma_f32 v120, v212, v116, -v102
	v_fma_f32 v103, v213, v117, v103
	s_waitcnt lgkmcnt(0)
	v_mov_b32_e32 v212, v108
	v_mov_b32_e32 v213, v107
	v_pk_mov_b32 v[106:107], v[108:109], v[106:107] op_sel:[1,0]
	v_pk_mul_f32 v[108:109], v[106:107], v[206:207]
	v_pk_mul_f32 v[206:207], v[212:213], v[206:207]
	v_fma_f32 v216, v212, v174, -v108
	v_fma_f32 v109, v213, v175, v109
	v_fma_f32 v213, v107, v175, -v207
	v_fma_f32 v106, v106, v174, v206
	v_mov_b32_e32 v207, v105
	v_mov_b32_e32 v206, v110
	v_mul_f32_e32 v105, v104, v219
	v_mul_f32_e32 v104, v111, v218
	v_fma_f32 v234, v206, v208, -v104
	v_fma_f32 v105, v207, v209, v105
	v_pk_mov_b32 v[206:207], v[96:97], v[110:111] op_sel:[1,0]
	v_mul_f32_e32 v206, v206, v215
	v_mul_f32_e32 v207, v207, v218
	v_fma_f32 v110, v96, v182, -v206
	v_fma_f32 v97, v111, v208, v207
	v_mov_b32_e32 v111, v97
	v_add_f32_e32 v206, v118, v232
	v_add_f32_e32 v207, v3, v211
	v_mov_b32_e32 v233, v98
	v_mov_b32_e32 v225, v87
	v_mov_b32_e32 v117, v103
	v_mov_b32_e32 v183, v94
	v_add_f32_e32 v208, v180, v234
	v_add_f32_e32 v209, v89, v105
	v_add_f32_e32 v112, v221, v203
	v_add_f32_e32 v113, v4, v98
	v_add_f32_e32 v114, v229, v213
	v_add_f32_e32 v115, v90, v106
	v_add_f32_e32 v174, v222, v204
	v_add_f32_e32 v175, v85, v101
	v_sub_f32_e32 v84, v4, v98
	v_sub_f32_e32 v85, v85, v101
	v_mov_b32_e32 v235, v106
	v_sub_f32_e32 v5, v4, v233
	v_sub_f32_e32 v4, v118, v232
	v_sub_f32_e32 v94, v94, v97
	v_sub_f32_e32 v95, v230, v216
	v_add_f32_e32 v176, v230, v216
	v_add_f32_e32 v177, v93, v109
	v_mov_b32_e32 v220, v222
	v_sub_f32_e32 v92, v90, v106
	v_sub_f32_e32 v93, v93, v109
	v_mov_b32_e32 v231, v229
	v_sub_f32_e32 v86, v87, v103
	v_sub_f32_e32 v87, v222, v204
	v_sub_f32_e32 v91, v90, v235
	v_sub_f32_e32 v90, v180, v234
	v_pk_add_f32 v[96:97], v[4:5], v[94:95]
	v_pk_add_f32 v[4:5], v[4:5], v[94:95] neg_lo:[0,1] neg_hi:[0,1]
	v_add_f32_e32 v182, v2, v110
	v_add_f32_e32 v183, v183, v111
	v_sub_f32_e32 v202, v220, v204
	v_sub_f32_e32 v203, v221, v203
	v_sub_f32_e32 v100, v230, v216
	v_sub_f32_e32 v101, v231, v213
	v_pk_add_f32 v[102:103], v[86:87], v[90:91] neg_lo:[0,1] neg_hi:[0,1]
	v_pk_add_f32 v[86:87], v[86:87], v[90:91]
	v_sub_f32_e32 v2, v2, v110
	v_sub_f32_e32 v3, v3, v211
	v_sub_f32_e32 v88, v89, v105
	v_sub_f32_e32 v89, v226, v120
	v_pk_add_f32 v[98:99], v[202:203], v[92:93]
	v_pk_add_f32 v[106:107], v[84:85], v[100:101] neg_lo:[0,1] neg_hi:[0,1]
	v_mul_f32_e32 v109, 0x3f3504f3, v97
	v_mul_f32_e32 v90, s74, v96
	v_mul_f32_e32 v91, s75, v5
	v_mul_f32_e32 v84, 0x3f6c835e, v102
	v_add_f32_e32 v116, v226, v120
	v_add_f32_e32 v117, v225, v117
	v_sub_f32_e32 v104, v2, v88
	v_pk_add_f32 v[110:111], v[2:3], v[88:89]
	v_mul_f32_e32 v2, 0x3ec3ef15, v99
	v_mul_f32_e32 v88, 0x3f6c835e, v107
	v_fma_f32 v90, v102, s72, -v90
	v_fma_f32 v91, v87, s73, -v91
	v_fma_f32 v94, v96, s80, -v84
	v_add_f32_e32 v84, v85, v101
	v_pk_add_f32 v[2:3], v[2:3], v[88:89] neg_lo:[0,1] neg_hi:[0,1]
	v_pk_mul_f32 v[84:85], v[84:85], s[0:1] op_sel_hi:[0,1]
	v_sub_f32_e32 v88, v203, v93
	v_pk_add_f32 v[218:219], v[112:113], v[114:115]
	v_pk_add_f32 v[236:237], v[116:117], v[182:183]
	v_sub_f32_e32 v120, v182, v116
	v_sub_f32_e32 v121, v174, v176
	v_mov_b32_e32 v210, v113
	v_mov_b32_e32 v226, v115
	v_fma_f32 v92, v88, s22, -v84
	v_fma_f32 v93, v88, s23, v85
	v_sub_f32_e32 v112, v112, v114
	v_sub_f32_e32 v113, v206, v208
	v_sub_f32_e32 v114, v175, v177
	v_sub_f32_e32 v115, v117, v183
	v_pk_mul_f32 v[106:107], v[106:107], s[70:71]
	v_pk_mul_f32 v[84:85], v[86:87], s[22:23] op_sel_hi:[0,1]
	v_mov_b32_e32 v227, v209
	v_pk_mul_f32 v[114:115], v[114:115], s[20:21] op_sel_hi:[1,0]
	v_mul_f32_e32 v100, 0x3f3504f3, v103
	v_fma_f32 v118, v98, s38, -v106
	v_fma_f32 v99, v99, s39, v107
	v_fma_f32 v86, v4, s0, -v84
	v_fma_f32 v87, v4, s1, v85
	v_pk_add_f32 v[214:215], v[174:175], v[176:177]
	v_pk_add_f32 v[224:225], v[206:207], v[208:209]
	v_mov_b32_e32 v105, v111
	v_sub_f32_e32 v210, v210, v226
	v_sub_f32_e32 v211, v207, v227
	v_fma_f32 v117, v113, s3, -v115
	v_fma_f32 v174, v112, s2, v114
	v_sub_f32_e32 v108, v100, v109
	v_fmac_f32_e32 v109, 0x3f3504f3, v103
	v_pk_add_f32 v[238:239], v[218:219], v[224:225]
	v_pk_add_f32 v[240:241], v[214:215], v[236:237]
	v_pk_fma_f32 v[112:113], v[112:113], s[20:21], v[114:115] op_sel_hi:[1,0,1] neg_lo:[0,0,1] neg_hi:[0,0,1]
	v_sub_f32_e32 v114, v120, v210
	v_pk_add_f32 v[182:183], v[120:121], v[210:211]
	v_pk_add_f32 v[4:5], v[104:105], v[108:109]
	v_pk_add_f32 v[84:85], v[92:93], v[86:87]
	v_add_f32_e32 v96, v118, v110
	v_add_f32_e32 v97, v99, v94
	v_pk_add_f32 v[100:101], v[2:3], v[90:91]
	v_pk_add_f32 v[242:243], v[240:241], v[238:239]
	v_mov_b32_e32 v115, v183
	v_add_f32_e32 v176, v112, v117
	v_add_f32_e32 v177, v113, v174
	v_pk_add_f32 v[88:89], v[4:5], v[84:85]
	v_pk_add_f32 v[102:103], v[100:101], v[96:97]
	v_pk_add_f32 v[206:207], v[114:115], v[176:177]
	ds_write2_b64 v179, v[242:243], v[88:89] offset1:17
	ds_write2_b64 v179, v[206:207], v[102:103] offset0:34 offset1:51
	v_mov_b32_e32 v89, v218
	v_mov_b32_e32 v103, v224
	v_mov_b32_e32 v224, v215
	v_mov_b32_e32 v218, v237
	v_sub_f32_e32 v88, v236, v214
	v_sub_f32_e32 v89, v89, v103
	v_pk_add_f32 v[102:103], v[224:225], v[218:219] neg_lo:[0,1] neg_hi:[0,1]
	v_pk_add_f32 v[104:105], v[104:105], v[108:109] neg_lo:[0,1] neg_hi:[0,1]
	v_pk_add_f32 v[86:87], v[92:93], v[86:87] neg_lo:[0,1] neg_hi:[0,1]
	v_sub_f32_e32 v106, v88, v102
	v_pk_add_f32 v[180:181], v[88:89], v[102:103]
	v_pk_add_f32 v[92:93], v[104:105], v[86:87] op_sel:[0,1] op_sel_hi:[1,0] neg_lo:[0,1] neg_hi:[0,1]
	v_pk_add_f32 v[86:87], v[104:105], v[86:87] op_sel:[0,1] op_sel_hi:[1,0]
	v_mov_b32_e32 v107, v181
	v_mov_b32_e32 v104, v92
	v_mov_b32_e32 v105, v87
	ds_write2_b64 v179, v[106:107], v[104:105] offset0:68 offset1:85
	v_sub_f32_e32 v183, v211, v121
	v_sub_f32_e32 v104, v174, v113
	v_sub_f32_e32 v105, v112, v117
	v_sub_f32_e32 v94, v99, v94
	v_sub_f32_e32 v95, v2, v90
	v_sub_f32_e32 v2, v110, v118
	v_sub_f32_e32 v3, v3, v91
	v_pk_add_f32 v[106:107], v[182:183], v[104:105] neg_lo:[0,1] neg_hi:[0,1]
	v_pk_add_f32 v[104:105], v[182:183], v[104:105]
	v_pk_add_f32 v[90:91], v[2:3], v[94:95] neg_lo:[0,1] neg_hi:[0,1]
	v_pk_add_f32 v[2:3], v[2:3], v[94:95]
	v_mov_b32_e32 v108, v106
	v_mov_b32_e32 v109, v105
	v_mov_b32_e32 v94, v90
	v_mov_b32_e32 v95, v3
	ds_write2_b64 v179, v[108:109], v[94:95] offset0:102 offset1:119
	v_mov_b32_e32 v95, v239
	v_mov_b32_e32 v239, v241
	v_sub_f32_e32 v94, v240, v238
	v_sub_f32_e32 v95, v95, v239
	v_pk_add_f32 v[4:5], v[4:5], v[84:85] neg_lo:[0,1] neg_hi:[0,1]
	v_mov_b32_e32 v85, v101
	ds_write2_b64 v179, v[94:95], v[4:5] offset0:136 offset1:153
	v_pk_add_f32 v[4:5], v[114:115], v[176:177] neg_lo:[0,1] neg_hi:[0,1]
	v_sub_f32_e32 v84, v96, v100
	v_sub_f32_e32 v85, v85, v97
	ds_write2_b64 v179, v[4:5], v[84:85] offset0:170 offset1:187
	v_sub_f32_e32 v181, v103, v89
	v_mov_b32_e32 v105, v107
	v_mov_b32_e32 v3, v91
	v_add_u32_e32 v112, s43, v78
	v_mov_b32_e32 v87, v93
	ds_write2_b64 v179, v[104:105], v[2:3] offset0:238 offset1:255
	v_mov_b32_e32 v2, v78
	v_ashrrev_i32_e32 v113, 31, v112
	ds_write2_b64 v179, v[180:181], v[86:87] offset0:204 offset1:221
	s_waitcnt lgkmcnt(0)
	s_barrier
	v_lshl_add_u64 v[112:113], v[112:113], 2, s[94:95]
	v_ashrrev_i32_e32 v3, 31, v2
	s_movk_i32 s0, 0x1000
	v_lshrrev_b32_e32 v3, 24, v3
	v_add_co_u32_e32 v114, vcc, s0, v112
	v_and_b32_e32 v182, 0xff, v2
	v_add_lshl_u32 v2, v2, v3, 4
	v_addc_co_u32_e32 v115, vcc, 0, v113, vcc
	v_and_or_b32 v2, v2, s87, v182
	v_add_co_u32_e32 v202, vcc, s27, v112
	v_ashrrev_i32_e32 v3, 4, v2
	v_lshlrev_b32_e32 v2, 3, v2
	v_addc_co_u32_e32 v203, vcc, 0, v113, vcc
	v_lshl_add_u32 v2, v3, 3, v2
	v_add_co_u32_e32 v204, vcc, s86, v112
	ds_read_b64 v[84:85], v2
	ds_read_b64 v[110:111], v2 offset:2176
	ds_read_b64 v[108:109], v2 offset:4352
	ds_read_b64 v[106:107], v2 offset:6528
	ds_read_b64 v[104:105], v2 offset:8704
	ds_read_b64 v[102:103], v2 offset:10880
	ds_read_b64 v[100:101], v2 offset:13056
	ds_read_b64 v[98:99], v2 offset:15232
	ds_read_b64 v[96:97], v2 offset:17408
	ds_read_b64 v[94:95], v2 offset:19584
	ds_read_b64 v[92:93], v2 offset:21760
	ds_read_b64 v[90:91], v2 offset:23936
	ds_read_b64 v[88:89], v2 offset:26112
	ds_read_b64 v[86:87], v2 offset:28288
	ds_read_b64 v[4:5], v2 offset:30464
	ds_read_b64 v[2:3], v2 offset:32640
	v_addc_co_u32_e32 v205, vcc, 0, v113, vcc
	global_load_dword v180, v[112:113], off
	global_load_dword v179, v[112:113], off offset:1024
	global_load_dword v177, v[112:113], off offset:2048
	global_load_dword v176, v[112:113], off offset:3072
	global_load_dword v174, v[114:115], off offset:1024
	global_load_dword v121, v[114:115], off offset:2048
	global_load_dword v120, v[114:115], off offset:3072
	s_nop 0
	global_load_dword v115, v[204:205], off
	global_load_dword v175, v[202:203], off offset:-4096
	global_load_dword v119, v[202:203], off
	global_load_dword v118, v[202:203], off offset:1024
	global_load_dword v117, v[202:203], off offset:2048
	global_load_dword v116, v[202:203], off offset:3072
	global_load_dword v114, v[204:205], off offset:1024
	global_load_dword v113, v[204:205], off offset:2048
	global_load_dword v112, v[204:205], off offset:3072
	v_lshl_add_u64 v[202:203], s[40:41], 0, v[80:81]
	v_add_co_u32_e32 v206, vcc, s27, v202
	v_lshl_add_u64 v[214:215], s[40:41], 0, v[82:83]
	s_nop 0
	v_addc_co_u32_e32 v207, vcc, 0, v203, vcc
	s_nop 1
	s_waitcnt lgkmcnt(0)
	s_barrier
	global_load_dwordx4 v[202:205], v[202:203], off
	s_nop 0
	global_load_dwordx4 v[206:209], v[206:207], off
	s_nop 0
	global_load_dwordx4 v[210:213], v[214:215], off
	v_add_co_u32_e32 v214, vcc, 0x2000, v214
	s_nop 1
	v_addc_co_u32_e32 v215, vcc, 0, v215, vcc
	global_load_dwordx4 v[214:217], v[214:215], off
	s_andn2_b64 vcc, exec, s[90:91]
	s_waitcnt vmcnt(3)
	ds_write_b128 v79, v[202:205]
	s_waitcnt vmcnt(2)
	ds_write_b128 v79, v[206:209] offset:8192
	s_waitcnt vmcnt(1)
	ds_write_b128 v79, v[210:213] offset:4096
	s_waitcnt vmcnt(0)
	ds_write_b128 v79, v[214:217] offset:12288
	s_cbranch_vccnz .LBB0_512
	v_lshl_add_u64 v[80:81], s[68:69], 0, v[80:81]
	v_add_co_u32_e32 v202, vcc, 0xb04e000, v80
	s_nop 1
	v_addc_co_u32_e32 v203, vcc, 0, v81, vcc
	v_add_co_u32_e32 v80, vcc, 0xb050000, v80
	global_load_dwordx4 v[202:205], v[202:203], off
	s_nop 0
	v_addc_co_u32_e32 v81, vcc, 0, v81, vcc
	global_load_dwordx4 v[206:209], v[80:81], off
	s_waitcnt vmcnt(1)
	ds_write_b128 v79, v[202:205] offset:16384
	s_waitcnt vmcnt(0)
	ds_write_b128 v79, v[206:209] offset:24576
	v_lshl_add_u64 v[202:203], s[68:69], 0, v[82:83]
	v_add_co_u32_e32 v80, vcc, 0xb04e000, v202
	s_nop 1
	v_addc_co_u32_e32 v81, vcc, 0, v203, vcc
	v_add_co_u32_e32 v202, vcc, 0xb050000, v202
	global_load_dwordx4 v[80:83], v[80:81], off
	s_nop 0
	v_addc_co_u32_e32 v203, vcc, 0, v203, vcc
	global_load_dwordx4 v[202:205], v[202:203], off
	s_waitcnt vmcnt(1)
	ds_write_b128 v79, v[80:83] offset:20480
	s_waitcnt vmcnt(0)
	ds_write_b128 v79, v[202:205] offset:28672

.LBB0_586:
	v_add_u32_e32 v18, s2, v49
	v_ashrrev_i32_e32 v19, 31, v18
	v_lshlrev_b64 v[2:3], 12, v[18:19]
	v_lshl_add_u64 v[2:3], v[24:25], 0, v[2:3]
	global_load_dwordx4 v[14:17], v[2:3], off
	global_load_dwordx4 v[10:13], v[2:3], off offset:1024
	v_mov_b32_e32 v29, v0
	v_mov_b32_e32 v31, v0
	v_mov_b32_e32 v33, v0
	v_mov_b32_e32 v35, v0
	s_add_i32 s2, s2, 1
	s_cmp_lg_u32 s2, 4
	s_waitcnt vmcnt(1)
	s_waitcnt vmcnt(0)
	v_mul_f32_e32 v6, v15, v15
	v_mul_f32_e32 v7, v11, v11
	s_nop 0
	v_fma_f32 v4, v14, v14, v6
	v_fma_f32 v5, v10, v10, v7
	v_fma_f32 v4, v16, v16, v4
	v_fma_f32 v5, v12, v12, v5
	v_fma_f32 v20, v17, v17, v4
	v_fma_f32 v21, v13, v13, v5
	global_load_dwordx4 v[6:9], v[2:3], off offset:2048
	s_nop 0
	global_load_dwordx4 v[2:5], v[2:3], off offset:3072
	v_add_f32_e32 v20, v20, v21
	global_load_dwordx4 v[50:53], v[22:23], off
	s_waitcnt vmcnt(2)
	s_waitcnt vmcnt(1)
	v_mul_f32_e32 v40, v7, v7
	v_mul_f32_e32 v41, v3, v3
	s_nop 0
	v_fma_f32 v38, v6, v6, v40
	v_fma_f32 v39, v2, v2, v41
	v_fma_f32 v38, v8, v8, v38
	v_fma_f32 v39, v4, v4, v39
	v_fma_f32 v38, v9, v9, v38
	v_fma_f32 v39, v5, v5, v39
	s_nop 0
	v_add_f32_e32 v20, v20, v38
	v_add_f32_e32 v20, v20, v39
	ds_bpermute_b32 v21, v37, v20
	s_nop 2
	s_waitcnt lgkmcnt(0)
	v_add_f32_e32 v20, v20, v21
	ds_bpermute_b32 v21, v44, v20
	s_nop 2
	s_waitcnt lgkmcnt(0)
	v_add_f32_e32 v20, v20, v21
	ds_bpermute_b32 v21, v45, v20
	s_nop 2
	s_waitcnt lgkmcnt(0)
	v_add_f32_e32 v20, v20, v21
	ds_bpermute_b32 v21, v46, v20
	s_nop 2
	s_waitcnt lgkmcnt(0)
	v_add_f32_e32 v20, v20, v21
	ds_bpermute_b32 v21, v47, v20
	s_nop 2
	s_waitcnt lgkmcnt(0)
	v_add_f32_e32 v20, v20, v21
	ds_bpermute_b32 v21, v48, v20
	s_waitcnt lgkmcnt(0)
	v_add_f32_e32 v20, v20, v21
	v_fmamk_f32 v20, v20, 0x3a800000, v188
	v_cmp_gt_f32_e32 vcc, s6, v20
	s_nop 2
	v_mul_f32_e32 v21, 0x4b800000, v20
	s_nop 0
	v_cndmask_b32_e32 v20, v20, v21, vcc
	v_rsq_f32_e32 v20, v20
	s_nop 0
	v_mul_f32_e32 v21, 0x45800000, v20
	v_cndmask_b32_e32 v36, v20, v21, vcc
	v_cmp_lt_i32_e32 vcc, s43, v18
	v_pk_mul_f32 v[14:15], v[14:15], v[36:37] op_sel_hi:[1,0]
	v_pk_mul_f32 v[16:17], v[16:17], v[36:37] op_sel_hi:[1,0]
	v_cndmask_b32_e32 v20, v187, v1, vcc
	v_ashrrev_i32_e32 v21, 31, v20
	v_lshl_add_u64 v[20:21], v[20:21], 2, s[4:5]
	v_lshl_add_u64 v[38:39], v[20:21], 0, s[8:9]
	v_lshl_add_u64 v[42:43], v[20:21], 0, v[28:29]
	v_lshl_add_u64 v[20:21], v[38:39], 0, v[28:29]
	global_load_dwordx4 v[58:61], v[20:21], off
	global_load_dwordx4 v[54:57], v[42:43], off
	s_waitcnt vmcnt(2)
	v_pk_mul_f32 v[14:15], v[50:51], v[14:15]
	v_pk_mul_f32 v[16:17], v[52:53], v[16:17]
	v_lshlrev_b64 v[18:19], 11, v[18:19]
	v_lshl_add_u64 v[40:41], v[26:27], 0, v[18:19]
	v_lshl_add_u64 v[50:51], v[38:39], 0, v[30:31]
	v_pk_mul_f32 v[10:11], v[10:11], v[36:37] op_sel_hi:[1,0]
	v_pk_mul_f32 v[12:13], v[12:13], v[36:37] op_sel_hi:[1,0]
	v_pk_mul_f32 v[6:7], v[6:7], v[36:37] op_sel_hi:[1,0]
	v_pk_mul_f32 v[8:9], v[8:9], v[36:37] op_sel_hi:[1,0]
	v_pk_mul_f32 v[2:3], v[2:3], v[36:37] op_sel_hi:[1,0]
	v_pk_mul_f32 v[4:5], v[4:5], v[36:37] op_sel_hi:[1,0]
	s_waitcnt vmcnt(1)
	v_pk_add_f32 v[20:21], v[58:59], 1.0 op_sel_hi:[1,0]
	s_waitcnt vmcnt(0)
	v_pk_fma_f32 v[14:15], v[20:21], v[14:15], v[54:55]
	v_pk_add_f32 v[20:21], v[60:61], 1.0 op_sel_hi:[1,0]
	v_cvt_pk_bf16_f32 v14, v14, v15
	v_pk_fma_f32 v[16:17], v[20:21], v[16:17], v[56:57]
	s_nop 0
	v_cvt_pk_bf16_f32 v15, v16, v17
	global_store_dwordx2 v[40:41], v[14:15], off
	global_load_dwordx4 v[18:21], v[22:23], off offset:1024
	s_nop 0
	global_load_dwordx4 v[14:17], v[42:43], off offset:1024
	s_waitcnt vmcnt(1)
	v_pk_mul_f32 v[10:11], v[18:19], v[10:11]
	global_load_dwordx4 v[50:53], v[50:51], off
	v_pk_mul_f32 v[12:13], v[20:21], v[12:13]
	s_waitcnt vmcnt(0)
	v_pk_add_f32 v[18:19], v[50:51], 1.0 op_sel_hi:[1,0]
	s_nop 0
	v_pk_fma_f32 v[10:11], v[18:19], v[10:11], v[14:15]
	v_pk_add_f32 v[14:15], v[52:53], 1.0 op_sel_hi:[1,0]
	v_cvt_pk_bf16_f32 v10, v10, v11
	v_pk_fma_f32 v[12:13], v[14:15], v[12:13], v[16:17]
	v_lshl_add_u64 v[18:19], v[38:39], 0, v[32:33]
	v_cvt_pk_bf16_f32 v11, v12, v13
	global_store_dwordx2 v[40:41], v[10:11], off offset:512
	global_load_dwordx4 v[10:13], v[22:23], off offset:2048
	s_nop 0
	global_load_dwordx4 v[14:17], v[42:43], off offset:2048
	s_waitcnt vmcnt(1)
	v_pk_mul_f32 v[6:7], v[10:11], v[6:7]
	global_load_dwordx4 v[18:21], v[18:19], off
	v_pk_mul_f32 v[8:9], v[12:13], v[8:9]
	s_waitcnt vmcnt(0)
	v_pk_add_f32 v[10:11], v[18:19], 1.0 op_sel_hi:[1,0]
	s_nop 0
	v_pk_fma_f32 v[6:7], v[10:11], v[6:7], v[14:15]
	v_pk_add_f32 v[10:11], v[20:21], 1.0 op_sel_hi:[1,0]
	v_cvt_pk_bf16_f32 v6, v6, v7
	v_pk_fma_f32 v[8:9], v[10:11], v[8:9], v[16:17]
	v_lshl_add_u64 v[14:15], v[38:39], 0, v[34:35]
	v_cvt_pk_bf16_f32 v7, v8, v9
	global_store_dwordx2 v[40:41], v[6:7], off offset:1024
	global_load_dwordx4 v[6:9], v[22:23], off offset:3072
	s_nop 0
	global_load_dwordx4 v[10:13], v[42:43], off offset:3072
	s_waitcnt vmcnt(1)
	v_pk_mul_f32 v[2:3], v[6:7], v[2:3]
	global_load_dwordx4 v[14:17], v[14:15], off
	v_pk_mul_f32 v[4:5], v[8:9], v[4:5]
	s_waitcnt vmcnt(0)
	v_pk_add_f32 v[6:7], v[14:15], 1.0 op_sel_hi:[1,0]
	s_nop 0
	v_pk_fma_f32 v[2:3], v[2:3], v[6:7], v[10:11]
	v_pk_add_f32 v[6:7], v[16:17], 1.0 op_sel_hi:[1,0]
	v_cvt_pk_bf16_f32 v2, v2, v3
	v_pk_fma_f32 v[4:5], v[4:5], v[6:7], v[12:13]
	s_nop 0
	v_cvt_pk_bf16_f32 v3, v4, v5
	global_store_dwordx2 v[40:41], v[2:3], off offset:1536
	s_cbranch_scc1 .LBB0_586
	v_readlane_b32 s2, v245, 36
	s_add_i32 s1, s1, s94
	s_add_i32 s0, s0, s2
	s_cmpk_gt_i32 s1, 0x9ff
	s_cbranch_scc0 .LBB0_585

.LBB0_654:
	s_waitcnt vmcnt(1)
	v_lshlrev_b32_e32 v18, 16, v34
	v_lshlrev_b32_e32 v34, 16, v32
	v_lshlrev_b32_e32 v32, 16, v22
	v_lshlrev_b32_e32 v22, 16, v10
	v_lshlrev_b32_e32 v10, 16, v3
	v_mov_b32_e32 v3, v1
	v_lshlrev_b32_e32 v52, 16, v6
	v_lshlrev_b32_e32 v6, 16, v5
	s_barrier
	v_lshlrev_b32_e32 v48, 16, v14
	v_ashrrev_i32_e32 v5, 31, v3
	v_lshrrev_b32_e32 v5, 28, v5
	v_and_b32_e32 v41, 15, v3
	v_add_u32_e32 v3, v3, v5
	v_lshlrev_b32_e32 v14, 16, v13
	v_ashrrev_i32_e32 v3, 4, v3
	v_lshlrev_b32_e32 v36, 16, v31
	v_lshlrev_b32_e32 v44, 16, v26
	v_lshlrev_b32_e32 v26, 16, v25
	v_lshlrev_b32_e32 v5, 11, v3
	s_waitcnt vmcnt(0)
	v_lshlrev_b32_e32 v16, 16, v16
	v_lshlrev_b32_e32 v42, 16, v29
	v_lshlrev_b32_e32 v46, 16, v21
	v_lshlrev_b32_e32 v50, 16, v9
	v_lshl_add_u32 v3, v3, 7, v5
	v_pk_add_f32 v[54:55], v[10:11], v[32:33]
	v_pk_add_f32 v[10:11], v[10:11], v[32:33] neg_lo:[0,1] neg_hi:[0,1]
	v_pk_add_f32 v[32:33], v[22:23], v[36:37]
	v_mov_b32_e32 v56, v23
	v_mov_b32_e32 v57, v22
	v_sub_f32_e32 v58, v48, v18
	v_sub_f32_e32 v59, v14, v34
	v_sub_f32_e32 v22, v56, v37
	v_sub_f32_e32 v23, v57, v36
	v_pk_add_f32 v[36:37], v[6:7], v[26:27]
	v_sub_f32_e32 v56, v52, v44
	v_sub_f32_e32 v57, v6, v26
	v_sub_f32_e32 v6, v4, v24
	v_sub_f32_e32 v7, v7, v27
	v_pk_add_f32 v[26:27], v[14:15], v[34:35]
	v_sub_f32_e32 v14, v12, v30
	v_sub_f32_e32 v15, v15, v35
	v_mov_b32_e32 v53, v4
	v_mov_b32_e32 v45, v24
	v_sub_f32_e32 v5, v4, v24
	v_sub_f32_e32 v4, v50, v42
	v_add_f32_e32 v24, v48, v18
	v_add_f32_e32 v25, v12, v30
	v_sub_f32_e32 v19, v48, v18
	v_sub_f32_e32 v18, v8, v28
	v_sub_f32_e32 v13, v12, v30
	v_sub_f32_e32 v12, v46, v16
	v_lshl_or_b32 v96, v41, 3, v3
	v_pk_add_f32 v[34:35], v[52:53], v[44:45]
	v_mov_b32_e32 v3, v52
	v_pk_add_f32 v[52:53], v[4:5], v[18:19] neg_lo:[0,1] neg_hi:[0,1]
	v_add_f32_e32 v9, v8, v28
	v_add_f32_e32 v8, v46, v16
	v_pk_add_f32 v[16:17], v[4:5], v[18:19]
	v_pk_add_f32 v[4:5], v[36:37], v[26:27] neg_lo:[0,1] neg_hi:[0,1]
	v_pk_mul_f32 v[18:19], v[4:5], s[20:21] op_sel_hi:[1,0]
	v_pk_fma_f32 v[28:29], v[4:5], s[20:21], v[18:19] op_sel:[0,0,1] op_sel_hi:[1,0,0]
	v_cvt_f32_i32_e32 v4, v41
	v_sub_f32_e32 v45, v3, v44
	v_sub_f32_e32 v44, v2, v20
	v_add_f32_e32 v21, v2, v20
	v_add_f32_e32 v20, v50, v42
	v_pk_add_f32 v[30:31], v[34:35], v[24:25] neg_lo:[0,1] neg_hi:[0,1]
	v_pk_add_f32 v[2:3], v[20:21], v[8:9] neg_lo:[0,1] neg_hi:[0,1]
	v_add_f32_e32 v64, v10, v22
	v_mul_f32_e32 v42, 0x3f3504f3, v2
	v_add_f32_e32 v2, v4, v4
	v_mul_f32_e32 v2, 0x3b800000, v2
	v_pk_add_f32 v[4:5], v[36:37], v[26:27]
	v_pk_add_f32 v[26:27], v[34:35], v[24:25]
	v_sub_f32_e32 v65, v11, v23
	s_mov_b32 s28, s71
	s_mov_b32 s29, s21
	v_add_f32_e32 v34, v57, v15
	s_mov_b32 s70, s21
	v_pk_add_f32 v[48:49], v[44:45], v[12:13]
	v_pk_add_f32 v[12:13], v[44:45], v[12:13] neg_lo:[0,1] neg_hi:[0,1]
	v_mul_f32_e32 v2, 0.5, v2
	v_sub_f32_e32 v24, v7, v59
	v_pk_mul_f32 v[66:67], v[34:35], s[70:71] op_sel_hi:[0,1]
	v_pk_mul_f32 v[70:71], v[16:17], s[28:29] op_sel_hi:[0,1]
	v_mul_f32_e32 v41, 0x3f3504f3, v49
	v_mul_f32_e32 v43, 0x3f3504f3, v53
	v_sin_f32_e32 v44, v2
	v_fma_f32 v68, v24, s28, v66
	v_fma_f32 v69, v24, s29, -v67
	v_fma_f32 v72, v12, s70, v70
	v_fma_f32 v73, v12, s71, -v71
	v_cos_f32_e32 v60, v2
	s_nop 1
	v_add_f32_e32 v66, v43, v41
	v_fma_f32 v67, v53, s20, -v41
	v_pk_add_f32 v[70:71], v[64:65], v[66:67]
	v_pk_add_f32 v[74:75], v[68:69], v[72:73]
	v_mul_f32_e32 v46, 0x3f3504f3, v3
	v_pk_add_f32 v[76:77], v[70:71], v[74:75]
	v_mul_f32_e32 v51, 0xbf3504f3, v3
	v_xor_b32_e32 v61, 0x80000000, v44
	v_pk_add_f32 v[2:3], v[54:55], v[32:33]
	v_pk_add_f32 v[8:9], v[20:21], v[8:9]
	v_pk_add_f32 v[70:71], v[70:71], v[74:75] neg_lo:[0,1] neg_hi:[0,1]
	v_pk_mul_f32 v[74:75], v[76:77], v[44:45] op_sel_hi:[1,0]
	v_pk_add_f32 v[20:21], v[2:3], v[26:27]
	v_pk_add_f32 v[36:37], v[4:5], v[8:9]
	v_fma_f32 v78, v76, v60, v75
	v_fma_f32 v79, v77, v60, -v74
	v_pk_add_f32 v[62:63], v[20:21], v[36:37]
	v_mov_b32_e32 v24, v25
	v_pk_add_f32 v[14:15], v[56:57], v[14:15] neg_lo:[0,1] neg_hi:[0,1]
	v_pk_add_f32 v[6:7], v[6:7], v[58:59]
	v_readlane_b32 s4, v245, 26
	s_nop 1
	ds_write2_b64 v96, v[62:63], v[78:79] offset1:17
	v_mov_b32_e32 v74, v32
	v_sub_f32_e32 v32, v46, v42
	v_sub_f32_e32 v33, v55, v33
	v_sub_f32_e32 v24, v35, v24
	v_sub_f32_e32 v25, v51, v42
	v_mov_b32_e32 v42, v28
	v_mov_b32_e32 v43, v30
	v_mov_b32_e32 v53, v17
	v_mov_b32_e32 v49, v13
	v_mul_f32_e32 v12, 0x3ec3ef15, v15
	v_mul_f32_e32 v16, 0x3f6c835e, v7
	s_mov_b32 s28, s3
	s_mov_b32 s29, s76
	v_readlane_b32 s5, v245, 27
	s_nop 0
	v_mov_b32_e32 v45, v60
	v_sub_f32_e32 v19, v19, v18
	v_sub_f32_e32 v18, v54, v74
	v_pk_add_f32 v[34:35], v[32:33], v[30:31] op_sel:[1,0] op_sel_hi:[0,1]
	v_add_f32_e32 v30, v32, v42
	v_sub_f32_e32 v43, v33, v43
	v_add_f32_e32 v12, v16, v12
	v_add_f32_e32 v13, v11, v23
	v_pk_mul_f32 v[14:15], v[14:15], s[28:29]
	s_mov_b32 s70, s20
	v_pk_mul_f32 v[16:17], v[48:49], s[4:5]
	v_mul_f32_e32 v50, v44, v44
	v_mul_f32_e32 v51, v45, v61
	v_pk_add_f32 v[46:47], v[18:19], v[24:25]
	v_pk_fma_f32 v[6:7], v[6:7], s[70:71], v[14:15]
	v_pk_fma_f32 v[14:15], v[52:53], s[30:31], v[16:17]
	v_mul_f32_e32 v11, 0x3ec3ef15, v52
	v_pk_fma_f32 v[52:53], v[60:61], v[60:61], v[50:51] op_sel_hi:[0,1,1] neg_lo:[0,0,1] neg_hi:[0,0,1]
	v_pk_fma_f32 v[50:51], v[60:61], v[60:61], v[50:51] op_sel_hi:[0,1,1]
	v_pk_add_f32 v[18:19], v[18:19], v[24:25] neg_lo:[0,1] neg_hi:[0,1]
	v_add_f32_e32 v24, v46, v30
	v_add_f32_e32 v25, v47, v43
	v_mov_b32_e32 v54, v52
	v_mov_b32_e32 v55, v51
	v_mul_f32_e32 v62, v51, v51
	v_mul_f32_e32 v63, v51, v52
	v_pk_mul_f32 v[50:51], v[24:25], v[50:51] op_sel:[1,1] op_sel_hi:[0,1]
	v_pk_fma_f32 v[74:75], v[52:53], v[54:55], v[62:63] op_sel_hi:[0,1,1] neg_lo:[0,0,1] neg_hi:[0,0,1]
	v_pk_fma_f32 v[62:63], v[52:53], v[54:55], v[62:63] op_sel_hi:[0,1,1]
	v_fma_f32 v84, v24, v52, -v50
	v_fma_f32 v85, v25, v52, v51
	v_pk_add_f32 v[28:29], v[28:29], v[32:33] neg_lo:[0,1] neg_hi:[0,1]
	v_pk_add_f32 v[24:25], v[64:65], v[66:67] neg_lo:[0,1] neg_hi:[0,1]
	v_pk_mul_f32 v[66:67], v[54:55], v[62:63] op_sel:[0,1]
	v_pk_add_f32 v[50:51], v[68:69], v[72:73] neg_lo:[0,1] neg_hi:[0,1]
	v_fma_f32 v68, v54, v74, -v67
	v_fma_f32 v67, v55, v74, v66
	v_pk_add_f32 v[32:33], v[34:35], v[28:29]
	v_sub_f32_e32 v28, v34, v28
	v_mov_b32_e32 v72, v68
	v_mov_b32_e32 v73, v67
	v_pk_add_f32 v[86:87], v[18:19], v[18:19] op_sel:[0,1] op_sel_hi:[0,1]
	v_mul_f32_e32 v29, v28, v68
	v_mul_f32_e32 v28, v28, v67
	v_mov_b32_e32 v76, v74
	v_mov_b32_e32 v77, v63
	v_fma_f32 v34, v86, v68, -v28
	v_fma_f32 v35, v87, v73, v29
	v_pk_add_f32 v[20:21], v[20:21], v[36:37] neg_lo:[0,1] neg_hi:[0,1]
	v_pk_mul_f32 v[28:29], v[76:77], v[62:63] op_sel:[0,1]
	v_mov_b32_e32 v61, v44
	v_pk_fma_f32 v[36:37], v[74:75], v[76:77], v[28:29] op_sel:[0,0,1] op_sel_hi:[0,1,0] neg_lo:[0,0,1] neg_hi:[0,0,1]
	v_pk_fma_f32 v[28:29], v[74:75], v[76:77], v[28:29] op_sel:[0,0,1] op_sel_hi:[0,1,0]
	v_pk_mov_b32 v[66:67], v[28:29], v[36:37] op_sel:[1,0]
	v_pk_mul_f32 v[58:59], v[44:45], v[54:55]
	v_pk_mul_f32 v[80:81], v[44:45], v[76:77]
	v_pk_mov_b32 v[82:83], v[62:63], v[74:75] op_sel:[1,0]
	v_mov_b32_e32 v62, v36
	v_mov_b32_e32 v63, v29
	v_pk_mul_f32 v[44:45], v[44:45], v[66:67] op_sel_hi:[0,1]
	v_mul_f32_e32 v23, 0x3f6c835e, v48
	v_fma_f32 v68, v60, v62, v44
	v_fma_f32 v45, v60, v63, -v45
	v_pk_add_f32 v[10:11], v[10:11], v[22:23] neg_lo:[0,1] neg_hi:[0,1]
	v_pk_mul_f32 v[56:57], v[60:61], v[54:55]
	v_pk_mul_f32 v[78:79], v[60:61], v[76:77]
	v_mov_b32_e32 v61, v45
	v_pk_add_f32 v[16:17], v[12:13], v[14:15]
	v_pk_add_f32 v[22:23], v[6:7], v[10:11]
	v_mov_b32_e32 v88, v56
	v_mov_b32_e32 v89, v59
	v_pk_mov_b32 v[56:57], v[56:57], v[58:59] op_sel:[1,0]
	v_mul_f32_e32 v44, v71, v45
	v_mul_f32_e32 v45, v71, v68
	v_pk_mul_f32 v[28:29], v[20:21], v[28:29] op_sel:[1,1] op_sel_hi:[0,1]
	v_pk_add_f32 v[48:49], v[16:17], v[22:23]
	v_pk_mul_f32 v[86:87], v[54:55], v[62:63]
	v_pk_mul_f32 v[54:55], v[54:55], v[66:67]
	v_pk_add_f32 v[58:59], v[88:89], v[56:57]
	v_pk_add_f32 v[56:57], v[88:89], v[56:57] neg_lo:[0,1] neg_hi:[0,1]
	v_fma_f32 v68, v70, v68, -v44
	v_fma_f32 v69, v70, v61, v45
	v_fma_f32 v70, v20, v36, -v28
	v_fma_f32 v71, v21, v36, v29
	v_mov_b32_e32 v42, v46
	v_pk_mul_f32 v[90:91], v[48:49], v[56:57] op_sel:[0,1]
	v_sub_f32_e32 v20, v42, v30
	v_sub_f32_e32 v21, v43, v47
	v_pk_add_f32 v[28:29], v[54:55], v[54:55] op_sel:[0,1] op_sel_hi:[0,1]
	v_fma_f32 v92, v48, v58, -v91
	v_fma_f32 v93, v49, v58, v90
	v_pk_mul_f32 v[28:29], v[20:21], v[28:29] op_sel:[1,0] op_sel_hi:[0,1]
	v_pk_add_f32 v[30:31], v[86:87], v[86:87] op_sel:[0,1] op_sel_hi:[0,1] neg_lo:[0,1] neg_hi:[0,1]
	v_fma_f32 v36, v20, v30, -v28
	v_fma_f32 v37, v21, v31, v29
	ds_write2_b64 v96, v[84:85], v[92:93] offset0:34 offset1:51
	v_mul_f32_e32 v84, v58, v62
	v_mul_f32_e32 v85, v57, v63
	v_mul_f32_e32 v88, v58, v66
	v_mul_f32_e32 v89, v57, v67
	v_mov_b32_e32 v21, v17
	v_sub_f32_e32 v16, v22, v16
	v_sub_f32_e32 v17, v21, v23
	v_pk_add_f32 v[20:21], v[88:89], v[88:89] op_sel:[0,1] op_sel_hi:[0,1]
	v_pk_mul_f32 v[20:21], v[16:17], v[20:21] op_sel:[1,0] op_sel_hi:[0,1]
	v_pk_add_f32 v[22:23], v[84:85], v[84:85] op_sel:[0,1] op_sel_hi:[0,1] neg_lo:[0,1] neg_hi:[0,1]
	v_pk_add_f32 v[2:3], v[2:3], v[26:27] neg_lo:[0,1] neg_hi:[0,1]
	v_pk_add_f32 v[4:5], v[4:5], v[8:9] neg_lo:[0,1] neg_hi:[0,1]
	v_fma_f32 v28, v16, v22, -v20
	v_fma_f32 v29, v17, v23, v21
	v_pk_add_f32 v[8:9], v[2:3], v[4:5] op_sel:[0,1] op_sel_hi:[1,0]
	v_pk_add_f32 v[2:3], v[2:3], v[4:5] op_sel:[0,1] op_sel_hi:[1,0] neg_lo:[0,1] neg_hi:[0,1]
	v_pk_add_f32 v[52:53], v[24:25], v[50:51] op_sel:[0,1] op_sel_hi:[1,0]
	v_pk_add_f32 v[24:25], v[24:25], v[50:51] op_sel:[0,1] op_sel_hi:[1,0] neg_lo:[0,1] neg_hi:[0,1]
	v_mov_b32_e32 v94, v78
	v_mov_b32_e32 v95, v81
	v_pk_mov_b32 v[78:79], v[78:79], v[80:81] op_sel:[1,0]
	v_pk_mul_f32 v[16:17], v[2:3], v[82:83] op_sel:[1,0]
	v_pk_mul_f32 v[92:93], v[76:77], v[66:67]
	v_pk_add_f32 v[80:81], v[94:95], v[78:79]
	v_sub_f32_e32 v79, v95, v79
	v_fma_f32 v20, v8, v74, -v16
	v_fma_f32 v21, v8, v77, v17
	v_mov_b32_e32 v51, v25
	v_pk_mul_f32 v[90:91], v[76:77], v[62:63]
	v_mov_b32_e32 v94, v80
	v_mov_b32_e32 v95, v79
	v_mul_f32_e32 v64, v25, v79
	v_mul_f32_e32 v65, v52, v79
	v_mov_b32_e32 v5, v9
	v_pk_add_f32 v[16:17], v[92:93], v[92:93] op_sel:[0,1] op_sel_hi:[0,1]
	v_fma_f32 v78, v52, v80, -v64
	v_fma_f32 v79, v51, v80, v65
	v_pk_mul_f32 v[64:65], v[66:67], v[94:95]
	v_mul_f32_e32 v8, v9, v16
	v_mul_f32_e32 v9, v2, v17
	v_pk_add_f32 v[16:17], v[90:91], v[90:91] op_sel:[0,1] op_sel_hi:[0,1] neg_lo:[0,1] neg_hi:[0,1]
	v_pk_mul_f32 v[50:51], v[62:63], v[94:95]
	v_fma_f32 v2, v2, v16, -v8
	v_fma_f32 v3, v5, v17, v9
	v_pk_add_f32 v[16:17], v[64:65], v[64:65] op_sel:[0,1] op_sel_hi:[0,1]
	v_mov_b32_e32 v5, v53
	v_mul_f32_e32 v8, v53, v16
	v_mul_f32_e32 v9, v24, v17
	v_pk_add_f32 v[16:17], v[50:51], v[50:51] op_sel:[0,1] op_sel_hi:[0,1] neg_lo:[0,1] neg_hi:[0,1]
	ds_write2_b64 v96, v[20:21], v[78:79] offset0:68 offset1:85
	v_fma_f32 v20, v24, v16, -v8
	v_fma_f32 v21, v5, v17, v9
	v_pk_mul_f32 v[44:45], v[62:63], v[72:73]
	ds_write2_b64 v96, v[2:3], v[20:21] offset0:204 offset1:221
	v_mov_b32_e32 v3, v44
	v_mov_b32_e32 v44, v19
	v_pk_mul_f32 v[60:61], v[66:67], v[72:73]
	v_sub_f32_e32 v2, v18, v44
	v_sub_f32_e32 v3, v3, v45
	v_pk_add_f32 v[8:9], v[60:61], v[60:61] op_sel:[0,1] op_sel_hi:[0,1]
	v_mul_f32_e32 v4, v32, v8
	v_mul_f32_e32 v5, v2, v9
	v_pk_mov_b32 v[8:9], v[2:3], v[32:33] op_sel:[1,0]
	v_pk_mul_f32 v[48:49], v[76:77], v[56:57] op_sel:[0,1]
	v_fma_f32 v16, v2, v8, -v4
	v_fma_f32 v17, v3, v9, v5
	v_sub_f32_e32 v2, v10, v6
	v_sub_f32_e32 v3, v13, v15
	v_pk_mov_b32 v[4:5], v[6:7], v[12:13] op_sel:[1,0]
	v_pk_fma_f32 v[56:57], v[76:77], v[58:59], v[48:49] op_sel:[0,0,1] op_sel_hi:[1,0,0] neg_lo:[0,0,1] neg_hi:[0,0,1]
	v_pk_fma_f32 v[48:49], v[76:77], v[58:59], v[48:49] op_sel:[0,0,1] op_sel_hi:[1,0,0]
	v_sub_f32_e32 v4, v4, v11
	v_sub_f32_e32 v5, v5, v14
	v_mov_b32_e32 v59, v49
	v_pk_mov_b32 v[48:49], v[48:49], v[56:57] op_sel:[1,0]
	v_pk_add_f32 v[6:7], v[2:3], v[4:5]
	v_pk_add_f32 v[2:3], v[2:3], v[4:5] neg_lo:[0,1] neg_hi:[0,1]
	v_mov_b32_e32 v58, v56
	v_pk_mul_f32 v[8:9], v[2:3], v[48:49] op_sel:[1,0]
	v_pk_mul_f32 v[66:67], v[66:67], v[58:59]
	v_fma_f32 v10, v6, v56, -v8
	v_fma_f32 v11, v6, v59, v9
	v_pk_mul_f32 v[62:63], v[62:63], v[58:59]
	v_mov_b32_e32 v5, v7
	v_pk_add_f32 v[8:9], v[66:67], v[66:67] op_sel:[0,1] op_sel_hi:[0,1]
	v_mul_f32_e32 v6, v7, v8
	v_mul_f32_e32 v7, v2, v9
	v_pk_add_f32 v[8:9], v[62:63], v[62:63] op_sel:[0,1] op_sel_hi:[0,1] neg_lo:[0,1] neg_hi:[0,1]
	v_fma_f32 v2, v2, v8, -v6
	v_fma_f32 v3, v5, v9, v7
	ds_write2_b64 v96, v[70:71], v[68:69] offset0:136 offset1:153
	ds_write2_b64 v96, v[16:17], v[2:3] offset0:238 offset1:255
	v_mov_b32_e32 v2, v1
	ds_write2_b64 v96, v[36:37], v[28:29] offset0:170 offset1:187
	ds_write2_b64 v96, v[34:35], v[10:11] offset0:102 offset1:119
	s_waitcnt lgkmcnt(0)
	s_barrier
	v_readlane_b32 s4, v246, 28
	v_mul_lo_u32 v26, v2, s33
	ds_read2_b64 v[2:5], v26 offset0:1 offset1:2
	ds_read_b32 v32, v26
	ds_read_b64 v[30:31], v26 offset:56
	ds_read2_b64 v[6:9], v26 offset0:8 offset1:9
	ds_read2_b64 v[10:13], v26 offset0:10 offset1:11
	ds_read2_b64 v[14:17], v26 offset0:12 offset1:13
	ds_read2_b64 v[18:21], v26 offset0:3 offset1:4
	ds_read2_b64 v[22:25], v26 offset0:5 offset1:6
	ds_read2_b64 v[26:29], v26 offset0:14 offset1:15
	s_waitcnt lgkmcnt(5)
	v_add_f32_e32 v7, v32, v6
	v_sub_f32_e32 v6, v32, v6
	s_waitcnt lgkmcnt(2)
	v_add_f32_e32 v14, v20, v14
	v_sub_f32_e32 v15, v21, v15
	v_add_f32_e32 v20, v7, v14
	v_sub_f32_e32 v7, v7, v14
	v_add_f32_e32 v14, v6, v15
	v_sub_f32_e32 v6, v6, v15
	v_add_f32_e32 v15, v2, v8
	v_add_f32_e32 v21, v3, v9
	v_sub_f32_e32 v2, v2, v8
	v_sub_f32_e32 v3, v3, v9
	s_waitcnt lgkmcnt(1)
	v_add_f32_e32 v8, v22, v16
	v_add_f32_e32 v9, v23, v17
	v_sub_f32_e32 v16, v22, v16
	v_sub_f32_e32 v17, v23, v17
	v_add_f32_e32 v22, v15, v8
	v_add_f32_e32 v23, v21, v9
	v_sub_f32_e32 v8, v15, v8
	v_sub_f32_e32 v9, v21, v9
	v_add_f32_e32 v15, v2, v17
	v_sub_f32_e32 v21, v3, v16
	v_sub_f32_e32 v2, v2, v17
	v_add_f32_e32 v3, v3, v16
	v_add_f32_e32 v16, v4, v10
	v_add_f32_e32 v17, v5, v11
	v_sub_f32_e32 v4, v4, v10
	v_sub_f32_e32 v5, v5, v11
	s_waitcnt lgkmcnt(0)
	v_add_f32_e32 v10, v24, v26
	v_add_f32_e32 v11, v25, v27
	v_sub_f32_e32 v25, v25, v27
	v_sub_f32_e32 v24, v24, v26
	v_add_f32_e32 v10, v16, v10
	v_add_f32_e32 v16, v4, v25
	v_sub_f32_e32 v4, v4, v25
	v_add_f32_e32 v25, v19, v13
	v_sub_f32_e32 v13, v19, v13
	v_add_f32_e32 v19, v31, v29
	v_sub_f32_e32 v26, v30, v28
	v_sub_f32_e32 v27, v31, v29
	v_add_f32_e32 v29, v25, v19
	v_sub_f32_e32 v19, v25, v19
	v_sub_f32_e32 v25, v13, v26
	v_add_f32_e32 v13, v13, v26
	v_mul_f32_e32 v26, 0x3f6c835e, v15
	v_mul_f32_e32 v15, 0xbec3ef15, v15
	v_mul_f32_e32 v8, 0x3f3504f3, v8
	v_sub_f32_e32 v11, v17, v11
	v_sub_f32_e32 v17, v5, v24
	v_add_f32_e32 v5, v5, v24
	v_add_f32_e32 v24, v18, v12
	v_sub_f32_e32 v12, v18, v12
	v_add_f32_e32 v18, v30, v28
	v_fmac_f32_e32 v26, 0x3ec3ef15, v21
	v_fmac_f32_e32 v15, 0x3f6c835e, v21
	v_fmamk_f32 v21, v9, 0x3f3504f3, v8
	v_fma_f32 v8, v9, s20, -v8
	v_mul_f32_e32 v9, 0x3ec3ef15, v2
	v_mul_f32_e32 v2, 0xbf6c835e, v2
	v_add_f32_e32 v28, v24, v18
	v_sub_f32_e32 v18, v24, v18
	v_fmac_f32_e32 v9, 0x3f6c835e, v3
	v_fmac_f32_e32 v2, 0x3ec3ef15, v3
	v_mul_f32_e32 v3, 0x3f3504f3, v16
	v_add_f32_e32 v24, v12, v27
	v_fmac_f32_e32 v3, 0x3f3504f3, v17
	v_mul_f32_e32 v17, 0xbf3504f3, v18
	v_sub_f32_e32 v12, v12, v27
	v_mul_f32_e32 v16, 0xbf6c835e, v24
	v_fmamk_f32 v18, v19, 0x3f3504f3, v17
	v_fmac_f32_e32 v17, 0xbf3504f3, v19
	v_mul_f32_e32 v19, 0xbec3ef15, v13
	v_mul_f32_e32 v13, 0xbf6c835e, v13
	v_fmac_f32_e32 v16, 0x3ec3ef15, v25
	v_fmac_f32_e32 v19, 0xbf6c835e, v12
	v_fmac_f32_e32 v13, 0x3ec3ef15, v12
	v_add_f32_e32 v12, v20, v10
	v_sub_f32_e32 v10, v20, v10
	v_add_f32_e32 v20, v22, v28
	v_sub_f32_e32 v22, v23, v29
	v_mul_f32_e32 v4, 0xbf3504f3, v4
	v_add_f32_e32 v23, v12, v20
	v_sub_f32_e32 v12, v12, v20
	v_add_f32_e32 v20, v10, v22
	v_sub_f32_e32 v10, v10, v22
	v_add_f32_e32 v22, v14, v3
	v_sub_f32_e32 v3, v14, v3
	v_sub_f32_e32 v14, v15, v16
	v_fmac_f32_e32 v4, 0x3f3504f3, v5
	v_add_f32_e32 v16, v3, v14
	v_sub_f32_e32 v3, v3, v14
	v_add_f32_e32 v14, v7, v11
	v_sub_f32_e32 v7, v7, v11
	v_add_f32_e32 v11, v21, v18
	v_sub_f32_e32 v8, v8, v17
	v_add_f32_e32 v17, v14, v11
	v_sub_f32_e32 v11, v14, v11
	v_add_f32_e32 v14, v7, v8
	v_sub_f32_e32 v7, v7, v8
	v_add_f32_e32 v8, v6, v4
	v_sub_f32_e32 v4, v6, v4
	v_add_f32_e32 v6, v9, v19
	v_sub_f32_e32 v2, v2, v13
	v_add_f32_e32 v9, v8, v6
	v_sub_f32_e32 v6, v8, v6
	v_add_f32_e32 v8, v4, v2
	v_sub_f32_e32 v2, v4, v2
	v_lshlrev_b32_e32 v4, 2, v40
	v_mul_f32_e32 v5, 0x3ec3ef15, v24
	v_lshl_add_u32 v18, v39, 2, v4
	v_ashrrev_i32_e32 v19, 2, v39
	v_fmac_f32_e32 v5, 0x3f6c835e, v25
	v_mul_f32_e32 v13, 0x3bb504f3, v23
	v_add_u32_e32 v19, v18, v19
	v_add_f32_e32 v5, v26, v5
	s_barrier
	ds_write_b32 v19, v13
	v_or_b32_e32 v13, 16, v39
	v_add_f32_e32 v15, v22, v5
	v_ashrrev_i32_e32 v13, 2, v13
	v_mul_f32_e32 v15, 0x3bb504f3, v15
	v_add_u32_e32 v13, v18, v13
	ds_write_b32 v13, v15 offset:64
	v_or_b32_e32 v13, 32, v39
	v_ashrrev_i32_e32 v13, 2, v13
	v_mul_f32_e32 v15, 0x3bb504f3, v17
	v_add_u32_e32 v13, v18, v13
	ds_write_b32 v13, v15 offset:128
	v_or_b32_e32 v13, 48, v39
	v_ashrrev_i32_e32 v13, 2, v13
	v_mul_f32_e32 v9, 0x3bb504f3, v9
	v_add_u32_e32 v13, v18, v13
	ds_write_b32 v13, v9 offset:192
	v_or_b32_e32 v9, 64, v39
	v_ashrrev_i32_e32 v9, 2, v9
	v_mul_f32_e32 v13, 0x3bb504f3, v20
	v_add_u32_e32 v9, v18, v9
	ds_write_b32 v9, v13 offset:256
	v_or_b32_e32 v9, 0x50, v39
	v_ashrrev_i32_e32 v9, 2, v9
	v_mul_f32_e32 v13, 0x3bb504f3, v16
	v_add_u32_e32 v9, v18, v9
	ds_write_b32 v9, v13 offset:320
	v_or_b32_e32 v9, 0x60, v39
	v_ashrrev_i32_e32 v9, 2, v9
	v_mul_f32_e32 v13, 0x3bb504f3, v14
	v_add_u32_e32 v9, v18, v9
	ds_write_b32 v9, v13 offset:384
	v_or_b32_e32 v9, 0x70, v39
	v_ashrrev_i32_e32 v9, 2, v9
	v_mul_f32_e32 v8, 0x3bb504f3, v8
	v_add_u32_e32 v9, v18, v9
	ds_write_b32 v9, v8 offset:448
	v_or_b32_e32 v8, 0x80, v39
	v_ashrrev_i32_e32 v8, 2, v8
	v_mul_f32_e32 v9, 0x3bb504f3, v12
	v_add_u32_e32 v8, v18, v8
	ds_write_b32 v8, v9 offset:512
	v_or_b32_e32 v8, 0x90, v39
	v_sub_f32_e32 v5, v22, v5
	v_ashrrev_i32_e32 v8, 2, v8
	v_mul_f32_e32 v5, 0x3bb504f3, v5
	v_add_u32_e32 v8, v18, v8
	ds_write_b32 v8, v5 offset:576
	v_or_b32_e32 v5, 0xa0, v39
	v_ashrrev_i32_e32 v5, 2, v5
	v_mul_f32_e32 v8, 0x3bb504f3, v11
	v_add_u32_e32 v5, v18, v5
	ds_write_b32 v5, v8 offset:640
	v_or_b32_e32 v5, 0xb0, v39
	v_ashrrev_i32_e32 v5, 2, v5
	v_mul_f32_e32 v6, 0x3bb504f3, v6
	v_add_u32_e32 v5, v18, v5
	ds_write_b32 v5, v6 offset:704
	v_or_b32_e32 v5, 0xc0, v39
	v_ashrrev_i32_e32 v5, 2, v5
	v_mul_f32_e32 v6, 0x3bb504f3, v10
	v_add_u32_e32 v5, v18, v5
	ds_write_b32 v5, v6 offset:768
	v_or_b32_e32 v5, 0xd0, v39
	v_ashrrev_i32_e32 v5, 2, v5
	v_mul_f32_e32 v3, 0x3bb504f3, v3
	v_add_u32_e32 v5, v18, v5
	ds_write_b32 v5, v3 offset:832
	v_or_b32_e32 v3, 0xe0, v39
	v_ashrrev_i32_e32 v3, 2, v3
	v_mul_f32_e32 v5, 0x3bb504f3, v7
	v_add_u32_e32 v3, v18, v3
	v_readlane_b32 s5, v246, 29
	s_add_u32 s24, s4, s0
	ds_write_b32 v3, v5 offset:896
	v_or_b32_e32 v3, 0xf0, v38
	s_addc_u32 s35, s5, s1
	s_lshl_b64 s[28:29], s[22:23], 1
	v_lshlrev_b32_e32 v8, 3, v1
	v_lshlrev_b32_e32 v5, 2, v3
	v_ashrrev_i32_e32 v3, 2, v3
	s_add_u32 s22, s24, s28
	v_ashrrev_i32_e32 v9, 31, v8
	v_mul_f32_e32 v2, 0x3bb504f3, v2
	v_add3_u32 v3, v4, v5, v3
	s_addc_u32 s23, s35, s29
	v_lshlrev_b64 v[12:13], 1, v[8:9]
	ds_write_b32 v3, v2
	v_lshl_add_u64 v[2:3], s[22:23], 0, v[12:13]
	s_waitcnt lgkmcnt(0)
	s_barrier
	global_load_dwordx4 v[2:5], v[2:3], off
	v_bfe_i32 v6, v1, 1, 28
	v_lshlrev_b32_e32 v1, 5, v1
	v_lshl_add_u32 v9, v6, 2, v1
	ds_read2_b32 v[10:11], v9 offset1:1
	ds_read2_b32 v[14:15], v9 offset0:2 offset1:3
	ds_read2_b32 v[16:17], v9 offset0:4 offset1:5
	ds_read2_b32 v[18:19], v9 offset0:6 offset1:7
	v_readlane_b32 s4, v247, 56
	v_readlane_b32 s5, v247, 57
	s_add_u32 s0, s4, s0
	s_addc_u32 s1, s5, s1
	s_add_u32 s0, s0, s28
	s_addc_u32 s1, s1, s29
	s_and_b64 vcc, exec, s[36:37]
	s_waitcnt vmcnt(0)
	v_lshlrev_b32_e32 v6, 16, v2
	v_and_b32_e32 v7, 0xffff0000, v2
	s_waitcnt lgkmcnt(3)
	v_pk_mul_f32 v[6:7], v[10:11], v[6:7]
	v_add_u32_e32 v10, 0x800, v8
	v_cvt_pk_bf16_f32 v2, v6, v7
	v_lshlrev_b32_e32 v6, 16, v3
	v_and_b32_e32 v7, 0xffff0000, v3
	s_waitcnt lgkmcnt(2)
	v_pk_mul_f32 v[6:7], v[14:15], v[6:7]
	v_ashrrev_i32_e32 v11, 31, v10
	v_cvt_pk_bf16_f32 v3, v6, v7
	v_lshlrev_b32_e32 v6, 16, v4
	v_and_b32_e32 v7, 0xffff0000, v4
	s_waitcnt lgkmcnt(1)
	v_pk_mul_f32 v[6:7], v[16:17], v[6:7]
	v_ashrrev_i32_e32 v9, 4, v10
	v_cvt_pk_bf16_f32 v4, v6, v7
	v_lshlrev_b32_e32 v6, 16, v5
	v_and_b32_e32 v7, 0xffff0000, v5
	s_waitcnt lgkmcnt(0)
	v_pk_mul_f32 v[6:7], v[18:19], v[6:7]
	v_lshl_add_u32 v1, v9, 2, v1
	v_cvt_pk_bf16_f32 v5, v6, v7
	v_lshl_add_u64 v[6:7], s[0:1], 0, v[12:13]
	global_store_dwordx4 v[6:7], v[2:5], off
	v_lshlrev_b64 v[6:7], 1, v[10:11]
	v_add_u32_e32 v9, 0x2000, v1
	v_lshl_add_u64 v[2:3], s[22:23], 0, v[6:7]
	global_load_dwordx4 v[2:5], v[2:3], off
	ds_read2_b32 v[16:17], v9 offset1:1
	v_add_u32_e32 v11, 0x2008, v1
	v_add_u32_e32 v20, 0x2010, v1
	v_add_u32_e32 v1, 0x2018, v1
	ds_read2_b32 v[18:19], v11 offset1:1
	ds_read2_b32 v[20:21], v20 offset1:1
	ds_read2_b32 v[22:23], v1 offset1:1
	s_waitcnt vmcnt(0)
	v_lshlrev_b32_e32 v14, 16, v2
	v_and_b32_e32 v15, 0xffff0000, v2
	s_waitcnt lgkmcnt(3)
	v_pk_mul_f32 v[14:15], v[16:17], v[14:15]
	s_nop 0
	v_cvt_pk_bf16_f32 v2, v14, v15
	v_lshlrev_b32_e32 v14, 16, v3
	v_and_b32_e32 v15, 0xffff0000, v3
	s_waitcnt lgkmcnt(2)
	v_pk_mul_f32 v[14:15], v[18:19], v[14:15]
	s_nop 0
	v_cvt_pk_bf16_f32 v3, v14, v15
	v_lshlrev_b32_e32 v14, 16, v4
	v_and_b32_e32 v15, 0xffff0000, v4
	s_waitcnt lgkmcnt(1)
	v_pk_mul_f32 v[14:15], v[20:21], v[14:15]
	s_nop 0
	v_cvt_pk_bf16_f32 v4, v14, v15
	v_lshlrev_b32_e32 v14, 16, v5
	v_and_b32_e32 v15, 0xffff0000, v5
	s_waitcnt lgkmcnt(0)
	v_pk_mul_f32 v[14:15], v[22:23], v[14:15]
	s_nop 0
	v_cvt_pk_bf16_f32 v5, v14, v15
	v_lshl_add_u64 v[14:15], s[0:1], 0, v[6:7]
	global_store_dwordx4 v[14:15], v[2:5], off
	s_cbranch_vccnz .LBB0_656
	s_sub_i32 s0, s34, s2
	s_addk_i32 s0, 0x80
	s_mul_hi_i32 s1, s0, 0x14000
	s_mul_i32 s0, s0, 0x14000
	v_readlane_b32 s4, v246, 28
	v_readlane_b32 s5, v246, 29
	s_add_u32 s2, s4, s0
	s_addc_u32 s23, s5, s1
	s_add_u32 s22, s2, s28
	s_addc_u32 s23, s23, s29
	v_lshl_add_u64 v[2:3], s[22:23], 0, v[12:13]
	global_load_dwordx4 v[2:5], v[2:3], off
	v_sub_u32_e32 v9, 0, v8
	v_and_b32_e32 v14, 0xffffff00, v8
	v_and_b32_e32 v9, 0xf8, v9
	v_or_b32_e32 v11, v9, v14
	v_ashrrev_i32_e32 v15, 4, v11
	v_lshlrev_b32_e32 v15, 2, v15
	v_lshl_add_u32 v11, v11, 2, v15
	ds_read_b32 v11, v11
	v_readlane_b32 s4, v247, 56
	v_readlane_b32 s5, v247, 57
	s_add_u32 s0, s4, s0
	s_addc_u32 s1, s5, s1
	s_add_u32 s0, s0, s28
	s_addc_u32 s1, s1, s29
	v_lshl_add_u64 v[12:13], s[0:1], 0, v[12:13]
	v_and_b32_e32 v10, 0xffffff00, v10
	v_or_b32_e32 v9, v10, v9
	s_movk_i32 s2, 0xf0
	s_waitcnt vmcnt(0)
	v_lshlrev_b32_e32 v1, 16, v2
	s_waitcnt lgkmcnt(0)
	v_mul_f32_e32 v15, v11, v1
	v_and_b32_e32 v1, 0xffff0000, v2
	v_xor_b32_e32 v2, 0xf0, v8
	v_ashrrev_i32_e32 v2, 4, v2
	v_xor_b32_e32 v11, 0xf8, v8
	v_lshlrev_b32_e32 v2, 2, v2
	v_lshl_add_u32 v2, v11, 2, v2
	ds_read_b32 v2, v2 offset:28
	s_waitcnt lgkmcnt(0)
	v_mul_f32_e32 v16, v2, v1
	v_sub_u32_e32 v1, 0xfe, v8
	v_and_b32_e32 v1, 0xfe, v1
	v_or_b32_e32 v11, v1, v14
	v_ashrrev_i32_e32 v17, 4, v11
	v_lshlrev_b32_e32 v17, 2, v17
	v_lshl_add_u32 v11, v11, 2, v17
	ds_read_b32 v11, v11
	v_lshlrev_b32_e32 v2, 16, v3
	v_and_b32_e32 v3, 0xffff0000, v3
	v_or_b32_e32 v1, v1, v10
	s_waitcnt lgkmcnt(0)
	v_mul_f32_e32 v17, v11, v2
	v_sub_u32_e32 v2, 0xfd, v8
	v_and_b32_e32 v2, 0xfd, v2
	v_or_b32_e32 v11, v2, v14
	v_ashrrev_i32_e32 v18, 4, v11
	v_lshlrev_b32_e32 v18, 2, v18
	v_lshl_add_u32 v11, v11, 2, v18
	ds_read_b32 v11, v11
	v_or_b32_e32 v2, v2, v10
	s_waitcnt lgkmcnt(0)
	v_mul_f32_e32 v18, v11, v3
	v_sub_u32_e32 v3, 0xfc, v8
	v_and_b32_e32 v3, 0xfc, v3
	v_or_b32_e32 v19, v3, v14
	v_ashrrev_i32_e32 v20, 4, v19
	v_lshlrev_b32_e32 v20, 2, v20
	v_lshl_add_u32 v19, v19, 2, v20
	ds_read_b32 v19, v19
	v_lshlrev_b32_e32 v11, 16, v4
	v_or_b32_e32 v3, v3, v10
	s_waitcnt lgkmcnt(0)
	v_mul_f32_e32 v19, v19, v11
	v_and_b32_e32 v11, 0xffff0000, v4
	v_sub_u32_e32 v4, 0xfb, v8
	v_and_b32_e32 v4, 0xfb, v4
	v_or_b32_e32 v20, v4, v14
	v_ashrrev_i32_e32 v21, 4, v20
	v_lshlrev_b32_e32 v21, 2, v21
	v_lshl_add_u32 v20, v20, 2, v21
	ds_read_b32 v20, v20
	v_lshlrev_b32_e32 v21, 16, v5
	s_waitcnt lgkmcnt(0)
	v_mul_f32_e32 v20, v20, v11
	v_sub_u32_e32 v11, 0xfa, v8
	v_and_b32_e32 v11, 0xfa, v11
	v_or_b32_e32 v22, v11, v14
	v_ashrrev_i32_e32 v23, 4, v22
	v_lshlrev_b32_e32 v23, 2, v23
	v_lshl_add_u32 v22, v22, 2, v23
	ds_read_b32 v22, v22
	s_waitcnt lgkmcnt(0)
	v_mul_f32_e32 v21, v22, v21
	v_and_b32_e32 v22, 0xffff0000, v5
	v_sub_u32_e32 v5, 0xf9, v8
	v_and_b32_e32 v5, 0xf9, v5
	v_or_b32_e32 v14, v5, v14
	v_ashrrev_i32_e32 v23, 4, v14
	v_lshlrev_b32_e32 v23, 2, v23
	v_lshl_add_u32 v14, v14, 2, v23
	ds_read_b32 v14, v14
	s_waitcnt lgkmcnt(0)
	v_mul_f32_e32 v22, v14, v22
	v_cvt_pk_bf16_f32 v14, v15, v16
	v_cvt_pk_bf16_f32 v15, v17, v18
	v_cvt_pk_bf16_f32 v16, v19, v20
	v_cvt_pk_bf16_f32 v17, v21, v22
	global_store_dwordx4 v[12:13], v[14:17], off
	v_lshl_add_u64 v[12:13], s[22:23], 0, v[6:7]
	global_load_dwordx4 v[12:15], v[12:13], off
	v_ashrrev_i32_e32 v17, 4, v9
	v_lshlrev_b32_e32 v17, 2, v17
	v_lshl_add_u32 v9, v9, 2, v17
	ds_read_b32 v9, v9
	v_lshl_add_u64 v[6:7], s[0:1], 0, v[6:7]
	s_waitcnt vmcnt(0)
	v_lshlrev_b32_e32 v16, 16, v12
	s_waitcnt lgkmcnt(0)
	v_mul_f32_e32 v9, v9, v16
	v_and_b32_e32 v16, 0xf8, v8
	v_bitop3_b32 v16, v10, s2, v16 bitop3:0x36
	v_ashrrev_i32_e32 v16, 4, v16
	s_movk_i32 s2, 0xf8
	v_bitop3_b32 v8, v10, s2, v8 bitop3:0x34
	v_lshlrev_b32_e32 v16, 2, v16
	v_lshl_add_u32 v8, v8, 2, v16
	v_ashrrev_i32_e32 v16, 4, v1
	v_lshlrev_b32_e32 v16, 2, v16
	ds_read_b32 v8, v8 offset:28
	v_lshl_add_u32 v1, v1, 2, v16
	ds_read_b32 v1, v1
	v_and_b32_e32 v12, 0xffff0000, v12
	s_waitcnt lgkmcnt(1)
	v_mul_f32_e32 v8, v8, v12
	v_lshlrev_b32_e32 v12, 16, v13
	s_waitcnt lgkmcnt(0)
	v_mul_f32_e32 v1, v1, v12
	v_and_b32_e32 v12, 0xffff0000, v13
	v_ashrrev_i32_e32 v13, 4, v2
	v_lshlrev_b32_e32 v13, 2, v13
	v_lshl_add_u32 v2, v2, 2, v13
	v_ashrrev_i32_e32 v13, 4, v3
	v_lshlrev_b32_e32 v13, 2, v13
	ds_read_b32 v2, v2
	v_lshl_add_u32 v3, v3, 2, v13
	ds_read_b32 v3, v3
	s_waitcnt lgkmcnt(1)
	v_mul_f32_e32 v12, v2, v12
	v_lshlrev_b32_e32 v2, 16, v14
	s_waitcnt lgkmcnt(0)
	v_mul_f32_e32 v13, v3, v2
	v_or_b32_e32 v3, v4, v10
	v_ashrrev_i32_e32 v4, 4, v3
	v_lshlrev_b32_e32 v4, 2, v4
	v_lshl_add_u32 v3, v3, 2, v4
	ds_read_b32 v3, v3
	v_and_b32_e32 v2, 0xffff0000, v14
	s_waitcnt lgkmcnt(0)
	v_mul_f32_e32 v4, v3, v2
	v_or_b32_e32 v3, v11, v10
	v_ashrrev_i32_e32 v11, 4, v3
	v_lshlrev_b32_e32 v11, 2, v11
	v_lshl_add_u32 v3, v3, 2, v11
	ds_read_b32 v3, v3
	v_lshlrev_b32_e32 v2, 16, v15
	v_cvt_pk_bf16_f32 v4, v13, v4
	s_waitcnt lgkmcnt(0)
	v_mul_f32_e32 v11, v3, v2
	v_or_b32_e32 v3, v5, v10
	v_ashrrev_i32_e32 v5, 4, v3
	v_lshlrev_b32_e32 v5, 2, v5
	v_lshl_add_u32 v3, v3, 2, v5
	ds_read_b32 v3, v3
	v_and_b32_e32 v2, 0xffff0000, v15
	s_waitcnt lgkmcnt(0)
	v_mul_f32_e32 v5, v3, v2
	v_cvt_pk_bf16_f32 v2, v9, v8
	v_cvt_pk_bf16_f32 v3, v1, v12
	v_cvt_pk_bf16_f32 v5, v11, v5
	global_store_dwordx4 v[6:7], v[2:5], off

.LBB0_690:
	s_waitcnt vmcnt(9)
	v_lshlrev_b32_e32 v46, 16, v12
	v_lshlrev_b32_e32 v12, 16, v1
	v_mov_b32_e32 v1, v2
	v_lshlrev_b32_e32 v50, 16, v5
	s_barrier
	s_waitcnt vmcnt(1)
	v_lshlrev_b32_e32 v20, 16, v32
	v_ashrrev_i32_e32 v5, 31, v1
	v_lshrrev_b32_e32 v5, 24, v5
	v_lshlrev_b32_e32 v32, 16, v31
	v_lshlrev_b32_e32 v38, 16, v28
	v_lshlrev_b32_e32 v42, 16, v24
	v_lshlrev_b32_e32 v24, 16, v22
	v_lshlrev_b32_e32 v28, 16, v16
	v_lshlrev_b32_e32 v16, 16, v11
	v_lshlrev_b32_e32 v22, 16, v8
	v_lshlrev_b32_e32 v8, 16, v3
	v_and_b32_e32 v3, 0xff, v1
	v_add_lshl_u32 v1, v1, v5, 4
	v_and_or_b32 v1, v1, s87, v3
	s_waitcnt vmcnt(0)
	v_lshlrev_b32_e32 v18, 16, v18
	v_lshlrev_b32_e32 v40, 16, v27
	v_lshlrev_b32_e32 v44, 16, v15
	v_lshlrev_b32_e32 v48, 16, v7
	v_ashrrev_i32_e32 v5, 4, v1
	v_lshlrev_b32_e32 v1, 3, v1
	v_pk_add_f32 v[52:53], v[12:13], v[28:29]
	v_pk_add_f32 v[12:13], v[12:13], v[28:29] neg_lo:[0,1] neg_hi:[0,1]
	v_pk_add_f32 v[28:29], v[22:23], v[38:39]
	v_mov_b32_e32 v54, v23
	v_mov_b32_e32 v55, v22
	v_sub_f32_e32 v56, v46, v20
	v_sub_f32_e32 v57, v16, v32
	v_lshl_add_u32 v1, v5, 3, v1
	v_sub_f32_e32 v22, v54, v39
	v_sub_f32_e32 v23, v55, v38
	v_pk_add_f32 v[38:39], v[8:9], v[24:25]
	v_sub_f32_e32 v54, v50, v42
	v_sub_f32_e32 v55, v8, v24
	v_sub_f32_e32 v24, v6, v30
	v_sub_f32_e32 v25, v9, v25
	v_pk_add_f32 v[8:9], v[16:17], v[32:33]
	v_sub_f32_e32 v16, v14, v36
	v_sub_f32_e32 v17, v17, v33
	v_mov_b32_e32 v51, v6
	v_mov_b32_e32 v43, v30
	v_sub_f32_e32 v7, v6, v30
	v_sub_f32_e32 v6, v48, v40
	v_add_f32_e32 v30, v46, v20
	v_add_f32_e32 v31, v14, v36
	v_sub_f32_e32 v21, v46, v20
	v_sub_f32_e32 v20, v10, v34
	v_sub_f32_e32 v15, v14, v36
	v_sub_f32_e32 v14, v44, v18
	v_pk_add_f32 v[32:33], v[50:51], v[42:43]
	v_sub_f32_e32 v43, v50, v42
	v_sub_f32_e32 v42, v4, v26
	v_pk_add_f32 v[50:51], v[6:7], v[20:21] neg_lo:[0,1] neg_hi:[0,1]
	v_add_f32_e32 v27, v4, v26
	v_add_f32_e32 v26, v48, v40
	v_add_f32_e32 v11, v10, v34
	v_add_f32_e32 v10, v44, v18
	v_pk_add_f32 v[18:19], v[6:7], v[20:21]
	v_pk_add_f32 v[6:7], v[38:39], v[8:9] neg_lo:[0,1] neg_hi:[0,1]
	v_cvt_f32_i32_e32 v3, v3
	v_pk_add_f32 v[4:5], v[26:27], v[10:11] neg_lo:[0,1] neg_hi:[0,1]
	v_pk_mul_f32 v[20:21], v[6:7], s[20:21] op_sel_hi:[1,0]
	v_mul_f32_e32 v40, 0x3f3504f3, v4
	v_pk_fma_f32 v[34:35], v[6:7], s[20:21], v[20:21] op_sel:[0,0,1] op_sel_hi:[1,0,0]
	v_mul_f32_e32 v44, 0x3f3504f3, v5
	v_mul_f32_e32 v49, 0xbf3504f3, v5
	v_pk_add_f32 v[4:5], v[52:53], v[28:29]
	v_pk_add_f32 v[6:7], v[38:39], v[8:9]
	v_pk_add_f32 v[8:9], v[32:33], v[30:31]
	v_pk_add_f32 v[10:11], v[26:27], v[10:11]
	v_pk_add_f32 v[26:27], v[4:5], v[8:9]
	v_pk_add_f32 v[38:39], v[6:7], v[10:11]
	v_add_f32_e32 v3, v3, v3
	v_pk_add_f32 v[60:61], v[26:27], v[38:39]
	v_pk_add_f32 v[36:37], v[32:33], v[30:31] neg_lo:[0,1] neg_hi:[0,1]
	v_mul_f32_e32 v3, 0x39800000, v3
	ds_write_b64 v1, v[60:61]
	v_add_f32_e32 v60, v12, v22
	v_sub_f32_e32 v61, v13, v23
	s_mov_b32 s22, s71
	s_mov_b32 s23, s21
	v_add_f32_e32 v32, v55, v17
	s_mov_b32 s70, s21
	v_pk_add_f32 v[46:47], v[42:43], v[14:15]
	v_pk_add_f32 v[14:15], v[42:43], v[14:15] neg_lo:[0,1] neg_hi:[0,1]
	v_mul_f32_e32 v3, 0.5, v3
	v_sub_f32_e32 v30, v25, v57
	v_pk_mul_f32 v[62:63], v[32:33], s[70:71] op_sel_hi:[0,1]
	v_pk_mul_f32 v[66:67], v[18:19], s[22:23] op_sel_hi:[0,1]
	v_mul_f32_e32 v41, 0x3f3504f3, v47
	v_mul_f32_e32 v43, 0x3f3504f3, v51
	v_sin_f32_e32 v42, v3
	v_fma_f32 v64, v30, s22, v62
	v_fma_f32 v65, v30, s23, -v63
	v_fma_f32 v68, v14, s70, v66
	v_fma_f32 v69, v14, s71, -v67
	v_cos_f32_e32 v58, v3
	s_nop 1
	v_add_f32_e32 v62, v43, v41
	v_fma_f32 v63, v51, s20, -v41
	v_pk_add_f32 v[66:67], v[60:61], v[62:63]
	v_pk_add_f32 v[70:71], v[64:65], v[68:69]
	v_xor_b32_e32 v59, 0x80000000, v42
	v_pk_add_f32 v[72:73], v[66:67], v[70:71]
	v_pk_add_f32 v[66:67], v[66:67], v[70:71] neg_lo:[0,1] neg_hi:[0,1]
	v_pk_mul_f32 v[70:71], v[72:73], v[42:43] op_sel_hi:[1,0]
	v_fma_f32 v74, v72, v58, v71
	v_fma_f32 v75, v73, v58, -v70
	v_mov_b32_e32 v30, v31
	v_pk_add_f32 v[16:17], v[54:55], v[16:17] neg_lo:[0,1] neg_hi:[0,1]
	v_pk_add_f32 v[24:25], v[24:25], v[56:57]
	v_mov_b32_e32 v72, v28
	v_sub_f32_e32 v28, v44, v40
	v_sub_f32_e32 v29, v53, v29
	v_sub_f32_e32 v30, v33, v30
	v_sub_f32_e32 v31, v49, v40
	v_mov_b32_e32 v40, v34
	v_mov_b32_e32 v41, v36
	v_mov_b32_e32 v51, v19
	v_mov_b32_e32 v47, v15
	v_mul_f32_e32 v14, 0x3ec3ef15, v17
	v_mul_f32_e32 v18, 0x3f6c835e, v25
	v_mov_b32_e32 v43, v58
	v_sub_f32_e32 v21, v21, v20
	v_sub_f32_e32 v20, v52, v72
	v_pk_add_f32 v[32:33], v[28:29], v[36:37] op_sel:[1,0] op_sel_hi:[0,1]
	v_add_f32_e32 v36, v28, v40
	v_sub_f32_e32 v41, v29, v41
	v_add_f32_e32 v14, v18, v14
	v_add_f32_e32 v15, v13, v23
	v_pk_mul_f32 v[18:19], v[46:47], s[72:73]
	v_mul_f32_e32 v48, v42, v42
	v_mul_f32_e32 v49, v43, v59
	v_pk_add_f32 v[44:45], v[20:21], v[30:31]
	v_pk_fma_f32 v[18:19], v[50:51], s[30:31], v[18:19] neg_lo:[0,0,1] neg_hi:[0,0,1]
	v_mul_f32_e32 v13, 0x3ec3ef15, v50
	v_pk_fma_f32 v[50:51], v[58:59], v[58:59], v[48:49] op_sel_hi:[0,1,1] neg_lo:[0,0,1] neg_hi:[0,0,1]
	v_pk_fma_f32 v[48:49], v[58:59], v[58:59], v[48:49] op_sel_hi:[0,1,1]
	v_pk_add_f32 v[20:21], v[20:21], v[30:31] neg_lo:[0,1] neg_hi:[0,1]
	v_add_f32_e32 v30, v44, v36
	v_add_f32_e32 v31, v45, v41
	v_mov_b32_e32 v52, v50
	v_mov_b32_e32 v53, v49
	v_mul_f32_e32 v70, v49, v49
	v_mul_f32_e32 v71, v49, v50
	v_pk_mul_f32 v[48:49], v[30:31], v[48:49] op_sel:[1,1] op_sel_hi:[0,1]
	v_pk_fma_f32 v[72:73], v[50:51], v[52:53], v[70:71] op_sel_hi:[0,1,1] neg_lo:[0,0,1] neg_hi:[0,0,1]
	v_pk_fma_f32 v[70:71], v[50:51], v[52:53], v[70:71] op_sel_hi:[0,1,1]
	v_fma_f32 v82, v30, v50, -v48
	v_fma_f32 v83, v31, v50, v49
	v_pk_add_f32 v[28:29], v[34:35], v[28:29] neg_lo:[0,1] neg_hi:[0,1]
	v_pk_add_f32 v[30:31], v[60:61], v[62:63] neg_lo:[0,1] neg_hi:[0,1]
	v_pk_mul_f32 v[62:63], v[52:53], v[70:71] op_sel:[0,1]
	v_pk_add_f32 v[48:49], v[64:65], v[68:69] neg_lo:[0,1] neg_hi:[0,1]
	v_fma_f32 v64, v52, v72, -v63
	v_fma_f32 v63, v53, v72, v62
	v_pk_add_f32 v[34:35], v[32:33], v[28:29]
	v_sub_f32_e32 v28, v32, v28
	ds_write_b64 v1, v[82:83] offset:4352
	v_mov_b32_e32 v68, v64
	v_mov_b32_e32 v69, v63
	v_pk_add_f32 v[82:83], v[20:21], v[20:21] op_sel:[0,1] op_sel_hi:[0,1]
	v_mul_f32_e32 v29, v28, v64
	v_mul_f32_e32 v28, v28, v63
	ds_write_b64 v1, v[74:75] offset:2176
	v_mov_b32_e32 v74, v72
	v_mov_b32_e32 v75, v71
	v_fma_f32 v32, v82, v64, -v28
	v_fma_f32 v33, v83, v69, v29
	v_mov_b32_e32 v59, v42
	v_pk_mul_f32 v[28:29], v[74:75], v[70:71] op_sel:[0,1]
	ds_write_b64 v1, v[32:33] offset:13056
	v_pk_fma_f32 v[32:33], v[72:73], v[74:75], v[28:29] op_sel:[0,0,1] op_sel_hi:[0,1,0] neg_lo:[0,0,1] neg_hi:[0,0,1]
	v_pk_fma_f32 v[28:29], v[72:73], v[74:75], v[28:29] op_sel:[0,0,1] op_sel_hi:[0,1,0]
	v_pk_mov_b32 v[62:63], v[28:29], v[32:33] op_sel:[1,0]
	v_pk_mul_f32 v[56:57], v[42:43], v[52:53]
	v_pk_mul_f32 v[78:79], v[42:43], v[74:75]
	v_pk_add_f32 v[26:27], v[26:27], v[38:39] neg_lo:[0,1] neg_hi:[0,1]
	v_mov_b32_e32 v38, v32
	v_mov_b32_e32 v39, v29
	v_pk_mul_f32 v[42:43], v[42:43], v[62:63] op_sel_hi:[0,1]
	v_fma_f32 v64, v58, v38, v42
	v_fma_f32 v43, v58, v39, -v43
	v_pk_mul_f32 v[54:55], v[58:59], v[52:53]
	v_pk_mul_f32 v[76:77], v[58:59], v[74:75]
	v_mov_b32_e32 v59, v43
	v_pk_mul_f32 v[16:17], v[16:17], s[20:21]
	s_mov_b32 s28, s20
	s_mov_b32 s29, s71
	v_mul_f32_e32 v23, 0x3f6c835e, v46
	v_mul_f32_e32 v42, v67, v43
	v_mul_f32_e32 v43, v67, v64
	v_pk_mul_f32 v[28:29], v[26:27], v[28:29] op_sel:[1,1] op_sel_hi:[0,1]
	v_pk_fma_f32 v[16:17], v[24:25], s[28:29], v[16:17] neg_lo:[0,0,1] neg_hi:[0,0,1]
	v_pk_add_f32 v[12:13], v[12:13], v[22:23] neg_lo:[0,1] neg_hi:[0,1]
	v_pk_mov_b32 v[80:81], v[70:71], v[72:73] op_sel:[1,0]
	v_pk_mul_f32 v[70:71], v[52:53], v[38:39]
	v_pk_mul_f32 v[52:53], v[52:53], v[62:63]
	v_fma_f32 v64, v66, v64, -v42
	v_fma_f32 v65, v66, v59, v43
	v_fma_f32 v66, v26, v32, -v28
	v_fma_f32 v67, v27, v32, v29
	v_pk_add_f32 v[22:23], v[14:15], v[18:19]
	v_pk_add_f32 v[24:25], v[16:17], v[12:13]
	v_mov_b32_e32 v82, v54
	v_pk_mov_b32 v[54:55], v[54:55], v[56:57] op_sel:[1,0]
	v_sub_f32_e32 v26, v44, v36
	v_sub_f32_e32 v27, v41, v45
	v_pk_add_f32 v[28:29], v[52:53], v[52:53] op_sel:[0,1] op_sel_hi:[0,1]
	v_pk_add_f32 v[46:47], v[22:23], v[24:25]
	v_add_f32_e32 v56, v82, v54
	v_sub_f32_e32 v54, v82, v54
	v_sub_f32_e32 v55, v57, v55
	v_pk_mul_f32 v[28:29], v[26:27], v[28:29] op_sel:[1,0] op_sel_hi:[0,1]
	v_pk_add_f32 v[32:33], v[70:71], v[70:71] op_sel:[0,1] op_sel_hi:[0,1] neg_lo:[0,1] neg_hi:[0,1]
	v_pk_mul_f32 v[84:85], v[46:47], v[54:55] op_sel:[0,1]
	v_fma_f32 v36, v26, v32, -v28
	v_fma_f32 v37, v27, v33, v29
	v_fma_f32 v86, v46, v56, -v85
	v_fma_f32 v87, v47, v56, v84
	v_mul_f32_e32 v84, v56, v38
	v_mul_f32_e32 v85, v55, v39
	v_mul_f32_e32 v82, v56, v62
	v_mul_f32_e32 v83, v55, v63
	v_mov_b32_e32 v27, v23
	v_sub_f32_e32 v22, v24, v22
	v_sub_f32_e32 v23, v27, v25
	v_pk_add_f32 v[24:25], v[82:83], v[82:83] op_sel:[0,1] op_sel_hi:[0,1]
	v_pk_add_f32 v[4:5], v[4:5], v[8:9] neg_lo:[0,1] neg_hi:[0,1]
	v_pk_add_f32 v[6:7], v[6:7], v[10:11] neg_lo:[0,1] neg_hi:[0,1]
	v_pk_mul_f32 v[24:25], v[22:23], v[24:25] op_sel:[1,0] op_sel_hi:[0,1]
	v_pk_add_f32 v[26:27], v[84:85], v[84:85] op_sel:[0,1] op_sel_hi:[0,1] neg_lo:[0,1] neg_hi:[0,1]
	v_pk_add_f32 v[8:9], v[4:5], v[6:7] op_sel:[0,1] op_sel_hi:[1,0]
	v_pk_add_f32 v[4:5], v[4:5], v[6:7] op_sel:[0,1] op_sel_hi:[1,0] neg_lo:[0,1] neg_hi:[0,1]
	v_fma_f32 v28, v22, v26, -v24
	v_fma_f32 v29, v23, v27, v25
	v_pk_mul_f32 v[10:11], v[4:5], v[80:81] op_sel:[1,0]
	v_pk_add_f32 v[50:51], v[30:31], v[48:49] op_sel:[0,1] op_sel_hi:[1,0]
	v_pk_add_f32 v[30:31], v[30:31], v[48:49] op_sel:[0,1] op_sel_hi:[1,0] neg_lo:[0,1] neg_hi:[0,1]
	v_pk_mul_f32 v[88:89], v[74:75], v[62:63]
	v_mov_b32_e32 v90, v76
	v_mov_b32_e32 v91, v79
	v_pk_mov_b32 v[76:77], v[76:77], v[78:79] op_sel:[1,0]
	v_fma_f32 v22, v8, v72, -v10
	v_fma_f32 v23, v8, v75, v11
	ds_write_b64 v1, v[86:87] offset:6528
	v_pk_mul_f32 v[86:87], v[74:75], v[38:39]
	v_add_f32_e32 v78, v90, v76
	v_sub_f32_e32 v77, v91, v77
	v_mov_b32_e32 v7, v9
	v_pk_add_f32 v[10:11], v[88:89], v[88:89] op_sel:[0,1] op_sel_hi:[0,1]
	v_mov_b32_e32 v49, v31
	v_mov_b32_e32 v90, v78
	v_mov_b32_e32 v91, v77
	v_mul_f32_e32 v60, v31, v77
	v_mul_f32_e32 v61, v50, v77
	v_mul_f32_e32 v8, v9, v10
	v_mul_f32_e32 v9, v4, v11
	v_pk_add_f32 v[10:11], v[86:87], v[86:87] op_sel:[0,1] op_sel_hi:[0,1] neg_lo:[0,1] neg_hi:[0,1]
	v_fma_f32 v76, v50, v78, -v60
	v_fma_f32 v77, v49, v78, v61
	v_pk_mul_f32 v[60:61], v[62:63], v[90:91]
	v_fma_f32 v4, v4, v10, -v8
	v_fma_f32 v5, v7, v11, v9
	v_pk_mul_f32 v[48:49], v[38:39], v[90:91]
	v_pk_add_f32 v[8:9], v[60:61], v[60:61] op_sel:[0,1] op_sel_hi:[0,1]
	ds_write_b64 v1, v[76:77] offset:10880
	ds_write_b64 v1, v[66:67] offset:17408
	ds_write_b64 v1, v[64:65] offset:19584
	ds_write_b64 v1, v[4:5] offset:26112
	v_mov_b32_e32 v5, v51
	v_mul_f32_e32 v6, v51, v8
	v_mul_f32_e32 v7, v30, v9
	v_pk_add_f32 v[8:9], v[48:49], v[48:49] op_sel:[0,1] op_sel_hi:[0,1] neg_lo:[0,1] neg_hi:[0,1]
	v_pk_mul_f32 v[42:43], v[38:39], v[68:69]
	v_fma_f32 v10, v30, v8, -v6
	v_fma_f32 v11, v5, v9, v7
	v_pk_mul_f32 v[58:59], v[62:63], v[68:69]
	v_mov_b32_e32 v5, v42
	v_sub_f32_e32 v4, v20, v21
	v_sub_f32_e32 v5, v5, v43
	v_pk_add_f32 v[8:9], v[58:59], v[58:59] op_sel:[0,1] op_sel_hi:[0,1]
	v_mul_f32_e32 v6, v34, v8
	v_mul_f32_e32 v7, v4, v9
	v_pk_mov_b32 v[8:9], v[4:5], v[34:35] op_sel:[1,0]
	ds_write_b64 v1, v[10:11] offset:28288
	v_fma_f32 v10, v4, v8, -v6
	v_fma_f32 v11, v5, v9, v7
	v_pk_mul_f32 v[46:47], v[74:75], v[54:55] op_sel:[0,1]
	v_sub_f32_e32 v4, v12, v16
	v_sub_f32_e32 v5, v15, v19
	v_fma_f32 v54, v74, v56, -v47
	v_fma_f32 v47, v75, v56, v46
	v_sub_f32_e32 v6, v17, v13
	v_sub_f32_e32 v7, v14, v18
	v_mov_b32_e32 v57, v47
	v_pk_add_f32 v[8:9], v[4:5], v[6:7]
	v_pk_add_f32 v[4:5], v[4:5], v[6:7] neg_lo:[0,1] neg_hi:[0,1]
	v_mov_b32_e32 v56, v54
	ds_write_b64 v1, v[10:11] offset:30464
	v_mul_f32_e32 v10, v5, v47
	v_mul_f32_e32 v11, v5, v54
	v_pk_mul_f32 v[62:63], v[62:63], v[56:57]
	v_fma_f32 v12, v8, v54, -v10
	v_fma_f32 v13, v8, v57, v11
	v_pk_mul_f32 v[38:39], v[38:39], v[56:57]
	v_mov_b32_e32 v7, v9
	v_pk_add_f32 v[10:11], v[62:63], v[62:63] op_sel:[0,1] op_sel_hi:[0,1]
	v_mul_f32_e32 v8, v9, v10
	v_mul_f32_e32 v9, v4, v11
	v_pk_add_f32 v[10:11], v[38:39], v[38:39] op_sel:[0,1] op_sel_hi:[0,1] neg_lo:[0,1] neg_hi:[0,1]
	v_fma_f32 v4, v4, v10, -v8
	v_fma_f32 v5, v7, v11, v9
	ds_write_b64 v1, v[36:37] offset:21760
	ds_write_b64 v1, v[28:29] offset:23936
	ds_write_b64 v1, v[22:23] offset:8704
	ds_write_b64 v1, v[12:13] offset:15232
	ds_write_b64 v1, v[4:5] offset:32640
	v_mov_b32_e32 v1, v2
	s_waitcnt lgkmcnt(0)
	s_barrier
	v_readlane_b32 s4, v246, 28
	v_ashrrev_i32_e32 v4, 31, v1
	v_lshrrev_b32_e32 v4, 28, v4
	v_and_b32_e32 v3, 15, v1
	v_add_u32_e32 v1, v1, v4
	v_ashrrev_i32_e32 v1, 4, v1
	v_lshlrev_b32_e32 v4, 11, v1
	v_lshl_add_u32 v1, v1, 7, v4
	v_lshl_or_b32 v1, v3, 3, v1
	ds_read2_b64 v[14:17], v1 offset1:17
	ds_read2_b64 v[18:21], v1 offset0:68 offset1:85
	ds_read2_b64 v[22:25], v1 offset0:136 offset1:153
	ds_read2_b64 v[26:29], v1 offset0:170 offset1:187
	ds_read2_b64 v[30:33], v1 offset0:204 offset1:221
	ds_read2_b64 v[34:37], v1 offset0:238 offset1:255
	ds_read2_b64 v[38:41], v1 offset0:34 offset1:51
	ds_read2_b64 v[42:45], v1 offset0:102 offset1:119
	s_waitcnt lgkmcnt(5)
	v_pk_add_f32 v[12:13], v[22:23], v[14:15]
	v_pk_add_f32 v[22:23], v[14:15], v[22:23] neg_lo:[0,1] neg_hi:[0,1]
	s_waitcnt lgkmcnt(2)
	v_pk_mov_b32 v[62:63], v[28:29], v[36:37] op_sel:[1,0]
	s_waitcnt lgkmcnt(1)
	v_pk_add_f32 v[58:59], v[40:41], v[28:29]
	s_waitcnt lgkmcnt(0)
	v_sub_f32_e32 v28, v40, v28
	v_sub_f32_e32 v29, v45, v37
	v_pk_add_f32 v[14:15], v[18:19], v[30:31] neg_lo:[0,1] neg_hi:[0,1]
	v_pk_add_f32 v[46:47], v[30:31], v[18:19]
	v_pk_add_f32 v[48:49], v[16:17], v[24:25]
	v_pk_add_f32 v[50:51], v[20:21], v[32:33]
	v_pk_add_f32 v[60:61], v[44:45], v[36:37]
	v_sub_f32_e32 v62, v41, v62
	v_sub_f32_e32 v63, v44, v63
	v_sub_f32_e32 v40, v28, v29
	v_pk_mov_b32 v[18:19], v[14:15], v[14:15] op_sel:[1,0]
	v_add_f32_e32 v30, v22, v15
	v_sub_f32_e32 v31, v23, v14
	v_pk_add_f32 v[28:29], v[28:29], v[28:29] op_sel:[0,1] op_sel_hi:[0,1]
	v_pk_add_f32 v[6:7], v[48:49], v[50:51]
	v_pk_add_f32 v[36:37], v[58:59], v[60:61] neg_lo:[0,1] neg_hi:[0,1]
	v_pk_add_f32 v[48:49], v[48:49], v[50:51] neg_lo:[0,1] neg_hi:[0,1]
	v_pk_add_f32 v[14:15], v[62:63], v[62:63] op_sel:[0,1] op_sel_hi:[0,1] neg_lo:[0,1] neg_hi:[0,1]
	v_pk_mul_f32 v[28:29], v[28:29], s[22:23]
	v_pk_add_f32 v[52:53], v[38:39], v[26:27]
	v_pk_add_f32 v[54:55], v[42:43], v[34:35]
	v_pk_add_f32 v[10:11], v[58:59], v[60:61]
	v_add_f32_e32 v44, v62, v63
	v_pk_mul_f32 v[50:51], v[48:49], s[20:21] op_sel_hi:[1,0]
	v_mul_f32_e32 v36, 0x3f3504f3, v36
	v_mul_f32_e32 v58, 0x3f3504f3, v37
	v_mul_f32_e32 v61, 0xbf3504f3, v37
	v_fma_f32 v62, v14, s70, v28
	v_fma_f32 v63, v15, s71, -v29
	v_pk_add_f32 v[4:5], v[12:13], v[46:47]
	v_pk_add_f32 v[56:57], v[52:53], v[54:55] neg_lo:[0,1] neg_hi:[0,1]
	v_cvt_f32_i32_e32 v3, v3
	v_mov_b32_e32 v14, v12
	v_sub_f32_e32 v12, v58, v36
	v_sub_f32_e32 v13, v13, v47
	v_sub_f32_e32 v14, v14, v46
	v_sub_f32_e32 v15, v51, v50
	v_mov_b32_e32 v29, v36
	v_pk_add_f32 v[36:37], v[12:13], v[56:57] op_sel:[1,0] op_sel_hi:[0,1]
	v_mov_b32_e32 v47, v56
	v_sub_f32_e32 v28, v53, v55
	v_sub_f32_e32 v29, v61, v29
	v_sub_f32_e32 v56, v38, v26
	v_sub_f32_e32 v57, v16, v24
	v_sub_f32_e32 v58, v43, v35
	v_sub_f32_e32 v59, v21, v33
	v_mul_f32_e32 v72, 0x3f6c835e, v44
	v_mul_f32_e32 v73, 0x3ec3ef15, v40
	v_add_f32_e32 v3, v3, v3
	v_sub_f32_e32 v16, v39, v27
	v_sub_f32_e32 v17, v17, v25
	v_sub_f32_e32 v21, v20, v32
	v_sub_f32_e32 v20, v42, v34
	v_pk_add_f32 v[26:27], v[56:57], v[58:59] neg_lo:[0,1] neg_hi:[0,1]
	v_pk_fma_f32 v[48:49], v[48:49], s[20:21], v[50:51] op_sel:[0,0,1] op_sel_hi:[1,0,0]
	v_mul_f32_e32 v3, 0x3b800000, v3
	v_pk_add_f32 v[60:61], v[56:57], v[58:59]
	v_pk_add_f32 v[24:25], v[16:17], v[20:21] neg_lo:[0,1] neg_hi:[0,1]
	v_pk_add_f32 v[16:17], v[16:17], v[20:21]
	v_mov_b32_e32 v33, v23
	v_mov_b32_e32 v21, v19
	v_mul_f32_e32 v3, 0.5, v3
	v_mov_b32_e32 v46, v48
	v_pk_add_f32 v[48:49], v[48:49], v[12:13] neg_lo:[0,1] neg_hi:[0,1]
	v_mul_f32_e32 v20, 0x3ec3ef15, v27
	v_pk_mul_f32 v[34:35], v[26:27], s[20:21]
	v_mul_f32_e32 v27, s73, v26
	v_mul_f32_e32 v26, s72, v44
	v_sub_f32_e32 v18, v22, v18
	v_sub_f32_e32 v19, v73, v72
	v_pk_mul_f32 v[22:23], v[60:61], s[70:71] op_sel:[1,0]
	v_pk_add_f32 v[8:9], v[52:53], v[54:55]
	v_sin_f32_e32 v52, v3
	v_cos_f32_e32 v70, v3
	v_add_f32_e32 v50, v12, v46
	v_sub_f32_e32 v47, v13, v47
	v_pk_add_f32 v[12:13], v[36:37], v[48:49]
	v_mul_f32_e32 v32, 0x3f6c835e, v17
	v_mul_f32_e32 v3, 0x3f3504f3, v60
	v_mul_f32_e32 v37, 0x3f3504f3, v24
	v_pk_fma_f32 v[34:35], v[16:17], s[28:29], v[34:35] neg_lo:[0,0,1] neg_hi:[0,0,1]
	v_fma_f32 v17, v16, s31, -v27
	v_fma_f32 v16, v40, s30, -v26
	v_fma_f32 v26, v25, s22, v22
	v_fma_f32 v27, v25, s23, -v23
	v_pk_add_f32 v[20:21], v[32:33], v[20:21]
	v_add_f32_e32 v22, v37, v3
	v_fma_f32 v23, v24, s20, -v3
	v_pk_add_f32 v[24:25], v[30:31], v[22:23]
	v_pk_add_f32 v[32:33], v[26:27], v[62:63]
	v_xor_b32_e32 v71, 0x80000000, v52
	v_pk_add_f32 v[38:39], v[32:33], v[24:25]
	v_pk_add_f32 v[64:65], v[4:5], v[8:9]
	v_pk_mul_f32 v[44:45], v[52:53], v[38:39] op_sel_hi:[0,1]
	v_fma_f32 v56, v70, v38, v45
	v_fma_f32 v57, v70, v39, -v44
	v_mov_b32_e32 v53, v70
	v_pk_add_f32 v[66:67], v[6:7], v[10:11]
	v_mul_f32_e32 v38, v52, v52
	v_mul_f32_e32 v39, v53, v71
	v_pk_add_f32 v[68:69], v[66:67], v[64:65]
	v_pk_fma_f32 v[44:45], v[70:71], v[70:71], v[38:39] op_sel_hi:[0,1,1] neg_lo:[0,0,1] neg_hi:[0,0,1]
	v_pk_fma_f32 v[38:39], v[70:71], v[70:71], v[38:39] op_sel_hi:[0,1,1]
	v_pk_add_f32 v[54:55], v[14:15], v[28:29]
	ds_write2_b64 v1, v[68:69], v[56:57] offset1:17
	v_pk_add_f32 v[14:15], v[14:15], v[28:29] neg_lo:[0,1] neg_hi:[0,1]
	v_add_f32_e32 v28, v54, v50
	v_add_f32_e32 v29, v55, v47
	v_mov_b32_e32 v56, v44
	v_mov_b32_e32 v57, v39
	v_mul_f32_e32 v68, v39, v39
	v_mul_f32_e32 v69, v39, v44
	v_pk_mul_f32 v[38:39], v[28:29], v[38:39] op_sel:[1,1] op_sel_hi:[0,1]
	v_pk_fma_f32 v[72:73], v[44:45], v[56:57], v[68:69] op_sel_hi:[0,1,1] neg_lo:[0,0,1] neg_hi:[0,0,1]
	v_pk_fma_f32 v[68:69], v[44:45], v[56:57], v[68:69] op_sel_hi:[0,1,1]
	v_fma_f32 v82, v28, v44, -v38
	v_fma_f32 v83, v29, v44, v39
	v_pk_mul_f32 v[38:39], v[56:57], v[68:69] op_sel:[0,1]
	v_pk_add_f32 v[26:27], v[26:27], v[62:63] neg_lo:[0,1] neg_hi:[0,1]
	v_fma_f32 v44, v56, v72, -v39
	v_fma_f32 v39, v57, v72, v38
	v_sub_f32_e32 v36, v36, v48
	v_mov_b32_e32 v63, v39
	v_mov_b32_e32 v71, v52
	v_mov_b32_e32 v74, v72
	v_mov_b32_e32 v75, v69
	v_pk_add_f32 v[84:85], v[14:15], v[14:15] op_sel:[0,1] op_sel_hi:[0,1]
	v_mul_f32_e32 v37, v36, v44
	v_mul_f32_e32 v36, v36, v39
	v_pk_mul_f32 v[58:59], v[70:71], v[56:57]
	v_pk_mul_f32 v[60:61], v[52:53], v[56:57]
	v_mov_b32_e32 v62, v44
	v_fma_f32 v38, v84, v44, -v36
	v_pk_mul_f32 v[44:45], v[74:75], v[68:69] op_sel:[0,1]
	v_pk_add_f32 v[24:25], v[24:25], v[32:33] neg_lo:[0,1] neg_hi:[0,1]
	v_pk_add_f32 v[32:33], v[34:35], v[18:19]
	v_pk_add_f32 v[40:41], v[20:21], v[16:17]
	v_fma_f32 v39, v85, v63, v37
	v_pk_fma_f32 v[48:49], v[72:73], v[74:75], v[44:45] op_sel:[0,0,1] op_sel_hi:[0,1,0] neg_lo:[0,0,1] neg_hi:[0,0,1]
	v_pk_fma_f32 v[44:45], v[72:73], v[74:75], v[44:45] op_sel:[0,0,1] op_sel_hi:[0,1,0]
	v_mov_b32_e32 v86, v58
	v_mov_b32_e32 v87, v61
	v_pk_mov_b32 v[58:59], v[58:59], v[60:61] op_sel:[1,0]
	v_pk_add_f32 v[42:43], v[32:33], v[40:41]
	v_pk_add_f32 v[36:37], v[64:65], v[66:67] neg_lo:[0,1] neg_hi:[0,1]
	v_pk_mov_b32 v[66:67], v[44:45], v[48:49] op_sel:[1,0]
	v_pk_add_f32 v[60:61], v[86:87], v[58:59]
	v_pk_add_f32 v[58:59], v[86:87], v[58:59] neg_lo:[0,1] neg_hi:[0,1]
	v_pk_mul_f32 v[76:77], v[70:71], v[74:75]
	v_pk_mul_f32 v[78:79], v[52:53], v[74:75]
	v_pk_add_f32 v[22:23], v[30:31], v[22:23] neg_lo:[0,1] neg_hi:[0,1]
	v_mov_b32_e32 v64, v48
	v_mov_b32_e32 v65, v45
	v_pk_mul_f32 v[52:53], v[52:53], v[66:67] op_sel_hi:[0,1]
	v_pk_mul_f32 v[88:89], v[42:43], v[58:59] op_sel:[0,1]
	v_pk_mov_b32 v[80:81], v[68:69], v[72:73] op_sel:[1,0]
	v_pk_add_f32 v[28:29], v[22:23], v[26:27] op_sel:[0,1] op_sel_hi:[1,0]
	v_pk_add_f32 v[22:23], v[22:23], v[26:27] op_sel:[0,1] op_sel_hi:[1,0] neg_lo:[0,1] neg_hi:[0,1]
	v_fma_f32 v68, v70, v64, v52
	v_fma_f32 v53, v70, v65, -v53
	v_fma_f32 v90, v42, v60, -v89
	v_fma_f32 v91, v43, v60, v88
	v_mov_b32_e32 v92, v76
	v_mov_b32_e32 v93, v79
	v_pk_mov_b32 v[76:77], v[76:77], v[78:79] op_sel:[1,0]
	v_mov_b32_e32 v71, v53
	v_pk_mul_f32 v[42:43], v[74:75], v[58:59] op_sel:[0,1]
	v_pk_add_f32 v[78:79], v[92:93], v[76:77]
	v_sub_f32_e32 v77, v93, v77
	v_mov_b32_e32 v27, v23
	v_mov_b32_e32 v70, v68
	v_mov_b32_e32 v87, v59
	v_pk_fma_f32 v[58:59], v[74:75], v[60:61], v[42:43] op_sel:[0,0,1] op_sel_hi:[1,0,0] neg_lo:[0,0,1] neg_hi:[0,0,1]
	v_pk_fma_f32 v[42:43], v[74:75], v[60:61], v[42:43] op_sel:[0,0,1] op_sel_hi:[1,0,0]
	v_mul_f32_e32 v30, v23, v77
	v_mul_f32_e32 v31, v28, v77
	v_mul_f32_e32 v52, v25, v53
	v_mul_f32_e32 v53, v25, v68
	v_mov_b32_e32 v86, v60
	v_mov_b32_e32 v60, v58
	v_mov_b32_e32 v61, v43
	v_mov_b32_e32 v92, v78
	v_mov_b32_e32 v93, v77
	v_fma_f32 v76, v28, v78, -v30
	v_fma_f32 v77, v27, v78, v31
	v_fma_f32 v68, v24, v68, -v52
	v_fma_f32 v69, v24, v71, v53
	v_pk_mul_f32 v[44:45], v[36:37], v[44:45] op_sel:[1,1] op_sel_hi:[0,1]
	v_pk_mul_f32 v[84:85], v[56:57], v[64:65]
	v_pk_mul_f32 v[56:57], v[56:57], v[66:67]
	ds_write2_b64 v1, v[82:83], v[90:91] offset0:34 offset1:51
	v_pk_mul_f32 v[82:83], v[86:87], v[64:65]
	v_pk_mul_f32 v[86:87], v[86:87], v[66:67]
	v_pk_mul_f32 v[88:89], v[74:75], v[64:65]
	v_pk_mul_f32 v[90:91], v[74:75], v[66:67]
	v_pk_mul_f32 v[26:27], v[64:65], v[92:93]
	v_pk_mul_f32 v[30:31], v[66:67], v[92:93]
	v_pk_mul_f32 v[24:25], v[64:65], v[62:63]
	v_pk_mul_f32 v[52:53], v[66:67], v[62:63]
	v_pk_mul_f32 v[62:63], v[64:65], v[60:61]
	v_pk_mul_f32 v[64:65], v[66:67], v[60:61]
	v_fma_f32 v66, v36, v48, -v44
	v_fma_f32 v67, v37, v48, v45
	v_mov_b32_e32 v51, v55
	v_sub_f32_e32 v36, v54, v50
	v_sub_f32_e32 v37, v47, v51
	v_pk_add_f32 v[44:45], v[56:57], v[56:57] op_sel:[0,1] op_sel_hi:[0,1]
	v_pk_mul_f32 v[44:45], v[36:37], v[44:45] op_sel:[1,0] op_sel_hi:[0,1]
	v_pk_add_f32 v[46:47], v[84:85], v[84:85] op_sel:[0,1] op_sel_hi:[0,1] neg_lo:[0,1] neg_hi:[0,1]
	v_fma_f32 v48, v36, v46, -v44
	v_fma_f32 v49, v37, v47, v45
	v_pk_add_f32 v[4:5], v[4:5], v[8:9] neg_lo:[0,1] neg_hi:[0,1]
	v_mov_b32_e32 v37, v41
	v_sub_f32_e32 v32, v32, v40
	v_sub_f32_e32 v33, v37, v33
	v_pk_add_f32 v[36:37], v[86:87], v[86:87] op_sel:[0,1] op_sel_hi:[0,1]
	v_pk_add_f32 v[6:7], v[6:7], v[10:11] neg_lo:[0,1] neg_hi:[0,1]
	v_pk_mul_f32 v[36:37], v[32:33], v[36:37] op_sel:[1,0] op_sel_hi:[0,1]
	v_pk_add_f32 v[40:41], v[82:83], v[82:83] op_sel:[0,1] op_sel_hi:[0,1] neg_lo:[0,1] neg_hi:[0,1]
	v_pk_add_f32 v[8:9], v[4:5], v[6:7] op_sel:[0,1] op_sel_hi:[1,0]
	v_pk_add_f32 v[4:5], v[4:5], v[6:7] op_sel:[0,1] op_sel_hi:[1,0] neg_lo:[0,1] neg_hi:[0,1]
	v_fma_f32 v44, v32, v40, -v36
	v_fma_f32 v45, v33, v41, v37
	v_pk_mul_f32 v[10:11], v[4:5], v[80:81] op_sel:[1,0]
	v_fma_f32 v32, v8, v72, -v10
	v_fma_f32 v33, v8, v75, v11
	v_mov_b32_e32 v7, v9
	v_pk_add_f32 v[10:11], v[90:91], v[90:91] op_sel:[0,1] op_sel_hi:[0,1]
	v_mul_f32_e32 v8, v9, v10
	v_mul_f32_e32 v9, v4, v11
	v_pk_add_f32 v[10:11], v[88:89], v[88:89] op_sel:[0,1] op_sel_hi:[0,1] neg_lo:[0,1] neg_hi:[0,1]
	v_fma_f32 v4, v4, v10, -v8
	v_fma_f32 v5, v7, v11, v9
	v_pk_add_f32 v[10:11], v[30:31], v[30:31] op_sel:[0,1] op_sel_hi:[0,1]
	v_mov_b32_e32 v7, v29
	v_mul_f32_e32 v8, v29, v10
	v_mul_f32_e32 v9, v22, v11
	v_pk_add_f32 v[10:11], v[26:27], v[26:27] op_sel:[0,1] op_sel_hi:[0,1] neg_lo:[0,1] neg_hi:[0,1]
	v_fma_f32 v22, v22, v10, -v8
	v_fma_f32 v23, v7, v11, v9
	v_pk_add_f32 v[8:9], v[52:53], v[52:53] op_sel:[0,1] op_sel_hi:[0,1]
	ds_write2_b64 v1, v[4:5], v[22:23] offset0:204 offset1:221
	v_mov_b32_e32 v5, v24
	v_sub_f32_e32 v4, v14, v15
	v_sub_f32_e32 v5, v5, v25
	v_mul_f32_e32 v6, v12, v8
	v_mul_f32_e32 v7, v4, v9
	v_pk_mov_b32 v[8:9], v[4:5], v[12:13] op_sel:[1,0]
	v_pk_mov_b32 v[42:43], v[42:43], v[58:59] op_sel:[1,0]
	v_fma_f32 v10, v4, v8, -v6
	v_fma_f32 v11, v5, v9, v7
	v_mov_b32_e32 v5, v20
	v_mov_b32_e32 v7, v16
	v_sub_f32_e32 v4, v18, v34
	v_sub_f32_e32 v5, v5, v7
	v_sub_f32_e32 v6, v35, v19
	v_sub_f32_e32 v7, v21, v17
	ds_write2_b64 v1, v[66:67], v[68:69] offset0:136 offset1:153
	v_pk_add_f32 v[8:9], v[6:7], v[4:5]
	v_sub_f32_e32 v12, v4, v6
	v_sub_f32_e32 v4, v7, v5
	v_pk_mul_f32 v[4:5], v[4:5], v[42:43] op_sel_hi:[0,1]
	v_fma_f32 v6, v8, v58, -v4
	v_fma_f32 v7, v8, v61, v5
	ds_write2_b64 v1, v[38:39], v[6:7] offset0:102 offset1:119
	v_pk_add_f32 v[6:7], v[64:65], v[64:65] op_sel:[0,1] op_sel_hi:[0,1]
	v_mov_b32_e32 v15, v9
	v_mul_f32_e32 v4, v9, v6
	v_mul_f32_e32 v5, v12, v7
	v_pk_add_f32 v[6:7], v[62:63], v[62:63] op_sel:[0,1] op_sel_hi:[0,1] neg_lo:[0,1] neg_hi:[0,1]
	v_fma_f32 v8, v12, v6, -v4
	v_fma_f32 v9, v15, v7, v5
	ds_write2_b64 v1, v[48:49], v[44:45] offset0:170 offset1:187
	ds_write2_b64 v1, v[32:33], v[76:77] offset0:68 offset1:85
	ds_write2_b64 v1, v[10:11], v[8:9] offset0:238 offset1:255
	v_mov_b32_e32 v1, v2
	s_waitcnt lgkmcnt(0)
	s_barrier
	v_readlane_b32 s5, v246, 29
	v_mul_lo_u32 v1, v1, s33
	ds_read2_b64 v[4:7], v1 offset1:1
	ds_read2_b64 v[8:11], v1 offset0:2 offset1:3
	ds_read2_b64 v[12:15], v1 offset0:8 offset1:9
	ds_read2_b64 v[16:19], v1 offset0:14 offset1:15
	ds_read2_b64 v[20:23], v1 offset0:12 offset1:13
	ds_read2_b64 v[24:27], v1 offset0:4 offset1:5
	ds_read2_b64 v[28:31], v1 offset0:6 offset1:7
	ds_read2_b64 v[32:35], v1 offset0:10 offset1:11
	s_waitcnt lgkmcnt(5)
	v_add_f32_e32 v1, v4, v12
	v_sub_f32_e32 v3, v4, v12
	s_waitcnt lgkmcnt(2)
	v_add_f32_e32 v4, v24, v20
	v_sub_f32_e32 v5, v25, v21
	v_add_f32_e32 v12, v1, v4
	v_sub_f32_e32 v1, v1, v4
	v_add_f32_e32 v4, v3, v5
	v_sub_f32_e32 v3, v3, v5
	v_add_f32_e32 v5, v6, v14
	v_add_f32_e32 v13, v7, v15
	v_sub_f32_e32 v6, v6, v14
	v_sub_f32_e32 v7, v7, v15
	v_add_f32_e32 v14, v26, v22
	v_add_f32_e32 v15, v27, v23
	v_sub_f32_e32 v20, v26, v22
	v_sub_f32_e32 v21, v27, v23
	v_add_f32_e32 v22, v5, v14
	v_add_f32_e32 v23, v13, v15
	v_sub_f32_e32 v5, v5, v14
	v_sub_f32_e32 v13, v13, v15
	v_add_f32_e32 v14, v6, v21
	v_sub_f32_e32 v15, v7, v20
	v_sub_f32_e32 v6, v6, v21
	v_add_f32_e32 v7, v7, v20
	s_waitcnt lgkmcnt(0)
	v_add_f32_e32 v20, v8, v32
	v_add_f32_e32 v21, v9, v33
	v_sub_f32_e32 v8, v8, v32
	v_sub_f32_e32 v9, v9, v33
	v_add_f32_e32 v24, v28, v16
	v_add_f32_e32 v25, v29, v17
	v_sub_f32_e32 v16, v28, v16
	v_sub_f32_e32 v17, v29, v17
	v_add_f32_e32 v20, v20, v24
	v_sub_f32_e32 v21, v21, v25
	v_add_f32_e32 v24, v8, v17
	v_sub_f32_e32 v25, v9, v16
	v_sub_f32_e32 v8, v8, v17
	v_add_f32_e32 v9, v9, v16
	v_add_f32_e32 v16, v10, v34
	v_add_f32_e32 v17, v11, v35
	v_sub_f32_e32 v11, v11, v35
	v_add_f32_e32 v26, v30, v18
	v_add_f32_e32 v27, v31, v19
	v_sub_f32_e32 v18, v30, v18
	v_sub_f32_e32 v10, v10, v34
	v_sub_f32_e32 v19, v31, v19
	v_add_f32_e32 v28, v16, v26
	v_add_f32_e32 v29, v17, v27
	v_sub_f32_e32 v16, v16, v26
	v_sub_f32_e32 v17, v17, v27
	v_sub_f32_e32 v27, v11, v18
	v_add_f32_e32 v11, v11, v18
	v_mul_f32_e32 v18, 0x3f6c835e, v14
	v_mul_f32_e32 v14, 0x3ec3ef15, v14
	v_mul_f32_e32 v5, 0x3f3504f3, v5
	v_add_f32_e32 v26, v10, v19
	v_fmac_f32_e32 v18, 0x3ec3ef15, v15
	v_fma_f32 v14, v15, s21, -v14
	v_fmamk_f32 v15, v13, 0x3f3504f3, v5
	v_fma_f32 v5, v13, s20, -v5
	v_mul_f32_e32 v13, 0x3ec3ef15, v6
	v_mul_f32_e32 v6, 0xbf6c835e, v6
	v_mul_f32_e32 v8, 0xbf3504f3, v8
	v_mul_f32_e32 v16, 0xbf3504f3, v16
	v_sub_f32_e32 v10, v10, v19
	v_fmac_f32_e32 v13, 0x3f6c835e, v7
	v_fmac_f32_e32 v6, 0x3ec3ef15, v7
	v_mul_f32_e32 v7, 0x3f3504f3, v24
	v_fmac_f32_e32 v8, 0x3f3504f3, v9
	v_mul_f32_e32 v9, 0x3ec3ef15, v26
	v_mul_f32_e32 v19, 0xbf6c835e, v26
	v_fmamk_f32 v24, v17, 0x3f3504f3, v16
	v_fmac_f32_e32 v16, 0xbf3504f3, v17
	v_mul_f32_e32 v17, 0x3ec3ef15, v11
	v_mul_f32_e32 v11, 0xbf6c835e, v11
	v_fmac_f32_e32 v7, 0x3f3504f3, v25
	v_fmac_f32_e32 v9, 0x3f6c835e, v27
	v_fmac_f32_e32 v19, 0x3ec3ef15, v27
	v_fma_f32 v17, v10, s76, -v17
	v_fmac_f32_e32 v11, 0x3ec3ef15, v10
	v_add_f32_e32 v10, v12, v20
	v_sub_f32_e32 v12, v12, v20
	v_add_f32_e32 v20, v22, v28
	v_sub_f32_e32 v22, v23, v29
	v_add_f32_e32 v23, v20, v10
	v_sub_f32_e32 v10, v10, v20
	v_add_f32_e32 v20, v12, v22
	v_sub_f32_e32 v12, v12, v22
	v_add_f32_e32 v22, v4, v7
	v_sub_f32_e32 v4, v4, v7
	v_add_f32_e32 v7, v18, v9
	v_sub_f32_e32 v9, v14, v19
	v_add_f32_e32 v18, v9, v4
	v_sub_f32_e32 v4, v4, v9
	v_add_f32_e32 v9, v1, v21
	v_sub_f32_e32 v1, v1, v21
	v_add_f32_e32 v15, v15, v24
	v_sub_f32_e32 v5, v5, v16
	v_add_f32_e32 v16, v9, v15
	v_sub_f32_e32 v9, v9, v15
	v_add_f32_e32 v15, v1, v5
	v_sub_f32_e32 v1, v1, v5
	v_add_f32_e32 v5, v3, v8
	v_sub_f32_e32 v3, v3, v8
	v_add_f32_e32 v8, v13, v17
	v_sub_f32_e32 v6, v6, v11
	v_add_f32_e32 v11, v8, v5
	v_sub_f32_e32 v5, v5, v8
	v_add_f32_e32 v8, v6, v3
	v_sub_f32_e32 v3, v3, v6
	v_lshlrev_b32_e32 v6, 4, v2
	v_and_b32_e32 v6, 0xf0, v6
	v_ashrrev_i32_e32 v13, 4, v2
	v_add_u32_e32 v6, v6, v13
	v_ashrrev_i32_e32 v17, 4, v6
	v_lshlrev_b32_e32 v19, 2, v6
	v_mul_f32_e32 v13, 0x3ab504f3, v23
	v_lshl_add_u32 v17, v17, 2, v19
	s_barrier
	ds_write_b32 v17, v13
	v_add_u32_e32 v13, 0x100, v6
	v_add_f32_e32 v14, v7, v22
	v_ashrrev_i32_e32 v13, 4, v13
	v_mul_f32_e32 v14, 0x3ab504f3, v14
	v_lshl_add_u32 v13, v13, 2, v19
	ds_write_b32 v13, v14 offset:1024
	v_add_u32_e32 v13, 0x200, v6
	v_ashrrev_i32_e32 v13, 4, v13
	v_mul_f32_e32 v14, 0x3ab504f3, v16
	v_lshl_add_u32 v13, v13, 2, v19
	ds_write_b32 v13, v14 offset:2048
	v_add_u32_e32 v13, 0x300, v6
	v_ashrrev_i32_e32 v13, 4, v13
	v_mul_f32_e32 v11, 0x3ab504f3, v11
	v_lshl_add_u32 v13, v13, 2, v19
	ds_write_b32 v13, v11 offset:3072
	v_add_u32_e32 v11, 0x400, v6
	v_ashrrev_i32_e32 v11, 4, v11
	v_mul_f32_e32 v13, 0x3ab504f3, v20
	v_lshl_add_u32 v11, v11, 2, v19
	ds_write_b32 v11, v13 offset:4096
	v_add_u32_e32 v11, 0x500, v6
	v_ashrrev_i32_e32 v11, 4, v11
	v_mul_f32_e32 v13, 0x3ab504f3, v18
	v_lshl_add_u32 v11, v11, 2, v19
	ds_write_b32 v11, v13 offset:5120
	v_add_u32_e32 v11, 0x600, v6
	v_ashrrev_i32_e32 v11, 4, v11
	v_mul_f32_e32 v13, 0x3ab504f3, v15
	v_lshl_add_u32 v11, v11, 2, v19
	ds_write_b32 v11, v13 offset:6144
	v_add_u32_e32 v11, 0x700, v6
	v_ashrrev_i32_e32 v11, 4, v11
	v_mul_f32_e32 v8, 0x3ab504f3, v8
	v_lshl_add_u32 v11, v11, 2, v19
	ds_write_b32 v11, v8 offset:7168
	v_add_u32_e32 v8, 0x800, v6
	v_ashrrev_i32_e32 v8, 4, v8
	v_mul_f32_e32 v10, 0x3ab504f3, v10
	v_lshl_add_u32 v8, v8, 2, v19
	ds_write_b32 v8, v10 offset:8192
	v_add_u32_e32 v8, 0x900, v6
	v_sub_f32_e32 v7, v22, v7
	v_ashrrev_i32_e32 v8, 4, v8
	v_mul_f32_e32 v7, 0x3ab504f3, v7
	v_lshl_add_u32 v8, v8, 2, v19
	ds_write_b32 v8, v7 offset:9216
	v_add_u32_e32 v7, 0xa00, v6
	v_ashrrev_i32_e32 v7, 4, v7
	v_mul_f32_e32 v8, 0x3ab504f3, v9
	v_lshl_add_u32 v7, v7, 2, v19
	ds_write_b32 v7, v8 offset:10240
	v_add_u32_e32 v7, 0xb00, v6
	v_ashrrev_i32_e32 v7, 4, v7
	v_mul_f32_e32 v5, 0x3ab504f3, v5
	v_lshl_add_u32 v7, v7, 2, v19
	ds_write_b32 v7, v5 offset:11264
	v_add_u32_e32 v5, 0xc00, v6
	v_ashrrev_i32_e32 v5, 4, v5
	v_mul_f32_e32 v7, 0x3ab504f3, v12
	v_lshl_add_u32 v5, v5, 2, v19
	ds_write_b32 v5, v7 offset:12288
	v_add_u32_e32 v5, 0xd00, v6
	v_ashrrev_i32_e32 v5, 4, v5
	v_mul_f32_e32 v4, 0x3ab504f3, v4
	v_lshl_add_u32 v5, v5, 2, v19
	ds_write_b32 v5, v4 offset:13312
	v_add_u32_e32 v4, 0xe00, v6
	v_ashrrev_i32_e32 v4, 4, v4
	v_mul_f32_e32 v1, 0x3ab504f3, v1
	v_lshl_add_u32 v4, v4, 2, v19
	s_add_u32 s22, s4, s0
	ds_write_b32 v4, v1 offset:14336
	s_addc_u32 s23, s5, s1
	v_lshlrev_b32_e32 v4, 3, v2
	v_add_u32_e32 v1, 0xf00, v6
	s_add_u32 s22, s22, s2
	v_ashrrev_i32_e32 v5, 31, v4
	v_ashrrev_i32_e32 v1, 4, v1
	s_addc_u32 s23, s23, 0
	v_lshlrev_b64 v[6:7], 1, v[4:5]
	v_mul_f32_e32 v3, 0x3ab504f3, v3
	v_lshl_add_u32 v1, v1, 2, v19
	v_lshl_add_u64 v[8:9], s[22:23], 0, v[6:7]
	ds_write_b32 v1, v3 offset:15360
	s_waitcnt lgkmcnt(0)
	s_barrier
	global_load_dwordx4 v[8:11], v[8:9], off
	v_bfe_i32 v1, v2, 1, 28
	v_lshlrev_b32_e32 v5, 5, v2
	v_lshl_add_u32 v1, v1, 2, v5
	ds_read2_b32 v[12:13], v1 offset1:1
	ds_read2_b32 v[14:15], v1 offset0:2 offset1:3
	ds_read2_b32 v[16:17], v1 offset0:4 offset1:5
	ds_read2_b32 v[18:19], v1 offset0:6 offset1:7
	v_readlane_b32 s4, v247, 56
	v_readlane_b32 s5, v247, 57
	s_add_u32 s0, s4, s0
	s_addc_u32 s1, s5, s1
	s_add_u32 s0, s0, s2
	s_addc_u32 s1, s1, 0
	s_and_b64 vcc, exec, s[36:37]
	s_waitcnt vmcnt(0)
	v_lshlrev_b32_e32 v2, 16, v8
	v_and_b32_e32 v3, 0xffff0000, v8
	s_waitcnt lgkmcnt(3)
	v_pk_mul_f32 v[2:3], v[12:13], v[2:3]
	s_nop 0
	v_cvt_pk_bf16_f32 v8, v2, v3
	v_lshlrev_b32_e32 v2, 16, v9
	v_and_b32_e32 v3, 0xffff0000, v9
	s_waitcnt lgkmcnt(2)
	v_pk_mul_f32 v[2:3], v[14:15], v[2:3]
	s_nop 0
	v_cvt_pk_bf16_f32 v9, v2, v3
	v_lshlrev_b32_e32 v2, 16, v10
	v_and_b32_e32 v3, 0xffff0000, v10
	s_waitcnt lgkmcnt(1)
	v_pk_mul_f32 v[2:3], v[16:17], v[2:3]
	s_nop 0
	v_cvt_pk_bf16_f32 v10, v2, v3
	v_lshlrev_b32_e32 v2, 16, v11
	v_and_b32_e32 v3, 0xffff0000, v11
	s_waitcnt lgkmcnt(0)
	v_pk_mul_f32 v[2:3], v[18:19], v[2:3]
	s_nop 0
	v_cvt_pk_bf16_f32 v11, v2, v3
	v_lshl_add_u64 v[2:3], s[0:1], 0, v[6:7]
	global_store_dwordx4 v[2:3], v[8:11], off
	s_nop 1
	v_add_u32_e32 v8, 0x800, v4
	v_ashrrev_i32_e32 v9, 31, v8
	v_lshlrev_b64 v[2:3], 1, v[8:9]
	v_lshl_add_u64 v[10:11], s[22:23], 0, v[2:3]
	global_load_dwordx4 v[10:13], v[10:11], off
	v_ashrrev_i32_e32 v1, 4, v8
	v_lshl_add_u32 v1, v1, 2, v5
	v_add_u32_e32 v5, 0x2000, v1
	ds_read2_b32 v[16:17], v5 offset1:1
	v_add_u32_e32 v9, 0x2008, v1
	v_add_u32_e32 v20, 0x2010, v1
	v_add_u32_e32 v1, 0x2018, v1
	ds_read2_b32 v[18:19], v9 offset1:1
	ds_read2_b32 v[20:21], v20 offset1:1
	ds_read2_b32 v[22:23], v1 offset1:1
	s_waitcnt vmcnt(0)
	v_lshlrev_b32_e32 v14, 16, v10
	v_and_b32_e32 v15, 0xffff0000, v10
	s_waitcnt lgkmcnt(3)
	v_pk_mul_f32 v[14:15], v[16:17], v[14:15]
	s_nop 0
	v_cvt_pk_bf16_f32 v10, v14, v15
	v_lshlrev_b32_e32 v14, 16, v11
	v_and_b32_e32 v15, 0xffff0000, v11
	s_waitcnt lgkmcnt(2)
	v_pk_mul_f32 v[14:15], v[18:19], v[14:15]
	s_nop 0
	v_cvt_pk_bf16_f32 v11, v14, v15
	v_lshlrev_b32_e32 v14, 16, v12
	v_and_b32_e32 v15, 0xffff0000, v12
	s_waitcnt lgkmcnt(1)
	v_pk_mul_f32 v[14:15], v[20:21], v[14:15]
	s_nop 0
	v_cvt_pk_bf16_f32 v12, v14, v15
	v_lshlrev_b32_e32 v14, 16, v13
	v_and_b32_e32 v15, 0xffff0000, v13
	s_waitcnt lgkmcnt(0)
	v_pk_mul_f32 v[14:15], v[22:23], v[14:15]
	s_nop 0
	v_cvt_pk_bf16_f32 v13, v14, v15
	v_lshl_add_u64 v[14:15], s[0:1], 0, v[2:3]
	global_store_dwordx4 v[14:15], v[10:13], off
	s_cbranch_vccnz .LBB0_692
	s_sub_i32 s0, s34, s24
	s_addk_i32 s0, 0x80
	s_mul_hi_i32 s22, s0, 0x14000
	s_mul_i32 s23, s0, 0x14000
	v_readlane_b32 s0, v246, 28
	v_readlane_b32 s1, v246, 29
	s_add_u32 s0, s0, s23
	s_addc_u32 s1, s1, s22
	s_add_u32 s0, s0, s2
	s_addc_u32 s1, s1, 0
	v_lshl_add_u64 v[10:11], s[0:1], 0, v[6:7]
	global_load_dwordx4 v[10:13], v[10:11], off
	v_and_b32_e32 v1, 0xfffff000, v4
	v_sub_u32_e32 v5, 0, v4
	v_xor_b32_e32 v9, 0xff0, v4
	v_sub_u32_e32 v15, 0xffe, v4
	v_sub_u32_e32 v16, 0xffd, v4
	v_sub_u32_e32 v17, 0xffc, v4
	v_sub_u32_e32 v18, 0xffb, v4
	v_sub_u32_e32 v19, 0xffa, v4
	v_sub_u32_e32 v20, 0xff9, v4
	s_movk_i32 s7, 0xff8
	s_movk_i32 s6, 0xffe
	s_movk_i32 s8, 0xffd
	s_movk_i32 s9, 0xffc
	s_movk_i32 s10, 0xffb
	s_movk_i32 s11, 0xffa
	s_movk_i32 s12, 0xff9
	v_and_or_b32 v5, v5, s7, v1
	v_ashrrev_i32_e32 v9, 4, v9
	v_and_or_b32 v15, v15, s6, v1
	v_and_or_b32 v16, v16, s8, v1
	v_and_or_b32 v17, v17, s9, v1
	v_and_or_b32 v18, v18, s10, v1
	v_and_or_b32 v19, v19, s11, v1
	v_and_or_b32 v1, v20, s12, v1
	v_xor_b32_e32 v14, 0xff8, v4
	v_ashrrev_i32_e32 v20, 4, v5
	v_lshlrev_b32_e32 v9, 2, v9
	v_ashrrev_i32_e32 v21, 4, v15
	v_ashrrev_i32_e32 v22, 4, v16
	v_ashrrev_i32_e32 v23, 4, v17
	v_ashrrev_i32_e32 v24, 4, v18
	v_ashrrev_i32_e32 v25, 4, v19
	v_ashrrev_i32_e32 v26, 4, v1
	v_lshlrev_b32_e32 v20, 2, v20
	v_lshl_add_u32 v9, v14, 2, v9
	v_lshlrev_b32_e32 v14, 2, v21
	v_lshlrev_b32_e32 v21, 2, v22
	v_lshlrev_b32_e32 v22, 2, v23
	v_lshlrev_b32_e32 v23, 2, v24
	v_lshlrev_b32_e32 v24, 2, v25
	v_lshlrev_b32_e32 v25, 2, v26
	v_lshl_add_u32 v5, v5, 2, v20
	v_lshl_add_u32 v14, v15, 2, v14
	v_lshl_add_u32 v15, v16, 2, v21
	v_lshl_add_u32 v16, v17, 2, v22
	v_lshl_add_u32 v17, v18, 2, v23
	v_lshl_add_u32 v18, v19, 2, v24
	v_lshl_add_u32 v1, v1, 2, v25
	ds_read_b32 v5, v5
	ds_read_b32 v9, v9 offset:28
	ds_read_b32 v19, v14
	ds_read_b32 v20, v15
	ds_read_b32 v16, v16
	ds_read_b32 v17, v17
	ds_read_b32 v18, v18
	ds_read_b32 v1, v1
	v_readlane_b32 s4, v247, 56
	v_readlane_b32 s5, v247, 57
	s_add_u32 s23, s4, s23
	v_lshl_add_u64 v[14:15], s[0:1], 0, v[2:3]
	s_addc_u32 s1, s5, s22
	s_add_u32 s0, s23, s2
	s_addc_u32 s1, s1, 0
	v_lshl_add_u64 v[6:7], s[0:1], 0, v[6:7]
	v_lshl_add_u64 v[2:3], s[0:1], 0, v[2:3]
	s_waitcnt vmcnt(0)
	v_lshlrev_b32_e32 v21, 16, v10
	v_and_b32_e32 v10, 0xffff0000, v10
	v_lshlrev_b32_e32 v22, 16, v11
	v_and_b32_e32 v11, 0xffff0000, v11
	v_lshlrev_b32_e32 v23, 16, v12
	v_and_b32_e32 v12, 0xffff0000, v12
	v_lshlrev_b32_e32 v24, 16, v13
	v_and_b32_e32 v13, 0xffff0000, v13
	s_waitcnt lgkmcnt(7)
	v_mul_f32_e32 v5, v5, v21
	s_waitcnt lgkmcnt(6)
	v_mul_f32_e32 v9, v9, v10
	s_waitcnt lgkmcnt(5)
	v_mul_f32_e32 v19, v19, v22
	s_waitcnt lgkmcnt(4)
	v_mul_f32_e32 v11, v20, v11
	s_waitcnt lgkmcnt(3)
	v_mul_f32_e32 v16, v16, v23
	s_waitcnt lgkmcnt(2)
	v_mul_f32_e32 v12, v17, v12
	s_waitcnt lgkmcnt(1)
	v_mul_f32_e32 v17, v18, v24
	s_waitcnt lgkmcnt(0)
	v_mul_f32_e32 v1, v1, v13
	v_cvt_pk_bf16_f32 v10, v5, v9
	v_cvt_pk_bf16_f32 v11, v19, v11
	v_cvt_pk_bf16_f32 v12, v16, v12
	v_cvt_pk_bf16_f32 v13, v17, v1
	global_store_dwordx4 v[6:7], v[10:13], off
	global_load_dwordx4 v[10:13], v[14:15], off
	v_and_b32_e32 v1, 0xfffff000, v8
	v_sub_u32_e32 v5, 0x800, v4
	v_xor_b32_e32 v6, 0xff0, v8
	v_xor_b32_e32 v7, 0xff8, v8
	v_sub_u32_e32 v8, 0x7fe, v4
	v_sub_u32_e32 v9, 0x7fd, v4
	v_sub_u32_e32 v14, 0x7fc, v4
	v_sub_u32_e32 v15, 0x7fb, v4
	v_sub_u32_e32 v16, 0x7fa, v4
	v_sub_u32_e32 v4, 0x7f9, v4
	v_and_or_b32 v5, v5, s7, v1
	v_ashrrev_i32_e32 v6, 4, v6
	v_and_or_b32 v8, v8, s6, v1
	v_and_or_b32 v9, v9, s8, v1
	v_and_or_b32 v14, v14, s9, v1
	v_and_or_b32 v15, v15, s10, v1
	v_and_or_b32 v16, v16, s11, v1
	v_and_or_b32 v1, v4, s12, v1
	v_ashrrev_i32_e32 v4, 4, v5
	v_lshlrev_b32_e32 v6, 2, v6
	v_ashrrev_i32_e32 v17, 4, v8
	v_ashrrev_i32_e32 v18, 4, v9
	v_ashrrev_i32_e32 v19, 4, v14
	v_ashrrev_i32_e32 v20, 4, v15
	v_ashrrev_i32_e32 v21, 4, v16
	v_ashrrev_i32_e32 v22, 4, v1
	v_lshlrev_b32_e32 v4, 2, v4
	v_lshl_add_u32 v6, v7, 2, v6
	v_lshlrev_b32_e32 v7, 2, v17
	v_lshlrev_b32_e32 v17, 2, v18
	v_lshlrev_b32_e32 v18, 2, v19
	v_lshlrev_b32_e32 v19, 2, v20
	v_lshlrev_b32_e32 v20, 2, v21
	v_lshlrev_b32_e32 v21, 2, v22
	v_lshl_add_u32 v4, v5, 2, v4
	v_lshl_add_u32 v5, v8, 2, v7
	v_lshl_add_u32 v7, v9, 2, v17
	v_lshl_add_u32 v8, v14, 2, v18
	v_lshl_add_u32 v9, v15, 2, v19
	v_lshl_add_u32 v14, v16, 2, v20
	v_lshl_add_u32 v1, v1, 2, v21
	ds_read_b32 v4, v4
	ds_read_b32 v6, v6 offset:28
	ds_read_b32 v5, v5
	ds_read_b32 v7, v7
	ds_read_b32 v8, v8
	ds_read_b32 v9, v9
	ds_read_b32 v14, v14
	ds_read_b32 v1, v1
	s_waitcnt vmcnt(0)
	v_lshlrev_b32_e32 v15, 16, v10
	v_and_b32_e32 v10, 0xffff0000, v10
	v_lshlrev_b32_e32 v16, 16, v11
	v_and_b32_e32 v11, 0xffff0000, v11
	v_lshlrev_b32_e32 v17, 16, v12
	v_and_b32_e32 v12, 0xffff0000, v12
	v_lshlrev_b32_e32 v18, 16, v13
	v_and_b32_e32 v13, 0xffff0000, v13
	s_waitcnt lgkmcnt(7)
	v_mul_f32_e32 v4, v4, v15
	s_waitcnt lgkmcnt(6)
	v_mul_f32_e32 v6, v6, v10
	s_waitcnt lgkmcnt(5)
	v_mul_f32_e32 v5, v5, v16
	s_waitcnt lgkmcnt(4)
	v_mul_f32_e32 v7, v7, v11
	s_waitcnt lgkmcnt(3)
	v_mul_f32_e32 v8, v8, v17
	s_waitcnt lgkmcnt(2)
	v_mul_f32_e32 v9, v9, v12
	s_waitcnt lgkmcnt(1)
	v_mul_f32_e32 v10, v14, v18
	s_waitcnt lgkmcnt(0)
	v_mul_f32_e32 v1, v1, v13
	v_cvt_pk_bf16_f32 v4, v4, v6
	v_cvt_pk_bf16_f32 v5, v5, v7
	v_cvt_pk_bf16_f32 v6, v8, v9
	v_cvt_pk_bf16_f32 v7, v10, v1
	global_store_dwordx4 v[2:3], v[4:7], off

.LBB0_1076:
	s_or_b64 exec, exec, s[0:1]
	v_lshlrev_b32_e32 v1, 2, v1
	v_and_b32_e32 v47, 0xfc, v1
	v_lshlrev_b32_e32 v20, 2, v47
	v_mov_b32_e32 v21, v0
	v_lshl_add_u64 v[2:3], v[2:3], 0, v[20:21]
	global_load_dwordx4 v[14:17], v[2:3], off
	global_load_dwordx4 v[10:13], v[2:3], off offset:1024
	v_and_b32_e32 v1, 64, v195
	v_add_u32_e32 v4, 64, v1
	v_xor_b32_e32 v1, 32, v195
	v_cmp_lt_i32_e32 vcc, v1, v4
	v_xor_b32_e32 v5, 16, v195
	s_mov_b32 s0, 0x800000
	v_cndmask_b32_e32 v1, v195, v1, vcc
	v_cmp_lt_i32_e32 vcc, v5, v4
	v_lshlrev_b32_e32 v1, 2, v1
	v_readlane_b32 s36, v248, 6
	v_cndmask_b32_e32 v5, v195, v5, vcc
	v_lshlrev_b32_e32 v42, 2, v5
	v_xor_b32_e32 v5, 8, v195
	v_cmp_lt_i32_e32 vcc, v5, v4
	v_readlane_b32 s48, v248, 18
	v_readlane_b32 s49, v248, 19
	v_cndmask_b32_e32 v5, v195, v5, vcc
	v_lshlrev_b32_e32 v43, 2, v5
	v_xor_b32_e32 v5, 4, v195
	v_cmp_lt_i32_e32 vcc, v5, v4
	v_or_b32_e32 v33, 0x300, v47
	v_or_b32_e32 v37, 0x100, v47
	v_cndmask_b32_e32 v5, v195, v5, vcc
	v_lshlrev_b32_e32 v44, 2, v5
	v_xor_b32_e32 v5, 2, v195
	v_cmp_lt_i32_e32 vcc, v5, v4
	v_or_b32_e32 v36, 0x200, v47
	v_readlane_b32 s37, v248, 7
	v_cndmask_b32_e32 v5, v195, v5, vcc
	v_lshlrev_b32_e32 v45, 2, v5
	v_xor_b32_e32 v5, 1, v195
	v_cmp_lt_i32_e32 vcc, v5, v4
	v_readlane_b32 s38, v248, 8
	v_readlane_b32 s39, v248, 9
	v_cndmask_b32_e32 v4, v195, v5, vcc
	v_lshlrev_b32_e32 v46, 2, v4
	v_readlane_b32 s40, v248, 10
	v_readlane_b32 s41, v248, 11
	v_readlane_b32 s42, v248, 12
	v_readlane_b32 s43, v248, 13
	v_readlane_b32 s44, v248, 14
	v_readlane_b32 s45, v248, 15
	v_readlane_b32 s46, v248, 16
	s_nop 0
	v_readlane_b32 s47, v248, 17
	s_nop 0
	v_readlane_b32 s50, v248, 20
	s_nop 0
	v_readlane_b32 s51, v248, 21
	s_nop 0
	s_waitcnt vmcnt(1)
	s_waitcnt vmcnt(0)
	v_mul_f32_e32 v6, v15, v15
	v_mul_f32_e32 v7, v11, v11
	s_nop 0
	v_fma_f32 v4, v14, v14, v6
	v_fma_f32 v5, v10, v10, v7
	v_fma_f32 v4, v16, v16, v4
	v_fma_f32 v5, v12, v12, v5
	v_fma_f32 v26, v17, v17, v4
	v_fma_f32 v27, v13, v13, v5
	global_load_dwordx4 v[6:9], v[2:3], off offset:2048
	s_nop 0
	global_load_dwordx4 v[2:5], v[2:3], off offset:3072
	v_add_f32_e32 v26, v26, v27
	global_load_dwordx4 v[38:41], v20, s[48:49]
	s_waitcnt vmcnt(2)
	s_waitcnt vmcnt(1)
	v_mul_f32_e32 v30, v7, v7
	v_mul_f32_e32 v31, v3, v3
	s_nop 0
	v_fma_f32 v28, v6, v6, v30
	v_fma_f32 v29, v2, v2, v31
	v_fma_f32 v28, v8, v8, v28
	v_fma_f32 v29, v4, v4, v29
	v_fma_f32 v28, v9, v9, v28
	v_fma_f32 v29, v5, v5, v29
	s_nop 0
	v_add_f32_e32 v26, v26, v28
	v_add_f32_e32 v26, v26, v29
	ds_bpermute_b32 v27, v1, v26
	s_nop 2
	s_waitcnt lgkmcnt(0)
	v_add_f32_e32 v26, v26, v27
	ds_bpermute_b32 v27, v42, v26
	s_nop 2
	s_waitcnt lgkmcnt(0)
	v_add_f32_e32 v26, v26, v27
	ds_bpermute_b32 v27, v43, v26
	s_nop 2
	s_waitcnt lgkmcnt(0)
	v_add_f32_e32 v26, v26, v27
	ds_bpermute_b32 v27, v44, v26
	s_nop 2
	s_waitcnt lgkmcnt(0)
	v_add_f32_e32 v26, v26, v27
	ds_bpermute_b32 v27, v45, v26
	s_nop 2
	s_waitcnt lgkmcnt(0)
	v_add_f32_e32 v26, v26, v27
	ds_bpermute_b32 v27, v46, v26
	s_waitcnt lgkmcnt(0)
	v_add_f32_e32 v26, v26, v27
	v_fmamk_f32 v26, v26, 0x3a800000, v188
	v_cmp_gt_f32_e32 vcc, s0, v26
	v_readlane_b32 s0, v245, 5
	v_readlane_b32 s1, v245, 6
	v_mul_f32_e32 v27, 0x4b800000, v26
	v_cndmask_b32_e32 v26, v26, v27, vcc
	v_lshl_add_u64 v[22:23], v[22:23], 2, s[0:1]
	s_mov_b64 s[0:1], 0x1000
	v_lshl_add_u64 v[34:35], v[22:23], 0, s[0:1]
	v_lshl_add_u64 v[30:31], v[22:23], 0, v[20:21]
	v_lshl_add_u64 v[22:23], v[34:35], 0, v[20:21]
	global_load_dwordx4 v[48:51], v[30:31], off
	global_load_dwordx4 v[52:55], v[22:23], off
	v_rsq_f32_e32 v26, v26
	v_readlane_b32 s0, v247, 56
	v_readlane_b32 s1, v247, 57
	v_mul_f32_e32 v27, 0x45800000, v26
	v_cndmask_b32_e32 v32, v26, v27, vcc
	v_pk_mul_f32 v[14:15], v[14:15], v[32:33] op_sel_hi:[1,0]
	v_lshlrev_b64 v[26:27], 11, v[24:25]
	s_waitcnt vmcnt(2)
	v_pk_mul_f32 v[14:15], v[38:39], v[14:15]
	v_lshl_add_u64 v[26:27], s[0:1], 0, v[26:27]
	v_pk_mul_f32 v[10:11], v[10:11], v[32:33] op_sel_hi:[1,0]
	v_pk_mul_f32 v[12:13], v[12:13], v[32:33] op_sel_hi:[1,0]
	v_pk_mul_f32 v[6:7], v[6:7], v[32:33] op_sel_hi:[1,0]
	v_pk_mul_f32 v[8:9], v[8:9], v[32:33] op_sel_hi:[1,0]
	v_pk_mul_f32 v[2:3], v[2:3], v[32:33] op_sel_hi:[1,0]
	v_pk_mul_f32 v[4:5], v[4:5], v[32:33] op_sel_hi:[1,0]
	s_waitcnt vmcnt(0)
	v_pk_add_f32 v[22:23], v[52:53], 1.0 op_sel_hi:[1,0]
	s_nop 0
	v_pk_fma_f32 v[14:15], v[22:23], v[14:15], v[48:49]
	v_lshlrev_b32_e32 v22, 1, v47
	v_cvt_pk_bf16_f32 v28, v14, v15
	v_pk_mul_f32 v[14:15], v[16:17], v[32:33] op_sel_hi:[1,0]
	v_pk_add_f32 v[16:17], v[54:55], 1.0 op_sel_hi:[1,0]
	v_pk_mul_f32 v[14:15], v[40:41], v[14:15]
	v_mov_b32_e32 v23, v0
	v_pk_fma_f32 v[14:15], v[16:17], v[14:15], v[50:51]
	s_nop 0
	v_cvt_pk_bf16_f32 v29, v14, v15
	v_lshl_add_u64 v[14:15], v[26:27], 0, v[22:23]
	v_lshlrev_b32_e32 v26, 2, v37
	v_mov_b32_e32 v27, v0
	global_store_dwordx2 v[14:15], v[28:29], off
	v_lshl_add_u64 v[16:17], v[34:35], 0, v[26:27]
	global_load_dwordx4 v[38:41], v20, s[48:49] offset:1024
	global_load_dwordx4 v[48:51], v[30:31], off offset:1024
	global_load_dwordx4 v[52:55], v[16:17], off
	v_lshlrev_b32_e32 v28, 2, v36
	v_mov_b32_e32 v29, v0
	s_waitcnt vmcnt(2)
	v_pk_mul_f32 v[10:11], v[38:39], v[10:11]
	v_pk_mul_f32 v[12:13], v[40:41], v[12:13]
	s_waitcnt vmcnt(0)
	v_pk_add_f32 v[16:17], v[52:53], 1.0 op_sel_hi:[1,0]
	s_nop 0
	v_pk_fma_f32 v[10:11], v[16:17], v[10:11], v[48:49]
	v_pk_add_f32 v[16:17], v[54:55], 1.0 op_sel_hi:[1,0]
	v_cvt_pk_bf16_f32 v10, v10, v11
	v_pk_fma_f32 v[12:13], v[16:17], v[12:13], v[50:51]
	v_lshl_add_u64 v[16:17], v[34:35], 0, v[28:29]
	v_cvt_pk_bf16_f32 v11, v12, v13
	global_store_dwordx2 v[14:15], v[10:11], off offset:512
	global_load_dwordx4 v[10:13], v20, s[48:49] offset:2048
	s_nop 0
	global_load_dwordx4 v[38:41], v[30:31], off offset:2048
	global_load_dwordx4 v[48:51], v[16:17], off
	s_waitcnt vmcnt(2)
	v_pk_mul_f32 v[6:7], v[10:11], v[6:7]
	v_pk_mul_f32 v[8:9], v[12:13], v[8:9]
	s_waitcnt vmcnt(0)
	v_pk_add_f32 v[10:11], v[48:49], 1.0 op_sel_hi:[1,0]
	s_nop 0
	v_pk_fma_f32 v[6:7], v[10:11], v[6:7], v[38:39]
	v_pk_add_f32 v[10:11], v[50:51], 1.0 op_sel_hi:[1,0]
	v_cvt_pk_bf16_f32 v6, v6, v7
	v_pk_fma_f32 v[8:9], v[10:11], v[8:9], v[40:41]
	v_or_b32_e32 v38, 1, v24
	v_cvt_pk_bf16_f32 v7, v8, v9
	global_store_dwordx2 v[14:15], v[6:7], off offset:1024
	global_load_dwordx4 v[6:9], v20, s[48:49] offset:3072
	s_nop 0
	global_load_dwordx4 v[10:13], v[30:31], off offset:3072
	v_lshlrev_b32_e32 v30, 2, v33
	v_mov_b32_e32 v31, v0
	v_lshl_add_u64 v[16:17], v[34:35], 0, v[30:31]
	global_load_dwordx4 v[34:37], v[16:17], off
	v_cmp_lt_i32_e32 vcc, s4, v38
	s_waitcnt vmcnt(2)
	v_pk_mul_f32 v[2:3], v[6:7], v[2:3]
	v_pk_mul_f32 v[4:5], v[8:9], v[4:5]
	s_waitcnt vmcnt(0)
	v_pk_add_f32 v[6:7], v[34:35], 1.0 op_sel_hi:[1,0]
	s_nop 0
	v_pk_fma_f32 v[2:3], v[2:3], v[6:7], v[10:11]
	v_pk_add_f32 v[6:7], v[36:37], 1.0 op_sel_hi:[1,0]
	v_cvt_pk_bf16_f32 v2, v2, v3
	v_pk_fma_f32 v[4:5], v[4:5], v[6:7], v[12:13]
	s_nop 0
	v_cvt_pk_bf16_f32 v3, v4, v5
	global_store_dwordx2 v[14:15], v[2:3], off offset:1536
	s_and_saveexec_b64 s[0:1], vcc
	s_xor_b64 s[0:1], exec, s[0:1]
	s_cbranch_execz .LBB0_1078
	v_add_u32_e32 v2, 0xffffe001, v24
	v_mov_b32_e32 v3, v0
	v_readlane_b32 s36, v248, 6
	v_lshlrev_b64 v[2:3], 12, v[2:3]
	v_readlane_b32 s38, v248, 8
	v_readlane_b32 s39, v248, 9
	v_mov_b32_e32 v39, v0
	v_readlane_b32 s37, v248, 7
	v_lshl_add_u64 v[2:3], s[38:39], 0, v[2:3]
	v_readlane_b32 s40, v248, 10
	v_readlane_b32 s41, v248, 11
	v_readlane_b32 s42, v248, 12
	v_readlane_b32 s43, v248, 13
	v_readlane_b32 s44, v248, 14
	v_readlane_b32 s45, v248, 15
	v_readlane_b32 s46, v248, 16
	v_readlane_b32 s47, v248, 17
	v_readlane_b32 s48, v248, 18
	v_readlane_b32 s49, v248, 19
	v_readlane_b32 s50, v248, 20
	v_readlane_b32 s51, v248, 21

.LBB0_1080:
	s_or_b64 exec, exec, s[0:1]
	v_readlane_b32 s36, v248, 6
	v_readlane_b32 s48, v248, 18
	v_readlane_b32 s49, v248, 19
	s_mov_b32 s0, 0x800000
	v_lshlrev_b64 v[38:39], 11, v[38:39]
	v_lshl_add_u64 v[32:33], s[48:49], 0, v[20:21]
	v_mov_b32_e32 v21, v0
	v_lshl_add_u64 v[2:3], v[2:3], 0, v[20:21]
	global_load_dwordx4 v[14:17], v[2:3], off
	global_load_dwordx4 v[10:13], v[2:3], off offset:1024
	v_mov_b32_e32 v27, v0
	v_mov_b32_e32 v29, v0
	v_mov_b32_e32 v31, v0
	v_readlane_b32 s43, v248, 13
	s_movk_i32 s43, 0x1fff
	v_readlane_b32 s37, v248, 7
	v_readlane_b32 s38, v248, 8
	v_readlane_b32 s39, v248, 9
	v_readlane_b32 s40, v248, 10
	v_readlane_b32 s41, v248, 11
	v_readlane_b32 s42, v248, 12
	v_readlane_b32 s44, v248, 14
	v_readlane_b32 s45, v248, 15
	v_readlane_b32 s46, v248, 16
	s_nop 0
	v_readlane_b32 s47, v248, 17
	s_nop 0
	v_readlane_b32 s50, v248, 20
	s_nop 0
	v_readlane_b32 s51, v248, 21
	s_nop 0
	s_waitcnt vmcnt(1)
	s_waitcnt vmcnt(0)
	v_mul_f32_e32 v6, v15, v15
	v_mul_f32_e32 v7, v11, v11
	s_nop 0
	v_fma_f32 v4, v14, v14, v6
	v_fma_f32 v5, v10, v10, v7
	v_fma_f32 v4, v16, v16, v4
	v_fma_f32 v5, v12, v12, v5
	v_fma_f32 v34, v17, v17, v4
	v_fma_f32 v35, v13, v13, v5
	global_load_dwordx4 v[6:9], v[2:3], off offset:2048
	s_nop 0
	global_load_dwordx4 v[2:5], v[2:3], off offset:3072
	v_add_f32_e32 v23, v34, v35
	s_waitcnt vmcnt(1)
	s_waitcnt vmcnt(0)
	v_mul_f32_e32 v48, v7, v7
	v_mul_f32_e32 v49, v3, v3
	s_nop 0
	v_fma_f32 v40, v6, v6, v48
	v_fma_f32 v41, v2, v2, v49
	v_fma_f32 v40, v8, v8, v40
	v_fma_f32 v41, v4, v4, v41
	v_fma_f32 v40, v9, v9, v40
	v_fma_f32 v41, v5, v5, v41
	global_load_dwordx4 v[48:51], v[32:33], off
	v_add_f32_e32 v23, v23, v40
	v_add_f32_e32 v23, v23, v41
	ds_bpermute_b32 v25, v1, v23
	s_nop 2
	s_waitcnt lgkmcnt(0)
	v_add_f32_e32 v23, v23, v25
	ds_bpermute_b32 v25, v42, v23
	s_nop 2
	s_waitcnt lgkmcnt(0)
	v_add_f32_e32 v23, v23, v25
	ds_bpermute_b32 v25, v43, v23
	s_nop 2
	s_waitcnt lgkmcnt(0)
	v_add_f32_e32 v23, v23, v25
	ds_bpermute_b32 v25, v44, v23
	s_nop 2
	s_waitcnt lgkmcnt(0)
	v_add_f32_e32 v23, v23, v25
	ds_bpermute_b32 v25, v45, v23
	s_nop 2
	s_waitcnt lgkmcnt(0)
	v_add_f32_e32 v23, v23, v25
	ds_bpermute_b32 v25, v46, v23
	s_waitcnt lgkmcnt(0)
	v_add_f32_e32 v23, v23, v25
	v_fmamk_f32 v23, v23, 0x3a800000, v188
	v_cmp_gt_f32_e32 vcc, s0, v23
	v_readlane_b32 s0, v245, 5
	v_readlane_b32 s1, v245, 6
	v_mul_f32_e32 v25, 0x4b800000, v23
	v_cndmask_b32_e32 v23, v23, v25, vcc
	v_lshl_add_u64 v[52:53], v[36:37], 2, s[0:1]
	s_mov_b64 s[0:1], 0x1000
	v_lshl_add_u64 v[36:37], v[52:53], 0, s[0:1]
	v_readlane_b32 s0, v247, 56
	v_readlane_b32 s1, v247, 57
	v_lshl_add_u64 v[56:57], v[36:37], 0, v[20:21]
	global_load_dwordx4 v[56:59], v[56:57], off
	v_lshl_add_u64 v[40:41], s[0:1], 0, v[38:39]
	v_lshl_add_u64 v[38:39], v[52:53], 0, v[20:21]
	global_load_dwordx4 v[52:55], v[38:39], off
	v_rsq_f32_e32 v23, v23
	s_nop 0
	v_mul_f32_e32 v25, 0x45800000, v23
	v_cndmask_b32_e32 v34, v23, v25, vcc
	v_pk_mul_f32 v[14:15], v[14:15], v[34:35] op_sel_hi:[1,0]
	v_mov_b32_e32 v23, v0
	v_pk_mul_f32 v[10:11], v[10:11], v[34:35] op_sel_hi:[1,0]
	v_pk_mul_f32 v[12:13], v[12:13], v[34:35] op_sel_hi:[1,0]
	v_pk_mul_f32 v[6:7], v[6:7], v[34:35] op_sel_hi:[1,0]
	v_pk_mul_f32 v[8:9], v[8:9], v[34:35] op_sel_hi:[1,0]
	v_pk_mul_f32 v[2:3], v[2:3], v[34:35] op_sel_hi:[1,0]
	v_pk_mul_f32 v[4:5], v[4:5], v[34:35] op_sel_hi:[1,0]
	s_waitcnt vmcnt(2)
	v_pk_mul_f32 v[14:15], v[48:49], v[14:15]
	s_waitcnt vmcnt(1)
	v_pk_add_f32 v[48:49], v[56:57], 1.0 op_sel_hi:[1,0]
	s_waitcnt vmcnt(0)
	v_pk_fma_f32 v[14:15], v[48:49], v[14:15], v[52:53]
	s_nop 0
	v_cvt_pk_bf16_f32 v48, v14, v15
	v_pk_mul_f32 v[14:15], v[16:17], v[34:35] op_sel_hi:[1,0]
	v_pk_add_f32 v[16:17], v[58:59], 1.0 op_sel_hi:[1,0]
	v_pk_mul_f32 v[14:15], v[50:51], v[14:15]
	s_nop 0
	v_pk_fma_f32 v[14:15], v[16:17], v[14:15], v[54:55]
	v_lshl_add_u64 v[16:17], v[36:37], 0, v[26:27]
	v_cvt_pk_bf16_f32 v49, v14, v15
	v_lshl_add_u64 v[14:15], v[40:41], 0, v[22:23]
	global_store_dwordx2 v[14:15], v[48:49], off
	global_load_dwordx4 v[48:51], v[32:33], off offset:1024
	s_nop 0
	global_load_dwordx4 v[52:55], v[38:39], off offset:1024
	global_load_dwordx4 v[56:59], v[16:17], off
	s_waitcnt vmcnt(2)
	v_pk_mul_f32 v[10:11], v[48:49], v[10:11]
	v_pk_mul_f32 v[12:13], v[50:51], v[12:13]
	s_waitcnt vmcnt(0)
	v_pk_add_f32 v[16:17], v[56:57], 1.0 op_sel_hi:[1,0]
	s_nop 0
	v_pk_fma_f32 v[10:11], v[16:17], v[10:11], v[52:53]
	v_pk_add_f32 v[16:17], v[58:59], 1.0 op_sel_hi:[1,0]
	v_cvt_pk_bf16_f32 v10, v10, v11
	v_pk_fma_f32 v[12:13], v[16:17], v[12:13], v[54:55]
	v_lshl_add_u64 v[16:17], v[36:37], 0, v[28:29]
	v_cvt_pk_bf16_f32 v11, v12, v13
	global_store_dwordx2 v[14:15], v[10:11], off offset:512
	global_load_dwordx4 v[10:13], v[32:33], off offset:2048
	s_nop 0
	global_load_dwordx4 v[48:51], v[38:39], off offset:2048
	global_load_dwordx4 v[52:55], v[16:17], off
	v_lshl_add_u64 v[16:17], v[36:37], 0, v[30:31]
	s_waitcnt vmcnt(2)
	v_pk_mul_f32 v[6:7], v[10:11], v[6:7]
	v_pk_mul_f32 v[8:9], v[12:13], v[8:9]
	s_waitcnt vmcnt(0)
	v_pk_add_f32 v[10:11], v[52:53], 1.0 op_sel_hi:[1,0]
	s_nop 0
	v_pk_fma_f32 v[6:7], v[10:11], v[6:7], v[48:49]
	v_pk_add_f32 v[10:11], v[54:55], 1.0 op_sel_hi:[1,0]
	v_cvt_pk_bf16_f32 v6, v6, v7
	v_pk_fma_f32 v[8:9], v[10:11], v[8:9], v[50:51]
	s_nop 0
	v_cvt_pk_bf16_f32 v7, v8, v9
	global_store_dwordx2 v[14:15], v[6:7], off offset:1024
	global_load_dwordx4 v[6:9], v[32:33], off offset:3072
	s_nop 0
	global_load_dwordx4 v[10:13], v[38:39], off offset:3072
	s_waitcnt vmcnt(1)
	v_pk_mul_f32 v[2:3], v[6:7], v[2:3]
	global_load_dwordx4 v[36:39], v[16:17], off
	v_pk_mul_f32 v[4:5], v[8:9], v[4:5]
	s_waitcnt vmcnt(0)
	v_pk_add_f32 v[6:7], v[36:37], 1.0 op_sel_hi:[1,0]
	s_nop 0
	v_pk_fma_f32 v[2:3], v[2:3], v[6:7], v[10:11]
	v_pk_add_f32 v[6:7], v[38:39], 1.0 op_sel_hi:[1,0]
	v_or_b32_e32 v38, 2, v24
	v_pk_fma_f32 v[4:5], v[4:5], v[6:7], v[12:13]
	v_cvt_pk_bf16_f32 v2, v2, v3
	v_cvt_pk_bf16_f32 v3, v4, v5
	v_cmp_lt_i32_e32 vcc, s43, v38
	global_store_dwordx2 v[14:15], v[2:3], off offset:1536
	s_and_saveexec_b64 s[0:1], vcc
	s_xor_b64 s[0:1], exec, s[0:1]
	s_cbranch_execz .LBB0_1082
	v_add_u32_e32 v2, 0xffffe002, v24
	v_mov_b32_e32 v3, v0
	v_readlane_b32 s36, v248, 6
	v_lshlrev_b64 v[2:3], 12, v[2:3]
	v_readlane_b32 s38, v248, 8
	v_readlane_b32 s39, v248, 9
	v_readlane_b32 s43, v248, 13
	s_movk_i32 s43, 0x1fff
	v_lshl_add_u64 v[2:3], s[38:39], 0, v[2:3]
	v_mov_b32_e32 v39, v0
	v_readlane_b32 s37, v248, 7
	v_readlane_b32 s40, v248, 10
	v_readlane_b32 s41, v248, 11
	v_readlane_b32 s42, v248, 12
	v_readlane_b32 s44, v248, 14
	v_readlane_b32 s45, v248, 15
	v_readlane_b32 s46, v248, 16
	v_readlane_b32 s47, v248, 17
	v_readlane_b32 s48, v248, 18
	v_readlane_b32 s49, v248, 19
	v_readlane_b32 s50, v248, 20
	v_readlane_b32 s51, v248, 21

.LBB0_1084:
	s_or_b64 exec, exec, s[0:1]
	v_mov_b32_e32 v21, v0
	v_lshl_add_u64 v[2:3], v[2:3], 0, v[20:21]
	global_load_dwordx4 v[14:17], v[2:3], off
	global_load_dwordx4 v[10:13], v[2:3], off offset:1024
	s_mov_b32 s0, 0x800000
	v_lshlrev_b64 v[38:39], 11, v[38:39]
	v_mov_b32_e32 v27, v0
	v_mov_b32_e32 v29, v0
	v_mov_b32_e32 v31, v0
	s_waitcnt vmcnt(1)
	s_waitcnt vmcnt(0)
	v_mul_f32_e32 v6, v15, v15
	v_mul_f32_e32 v7, v11, v11
	s_nop 0
	v_fma_f32 v4, v14, v14, v6
	v_fma_f32 v5, v10, v10, v7
	v_fma_f32 v4, v16, v16, v4
	v_fma_f32 v5, v12, v12, v5
	v_fma_f32 v34, v17, v17, v4
	v_fma_f32 v35, v13, v13, v5
	global_load_dwordx4 v[6:9], v[2:3], off offset:2048
	s_nop 0
	global_load_dwordx4 v[2:5], v[2:3], off offset:3072
	v_add_f32_e32 v23, v34, v35
	s_waitcnt vmcnt(1)
	s_waitcnt vmcnt(0)
	v_mul_f32_e32 v48, v7, v7
	v_mul_f32_e32 v49, v3, v3
	s_nop 0
	v_fma_f32 v40, v6, v6, v48
	v_fma_f32 v41, v2, v2, v49
	v_fma_f32 v40, v8, v8, v40
	v_fma_f32 v41, v4, v4, v41
	v_fma_f32 v40, v9, v9, v40
	v_fma_f32 v41, v5, v5, v41
	global_load_dwordx4 v[48:51], v[32:33], off
	v_add_f32_e32 v23, v23, v40
	v_add_f32_e32 v23, v23, v41
	ds_bpermute_b32 v25, v1, v23
	s_nop 2
	s_waitcnt lgkmcnt(0)
	v_add_f32_e32 v23, v23, v25
	ds_bpermute_b32 v25, v42, v23
	s_nop 2
	s_waitcnt lgkmcnt(0)
	v_add_f32_e32 v23, v23, v25
	ds_bpermute_b32 v25, v43, v23
	s_nop 2
	s_waitcnt lgkmcnt(0)
	v_add_f32_e32 v23, v23, v25
	ds_bpermute_b32 v25, v44, v23
	s_nop 2
	s_waitcnt lgkmcnt(0)
	v_add_f32_e32 v23, v23, v25
	ds_bpermute_b32 v25, v45, v23
	s_nop 2
	s_waitcnt lgkmcnt(0)
	v_add_f32_e32 v23, v23, v25
	ds_bpermute_b32 v25, v46, v23
	s_waitcnt lgkmcnt(0)
	v_add_f32_e32 v23, v23, v25
	v_fmamk_f32 v23, v23, 0x3a800000, v188
	v_cmp_gt_f32_e32 vcc, s0, v23
	v_readlane_b32 s0, v245, 5
	v_readlane_b32 s1, v245, 6
	v_mul_f32_e32 v25, 0x4b800000, v23
	v_cndmask_b32_e32 v23, v23, v25, vcc
	v_lshl_add_u64 v[52:53], v[36:37], 2, s[0:1]
	s_mov_b64 s[0:1], 0x1000
	v_lshl_add_u64 v[36:37], v[52:53], 0, s[0:1]
	v_readlane_b32 s0, v247, 56
	v_readlane_b32 s1, v247, 57
	v_lshl_add_u64 v[56:57], v[36:37], 0, v[20:21]
	global_load_dwordx4 v[56:59], v[56:57], off
	v_lshl_add_u64 v[40:41], s[0:1], 0, v[38:39]
	v_lshl_add_u64 v[38:39], v[52:53], 0, v[20:21]
	global_load_dwordx4 v[52:55], v[38:39], off
	v_rsq_f32_e32 v23, v23
	s_nop 0
	v_mul_f32_e32 v25, 0x45800000, v23
	v_cndmask_b32_e32 v34, v23, v25, vcc
	v_pk_mul_f32 v[14:15], v[14:15], v[34:35] op_sel_hi:[1,0]
	v_mov_b32_e32 v23, v0
	v_pk_mul_f32 v[10:11], v[10:11], v[34:35] op_sel_hi:[1,0]
	v_pk_mul_f32 v[12:13], v[12:13], v[34:35] op_sel_hi:[1,0]
	v_pk_mul_f32 v[6:7], v[6:7], v[34:35] op_sel_hi:[1,0]
	v_pk_mul_f32 v[8:9], v[8:9], v[34:35] op_sel_hi:[1,0]
	v_pk_mul_f32 v[2:3], v[2:3], v[34:35] op_sel_hi:[1,0]
	v_pk_mul_f32 v[4:5], v[4:5], v[34:35] op_sel_hi:[1,0]
	s_waitcnt vmcnt(2)
	v_pk_mul_f32 v[14:15], v[48:49], v[14:15]
	s_waitcnt vmcnt(1)
	v_pk_add_f32 v[48:49], v[56:57], 1.0 op_sel_hi:[1,0]
	s_waitcnt vmcnt(0)
	v_pk_fma_f32 v[14:15], v[48:49], v[14:15], v[52:53]
	s_nop 0
	v_cvt_pk_bf16_f32 v48, v14, v15
	v_pk_mul_f32 v[14:15], v[16:17], v[34:35] op_sel_hi:[1,0]
	v_pk_add_f32 v[16:17], v[58:59], 1.0 op_sel_hi:[1,0]
	v_pk_mul_f32 v[14:15], v[50:51], v[14:15]
	v_or_b32_e32 v34, 3, v24
	v_pk_fma_f32 v[14:15], v[16:17], v[14:15], v[54:55]
	v_lshl_add_u64 v[16:17], v[36:37], 0, v[26:27]
	v_cvt_pk_bf16_f32 v49, v14, v15
	v_lshl_add_u64 v[14:15], v[40:41], 0, v[22:23]
	global_store_dwordx2 v[14:15], v[48:49], off
	global_load_dwordx4 v[48:51], v[32:33], off offset:1024
	s_nop 0
	global_load_dwordx4 v[52:55], v[38:39], off offset:1024
	global_load_dwordx4 v[56:59], v[16:17], off
	v_cmp_lt_i32_e32 vcc, s43, v34
	s_waitcnt vmcnt(2)
	v_pk_mul_f32 v[10:11], v[48:49], v[10:11]
	v_pk_mul_f32 v[12:13], v[50:51], v[12:13]
	s_waitcnt vmcnt(0)
	v_pk_add_f32 v[16:17], v[56:57], 1.0 op_sel_hi:[1,0]
	s_nop 0
	v_pk_fma_f32 v[10:11], v[16:17], v[10:11], v[52:53]
	v_pk_add_f32 v[16:17], v[58:59], 1.0 op_sel_hi:[1,0]
	v_cvt_pk_bf16_f32 v10, v10, v11
	v_pk_fma_f32 v[12:13], v[16:17], v[12:13], v[54:55]
	v_lshl_add_u64 v[16:17], v[36:37], 0, v[28:29]
	v_cvt_pk_bf16_f32 v11, v12, v13
	global_store_dwordx2 v[14:15], v[10:11], off offset:512
	global_load_dwordx4 v[10:13], v[32:33], off offset:2048
	s_nop 0
	global_load_dwordx4 v[48:51], v[38:39], off offset:2048
	global_load_dwordx4 v[52:55], v[16:17], off
	v_lshl_add_u64 v[16:17], v[36:37], 0, v[30:31]
	s_waitcnt vmcnt(2)
	v_pk_mul_f32 v[6:7], v[10:11], v[6:7]
	v_pk_mul_f32 v[8:9], v[12:13], v[8:9]
	s_waitcnt vmcnt(0)
	v_pk_add_f32 v[10:11], v[52:53], 1.0 op_sel_hi:[1,0]
	s_nop 0
	v_pk_fma_f32 v[6:7], v[10:11], v[6:7], v[48:49]
	v_pk_add_f32 v[10:11], v[54:55], 1.0 op_sel_hi:[1,0]
	v_cvt_pk_bf16_f32 v6, v6, v7
	v_pk_fma_f32 v[8:9], v[10:11], v[8:9], v[50:51]
	s_nop 0
	v_cvt_pk_bf16_f32 v7, v8, v9
	global_store_dwordx2 v[14:15], v[6:7], off offset:1024
	global_load_dwordx4 v[6:9], v[32:33], off offset:3072
	s_nop 0
	global_load_dwordx4 v[10:13], v[38:39], off offset:3072
	s_waitcnt vmcnt(1)
	v_pk_mul_f32 v[2:3], v[6:7], v[2:3]
	global_load_dwordx4 v[36:39], v[16:17], off
	v_pk_mul_f32 v[4:5], v[8:9], v[4:5]
	s_waitcnt vmcnt(0)
	v_pk_add_f32 v[6:7], v[36:37], 1.0 op_sel_hi:[1,0]
	s_nop 0
	v_pk_fma_f32 v[2:3], v[2:3], v[6:7], v[10:11]
	v_pk_add_f32 v[6:7], v[38:39], 1.0 op_sel_hi:[1,0]
	v_cvt_pk_bf16_f32 v2, v2, v3
	v_pk_fma_f32 v[4:5], v[4:5], v[6:7], v[12:13]
	s_nop 0
	v_cvt_pk_bf16_f32 v3, v4, v5
	global_store_dwordx2 v[14:15], v[2:3], off offset:1536
	s_and_saveexec_b64 s[0:1], vcc
	s_xor_b64 s[0:1], exec, s[0:1]
	s_cbranch_execz .LBB0_1086
	v_add_u32_e32 v2, 0xffffe003, v24
	v_mov_b32_e32 v3, v0
	v_readlane_b32 s36, v248, 6
	v_lshlrev_b64 v[2:3], 12, v[2:3]
	v_readlane_b32 s38, v248, 8
	v_readlane_b32 s39, v248, 9
	v_readlane_b32 s43, v248, 13
	s_movk_i32 s43, 0x1fff
	v_lshl_add_u64 v[2:3], s[38:39], 0, v[2:3]
	v_mov_b32_e32 v35, v0
	v_readlane_b32 s37, v248, 7
	v_readlane_b32 s40, v248, 10
	v_readlane_b32 s41, v248, 11
	v_readlane_b32 s42, v248, 12
	v_readlane_b32 s44, v248, 14
	v_readlane_b32 s45, v248, 15
	v_readlane_b32 s46, v248, 16
	v_readlane_b32 s47, v248, 17
	v_readlane_b32 s48, v248, 18
	v_readlane_b32 s49, v248, 19
	v_readlane_b32 s50, v248, 20
	v_readlane_b32 s51, v248, 21

.LBB0_1088:
	s_or_b64 exec, exec, s[0:1]
	v_mov_b32_e32 v21, v0
	v_lshl_add_u64 v[2:3], v[2:3], 0, v[20:21]
	global_load_dwordx4 v[14:17], v[2:3], off
	global_load_dwordx4 v[10:13], v[2:3], off offset:1024
	s_mov_b32 s0, 0x800000
	v_lshlrev_b64 v[34:35], 11, v[34:35]
	v_mov_b32_e32 v27, v0
	v_mov_b32_e32 v29, v0
	v_mov_b32_e32 v31, v0
	s_waitcnt vmcnt(1)
	s_waitcnt vmcnt(0)
	v_mul_f32_e32 v6, v15, v15
	v_mul_f32_e32 v7, v11, v11
	s_nop 0
	v_fma_f32 v4, v14, v14, v6
	v_fma_f32 v5, v10, v10, v7
	v_fma_f32 v4, v16, v16, v4
	v_fma_f32 v5, v12, v12, v5
	v_fma_f32 v24, v17, v17, v4
	v_fma_f32 v25, v13, v13, v5
	global_load_dwordx4 v[6:9], v[2:3], off offset:2048
	s_nop 0
	global_load_dwordx4 v[2:5], v[2:3], off offset:3072
	v_add_f32_e32 v23, v24, v25
	s_waitcnt vmcnt(1)
	s_waitcnt vmcnt(0)
	v_mul_f32_e32 v38, v7, v7
	v_mul_f32_e32 v39, v3, v3
	s_nop 0
	v_fma_f32 v36, v6, v6, v38
	v_fma_f32 v37, v2, v2, v39
	v_fma_f32 v36, v8, v8, v36
	v_fma_f32 v37, v4, v4, v37
	v_fma_f32 v36, v9, v9, v36
	v_fma_f32 v37, v5, v5, v37
	global_load_dwordx4 v[38:41], v[32:33], off
	v_add_f32_e32 v23, v23, v36
	v_add_f32_e32 v23, v23, v37
	ds_bpermute_b32 v1, v1, v23
	s_nop 2
	s_waitcnt lgkmcnt(0)
	v_add_f32_e32 v1, v23, v1
	ds_bpermute_b32 v23, v42, v1
	s_nop 2
	s_waitcnt lgkmcnt(0)
	v_add_f32_e32 v1, v1, v23
	ds_bpermute_b32 v23, v43, v1
	s_nop 2
	s_waitcnt lgkmcnt(0)
	v_add_f32_e32 v1, v1, v23
	ds_bpermute_b32 v23, v44, v1
	s_nop 2
	s_waitcnt lgkmcnt(0)
	v_add_f32_e32 v1, v1, v23
	ds_bpermute_b32 v23, v45, v1
	s_nop 2
	s_waitcnt lgkmcnt(0)
	v_add_f32_e32 v1, v1, v23
	ds_bpermute_b32 v23, v46, v1
	s_waitcnt lgkmcnt(0)
	v_add_f32_e32 v1, v1, v23
	v_fmamk_f32 v1, v1, 0x3a800000, v188
	v_cmp_gt_f32_e32 vcc, s0, v1
	v_readlane_b32 s0, v245, 5
	v_readlane_b32 s1, v245, 6
	v_mul_f32_e32 v23, 0x4b800000, v1
	v_cndmask_b32_e32 v1, v1, v23, vcc
	v_lshl_add_u64 v[42:43], v[18:19], 2, s[0:1]
	s_mov_b64 s[0:1], 0x1000
	v_lshl_add_u64 v[18:19], v[42:43], 0, s[0:1]
	v_readlane_b32 s0, v247, 56
	v_readlane_b32 s1, v247, 57
	v_rsq_f32_e32 v1, v1
	s_nop 0
	v_lshl_add_u64 v[36:37], s[0:1], 0, v[34:35]
	v_lshl_add_u64 v[34:35], v[42:43], 0, v[20:21]
	v_lshl_add_u64 v[20:21], v[18:19], 0, v[20:21]
	global_load_dwordx4 v[46:49], v[20:21], off
	global_load_dwordx4 v[42:45], v[34:35], off
	v_mul_f32_e32 v23, 0x45800000, v1
	v_cndmask_b32_e32 v24, v1, v23, vcc
	v_pk_mul_f32 v[14:15], v[14:15], v[24:25] op_sel_hi:[1,0]
	v_mov_b32_e32 v23, v0
	v_pk_mul_f32 v[10:11], v[10:11], v[24:25] op_sel_hi:[1,0]
	v_pk_mul_f32 v[12:13], v[12:13], v[24:25] op_sel_hi:[1,0]
	v_pk_mul_f32 v[6:7], v[6:7], v[24:25] op_sel_hi:[1,0]
	v_pk_mul_f32 v[8:9], v[8:9], v[24:25] op_sel_hi:[1,0]
	v_pk_mul_f32 v[2:3], v[2:3], v[24:25] op_sel_hi:[1,0]
	v_pk_mul_f32 v[4:5], v[4:5], v[24:25] op_sel_hi:[1,0]
	s_mov_b64 s[0:1], 0
	s_waitcnt vmcnt(2)
	v_pk_mul_f32 v[14:15], v[38:39], v[14:15]
	s_waitcnt vmcnt(1)
	v_pk_add_f32 v[20:21], v[46:47], 1.0 op_sel_hi:[1,0]
	s_waitcnt vmcnt(0)
	v_pk_fma_f32 v[14:15], v[20:21], v[14:15], v[42:43]
	s_nop 0
	v_cvt_pk_bf16_f32 v20, v14, v15
	v_pk_mul_f32 v[14:15], v[16:17], v[24:25] op_sel_hi:[1,0]
	v_pk_add_f32 v[16:17], v[48:49], 1.0 op_sel_hi:[1,0]
	v_pk_mul_f32 v[14:15], v[40:41], v[14:15]
	s_nop 0
	v_pk_fma_f32 v[14:15], v[16:17], v[14:15], v[44:45]
	v_lshl_add_u64 v[16:17], v[18:19], 0, v[26:27]
	v_cvt_pk_bf16_f32 v21, v14, v15
	v_lshl_add_u64 v[14:15], v[36:37], 0, v[22:23]
	global_store_dwordx2 v[14:15], v[20:21], off
	global_load_dwordx4 v[20:23], v[32:33], off offset:1024
	s_nop 0
	global_load_dwordx4 v[36:39], v[34:35], off offset:1024
	global_load_dwordx4 v[40:43], v[16:17], off
	s_waitcnt vmcnt(2)
	v_pk_mul_f32 v[10:11], v[20:21], v[10:11]
	v_pk_mul_f32 v[12:13], v[22:23], v[12:13]
	s_waitcnt vmcnt(0)
	v_pk_add_f32 v[16:17], v[40:41], 1.0 op_sel_hi:[1,0]
	s_nop 0
	v_pk_fma_f32 v[10:11], v[16:17], v[10:11], v[36:37]
	v_pk_add_f32 v[16:17], v[42:43], 1.0 op_sel_hi:[1,0]
	v_cvt_pk_bf16_f32 v10, v10, v11
	v_pk_fma_f32 v[12:13], v[16:17], v[12:13], v[38:39]
	v_lshl_add_u64 v[16:17], v[18:19], 0, v[28:29]
	v_cvt_pk_bf16_f32 v11, v12, v13
	global_store_dwordx2 v[14:15], v[10:11], off offset:512
	global_load_dwordx4 v[10:13], v[32:33], off offset:2048
	s_nop 0
	global_load_dwordx4 v[20:23], v[34:35], off offset:2048
	global_load_dwordx4 v[26:29], v[16:17], off
	v_lshl_add_u64 v[16:17], v[18:19], 0, v[30:31]
	s_waitcnt vmcnt(2)
	v_pk_mul_f32 v[6:7], v[10:11], v[6:7]
	v_pk_mul_f32 v[8:9], v[12:13], v[8:9]
	s_waitcnt vmcnt(0)
	v_pk_add_f32 v[10:11], v[26:27], 1.0 op_sel_hi:[1,0]
	s_nop 0
	v_pk_fma_f32 v[6:7], v[10:11], v[6:7], v[20:21]
	v_pk_add_f32 v[10:11], v[28:29], 1.0 op_sel_hi:[1,0]
	v_cvt_pk_bf16_f32 v6, v6, v7
	v_pk_fma_f32 v[8:9], v[10:11], v[8:9], v[22:23]
	s_nop 0
	v_cvt_pk_bf16_f32 v7, v8, v9
	global_store_dwordx2 v[14:15], v[6:7], off offset:1024
	global_load_dwordx4 v[6:9], v[32:33], off offset:3072
	s_nop 0
	global_load_dwordx4 v[10:13], v[34:35], off offset:3072
	s_waitcnt vmcnt(1)
	v_pk_mul_f32 v[2:3], v[6:7], v[2:3]
	global_load_dwordx4 v[16:19], v[16:17], off
	v_pk_mul_f32 v[4:5], v[8:9], v[4:5]
	s_waitcnt vmcnt(0)
	v_pk_add_f32 v[6:7], v[16:17], 1.0 op_sel_hi:[1,0]
	s_nop 0
	v_pk_fma_f32 v[2:3], v[2:3], v[6:7], v[10:11]
	v_pk_add_f32 v[6:7], v[18:19], 1.0 op_sel_hi:[1,0]
	v_cvt_pk_bf16_f32 v2, v2, v3
	v_pk_fma_f32 v[4:5], v[4:5], v[6:7], v[12:13]
	s_nop 0
	v_cvt_pk_bf16_f32 v3, v4, v5
	global_store_dwordx2 v[14:15], v[2:3], off offset:1536
